# gather token epilogue (LayerNorm2): all eight gamma/beta loads issued together before the reductions into idle gather slots (3 fewer load-wait round trips per token)
# speedup vs baseline: 1.0050x; 1.0050x over previous
; __device__ void peer_gather_phase(const Params& P, int l, bool do_store) {
;     ...
;         const int ea = __builtin_amdgcn_readlane(evs, kb + 2 * pr), eb = __builtin_amdgcn_readlane(evs, kb + 2 * pr + 1);
;         const uint2* up = (const uint2*)(U + (size_t)(uphi ? eb : ea) * 768);
;         u6[3 * pr] = up[0]; u6[3 * pr + 1] = up[1]; u6[3 * pr + 2] = up[2];
;         v8[2 * pr] = *(const uint2*)(V + (size_t)ea * 512);
;         v8[2 * pr + 1] = *(const uint2*)(V + (size_t)eb * 512);
;       }
;     };
;     auto compute_batch = [&](const uint2 (&u6)[12], const uint2 (&v8)[8], int bt) {
;       const int kb = (bt & 7) * 8;
;       float dvec = 0.f;
; #pragma unroll
;       for (int pr = 0; pr < 4; ++pr) {
;         v6u_t qv; qv[0] = u6[3 * pr].x; qv[1] = u6[3 * pr].y; qv[2] = u6[3 * pr + 1].x; qv[3] = u6[3 * pr + 1].y; qv[4] = u6[3 * pr + 2].x; qv[5] = u6[3 * pr + 2].y;
;         const v32f_t wv = __builtin_amdgcn_cvt_scalef32_pk32_f32_fp6(qv, 1.0f);
;         f32x2 a2 = f32x2{0.f, 0.f};
; #pragma unroll
;         for (int i = 0; i < 16; ++i) a2 += f32x2{wv[2 * i], wv[2 * i + 1]} * xu[i];
;         float hs = a2.x + a2.y;
;         hs += dpp_row_shr(hs, 1); hs += dpp_row_shr(hs, 2); hs += dpp_row_shr(hs, 4); hs += dpp_row_shr(hs, 8);
;         hs += __builtin_bit_cast(float, __builtin_amdgcn_update_dpp(0, __builtin_bit_cast(int, hs), 0x142, 0xa, 0xf, false));
;         const float da = __builtin_bit_cast(float, __builtin_amdgcn_readlane(__builtin_bit_cast(int, hs), 31));
;         const float db = __builtin_bit_cast(float, __builtin_amdgcn_readlane(__builtin_bit_cast(int, hs), 63));
;         dvec = (lane == kb + 2 * pr) ? da : dvec;
;         dvec = (lane == kb + 2 * pr + 1) ? db : dvec;
;       }
.LBB0_22:
	v_readlane_b32 s54, v92, 16
	v_readlane_b32 s55, v92, 17
	s_mul_i32 s0, s54, 0x300
	s_mul_i32 s1, s55, 0x300
	v_add_u32_e32 v167, s0, v195
	s_and_saveexec_b64 s[98:99], s[40:41]
	v_add_u32_e32 v167, s1, v195
	s_mov_b64 exec, s[98:99]
	s_waitcnt vmcnt(32)
	v_cvt_scalef32_pk32_f32_fp6 v[0:31], v[50:55], 1.0
	global_load_dwordx2 v[54:55], v167, s[62:63] offset:16
	global_load_dwordx4 v[50:53], v167, s[62:63]
	v_pk_mul_f32 v[246:247], v[0:1], v[96:97]
	v_pk_mul_f32 v[254:255], v[2:3], v[98:99]
	v_pk_mul_f32 v[160:161], v[4:5], v[100:101]
	v_pk_fma_f32 v[246:247], v[6:7], v[102:103], v[246:247]
	v_pk_fma_f32 v[254:255], v[8:9], v[104:105], v[254:255]
	v_pk_fma_f32 v[160:161], v[10:11], v[106:107], v[160:161]
	v_pk_fma_f32 v[246:247], v[12:13], v[108:109], v[246:247]
	v_pk_fma_f32 v[254:255], v[14:15], v[110:111], v[254:255]
	v_pk_fma_f32 v[160:161], v[16:17], v[112:113], v[160:161]
	v_pk_fma_f32 v[246:247], v[18:19], v[114:115], v[246:247]
	v_pk_fma_f32 v[254:255], v[20:21], v[116:117], v[254:255]
	v_pk_fma_f32 v[160:161], v[22:23], v[118:119], v[160:161]
	v_pk_fma_f32 v[246:247], v[24:25], v[120:121], v[246:247]
	v_pk_fma_f32 v[254:255], v[26:27], v[122:123], v[254:255]
	v_pk_fma_f32 v[160:161], v[28:29], v[124:125], v[160:161]
	v_pk_fma_f32 v[246:247], v[30:31], v[126:127], v[246:247]
	v_pk_add_f32 v[254:255], v[254:255], v[160:161]
	s_nop 0
	v_pk_add_f32 v[246:247], v[246:247], v[254:255]
	s_nop 0
	v_add_f32_e32 v162, v246, v247
	v_readlane_b32 s54, v92, 18
	v_readlane_b32 s55, v92, 19
	s_mul_i32 s0, s54, 0x300
	s_mul_i32 s1, s55, 0x300
	v_add_u32_e32 v167, s0, v195
	s_and_saveexec_b64 s[98:99], s[40:41]
	v_add_u32_e32 v167, s1, v195
	s_mov_b64 exec, s[98:99]
	s_waitcnt vmcnt(32)
	v_cvt_scalef32_pk32_f32_fp6 v[0:31], v[44:49], 1.0
	global_load_dwordx2 v[48:49], v167, s[62:63] offset:16
	global_load_dwordx4 v[44:47], v167, s[62:63]
	v_pk_mul_f32 v[246:247], v[0:1], v[96:97]
	v_pk_mul_f32 v[254:255], v[2:3], v[98:99]
	v_pk_mul_f32 v[160:161], v[4:5], v[100:101]
	v_pk_fma_f32 v[246:247], v[6:7], v[102:103], v[246:247]
	v_pk_fma_f32 v[254:255], v[8:9], v[104:105], v[254:255]
	v_pk_fma_f32 v[160:161], v[10:11], v[106:107], v[160:161]
	v_pk_fma_f32 v[246:247], v[12:13], v[108:109], v[246:247]
	v_pk_fma_f32 v[254:255], v[14:15], v[110:111], v[254:255]
	v_pk_fma_f32 v[160:161], v[16:17], v[112:113], v[160:161]
	v_pk_fma_f32 v[246:247], v[18:19], v[114:115], v[246:247]
	v_pk_fma_f32 v[254:255], v[20:21], v[116:117], v[254:255]
	v_pk_fma_f32 v[160:161], v[22:23], v[118:119], v[160:161]
	v_pk_fma_f32 v[246:247], v[24:25], v[120:121], v[246:247]
	v_pk_fma_f32 v[254:255], v[26:27], v[122:123], v[254:255]
	v_pk_fma_f32 v[160:161], v[28:29], v[124:125], v[160:161]
	v_pk_fma_f32 v[246:247], v[30:31], v[126:127], v[246:247]
	v_pk_add_f32 v[254:255], v[254:255], v[160:161]
	s_nop 0
	v_pk_add_f32 v[246:247], v[246:247], v[254:255]
	s_nop 0
	v_add_f32_e32 v163, v246, v247
	v_readlane_b32 s54, v92, 20
	v_readlane_b32 s55, v92, 21
	s_mul_i32 s0, s54, 0x300
	s_mul_i32 s1, s55, 0x300
	v_add_u32_e32 v167, s0, v195
	s_and_saveexec_b64 s[98:99], s[40:41]
	v_add_u32_e32 v167, s1, v195
	s_mov_b64 exec, s[98:99]
	s_waitcnt vmcnt(32)
	v_cvt_scalef32_pk32_f32_fp6 v[0:31], v[38:43], 1.0
	global_load_dwordx2 v[42:43], v167, s[62:63] offset:16
	global_load_dwordx4 v[38:41], v167, s[62:63]
	v_pk_mul_f32 v[246:247], v[0:1], v[96:97]
	v_pk_mul_f32 v[254:255], v[2:3], v[98:99]
	v_pk_mul_f32 v[160:161], v[4:5], v[100:101]
	v_pk_fma_f32 v[246:247], v[6:7], v[102:103], v[246:247]
	v_pk_fma_f32 v[254:255], v[8:9], v[104:105], v[254:255]
	v_pk_fma_f32 v[160:161], v[10:11], v[106:107], v[160:161]
	v_pk_fma_f32 v[246:247], v[12:13], v[108:109], v[246:247]
	v_pk_fma_f32 v[254:255], v[14:15], v[110:111], v[254:255]
	v_pk_fma_f32 v[160:161], v[16:17], v[112:113], v[160:161]
	v_pk_fma_f32 v[246:247], v[18:19], v[114:115], v[246:247]
	v_pk_fma_f32 v[254:255], v[20:21], v[116:117], v[254:255]
	v_pk_fma_f32 v[160:161], v[22:23], v[118:119], v[160:161]
	v_pk_fma_f32 v[246:247], v[24:25], v[120:121], v[246:247]
	v_pk_fma_f32 v[254:255], v[26:27], v[122:123], v[254:255]
	v_pk_fma_f32 v[160:161], v[28:29], v[124:125], v[160:161]
	v_pk_fma_f32 v[246:247], v[30:31], v[126:127], v[246:247]
	v_pk_add_f32 v[254:255], v[254:255], v[160:161]
	s_nop 0
	v_pk_add_f32 v[246:247], v[246:247], v[254:255]
	s_nop 0
	v_add_f32_e32 v164, v246, v247
	v_readlane_b32 s54, v92, 22
	v_readlane_b32 s55, v92, 23
	s_mul_i32 s0, s54, 0x300
	s_mul_i32 s1, s55, 0x300
	v_add_u32_e32 v167, s0, v195
	s_and_saveexec_b64 s[98:99], s[40:41]
	v_add_u32_e32 v167, s1, v195
	s_mov_b64 exec, s[98:99]
	s_waitcnt vmcnt(32)
; __device__ void peer_gather_phase(const Params& P, int l, bool do_store) {
;     ...
;         const int ea = __builtin_amdgcn_readlane(evs, kb + 2 * pr), eb = __builtin_amdgcn_readlane(evs, kb + 2 * pr + 1);
;         const uint2* up = (const uint2*)(U + (size_t)(uphi ? eb : ea) * 768);
;         u6[3 * pr] = up[0]; u6[3 * pr + 1] = up[1]; u6[3 * pr + 2] = up[2];
;         v8[2 * pr] = *(const uint2*)(V + (size_t)ea * 512);
;         v8[2 * pr + 1] = *(const uint2*)(V + (size_t)eb * 512);
;       }
;     };
;     auto compute_batch = [&](const uint2 (&u6)[12], const uint2 (&v8)[8], int bt) {
;       const int kb = (bt & 7) * 8;
;       float dvec = 0.f;
; #pragma unroll
;       for (int pr = 0; pr < 4; ++pr) {
;         v6u_t qv; qv[0] = u6[3 * pr].x; qv[1] = u6[3 * pr].y; qv[2] = u6[3 * pr + 1].x; qv[3] = u6[3 * pr + 1].y; qv[4] = u6[3 * pr + 2].x; qv[5] = u6[3 * pr + 2].y;
;         const v32f_t wv = __builtin_amdgcn_cvt_scalef32_pk32_f32_fp6(qv, 1.0f);
;         f32x2 a2 = f32x2{0.f, 0.f};
; #pragma unroll
;         for (int i = 0; i < 16; ++i) a2 += f32x2{wv[2 * i], wv[2 * i + 1]} * xu[i];
;         float hs = a2.x + a2.y;
;         hs += dpp_row_shr(hs, 1); hs += dpp_row_shr(hs, 2); hs += dpp_row_shr(hs, 4); hs += dpp_row_shr(hs, 8);
;         hs += __builtin_bit_cast(float, __builtin_amdgcn_update_dpp(0, __builtin_bit_cast(int, hs), 0x142, 0xa, 0xf, false));
;         const float da = __builtin_bit_cast(float, __builtin_amdgcn_readlane(__builtin_bit_cast(int, hs), 31));
;         const float db = __builtin_bit_cast(float, __builtin_amdgcn_readlane(__builtin_bit_cast(int, hs), 63));
;         dvec = (lane == kb + 2 * pr) ? da : dvec;
;         dvec = (lane == kb + 2 * pr + 1) ? db : dvec;
;       }
	v_cvt_scalef32_pk32_f32_fp6 v[0:31], v[32:37], 1.0
	global_load_dwordx2 v[36:37], v167, s[62:63] offset:16
	global_load_dwordx4 v[32:35], v167, s[62:63]
	v_pk_mul_f32 v[246:247], v[0:1], v[96:97]
	v_pk_mul_f32 v[254:255], v[2:3], v[98:99]
	v_pk_mul_f32 v[160:161], v[4:5], v[100:101]
	v_pk_fma_f32 v[246:247], v[6:7], v[102:103], v[246:247]
	v_pk_fma_f32 v[254:255], v[8:9], v[104:105], v[254:255]
	v_pk_fma_f32 v[160:161], v[10:11], v[106:107], v[160:161]
	v_pk_fma_f32 v[246:247], v[12:13], v[108:109], v[246:247]
	v_pk_fma_f32 v[254:255], v[14:15], v[110:111], v[254:255]
	v_pk_fma_f32 v[160:161], v[16:17], v[112:113], v[160:161]
	v_pk_fma_f32 v[246:247], v[18:19], v[114:115], v[246:247]
	v_pk_fma_f32 v[254:255], v[20:21], v[116:117], v[254:255]
	v_pk_fma_f32 v[160:161], v[22:23], v[118:119], v[160:161]
	v_pk_fma_f32 v[246:247], v[24:25], v[120:121], v[246:247]
	v_pk_fma_f32 v[254:255], v[26:27], v[122:123], v[254:255]
	v_pk_fma_f32 v[160:161], v[28:29], v[124:125], v[160:161]
	v_pk_fma_f32 v[246:247], v[30:31], v[126:127], v[246:247]
	v_pk_add_f32 v[254:255], v[254:255], v[160:161]
	s_nop 0
	v_pk_add_f32 v[246:247], v[246:247], v[254:255]
	s_nop 0
	v_add_f32_e32 v165, v246, v247
	v_add_f32_dpp v162, v162, v162 row_shr:1 row_mask:0xf bank_mask:0xf bound_ctrl:1
	v_add_f32_dpp v163, v163, v163 row_shr:1 row_mask:0xf bank_mask:0xf bound_ctrl:1
	v_add_f32_dpp v164, v164, v164 row_shr:1 row_mask:0xf bank_mask:0xf bound_ctrl:1
	v_add_f32_dpp v165, v165, v165 row_shr:1 row_mask:0xf bank_mask:0xf bound_ctrl:1
	v_add_f32_dpp v162, v162, v162 row_shr:2 row_mask:0xf bank_mask:0xf bound_ctrl:1
	v_add_f32_dpp v163, v163, v163 row_shr:2 row_mask:0xf bank_mask:0xf bound_ctrl:1
	v_add_f32_dpp v164, v164, v164 row_shr:2 row_mask:0xf bank_mask:0xf bound_ctrl:1
	v_add_f32_dpp v165, v165, v165 row_shr:2 row_mask:0xf bank_mask:0xf bound_ctrl:1
	v_add_f32_dpp v162, v162, v162 row_shr:4 row_mask:0xf bank_mask:0xf bound_ctrl:1
	v_add_f32_dpp v163, v163, v163 row_shr:4 row_mask:0xf bank_mask:0xf bound_ctrl:1
	v_add_f32_dpp v164, v164, v164 row_shr:4 row_mask:0xf bank_mask:0xf bound_ctrl:1
	v_add_f32_dpp v165, v165, v165 row_shr:4 row_mask:0xf bank_mask:0xf bound_ctrl:1
	v_add_f32_dpp v162, v162, v162 row_shr:8 row_mask:0xf bank_mask:0xf bound_ctrl:1
	v_add_f32_dpp v163, v163, v163 row_shr:8 row_mask:0xf bank_mask:0xf bound_ctrl:1
	v_add_f32_dpp v164, v164, v164 row_shr:8 row_mask:0xf bank_mask:0xf bound_ctrl:1
	v_add_f32_dpp v165, v165, v165 row_shr:8 row_mask:0xf bank_mask:0xf bound_ctrl:1
	v_add_f32_dpp v162, v162, v162 row_bcast:15 row_mask:0xa bank_mask:0xf
	v_add_f32_dpp v163, v163, v163 row_bcast:15 row_mask:0xa bank_mask:0xf
	v_add_f32_dpp v164, v164, v164 row_bcast:15 row_mask:0xa bank_mask:0xf
	v_add_f32_dpp v165, v165, v165 row_bcast:15 row_mask:0xa bank_mask:0xf
	s_nop 1
	v_readlane_b32 s46, v162, 31
	v_readlane_b32 s47, v162, 63
	v_readlane_b32 s48, v163, 31
	v_readlane_b32 s49, v163, 63
	v_readlane_b32 s50, v164, 31
	v_readlane_b32 s51, v164, 63
	v_readlane_b32 s52, v165, 31
	v_readlane_b32 s53, v165, 63
	v_writelane_b32 v166, s46, 0
	s_nop 1
	v_writelane_b32 v166, s47, 1
	v_writelane_b32 v166, s48, 2
	v_writelane_b32 v166, s49, 3
	v_writelane_b32 v166, s50, 4
	v_writelane_b32 v166, s51, 5
	v_writelane_b32 v166, s52, 6
	v_writelane_b32 v166, s53, 7
	v_readlane_b32 s54, v92, 24
	v_readlane_b32 s55, v92, 25
	s_mul_i32 s0, s54, 0x300
	s_mul_i32 s1, s55, 0x300
	v_add_u32_e32 v167, s0, v195
	s_and_saveexec_b64 s[98:99], s[40:41]
	v_add_u32_e32 v167, s1, v195
	s_mov_b64 exec, s[98:99]
	s_waitcnt vmcnt(32)
	v_cvt_scalef32_pk32_f32_fp6 v[0:31], v[196:201], 1.0
	global_load_dwordx2 v[200:201], v167, s[62:63] offset:16
	global_load_dwordx4 v[196:199], v167, s[62:63]
	v_pk_mul_f32 v[246:247], v[0:1], v[96:97]
	v_pk_mul_f32 v[254:255], v[2:3], v[98:99]
	v_pk_mul_f32 v[160:161], v[4:5], v[100:101]
	v_pk_fma_f32 v[246:247], v[6:7], v[102:103], v[246:247]
	v_pk_fma_f32 v[254:255], v[8:9], v[104:105], v[254:255]
	v_pk_fma_f32 v[160:161], v[10:11], v[106:107], v[160:161]
	v_pk_fma_f32 v[246:247], v[12:13], v[108:109], v[246:247]
	v_pk_fma_f32 v[254:255], v[14:15], v[110:111], v[254:255]
	v_pk_fma_f32 v[160:161], v[16:17], v[112:113], v[160:161]
	v_pk_fma_f32 v[246:247], v[18:19], v[114:115], v[246:247]
	v_pk_fma_f32 v[254:255], v[20:21], v[116:117], v[254:255]
	v_pk_fma_f32 v[160:161], v[22:23], v[118:119], v[160:161]
	v_pk_fma_f32 v[246:247], v[24:25], v[120:121], v[246:247]
	v_pk_fma_f32 v[254:255], v[26:27], v[122:123], v[254:255]
	v_pk_fma_f32 v[160:161], v[28:29], v[124:125], v[160:161]
	v_pk_fma_f32 v[246:247], v[30:31], v[126:127], v[246:247]
	v_pk_add_f32 v[254:255], v[254:255], v[160:161]
	s_nop 0
	v_pk_add_f32 v[246:247], v[246:247], v[254:255]
	s_nop 0
	v_add_f32_e32 v162, v246, v247
	v_readlane_b32 s54, v92, 26
	v_readlane_b32 s55, v92, 27
	s_mul_i32 s0, s54, 0x300
	s_mul_i32 s1, s55, 0x300
	v_add_u32_e32 v167, s0, v195
	s_and_saveexec_b64 s[98:99], s[40:41]
	v_add_u32_e32 v167, s1, v195
	s_mov_b64 exec, s[98:99]
	s_waitcnt vmcnt(32)
; __device__ void peer_gather_phase(const Params& P, int l, bool do_store) {
;     ...
;         const int ea = __builtin_amdgcn_readlane(evs, kb + 2 * pr), eb = __builtin_amdgcn_readlane(evs, kb + 2 * pr + 1);
;         const uint2* up = (const uint2*)(U + (size_t)(uphi ? eb : ea) * 768);
;         u6[3 * pr] = up[0]; u6[3 * pr + 1] = up[1]; u6[3 * pr + 2] = up[2];
;         v8[2 * pr] = *(const uint2*)(V + (size_t)ea * 512);
;         v8[2 * pr + 1] = *(const uint2*)(V + (size_t)eb * 512);
;       }
;     };
;     auto compute_batch = [&](const uint2 (&u6)[12], const uint2 (&v8)[8], int bt) {
;       const int kb = (bt & 7) * 8;
;       float dvec = 0.f;
; #pragma unroll
;       for (int pr = 0; pr < 4; ++pr) {
;         v6u_t qv; qv[0] = u6[3 * pr].x; qv[1] = u6[3 * pr].y; qv[2] = u6[3 * pr + 1].x; qv[3] = u6[3 * pr + 1].y; qv[4] = u6[3 * pr + 2].x; qv[5] = u6[3 * pr + 2].y;
;         const v32f_t wv = __builtin_amdgcn_cvt_scalef32_pk32_f32_fp6(qv, 1.0f);
;         f32x2 a2 = f32x2{0.f, 0.f};
; #pragma unroll
;         for (int i = 0; i < 16; ++i) a2 += f32x2{wv[2 * i], wv[2 * i + 1]} * xu[i];
;         float hs = a2.x + a2.y;
;         hs += dpp_row_shr(hs, 1); hs += dpp_row_shr(hs, 2); hs += dpp_row_shr(hs, 4); hs += dpp_row_shr(hs, 8);
;         hs += __builtin_bit_cast(float, __builtin_amdgcn_update_dpp(0, __builtin_bit_cast(int, hs), 0x142, 0xa, 0xf, false));
;         const float da = __builtin_bit_cast(float, __builtin_amdgcn_readlane(__builtin_bit_cast(int, hs), 31));
;         const float db = __builtin_bit_cast(float, __builtin_amdgcn_readlane(__builtin_bit_cast(int, hs), 63));
;         dvec = (lane == kb + 2 * pr) ? da : dvec;
;         dvec = (lane == kb + 2 * pr + 1) ? db : dvec;
;       }
	v_cvt_scalef32_pk32_f32_fp6 v[0:31], v[228:233], 1.0
	global_load_dwordx2 v[232:233], v167, s[62:63] offset:16
	global_load_dwordx4 v[228:231], v167, s[62:63]
	v_pk_mul_f32 v[246:247], v[0:1], v[96:97]
	v_pk_mul_f32 v[254:255], v[2:3], v[98:99]
	v_pk_mul_f32 v[160:161], v[4:5], v[100:101]
	v_pk_fma_f32 v[246:247], v[6:7], v[102:103], v[246:247]
	v_pk_fma_f32 v[254:255], v[8:9], v[104:105], v[254:255]
	v_pk_fma_f32 v[160:161], v[10:11], v[106:107], v[160:161]
	v_pk_fma_f32 v[246:247], v[12:13], v[108:109], v[246:247]
	v_pk_fma_f32 v[254:255], v[14:15], v[110:111], v[254:255]
	v_pk_fma_f32 v[160:161], v[16:17], v[112:113], v[160:161]
	v_pk_fma_f32 v[246:247], v[18:19], v[114:115], v[246:247]
	v_pk_fma_f32 v[254:255], v[20:21], v[116:117], v[254:255]
	v_pk_fma_f32 v[160:161], v[22:23], v[118:119], v[160:161]
	v_pk_fma_f32 v[246:247], v[24:25], v[120:121], v[246:247]
	v_pk_fma_f32 v[254:255], v[26:27], v[122:123], v[254:255]
	v_pk_fma_f32 v[160:161], v[28:29], v[124:125], v[160:161]
	v_pk_fma_f32 v[246:247], v[30:31], v[126:127], v[246:247]
	v_pk_add_f32 v[254:255], v[254:255], v[160:161]
	s_nop 0
	v_pk_add_f32 v[246:247], v[246:247], v[254:255]
	s_nop 0
	v_add_f32_e32 v163, v246, v247
	v_readlane_b32 s54, v92, 28
	v_readlane_b32 s55, v92, 29
	s_mul_i32 s0, s54, 0x300
	s_mul_i32 s1, s55, 0x300
	v_add_u32_e32 v167, s0, v195
	s_and_saveexec_b64 s[98:99], s[40:41]
	v_add_u32_e32 v167, s1, v195
	s_mov_b64 exec, s[98:99]
	s_waitcnt vmcnt(32)
	v_cvt_scalef32_pk32_f32_fp6 v[0:31], v[234:239], 1.0
	global_load_dwordx2 v[238:239], v167, s[62:63] offset:16
	global_load_dwordx4 v[234:237], v167, s[62:63]
	v_pk_mul_f32 v[246:247], v[0:1], v[96:97]
	v_pk_mul_f32 v[254:255], v[2:3], v[98:99]
	v_pk_mul_f32 v[160:161], v[4:5], v[100:101]
	v_pk_fma_f32 v[246:247], v[6:7], v[102:103], v[246:247]
	v_pk_fma_f32 v[254:255], v[8:9], v[104:105], v[254:255]
	v_pk_fma_f32 v[160:161], v[10:11], v[106:107], v[160:161]
	v_pk_fma_f32 v[246:247], v[12:13], v[108:109], v[246:247]
	v_pk_fma_f32 v[254:255], v[14:15], v[110:111], v[254:255]
	v_pk_fma_f32 v[160:161], v[16:17], v[112:113], v[160:161]
	v_pk_fma_f32 v[246:247], v[18:19], v[114:115], v[246:247]
	v_pk_fma_f32 v[254:255], v[20:21], v[116:117], v[254:255]
	v_pk_fma_f32 v[160:161], v[22:23], v[118:119], v[160:161]
	v_pk_fma_f32 v[246:247], v[24:25], v[120:121], v[246:247]
	v_pk_fma_f32 v[254:255], v[26:27], v[122:123], v[254:255]
	v_pk_fma_f32 v[160:161], v[28:29], v[124:125], v[160:161]
	v_pk_fma_f32 v[246:247], v[30:31], v[126:127], v[246:247]
	v_pk_add_f32 v[254:255], v[254:255], v[160:161]
	s_nop 0
	v_pk_add_f32 v[246:247], v[246:247], v[254:255]
	s_nop 0
	v_add_f32_e32 v164, v246, v247
	v_readlane_b32 s54, v92, 30
	v_readlane_b32 s55, v92, 31
	s_mul_i32 s0, s54, 0x300
	s_mul_i32 s1, s55, 0x300
	v_add_u32_e32 v167, s0, v195
	s_and_saveexec_b64 s[98:99], s[40:41]
	v_add_u32_e32 v167, s1, v195
	s_mov_b64 exec, s[98:99]
	s_waitcnt vmcnt(32)
	v_cvt_scalef32_pk32_f32_fp6 v[0:31], v[240:245], 1.0
	global_load_dwordx2 v[244:245], v167, s[62:63] offset:16
	global_load_dwordx4 v[240:243], v167, s[62:63]
	v_pk_mul_f32 v[246:247], v[0:1], v[96:97]
	v_pk_mul_f32 v[254:255], v[2:3], v[98:99]
	v_pk_mul_f32 v[160:161], v[4:5], v[100:101]
	v_pk_fma_f32 v[246:247], v[6:7], v[102:103], v[246:247]
	v_pk_fma_f32 v[254:255], v[8:9], v[104:105], v[254:255]
	v_pk_fma_f32 v[160:161], v[10:11], v[106:107], v[160:161]
	v_pk_fma_f32 v[246:247], v[12:13], v[108:109], v[246:247]
	v_pk_fma_f32 v[254:255], v[14:15], v[110:111], v[254:255]
	v_pk_fma_f32 v[160:161], v[16:17], v[112:113], v[160:161]
	v_pk_fma_f32 v[246:247], v[18:19], v[114:115], v[246:247]
	v_pk_fma_f32 v[254:255], v[20:21], v[116:117], v[254:255]
	v_pk_fma_f32 v[160:161], v[22:23], v[118:119], v[160:161]
	v_pk_fma_f32 v[246:247], v[24:25], v[120:121], v[246:247]
	v_pk_fma_f32 v[254:255], v[26:27], v[122:123], v[254:255]
	v_pk_fma_f32 v[160:161], v[28:29], v[124:125], v[160:161]
	v_pk_fma_f32 v[246:247], v[30:31], v[126:127], v[246:247]
	v_pk_add_f32 v[254:255], v[254:255], v[160:161]
	s_nop 0
	v_pk_add_f32 v[246:247], v[246:247], v[254:255]
	s_nop 0
	v_add_f32_e32 v165, v246, v247
	v_add_f32_dpp v162, v162, v162 row_shr:1 row_mask:0xf bank_mask:0xf bound_ctrl:1
	v_add_f32_dpp v163, v163, v163 row_shr:1 row_mask:0xf bank_mask:0xf bound_ctrl:1
	v_add_f32_dpp v164, v164, v164 row_shr:1 row_mask:0xf bank_mask:0xf bound_ctrl:1
	v_add_f32_dpp v165, v165, v165 row_shr:1 row_mask:0xf bank_mask:0xf bound_ctrl:1
	v_add_f32_dpp v162, v162, v162 row_shr:2 row_mask:0xf bank_mask:0xf bound_ctrl:1
	v_add_f32_dpp v163, v163, v163 row_shr:2 row_mask:0xf bank_mask:0xf bound_ctrl:1
	v_add_f32_dpp v164, v164, v164 row_shr:2 row_mask:0xf bank_mask:0xf bound_ctrl:1
	v_add_f32_dpp v165, v165, v165 row_shr:2 row_mask:0xf bank_mask:0xf bound_ctrl:1
	v_add_f32_dpp v162, v162, v162 row_shr:4 row_mask:0xf bank_mask:0xf bound_ctrl:1
	v_add_f32_dpp v163, v163, v163 row_shr:4 row_mask:0xf bank_mask:0xf bound_ctrl:1
	v_add_f32_dpp v164, v164, v164 row_shr:4 row_mask:0xf bank_mask:0xf bound_ctrl:1
	v_add_f32_dpp v165, v165, v165 row_shr:4 row_mask:0xf bank_mask:0xf bound_ctrl:1
	v_add_f32_dpp v162, v162, v162 row_shr:8 row_mask:0xf bank_mask:0xf bound_ctrl:1
	v_add_f32_dpp v163, v163, v163 row_shr:8 row_mask:0xf bank_mask:0xf bound_ctrl:1
	v_add_f32_dpp v164, v164, v164 row_shr:8 row_mask:0xf bank_mask:0xf bound_ctrl:1
	v_add_f32_dpp v165, v165, v165 row_shr:8 row_mask:0xf bank_mask:0xf bound_ctrl:1
	v_add_f32_dpp v162, v162, v162 row_bcast:15 row_mask:0xa bank_mask:0xf
	v_add_f32_dpp v163, v163, v163 row_bcast:15 row_mask:0xa bank_mask:0xf
	v_add_f32_dpp v164, v164, v164 row_bcast:15 row_mask:0xa bank_mask:0xf
	v_add_f32_dpp v165, v165, v165 row_bcast:15 row_mask:0xa bank_mask:0xf
	s_nop 1
	v_readlane_b32 s46, v162, 31
	v_readlane_b32 s47, v162, 63
	v_readlane_b32 s48, v163, 31
	v_readlane_b32 s49, v163, 63
	v_readlane_b32 s50, v164, 31
	v_readlane_b32 s51, v164, 63
	v_readlane_b32 s52, v165, 31
	v_readlane_b32 s53, v165, 63
	v_writelane_b32 v166, s46, 8
	s_nop 1
	v_writelane_b32 v166, s47, 9
	v_writelane_b32 v166, s48, 10
	v_writelane_b32 v166, s49, 11
	v_writelane_b32 v166, s50, 12
	v_writelane_b32 v166, s51, 13
	v_writelane_b32 v166, s52, 14
	v_writelane_b32 v166, s53, 15
	v_readlane_b32 s54, v92, 32
	v_readlane_b32 s55, v92, 33
	s_mul_i32 s0, s54, 0x300
	s_mul_i32 s1, s55, 0x300
	v_add_u32_e32 v167, s0, v195
	s_and_saveexec_b64 s[98:99], s[40:41]
	v_add_u32_e32 v167, s1, v195
	s_mov_b64 exec, s[98:99]
	s_waitcnt vmcnt(14)
; __device__ void peer_gather_phase(const Params& P, int l, bool do_store) {
;     ...
;         const int ea = __builtin_amdgcn_readlane(evs, kb + 2 * pr), eb = __builtin_amdgcn_readlane(evs, kb + 2 * pr + 1);
;         const uint2* up = (const uint2*)(U + (size_t)(uphi ? eb : ea) * 768);
;         u6[3 * pr] = up[0]; u6[3 * pr + 1] = up[1]; u6[3 * pr + 2] = up[2];
;         v8[2 * pr] = *(const uint2*)(V + (size_t)ea * 512);
;         v8[2 * pr + 1] = *(const uint2*)(V + (size_t)eb * 512);
;       }
;     };
;     auto compute_batch = [&](const uint2 (&u6)[12], const uint2 (&v8)[8], int bt) {
;       const int kb = (bt & 7) * 8;
;       float dvec = 0.f;
; #pragma unroll
;       for (int pr = 0; pr < 4; ++pr) {
;         v6u_t qv; qv[0] = u6[3 * pr].x; qv[1] = u6[3 * pr].y; qv[2] = u6[3 * pr + 1].x; qv[3] = u6[3 * pr + 1].y; qv[4] = u6[3 * pr + 2].x; qv[5] = u6[3 * pr + 2].y;
;         const v32f_t wv = __builtin_amdgcn_cvt_scalef32_pk32_f32_fp6(qv, 1.0f);
;         f32x2 a2 = f32x2{0.f, 0.f};
; #pragma unroll
;         for (int i = 0; i < 16; ++i) a2 += f32x2{wv[2 * i], wv[2 * i + 1]} * xu[i];
;         float hs = a2.x + a2.y;
;         hs += dpp_row_shr(hs, 1); hs += dpp_row_shr(hs, 2); hs += dpp_row_shr(hs, 4); hs += dpp_row_shr(hs, 8);
;         hs += __builtin_bit_cast(float, __builtin_amdgcn_update_dpp(0, __builtin_bit_cast(int, hs), 0x142, 0xa, 0xf, false));
;         const float da = __builtin_bit_cast(float, __builtin_amdgcn_readlane(__builtin_bit_cast(int, hs), 31));
;         const float db = __builtin_bit_cast(float, __builtin_amdgcn_readlane(__builtin_bit_cast(int, hs), 63));
;         dvec = (lane == kb + 2 * pr) ? da : dvec;
;         dvec = (lane == kb + 2 * pr + 1) ? db : dvec;
;       }
	v_cvt_scalef32_pk32_f32_fp6 v[0:31], v[50:55], 1.0
	global_load_dwordx2 v[54:55], v167, s[62:63] offset:16
	global_load_dwordx4 v[50:53], v167, s[62:63]
	v_pk_mul_f32 v[246:247], v[0:1], v[96:97]
	v_pk_mul_f32 v[254:255], v[2:3], v[98:99]
	v_pk_mul_f32 v[160:161], v[4:5], v[100:101]
	v_pk_fma_f32 v[246:247], v[6:7], v[102:103], v[246:247]
	v_pk_fma_f32 v[254:255], v[8:9], v[104:105], v[254:255]
	v_pk_fma_f32 v[160:161], v[10:11], v[106:107], v[160:161]
	v_pk_fma_f32 v[246:247], v[12:13], v[108:109], v[246:247]
	v_pk_fma_f32 v[254:255], v[14:15], v[110:111], v[254:255]
	v_pk_fma_f32 v[160:161], v[16:17], v[112:113], v[160:161]
	v_pk_fma_f32 v[246:247], v[18:19], v[114:115], v[246:247]
	v_pk_fma_f32 v[254:255], v[20:21], v[116:117], v[254:255]
	v_pk_fma_f32 v[160:161], v[22:23], v[118:119], v[160:161]
	v_pk_fma_f32 v[246:247], v[24:25], v[120:121], v[246:247]
	v_pk_fma_f32 v[254:255], v[26:27], v[122:123], v[254:255]
	v_pk_fma_f32 v[160:161], v[28:29], v[124:125], v[160:161]
	v_pk_fma_f32 v[246:247], v[30:31], v[126:127], v[246:247]
	v_pk_add_f32 v[254:255], v[254:255], v[160:161]
	s_nop 0
	v_pk_add_f32 v[246:247], v[246:247], v[254:255]
	s_nop 0
	v_add_f32_e32 v162, v246, v247
	v_readlane_b32 s54, v92, 34
	v_readlane_b32 s55, v92, 35
	s_mul_i32 s0, s54, 0x300
	s_mul_i32 s1, s55, 0x300
	v_add_u32_e32 v167, s0, v195
	s_and_saveexec_b64 s[98:99], s[40:41]
	v_add_u32_e32 v167, s1, v195
	s_mov_b64 exec, s[98:99]
	s_waitcnt vmcnt(14)
	v_cvt_scalef32_pk32_f32_fp6 v[0:31], v[44:49], 1.0
	global_load_dwordx2 v[48:49], v167, s[62:63] offset:16
	global_load_dwordx4 v[44:47], v167, s[62:63]
	v_pk_mul_f32 v[246:247], v[0:1], v[96:97]
	v_pk_mul_f32 v[254:255], v[2:3], v[98:99]
	v_pk_mul_f32 v[160:161], v[4:5], v[100:101]
	v_pk_fma_f32 v[246:247], v[6:7], v[102:103], v[246:247]
	v_pk_fma_f32 v[254:255], v[8:9], v[104:105], v[254:255]
	v_pk_fma_f32 v[160:161], v[10:11], v[106:107], v[160:161]
	v_pk_fma_f32 v[246:247], v[12:13], v[108:109], v[246:247]
	v_pk_fma_f32 v[254:255], v[14:15], v[110:111], v[254:255]
	v_pk_fma_f32 v[160:161], v[16:17], v[112:113], v[160:161]
	v_pk_fma_f32 v[246:247], v[18:19], v[114:115], v[246:247]
	v_pk_fma_f32 v[254:255], v[20:21], v[116:117], v[254:255]
	v_pk_fma_f32 v[160:161], v[22:23], v[118:119], v[160:161]
	v_pk_fma_f32 v[246:247], v[24:25], v[120:121], v[246:247]
	v_pk_fma_f32 v[254:255], v[26:27], v[122:123], v[254:255]
	v_pk_fma_f32 v[160:161], v[28:29], v[124:125], v[160:161]
	v_pk_fma_f32 v[246:247], v[30:31], v[126:127], v[246:247]
	v_pk_add_f32 v[254:255], v[254:255], v[160:161]
	s_nop 0
	v_pk_add_f32 v[246:247], v[246:247], v[254:255]
	s_nop 0
	v_add_f32_e32 v163, v246, v247
	v_readlane_b32 s54, v92, 36
	v_readlane_b32 s55, v92, 37
	s_mul_i32 s0, s54, 0x300
	s_mul_i32 s1, s55, 0x300
	v_add_u32_e32 v167, s0, v195
	s_and_saveexec_b64 s[98:99], s[40:41]
	v_add_u32_e32 v167, s1, v195
	s_mov_b64 exec, s[98:99]
	s_waitcnt vmcnt(14)
	v_cvt_scalef32_pk32_f32_fp6 v[0:31], v[38:43], 1.0
	global_load_dwordx2 v[42:43], v167, s[62:63] offset:16
	global_load_dwordx4 v[38:41], v167, s[62:63]
	v_pk_mul_f32 v[246:247], v[0:1], v[96:97]
	v_pk_mul_f32 v[254:255], v[2:3], v[98:99]
	v_pk_mul_f32 v[160:161], v[4:5], v[100:101]
	v_pk_fma_f32 v[246:247], v[6:7], v[102:103], v[246:247]
	v_pk_fma_f32 v[254:255], v[8:9], v[104:105], v[254:255]
	v_pk_fma_f32 v[160:161], v[10:11], v[106:107], v[160:161]
	v_pk_fma_f32 v[246:247], v[12:13], v[108:109], v[246:247]
	v_pk_fma_f32 v[254:255], v[14:15], v[110:111], v[254:255]
	v_pk_fma_f32 v[160:161], v[16:17], v[112:113], v[160:161]
	v_pk_fma_f32 v[246:247], v[18:19], v[114:115], v[246:247]
	v_pk_fma_f32 v[254:255], v[20:21], v[116:117], v[254:255]
	v_pk_fma_f32 v[160:161], v[22:23], v[118:119], v[160:161]
	v_pk_fma_f32 v[246:247], v[24:25], v[120:121], v[246:247]
	v_pk_fma_f32 v[254:255], v[26:27], v[122:123], v[254:255]
	v_pk_fma_f32 v[160:161], v[28:29], v[124:125], v[160:161]
	v_pk_fma_f32 v[246:247], v[30:31], v[126:127], v[246:247]
	v_pk_add_f32 v[254:255], v[254:255], v[160:161]
	s_nop 0
	v_pk_add_f32 v[246:247], v[246:247], v[254:255]
	s_nop 0
	v_add_f32_e32 v164, v246, v247
	v_readlane_b32 s54, v92, 38
	v_readlane_b32 s55, v92, 39
	s_mul_i32 s0, s54, 0x300
	s_mul_i32 s1, s55, 0x300
	v_add_u32_e32 v167, s0, v195
	s_and_saveexec_b64 s[98:99], s[40:41]
	v_add_u32_e32 v167, s1, v195
	s_mov_b64 exec, s[98:99]
	s_waitcnt vmcnt(14)
; __device__ void peer_gather_phase(const Params& P, int l, bool do_store) {
;     ...
;         const int ea = __builtin_amdgcn_readlane(evs, kb + 2 * pr), eb = __builtin_amdgcn_readlane(evs, kb + 2 * pr + 1);
;         const uint2* up = (const uint2*)(U + (size_t)(uphi ? eb : ea) * 768);
;         u6[3 * pr] = up[0]; u6[3 * pr + 1] = up[1]; u6[3 * pr + 2] = up[2];
;         v8[2 * pr] = *(const uint2*)(V + (size_t)ea * 512);
;         v8[2 * pr + 1] = *(const uint2*)(V + (size_t)eb * 512);
;       }
;     };
;     auto compute_batch = [&](const uint2 (&u6)[12], const uint2 (&v8)[8], int bt) {
;       const int kb = (bt & 7) * 8;
;       float dvec = 0.f;
; #pragma unroll
;       for (int pr = 0; pr < 4; ++pr) {
;         v6u_t qv; qv[0] = u6[3 * pr].x; qv[1] = u6[3 * pr].y; qv[2] = u6[3 * pr + 1].x; qv[3] = u6[3 * pr + 1].y; qv[4] = u6[3 * pr + 2].x; qv[5] = u6[3 * pr + 2].y;
;         const v32f_t wv = __builtin_amdgcn_cvt_scalef32_pk32_f32_fp6(qv, 1.0f);
;         f32x2 a2 = f32x2{0.f, 0.f};
; #pragma unroll
;         for (int i = 0; i < 16; ++i) a2 += f32x2{wv[2 * i], wv[2 * i + 1]} * xu[i];
;         float hs = a2.x + a2.y;
;         hs += dpp_row_shr(hs, 1); hs += dpp_row_shr(hs, 2); hs += dpp_row_shr(hs, 4); hs += dpp_row_shr(hs, 8);
;         hs += __builtin_bit_cast(float, __builtin_amdgcn_update_dpp(0, __builtin_bit_cast(int, hs), 0x142, 0xa, 0xf, false));
;         const float da = __builtin_bit_cast(float, __builtin_amdgcn_readlane(__builtin_bit_cast(int, hs), 31));
;         const float db = __builtin_bit_cast(float, __builtin_amdgcn_readlane(__builtin_bit_cast(int, hs), 63));
;         dvec = (lane == kb + 2 * pr) ? da : dvec;
;         dvec = (lane == kb + 2 * pr + 1) ? db : dvec;
;       }
	v_cvt_scalef32_pk32_f32_fp6 v[0:31], v[32:37], 1.0
	global_load_dwordx2 v[36:37], v167, s[62:63] offset:16
	global_load_dwordx4 v[32:35], v167, s[62:63]
	v_pk_mul_f32 v[246:247], v[0:1], v[96:97]
	v_pk_mul_f32 v[254:255], v[2:3], v[98:99]
	v_pk_mul_f32 v[160:161], v[4:5], v[100:101]
	v_pk_fma_f32 v[246:247], v[6:7], v[102:103], v[246:247]
	v_pk_fma_f32 v[254:255], v[8:9], v[104:105], v[254:255]
	v_pk_fma_f32 v[160:161], v[10:11], v[106:107], v[160:161]
	v_pk_fma_f32 v[246:247], v[12:13], v[108:109], v[246:247]
	v_pk_fma_f32 v[254:255], v[14:15], v[110:111], v[254:255]
	v_pk_fma_f32 v[160:161], v[16:17], v[112:113], v[160:161]
	v_pk_fma_f32 v[246:247], v[18:19], v[114:115], v[246:247]
	v_pk_fma_f32 v[254:255], v[20:21], v[116:117], v[254:255]
	v_pk_fma_f32 v[160:161], v[22:23], v[118:119], v[160:161]
	v_pk_fma_f32 v[246:247], v[24:25], v[120:121], v[246:247]
	v_pk_fma_f32 v[254:255], v[26:27], v[122:123], v[254:255]
	v_pk_fma_f32 v[160:161], v[28:29], v[124:125], v[160:161]
	v_pk_fma_f32 v[246:247], v[30:31], v[126:127], v[246:247]
	v_pk_add_f32 v[254:255], v[254:255], v[160:161]
	s_nop 0
	v_pk_add_f32 v[246:247], v[246:247], v[254:255]
	s_nop 0
	v_add_f32_e32 v165, v246, v247
	v_add_f32_dpp v162, v162, v162 row_shr:1 row_mask:0xf bank_mask:0xf bound_ctrl:1
	v_add_f32_dpp v163, v163, v163 row_shr:1 row_mask:0xf bank_mask:0xf bound_ctrl:1
	v_add_f32_dpp v164, v164, v164 row_shr:1 row_mask:0xf bank_mask:0xf bound_ctrl:1
	v_add_f32_dpp v165, v165, v165 row_shr:1 row_mask:0xf bank_mask:0xf bound_ctrl:1
	v_add_f32_dpp v162, v162, v162 row_shr:2 row_mask:0xf bank_mask:0xf bound_ctrl:1
	v_add_f32_dpp v163, v163, v163 row_shr:2 row_mask:0xf bank_mask:0xf bound_ctrl:1
	v_add_f32_dpp v164, v164, v164 row_shr:2 row_mask:0xf bank_mask:0xf bound_ctrl:1
	v_add_f32_dpp v165, v165, v165 row_shr:2 row_mask:0xf bank_mask:0xf bound_ctrl:1
	v_add_f32_dpp v162, v162, v162 row_shr:4 row_mask:0xf bank_mask:0xf bound_ctrl:1
	v_add_f32_dpp v163, v163, v163 row_shr:4 row_mask:0xf bank_mask:0xf bound_ctrl:1
	v_add_f32_dpp v164, v164, v164 row_shr:4 row_mask:0xf bank_mask:0xf bound_ctrl:1
	v_add_f32_dpp v165, v165, v165 row_shr:4 row_mask:0xf bank_mask:0xf bound_ctrl:1
	v_add_f32_dpp v162, v162, v162 row_shr:8 row_mask:0xf bank_mask:0xf bound_ctrl:1
	v_add_f32_dpp v163, v163, v163 row_shr:8 row_mask:0xf bank_mask:0xf bound_ctrl:1
	v_add_f32_dpp v164, v164, v164 row_shr:8 row_mask:0xf bank_mask:0xf bound_ctrl:1
	v_add_f32_dpp v165, v165, v165 row_shr:8 row_mask:0xf bank_mask:0xf bound_ctrl:1
	v_add_f32_dpp v162, v162, v162 row_bcast:15 row_mask:0xa bank_mask:0xf
	v_add_f32_dpp v163, v163, v163 row_bcast:15 row_mask:0xa bank_mask:0xf
	v_add_f32_dpp v164, v164, v164 row_bcast:15 row_mask:0xa bank_mask:0xf
	v_add_f32_dpp v165, v165, v165 row_bcast:15 row_mask:0xa bank_mask:0xf
	s_nop 1
	v_readlane_b32 s46, v162, 31
	v_readlane_b32 s47, v162, 63
	v_readlane_b32 s48, v163, 31
	v_readlane_b32 s49, v163, 63
	v_readlane_b32 s50, v164, 31
	v_readlane_b32 s51, v164, 63
	v_readlane_b32 s52, v165, 31
	v_readlane_b32 s53, v165, 63
	v_writelane_b32 v166, s46, 16
	s_nop 1
	v_writelane_b32 v166, s47, 17
	v_writelane_b32 v166, s48, 18
	v_writelane_b32 v166, s49, 19
	v_writelane_b32 v166, s50, 20
	v_writelane_b32 v166, s51, 21
	v_writelane_b32 v166, s52, 22
	v_writelane_b32 v166, s53, 23
	v_readlane_b32 s54, v92, 40
	v_readlane_b32 s55, v92, 41
	s_mul_i32 s0, s54, 0x300
	s_mul_i32 s1, s55, 0x300
	v_add_u32_e32 v167, s0, v195
	s_and_saveexec_b64 s[98:99], s[40:41]
	v_add_u32_e32 v167, s1, v195
	s_mov_b64 exec, s[98:99]
	s_waitcnt vmcnt(14)
	v_cvt_scalef32_pk32_f32_fp6 v[0:31], v[196:201], 1.0
	global_load_dwordx2 v[200:201], v167, s[62:63] offset:16
	global_load_dwordx4 v[196:199], v167, s[62:63]
	v_pk_mul_f32 v[246:247], v[0:1], v[96:97]
	v_pk_mul_f32 v[254:255], v[2:3], v[98:99]
	v_pk_mul_f32 v[160:161], v[4:5], v[100:101]
	v_pk_fma_f32 v[246:247], v[6:7], v[102:103], v[246:247]
	v_pk_fma_f32 v[254:255], v[8:9], v[104:105], v[254:255]
	v_pk_fma_f32 v[160:161], v[10:11], v[106:107], v[160:161]
	v_pk_fma_f32 v[246:247], v[12:13], v[108:109], v[246:247]
	v_pk_fma_f32 v[254:255], v[14:15], v[110:111], v[254:255]
	v_pk_fma_f32 v[160:161], v[16:17], v[112:113], v[160:161]
	v_pk_fma_f32 v[246:247], v[18:19], v[114:115], v[246:247]
	v_pk_fma_f32 v[254:255], v[20:21], v[116:117], v[254:255]
	v_pk_fma_f32 v[160:161], v[22:23], v[118:119], v[160:161]
	v_pk_fma_f32 v[246:247], v[24:25], v[120:121], v[246:247]
	v_pk_fma_f32 v[254:255], v[26:27], v[122:123], v[254:255]
	v_pk_fma_f32 v[160:161], v[28:29], v[124:125], v[160:161]
	v_pk_fma_f32 v[246:247], v[30:31], v[126:127], v[246:247]
	v_pk_add_f32 v[254:255], v[254:255], v[160:161]
	s_nop 0
	v_pk_add_f32 v[246:247], v[246:247], v[254:255]
	s_nop 0
	v_add_f32_e32 v162, v246, v247
	v_readlane_b32 s54, v92, 42
	v_readlane_b32 s55, v92, 43
	s_mul_i32 s0, s54, 0x300
	s_mul_i32 s1, s55, 0x300
	v_add_u32_e32 v167, s0, v195
	s_and_saveexec_b64 s[98:99], s[40:41]
	v_add_u32_e32 v167, s1, v195
	s_mov_b64 exec, s[98:99]
	s_waitcnt vmcnt(14)
; __device__ void peer_gather_phase(const Params& P, int l, bool do_store) {
;     ...
;         const int ea = __builtin_amdgcn_readlane(evs, kb + 2 * pr), eb = __builtin_amdgcn_readlane(evs, kb + 2 * pr + 1);
;         const uint2* up = (const uint2*)(U + (size_t)(uphi ? eb : ea) * 768);
;         u6[3 * pr] = up[0]; u6[3 * pr + 1] = up[1]; u6[3 * pr + 2] = up[2];
;         v8[2 * pr] = *(const uint2*)(V + (size_t)ea * 512);
;         v8[2 * pr + 1] = *(const uint2*)(V + (size_t)eb * 512);
;       }
;     };
;     auto compute_batch = [&](const uint2 (&u6)[12], const uint2 (&v8)[8], int bt) {
;       const int kb = (bt & 7) * 8;
;       float dvec = 0.f;
; #pragma unroll
;       for (int pr = 0; pr < 4; ++pr) {
;         v6u_t qv; qv[0] = u6[3 * pr].x; qv[1] = u6[3 * pr].y; qv[2] = u6[3 * pr + 1].x; qv[3] = u6[3 * pr + 1].y; qv[4] = u6[3 * pr + 2].x; qv[5] = u6[3 * pr + 2].y;
;         const v32f_t wv = __builtin_amdgcn_cvt_scalef32_pk32_f32_fp6(qv, 1.0f);
;         f32x2 a2 = f32x2{0.f, 0.f};
; #pragma unroll
;         for (int i = 0; i < 16; ++i) a2 += f32x2{wv[2 * i], wv[2 * i + 1]} * xu[i];
;         float hs = a2.x + a2.y;
;         hs += dpp_row_shr(hs, 1); hs += dpp_row_shr(hs, 2); hs += dpp_row_shr(hs, 4); hs += dpp_row_shr(hs, 8);
;         hs += __builtin_bit_cast(float, __builtin_amdgcn_update_dpp(0, __builtin_bit_cast(int, hs), 0x142, 0xa, 0xf, false));
;         const float da = __builtin_bit_cast(float, __builtin_amdgcn_readlane(__builtin_bit_cast(int, hs), 31));
;         const float db = __builtin_bit_cast(float, __builtin_amdgcn_readlane(__builtin_bit_cast(int, hs), 63));
;         dvec = (lane == kb + 2 * pr) ? da : dvec;
;         dvec = (lane == kb + 2 * pr + 1) ? db : dvec;
;       }
	v_cvt_scalef32_pk32_f32_fp6 v[0:31], v[228:233], 1.0
	global_load_dwordx2 v[232:233], v167, s[62:63] offset:16
	global_load_dwordx4 v[228:231], v167, s[62:63]
	v_pk_mul_f32 v[246:247], v[0:1], v[96:97]
	v_pk_mul_f32 v[254:255], v[2:3], v[98:99]
	v_pk_mul_f32 v[160:161], v[4:5], v[100:101]
	v_pk_fma_f32 v[246:247], v[6:7], v[102:103], v[246:247]
	v_pk_fma_f32 v[254:255], v[8:9], v[104:105], v[254:255]
	v_pk_fma_f32 v[160:161], v[10:11], v[106:107], v[160:161]
	v_pk_fma_f32 v[246:247], v[12:13], v[108:109], v[246:247]
	v_pk_fma_f32 v[254:255], v[14:15], v[110:111], v[254:255]
	v_pk_fma_f32 v[160:161], v[16:17], v[112:113], v[160:161]
	v_pk_fma_f32 v[246:247], v[18:19], v[114:115], v[246:247]
	v_pk_fma_f32 v[254:255], v[20:21], v[116:117], v[254:255]
	v_pk_fma_f32 v[160:161], v[22:23], v[118:119], v[160:161]
	v_pk_fma_f32 v[246:247], v[24:25], v[120:121], v[246:247]
	v_pk_fma_f32 v[254:255], v[26:27], v[122:123], v[254:255]
	v_pk_fma_f32 v[160:161], v[28:29], v[124:125], v[160:161]
	v_pk_fma_f32 v[246:247], v[30:31], v[126:127], v[246:247]
	v_pk_add_f32 v[254:255], v[254:255], v[160:161]
	s_nop 0
	v_pk_add_f32 v[246:247], v[246:247], v[254:255]
	s_nop 0
	v_add_f32_e32 v163, v246, v247
	v_readlane_b32 s54, v92, 44
	v_readlane_b32 s55, v92, 45
	s_mul_i32 s0, s54, 0x300
	s_mul_i32 s1, s55, 0x300
	v_add_u32_e32 v167, s0, v195
	s_and_saveexec_b64 s[98:99], s[40:41]
	v_add_u32_e32 v167, s1, v195
	s_mov_b64 exec, s[98:99]
	s_waitcnt vmcnt(14)
	v_cvt_scalef32_pk32_f32_fp6 v[0:31], v[234:239], 1.0
	global_load_dwordx2 v[238:239], v167, s[62:63] offset:16
	global_load_dwordx4 v[234:237], v167, s[62:63]
	v_pk_mul_f32 v[246:247], v[0:1], v[96:97]
	v_pk_mul_f32 v[254:255], v[2:3], v[98:99]
	v_pk_mul_f32 v[160:161], v[4:5], v[100:101]
	v_pk_fma_f32 v[246:247], v[6:7], v[102:103], v[246:247]
	v_pk_fma_f32 v[254:255], v[8:9], v[104:105], v[254:255]
	v_pk_fma_f32 v[160:161], v[10:11], v[106:107], v[160:161]
	v_pk_fma_f32 v[246:247], v[12:13], v[108:109], v[246:247]
	v_pk_fma_f32 v[254:255], v[14:15], v[110:111], v[254:255]
	v_pk_fma_f32 v[160:161], v[16:17], v[112:113], v[160:161]
	v_pk_fma_f32 v[246:247], v[18:19], v[114:115], v[246:247]
	v_pk_fma_f32 v[254:255], v[20:21], v[116:117], v[254:255]
	v_pk_fma_f32 v[160:161], v[22:23], v[118:119], v[160:161]
	v_pk_fma_f32 v[246:247], v[24:25], v[120:121], v[246:247]
	v_pk_fma_f32 v[254:255], v[26:27], v[122:123], v[254:255]
	v_pk_fma_f32 v[160:161], v[28:29], v[124:125], v[160:161]
	v_pk_fma_f32 v[246:247], v[30:31], v[126:127], v[246:247]
	v_pk_add_f32 v[254:255], v[254:255], v[160:161]
	s_nop 0
	v_pk_add_f32 v[246:247], v[246:247], v[254:255]
	s_nop 0
	v_add_f32_e32 v164, v246, v247
	v_readlane_b32 s54, v92, 46
	v_readlane_b32 s55, v92, 47
	s_mul_i32 s0, s54, 0x300
	s_mul_i32 s1, s55, 0x300
	v_add_u32_e32 v167, s0, v195
	s_and_saveexec_b64 s[98:99], s[40:41]
	v_add_u32_e32 v167, s1, v195
	s_mov_b64 exec, s[98:99]
	s_waitcnt vmcnt(14)
	v_cvt_scalef32_pk32_f32_fp6 v[0:31], v[240:245], 1.0
	global_load_dwordx2 v[244:245], v167, s[62:63] offset:16
	global_load_dwordx4 v[240:243], v167, s[62:63]
	v_pk_mul_f32 v[246:247], v[0:1], v[96:97]
	v_pk_mul_f32 v[254:255], v[2:3], v[98:99]
	v_pk_mul_f32 v[160:161], v[4:5], v[100:101]
	v_pk_fma_f32 v[246:247], v[6:7], v[102:103], v[246:247]
	v_pk_fma_f32 v[254:255], v[8:9], v[104:105], v[254:255]
	v_pk_fma_f32 v[160:161], v[10:11], v[106:107], v[160:161]
	v_pk_fma_f32 v[246:247], v[12:13], v[108:109], v[246:247]
	v_pk_fma_f32 v[254:255], v[14:15], v[110:111], v[254:255]
	v_pk_fma_f32 v[160:161], v[16:17], v[112:113], v[160:161]
	v_pk_fma_f32 v[246:247], v[18:19], v[114:115], v[246:247]
	v_pk_fma_f32 v[254:255], v[20:21], v[116:117], v[254:255]
	v_pk_fma_f32 v[160:161], v[22:23], v[118:119], v[160:161]
	v_pk_fma_f32 v[246:247], v[24:25], v[120:121], v[246:247]
	v_pk_fma_f32 v[254:255], v[26:27], v[122:123], v[254:255]
	v_pk_fma_f32 v[160:161], v[28:29], v[124:125], v[160:161]
	v_pk_fma_f32 v[246:247], v[30:31], v[126:127], v[246:247]
	v_pk_add_f32 v[254:255], v[254:255], v[160:161]
	s_nop 0
	v_pk_add_f32 v[246:247], v[246:247], v[254:255]
	s_nop 0
	v_add_f32_e32 v165, v246, v247
	v_add_f32_dpp v162, v162, v162 row_shr:1 row_mask:0xf bank_mask:0xf bound_ctrl:1
	v_add_f32_dpp v163, v163, v163 row_shr:1 row_mask:0xf bank_mask:0xf bound_ctrl:1
	v_add_f32_dpp v164, v164, v164 row_shr:1 row_mask:0xf bank_mask:0xf bound_ctrl:1
	v_add_f32_dpp v165, v165, v165 row_shr:1 row_mask:0xf bank_mask:0xf bound_ctrl:1
	v_add_f32_dpp v162, v162, v162 row_shr:2 row_mask:0xf bank_mask:0xf bound_ctrl:1
	v_add_f32_dpp v163, v163, v163 row_shr:2 row_mask:0xf bank_mask:0xf bound_ctrl:1
	v_add_f32_dpp v164, v164, v164 row_shr:2 row_mask:0xf bank_mask:0xf bound_ctrl:1
	v_add_f32_dpp v165, v165, v165 row_shr:2 row_mask:0xf bank_mask:0xf bound_ctrl:1
	v_add_f32_dpp v162, v162, v162 row_shr:4 row_mask:0xf bank_mask:0xf bound_ctrl:1
	v_add_f32_dpp v163, v163, v163 row_shr:4 row_mask:0xf bank_mask:0xf bound_ctrl:1
	v_add_f32_dpp v164, v164, v164 row_shr:4 row_mask:0xf bank_mask:0xf bound_ctrl:1
	v_add_f32_dpp v165, v165, v165 row_shr:4 row_mask:0xf bank_mask:0xf bound_ctrl:1
	v_add_f32_dpp v162, v162, v162 row_shr:8 row_mask:0xf bank_mask:0xf bound_ctrl:1
	v_add_f32_dpp v163, v163, v163 row_shr:8 row_mask:0xf bank_mask:0xf bound_ctrl:1
	v_add_f32_dpp v164, v164, v164 row_shr:8 row_mask:0xf bank_mask:0xf bound_ctrl:1
	v_add_f32_dpp v165, v165, v165 row_shr:8 row_mask:0xf bank_mask:0xf bound_ctrl:1
	v_add_f32_dpp v162, v162, v162 row_bcast:15 row_mask:0xa bank_mask:0xf
	v_add_f32_dpp v163, v163, v163 row_bcast:15 row_mask:0xa bank_mask:0xf
	v_add_f32_dpp v164, v164, v164 row_bcast:15 row_mask:0xa bank_mask:0xf
	v_add_f32_dpp v165, v165, v165 row_bcast:15 row_mask:0xa bank_mask:0xf
	s_nop 1
	v_readlane_b32 s46, v162, 31
	v_readlane_b32 s47, v162, 63
	v_readlane_b32 s48, v163, 31
	v_readlane_b32 s49, v163, 63
	v_readlane_b32 s50, v164, 31
	v_readlane_b32 s51, v164, 63
	v_readlane_b32 s52, v165, 31
	v_readlane_b32 s53, v165, 63
	v_writelane_b32 v166, s46, 24
	s_nop 1
	v_writelane_b32 v166, s47, 25
	v_writelane_b32 v166, s48, 26
	v_writelane_b32 v166, s49, 27
	v_writelane_b32 v166, s50, 28
	v_writelane_b32 v166, s51, 29
	v_writelane_b32 v166, s52, 30
	v_writelane_b32 v166, s53, 31
	v_readlane_b32 s54, v92, 48
	v_readlane_b32 s55, v92, 49
	s_mul_i32 s0, s54, 0x300
	s_mul_i32 s1, s55, 0x300
	v_add_u32_e32 v167, s0, v195
	s_and_saveexec_b64 s[98:99], s[40:41]
	v_add_u32_e32 v167, s1, v195
	s_mov_b64 exec, s[98:99]
	s_waitcnt vmcnt(14)
; __device__ void peer_gather_phase(const Params& P, int l, bool do_store) {
;     ...
;         const int ea = __builtin_amdgcn_readlane(evs, kb + 2 * pr), eb = __builtin_amdgcn_readlane(evs, kb + 2 * pr + 1);
;         const uint2* up = (const uint2*)(U + (size_t)(uphi ? eb : ea) * 768);
;         u6[3 * pr] = up[0]; u6[3 * pr + 1] = up[1]; u6[3 * pr + 2] = up[2];
;         v8[2 * pr] = *(const uint2*)(V + (size_t)ea * 512);
;         v8[2 * pr + 1] = *(const uint2*)(V + (size_t)eb * 512);
;       }
;     };
;     auto compute_batch = [&](const uint2 (&u6)[12], const uint2 (&v8)[8], int bt) {
;       const int kb = (bt & 7) * 8;
;       float dvec = 0.f;
; #pragma unroll
;       for (int pr = 0; pr < 4; ++pr) {
;         v6u_t qv; qv[0] = u6[3 * pr].x; qv[1] = u6[3 * pr].y; qv[2] = u6[3 * pr + 1].x; qv[3] = u6[3 * pr + 1].y; qv[4] = u6[3 * pr + 2].x; qv[5] = u6[3 * pr + 2].y;
;         const v32f_t wv = __builtin_amdgcn_cvt_scalef32_pk32_f32_fp6(qv, 1.0f);
;         f32x2 a2 = f32x2{0.f, 0.f};
; #pragma unroll
;         for (int i = 0; i < 16; ++i) a2 += f32x2{wv[2 * i], wv[2 * i + 1]} * xu[i];
;         float hs = a2.x + a2.y;
;         hs += dpp_row_shr(hs, 1); hs += dpp_row_shr(hs, 2); hs += dpp_row_shr(hs, 4); hs += dpp_row_shr(hs, 8);
;         hs += __builtin_bit_cast(float, __builtin_amdgcn_update_dpp(0, __builtin_bit_cast(int, hs), 0x142, 0xa, 0xf, false));
;         const float da = __builtin_bit_cast(float, __builtin_amdgcn_readlane(__builtin_bit_cast(int, hs), 31));
;         const float db = __builtin_bit_cast(float, __builtin_amdgcn_readlane(__builtin_bit_cast(int, hs), 63));
;         dvec = (lane == kb + 2 * pr) ? da : dvec;
;         dvec = (lane == kb + 2 * pr + 1) ? db : dvec;
;       }
	v_cvt_scalef32_pk32_f32_fp6 v[0:31], v[50:55], 1.0
	global_load_dwordx2 v[54:55], v167, s[62:63] offset:16
	global_load_dwordx4 v[50:53], v167, s[62:63]
	v_pk_mul_f32 v[246:247], v[0:1], v[96:97]
	v_pk_mul_f32 v[254:255], v[2:3], v[98:99]
	v_pk_mul_f32 v[160:161], v[4:5], v[100:101]
	v_pk_fma_f32 v[246:247], v[6:7], v[102:103], v[246:247]
	v_pk_fma_f32 v[254:255], v[8:9], v[104:105], v[254:255]
	v_pk_fma_f32 v[160:161], v[10:11], v[106:107], v[160:161]
	v_pk_fma_f32 v[246:247], v[12:13], v[108:109], v[246:247]
	v_pk_fma_f32 v[254:255], v[14:15], v[110:111], v[254:255]
	v_pk_fma_f32 v[160:161], v[16:17], v[112:113], v[160:161]
	v_pk_fma_f32 v[246:247], v[18:19], v[114:115], v[246:247]
	v_pk_fma_f32 v[254:255], v[20:21], v[116:117], v[254:255]
	v_pk_fma_f32 v[160:161], v[22:23], v[118:119], v[160:161]
	v_pk_fma_f32 v[246:247], v[24:25], v[120:121], v[246:247]
	v_pk_fma_f32 v[254:255], v[26:27], v[122:123], v[254:255]
	v_pk_fma_f32 v[160:161], v[28:29], v[124:125], v[160:161]
	v_pk_fma_f32 v[246:247], v[30:31], v[126:127], v[246:247]
	v_pk_add_f32 v[254:255], v[254:255], v[160:161]
	s_nop 0
	v_pk_add_f32 v[246:247], v[246:247], v[254:255]
	s_nop 0
	v_add_f32_e32 v162, v246, v247
	v_readlane_b32 s54, v92, 50
	v_readlane_b32 s55, v92, 51
	s_mul_i32 s0, s54, 0x300
	s_mul_i32 s1, s55, 0x300
	v_add_u32_e32 v167, s0, v195
	s_and_saveexec_b64 s[98:99], s[40:41]
	v_add_u32_e32 v167, s1, v195
	s_mov_b64 exec, s[98:99]
	s_waitcnt vmcnt(14)
	v_cvt_scalef32_pk32_f32_fp6 v[0:31], v[44:49], 1.0
	global_load_dwordx2 v[48:49], v167, s[62:63] offset:16
	global_load_dwordx4 v[44:47], v167, s[62:63]
	v_pk_mul_f32 v[246:247], v[0:1], v[96:97]
	v_pk_mul_f32 v[254:255], v[2:3], v[98:99]
	v_pk_mul_f32 v[160:161], v[4:5], v[100:101]
	v_pk_fma_f32 v[246:247], v[6:7], v[102:103], v[246:247]
	v_pk_fma_f32 v[254:255], v[8:9], v[104:105], v[254:255]
	v_pk_fma_f32 v[160:161], v[10:11], v[106:107], v[160:161]
	v_pk_fma_f32 v[246:247], v[12:13], v[108:109], v[246:247]
	v_pk_fma_f32 v[254:255], v[14:15], v[110:111], v[254:255]
	v_pk_fma_f32 v[160:161], v[16:17], v[112:113], v[160:161]
	v_pk_fma_f32 v[246:247], v[18:19], v[114:115], v[246:247]
	v_pk_fma_f32 v[254:255], v[20:21], v[116:117], v[254:255]
	v_pk_fma_f32 v[160:161], v[22:23], v[118:119], v[160:161]
	v_pk_fma_f32 v[246:247], v[24:25], v[120:121], v[246:247]
	v_pk_fma_f32 v[254:255], v[26:27], v[122:123], v[254:255]
	v_pk_fma_f32 v[160:161], v[28:29], v[124:125], v[160:161]
	v_pk_fma_f32 v[246:247], v[30:31], v[126:127], v[246:247]
	v_pk_add_f32 v[254:255], v[254:255], v[160:161]
	s_nop 0
	v_pk_add_f32 v[246:247], v[246:247], v[254:255]
	s_nop 0
	v_add_f32_e32 v163, v246, v247
	v_readlane_b32 s54, v92, 52
	v_readlane_b32 s55, v92, 53
	s_mul_i32 s0, s54, 0x300
	s_mul_i32 s1, s55, 0x300
	v_add_u32_e32 v167, s0, v195
	s_and_saveexec_b64 s[98:99], s[40:41]
	v_add_u32_e32 v167, s1, v195
	s_mov_b64 exec, s[98:99]
	s_waitcnt vmcnt(14)
	v_cvt_scalef32_pk32_f32_fp6 v[0:31], v[38:43], 1.0
	global_load_dwordx2 v[42:43], v167, s[62:63] offset:16
	global_load_dwordx4 v[38:41], v167, s[62:63]
	v_pk_mul_f32 v[246:247], v[0:1], v[96:97]
	v_pk_mul_f32 v[254:255], v[2:3], v[98:99]
	v_pk_mul_f32 v[160:161], v[4:5], v[100:101]
	v_pk_fma_f32 v[246:247], v[6:7], v[102:103], v[246:247]
	v_pk_fma_f32 v[254:255], v[8:9], v[104:105], v[254:255]
	v_pk_fma_f32 v[160:161], v[10:11], v[106:107], v[160:161]
	v_pk_fma_f32 v[246:247], v[12:13], v[108:109], v[246:247]
	v_pk_fma_f32 v[254:255], v[14:15], v[110:111], v[254:255]
	v_pk_fma_f32 v[160:161], v[16:17], v[112:113], v[160:161]
	v_pk_fma_f32 v[246:247], v[18:19], v[114:115], v[246:247]
	v_pk_fma_f32 v[254:255], v[20:21], v[116:117], v[254:255]
	v_pk_fma_f32 v[160:161], v[22:23], v[118:119], v[160:161]
	v_pk_fma_f32 v[246:247], v[24:25], v[120:121], v[246:247]
	v_pk_fma_f32 v[254:255], v[26:27], v[122:123], v[254:255]
	v_pk_fma_f32 v[160:161], v[28:29], v[124:125], v[160:161]
	v_pk_fma_f32 v[246:247], v[30:31], v[126:127], v[246:247]
	v_pk_add_f32 v[254:255], v[254:255], v[160:161]
	s_nop 0
	v_pk_add_f32 v[246:247], v[246:247], v[254:255]
	s_nop 0
	v_add_f32_e32 v164, v246, v247
	v_readlane_b32 s54, v92, 54
	v_readlane_b32 s55, v92, 55
	s_mul_i32 s0, s54, 0x300
	s_mul_i32 s1, s55, 0x300
	v_add_u32_e32 v167, s0, v195
	s_and_saveexec_b64 s[98:99], s[40:41]
	v_add_u32_e32 v167, s1, v195
	s_mov_b64 exec, s[98:99]
	s_waitcnt vmcnt(14)
; __device__ void peer_gather_phase(const Params& P, int l, bool do_store) {
;     ...
;         const int ea = __builtin_amdgcn_readlane(evs, kb + 2 * pr), eb = __builtin_amdgcn_readlane(evs, kb + 2 * pr + 1);
;         const uint2* up = (const uint2*)(U + (size_t)(uphi ? eb : ea) * 768);
;         u6[3 * pr] = up[0]; u6[3 * pr + 1] = up[1]; u6[3 * pr + 2] = up[2];
;         v8[2 * pr] = *(const uint2*)(V + (size_t)ea * 512);
;         v8[2 * pr + 1] = *(const uint2*)(V + (size_t)eb * 512);
;       }
;     };
;     auto compute_batch = [&](const uint2 (&u6)[12], const uint2 (&v8)[8], int bt) {
;       const int kb = (bt & 7) * 8;
;       float dvec = 0.f;
; #pragma unroll
;       for (int pr = 0; pr < 4; ++pr) {
;         v6u_t qv; qv[0] = u6[3 * pr].x; qv[1] = u6[3 * pr].y; qv[2] = u6[3 * pr + 1].x; qv[3] = u6[3 * pr + 1].y; qv[4] = u6[3 * pr + 2].x; qv[5] = u6[3 * pr + 2].y;
;         const v32f_t wv = __builtin_amdgcn_cvt_scalef32_pk32_f32_fp6(qv, 1.0f);
;         f32x2 a2 = f32x2{0.f, 0.f};
; #pragma unroll
;         for (int i = 0; i < 16; ++i) a2 += f32x2{wv[2 * i], wv[2 * i + 1]} * xu[i];
;         float hs = a2.x + a2.y;
;         hs += dpp_row_shr(hs, 1); hs += dpp_row_shr(hs, 2); hs += dpp_row_shr(hs, 4); hs += dpp_row_shr(hs, 8);
;         hs += __builtin_bit_cast(float, __builtin_amdgcn_update_dpp(0, __builtin_bit_cast(int, hs), 0x142, 0xa, 0xf, false));
;         const float da = __builtin_bit_cast(float, __builtin_amdgcn_readlane(__builtin_bit_cast(int, hs), 31));
;         const float db = __builtin_bit_cast(float, __builtin_amdgcn_readlane(__builtin_bit_cast(int, hs), 63));
;         dvec = (lane == kb + 2 * pr) ? da : dvec;
;         dvec = (lane == kb + 2 * pr + 1) ? db : dvec;
;       }
	v_cvt_scalef32_pk32_f32_fp6 v[0:31], v[32:37], 1.0
	global_load_dwordx2 v[36:37], v167, s[62:63] offset:16
	global_load_dwordx4 v[32:35], v167, s[62:63]
	v_pk_mul_f32 v[246:247], v[0:1], v[96:97]
	v_pk_mul_f32 v[254:255], v[2:3], v[98:99]
	v_pk_mul_f32 v[160:161], v[4:5], v[100:101]
	v_pk_fma_f32 v[246:247], v[6:7], v[102:103], v[246:247]
	v_pk_fma_f32 v[254:255], v[8:9], v[104:105], v[254:255]
	v_pk_fma_f32 v[160:161], v[10:11], v[106:107], v[160:161]
	v_pk_fma_f32 v[246:247], v[12:13], v[108:109], v[246:247]
	v_pk_fma_f32 v[254:255], v[14:15], v[110:111], v[254:255]
	v_pk_fma_f32 v[160:161], v[16:17], v[112:113], v[160:161]
	v_pk_fma_f32 v[246:247], v[18:19], v[114:115], v[246:247]
	v_pk_fma_f32 v[254:255], v[20:21], v[116:117], v[254:255]
	v_pk_fma_f32 v[160:161], v[22:23], v[118:119], v[160:161]
	v_pk_fma_f32 v[246:247], v[24:25], v[120:121], v[246:247]
	v_pk_fma_f32 v[254:255], v[26:27], v[122:123], v[254:255]
	v_pk_fma_f32 v[160:161], v[28:29], v[124:125], v[160:161]
	v_pk_fma_f32 v[246:247], v[30:31], v[126:127], v[246:247]
	v_pk_add_f32 v[254:255], v[254:255], v[160:161]
	s_nop 0
	v_pk_add_f32 v[246:247], v[246:247], v[254:255]
	s_nop 0
	v_add_f32_e32 v165, v246, v247
	v_add_f32_dpp v162, v162, v162 row_shr:1 row_mask:0xf bank_mask:0xf bound_ctrl:1
	v_add_f32_dpp v163, v163, v163 row_shr:1 row_mask:0xf bank_mask:0xf bound_ctrl:1
	v_add_f32_dpp v164, v164, v164 row_shr:1 row_mask:0xf bank_mask:0xf bound_ctrl:1
	v_add_f32_dpp v165, v165, v165 row_shr:1 row_mask:0xf bank_mask:0xf bound_ctrl:1
	v_add_f32_dpp v162, v162, v162 row_shr:2 row_mask:0xf bank_mask:0xf bound_ctrl:1
	v_add_f32_dpp v163, v163, v163 row_shr:2 row_mask:0xf bank_mask:0xf bound_ctrl:1
	v_add_f32_dpp v164, v164, v164 row_shr:2 row_mask:0xf bank_mask:0xf bound_ctrl:1
	v_add_f32_dpp v165, v165, v165 row_shr:2 row_mask:0xf bank_mask:0xf bound_ctrl:1
	v_add_f32_dpp v162, v162, v162 row_shr:4 row_mask:0xf bank_mask:0xf bound_ctrl:1
	v_add_f32_dpp v163, v163, v163 row_shr:4 row_mask:0xf bank_mask:0xf bound_ctrl:1
	v_add_f32_dpp v164, v164, v164 row_shr:4 row_mask:0xf bank_mask:0xf bound_ctrl:1
	v_add_f32_dpp v165, v165, v165 row_shr:4 row_mask:0xf bank_mask:0xf bound_ctrl:1
	v_add_f32_dpp v162, v162, v162 row_shr:8 row_mask:0xf bank_mask:0xf bound_ctrl:1
	v_add_f32_dpp v163, v163, v163 row_shr:8 row_mask:0xf bank_mask:0xf bound_ctrl:1
	v_add_f32_dpp v164, v164, v164 row_shr:8 row_mask:0xf bank_mask:0xf bound_ctrl:1
	v_add_f32_dpp v165, v165, v165 row_shr:8 row_mask:0xf bank_mask:0xf bound_ctrl:1
	v_add_f32_dpp v162, v162, v162 row_bcast:15 row_mask:0xa bank_mask:0xf
	v_add_f32_dpp v163, v163, v163 row_bcast:15 row_mask:0xa bank_mask:0xf
	v_add_f32_dpp v164, v164, v164 row_bcast:15 row_mask:0xa bank_mask:0xf
	v_add_f32_dpp v165, v165, v165 row_bcast:15 row_mask:0xa bank_mask:0xf
	s_nop 1
	v_readlane_b32 s46, v162, 31
	v_readlane_b32 s47, v162, 63
	v_readlane_b32 s48, v163, 31
	v_readlane_b32 s49, v163, 63
	v_readlane_b32 s50, v164, 31
	v_readlane_b32 s51, v164, 63
	v_readlane_b32 s52, v165, 31
	v_readlane_b32 s53, v165, 63
	v_writelane_b32 v166, s46, 32
	s_nop 1
	v_writelane_b32 v166, s47, 33
	v_writelane_b32 v166, s48, 34
	v_writelane_b32 v166, s49, 35
	v_writelane_b32 v166, s50, 36
	v_writelane_b32 v166, s51, 37
	v_writelane_b32 v166, s52, 38
	v_writelane_b32 v166, s53, 39
	v_readlane_b32 s54, v92, 56
	v_readlane_b32 s55, v92, 57
	s_mul_i32 s0, s54, 0x300
	s_mul_i32 s1, s55, 0x300
	v_add_u32_e32 v167, s0, v195
	s_and_saveexec_b64 s[98:99], s[40:41]
	v_add_u32_e32 v167, s1, v195
	s_mov_b64 exec, s[98:99]
	s_waitcnt vmcnt(14)
	v_cvt_scalef32_pk32_f32_fp6 v[0:31], v[196:201], 1.0
	global_load_dwordx2 v[200:201], v167, s[62:63] offset:16
	global_load_dwordx4 v[196:199], v167, s[62:63]
	v_pk_mul_f32 v[246:247], v[0:1], v[96:97]
	v_pk_mul_f32 v[254:255], v[2:3], v[98:99]
	v_pk_mul_f32 v[160:161], v[4:5], v[100:101]
	v_pk_fma_f32 v[246:247], v[6:7], v[102:103], v[246:247]
	v_pk_fma_f32 v[254:255], v[8:9], v[104:105], v[254:255]
	v_pk_fma_f32 v[160:161], v[10:11], v[106:107], v[160:161]
	v_pk_fma_f32 v[246:247], v[12:13], v[108:109], v[246:247]
	v_pk_fma_f32 v[254:255], v[14:15], v[110:111], v[254:255]
	v_pk_fma_f32 v[160:161], v[16:17], v[112:113], v[160:161]
	v_pk_fma_f32 v[246:247], v[18:19], v[114:115], v[246:247]
	v_pk_fma_f32 v[254:255], v[20:21], v[116:117], v[254:255]
	v_pk_fma_f32 v[160:161], v[22:23], v[118:119], v[160:161]
	v_pk_fma_f32 v[246:247], v[24:25], v[120:121], v[246:247]
	v_pk_fma_f32 v[254:255], v[26:27], v[122:123], v[254:255]
	v_pk_fma_f32 v[160:161], v[28:29], v[124:125], v[160:161]
	v_pk_fma_f32 v[246:247], v[30:31], v[126:127], v[246:247]
	v_pk_add_f32 v[254:255], v[254:255], v[160:161]
	s_nop 0
	v_pk_add_f32 v[246:247], v[246:247], v[254:255]
	s_nop 0
	v_add_f32_e32 v162, v246, v247
	v_readlane_b32 s54, v92, 58
	v_readlane_b32 s55, v92, 59
	s_mul_i32 s0, s54, 0x300
	s_mul_i32 s1, s55, 0x300
	v_add_u32_e32 v167, s0, v195
	s_and_saveexec_b64 s[98:99], s[40:41]
	v_add_u32_e32 v167, s1, v195
	s_mov_b64 exec, s[98:99]
	s_waitcnt vmcnt(14)
; __device__ void peer_gather_phase(const Params& P, int l, bool do_store) {
;     ...
;         const int ea = __builtin_amdgcn_readlane(evs, kb + 2 * pr), eb = __builtin_amdgcn_readlane(evs, kb + 2 * pr + 1);
;         const uint2* up = (const uint2*)(U + (size_t)(uphi ? eb : ea) * 768);
;         u6[3 * pr] = up[0]; u6[3 * pr + 1] = up[1]; u6[3 * pr + 2] = up[2];
;         v8[2 * pr] = *(const uint2*)(V + (size_t)ea * 512);
;         v8[2 * pr + 1] = *(const uint2*)(V + (size_t)eb * 512);
;       }
;     };
;     auto compute_batch = [&](const uint2 (&u6)[12], const uint2 (&v8)[8], int bt) {
;       const int kb = (bt & 7) * 8;
;       float dvec = 0.f;
; #pragma unroll
;       for (int pr = 0; pr < 4; ++pr) {
;         v6u_t qv; qv[0] = u6[3 * pr].x; qv[1] = u6[3 * pr].y; qv[2] = u6[3 * pr + 1].x; qv[3] = u6[3 * pr + 1].y; qv[4] = u6[3 * pr + 2].x; qv[5] = u6[3 * pr + 2].y;
;         const v32f_t wv = __builtin_amdgcn_cvt_scalef32_pk32_f32_fp6(qv, 1.0f);
;         f32x2 a2 = f32x2{0.f, 0.f};
; #pragma unroll
;         for (int i = 0; i < 16; ++i) a2 += f32x2{wv[2 * i], wv[2 * i + 1]} * xu[i];
;         float hs = a2.x + a2.y;
;         hs += dpp_row_shr(hs, 1); hs += dpp_row_shr(hs, 2); hs += dpp_row_shr(hs, 4); hs += dpp_row_shr(hs, 8);
;         hs += __builtin_bit_cast(float, __builtin_amdgcn_update_dpp(0, __builtin_bit_cast(int, hs), 0x142, 0xa, 0xf, false));
;         const float da = __builtin_bit_cast(float, __builtin_amdgcn_readlane(__builtin_bit_cast(int, hs), 31));
;         const float db = __builtin_bit_cast(float, __builtin_amdgcn_readlane(__builtin_bit_cast(int, hs), 63));
;         dvec = (lane == kb + 2 * pr) ? da : dvec;
;         dvec = (lane == kb + 2 * pr + 1) ? db : dvec;
;       }
	v_cvt_scalef32_pk32_f32_fp6 v[0:31], v[228:233], 1.0
	global_load_dwordx2 v[232:233], v167, s[62:63] offset:16
	global_load_dwordx4 v[228:231], v167, s[62:63]
	v_pk_mul_f32 v[246:247], v[0:1], v[96:97]
	v_pk_mul_f32 v[254:255], v[2:3], v[98:99]
	v_pk_mul_f32 v[160:161], v[4:5], v[100:101]
	v_pk_fma_f32 v[246:247], v[6:7], v[102:103], v[246:247]
	v_pk_fma_f32 v[254:255], v[8:9], v[104:105], v[254:255]
	v_pk_fma_f32 v[160:161], v[10:11], v[106:107], v[160:161]
	v_pk_fma_f32 v[246:247], v[12:13], v[108:109], v[246:247]
	v_pk_fma_f32 v[254:255], v[14:15], v[110:111], v[254:255]
	v_pk_fma_f32 v[160:161], v[16:17], v[112:113], v[160:161]
	v_pk_fma_f32 v[246:247], v[18:19], v[114:115], v[246:247]
	v_pk_fma_f32 v[254:255], v[20:21], v[116:117], v[254:255]
	v_pk_fma_f32 v[160:161], v[22:23], v[118:119], v[160:161]
	v_pk_fma_f32 v[246:247], v[24:25], v[120:121], v[246:247]
	v_pk_fma_f32 v[254:255], v[26:27], v[122:123], v[254:255]
	v_pk_fma_f32 v[160:161], v[28:29], v[124:125], v[160:161]
	v_pk_fma_f32 v[246:247], v[30:31], v[126:127], v[246:247]
	v_pk_add_f32 v[254:255], v[254:255], v[160:161]
	s_nop 0
	v_pk_add_f32 v[246:247], v[246:247], v[254:255]
	s_nop 0
	v_add_f32_e32 v163, v246, v247
	v_readlane_b32 s54, v92, 60
	v_readlane_b32 s55, v92, 61
	s_mul_i32 s0, s54, 0x300
	s_mul_i32 s1, s55, 0x300
	v_add_u32_e32 v167, s0, v195
	s_and_saveexec_b64 s[98:99], s[40:41]
	v_add_u32_e32 v167, s1, v195
	s_mov_b64 exec, s[98:99]
	s_waitcnt vmcnt(14)
	v_cvt_scalef32_pk32_f32_fp6 v[0:31], v[234:239], 1.0
	global_load_dwordx2 v[238:239], v167, s[62:63] offset:16
	global_load_dwordx4 v[234:237], v167, s[62:63]
	v_pk_mul_f32 v[246:247], v[0:1], v[96:97]
	v_pk_mul_f32 v[254:255], v[2:3], v[98:99]
	v_pk_mul_f32 v[160:161], v[4:5], v[100:101]
	v_pk_fma_f32 v[246:247], v[6:7], v[102:103], v[246:247]
	v_pk_fma_f32 v[254:255], v[8:9], v[104:105], v[254:255]
	v_pk_fma_f32 v[160:161], v[10:11], v[106:107], v[160:161]
	v_pk_fma_f32 v[246:247], v[12:13], v[108:109], v[246:247]
	v_pk_fma_f32 v[254:255], v[14:15], v[110:111], v[254:255]
	v_pk_fma_f32 v[160:161], v[16:17], v[112:113], v[160:161]
	v_pk_fma_f32 v[246:247], v[18:19], v[114:115], v[246:247]
	v_pk_fma_f32 v[254:255], v[20:21], v[116:117], v[254:255]
	v_pk_fma_f32 v[160:161], v[22:23], v[118:119], v[160:161]
	v_pk_fma_f32 v[246:247], v[24:25], v[120:121], v[246:247]
	v_pk_fma_f32 v[254:255], v[26:27], v[122:123], v[254:255]
	v_pk_fma_f32 v[160:161], v[28:29], v[124:125], v[160:161]
	v_pk_fma_f32 v[246:247], v[30:31], v[126:127], v[246:247]
	v_pk_add_f32 v[254:255], v[254:255], v[160:161]
	s_nop 0
	v_pk_add_f32 v[246:247], v[246:247], v[254:255]
	s_nop 0
	v_add_f32_e32 v164, v246, v247
	v_readlane_b32 s54, v92, 62
	v_readlane_b32 s55, v92, 63
	s_mul_i32 s0, s54, 0x300
	s_mul_i32 s1, s55, 0x300
	v_add_u32_e32 v167, s0, v195
	s_and_saveexec_b64 s[98:99], s[40:41]
	v_add_u32_e32 v167, s1, v195
	s_mov_b64 exec, s[98:99]
	s_waitcnt vmcnt(14)
	v_cvt_scalef32_pk32_f32_fp6 v[0:31], v[240:245], 1.0
	global_load_dwordx2 v[244:245], v167, s[62:63] offset:16
	global_load_dwordx4 v[240:243], v167, s[62:63]
	v_pk_mul_f32 v[246:247], v[0:1], v[96:97]
	v_pk_mul_f32 v[254:255], v[2:3], v[98:99]
	v_pk_mul_f32 v[160:161], v[4:5], v[100:101]
	v_pk_fma_f32 v[246:247], v[6:7], v[102:103], v[246:247]
	v_pk_fma_f32 v[254:255], v[8:9], v[104:105], v[254:255]
	v_pk_fma_f32 v[160:161], v[10:11], v[106:107], v[160:161]
	v_pk_fma_f32 v[246:247], v[12:13], v[108:109], v[246:247]
	v_pk_fma_f32 v[254:255], v[14:15], v[110:111], v[254:255]
	v_pk_fma_f32 v[160:161], v[16:17], v[112:113], v[160:161]
	v_pk_fma_f32 v[246:247], v[18:19], v[114:115], v[246:247]
	v_pk_fma_f32 v[254:255], v[20:21], v[116:117], v[254:255]
	v_pk_fma_f32 v[160:161], v[22:23], v[118:119], v[160:161]
	v_pk_fma_f32 v[246:247], v[24:25], v[120:121], v[246:247]
	v_pk_fma_f32 v[254:255], v[26:27], v[122:123], v[254:255]
	v_pk_fma_f32 v[160:161], v[28:29], v[124:125], v[160:161]
	v_pk_fma_f32 v[246:247], v[30:31], v[126:127], v[246:247]
	v_pk_add_f32 v[254:255], v[254:255], v[160:161]
	s_nop 0
	v_pk_add_f32 v[246:247], v[246:247], v[254:255]
	s_nop 0
	v_add_f32_e32 v165, v246, v247
	v_add_f32_dpp v162, v162, v162 row_shr:1 row_mask:0xf bank_mask:0xf bound_ctrl:1
	v_add_f32_dpp v163, v163, v163 row_shr:1 row_mask:0xf bank_mask:0xf bound_ctrl:1
	v_add_f32_dpp v164, v164, v164 row_shr:1 row_mask:0xf bank_mask:0xf bound_ctrl:1
	v_add_f32_dpp v165, v165, v165 row_shr:1 row_mask:0xf bank_mask:0xf bound_ctrl:1
	v_add_f32_dpp v162, v162, v162 row_shr:2 row_mask:0xf bank_mask:0xf bound_ctrl:1
	v_add_f32_dpp v163, v163, v163 row_shr:2 row_mask:0xf bank_mask:0xf bound_ctrl:1
	v_add_f32_dpp v164, v164, v164 row_shr:2 row_mask:0xf bank_mask:0xf bound_ctrl:1
	v_add_f32_dpp v165, v165, v165 row_shr:2 row_mask:0xf bank_mask:0xf bound_ctrl:1
	v_add_f32_dpp v162, v162, v162 row_shr:4 row_mask:0xf bank_mask:0xf bound_ctrl:1
	v_add_f32_dpp v163, v163, v163 row_shr:4 row_mask:0xf bank_mask:0xf bound_ctrl:1
	v_add_f32_dpp v164, v164, v164 row_shr:4 row_mask:0xf bank_mask:0xf bound_ctrl:1
	v_add_f32_dpp v165, v165, v165 row_shr:4 row_mask:0xf bank_mask:0xf bound_ctrl:1
	v_add_f32_dpp v162, v162, v162 row_shr:8 row_mask:0xf bank_mask:0xf bound_ctrl:1
	v_add_f32_dpp v163, v163, v163 row_shr:8 row_mask:0xf bank_mask:0xf bound_ctrl:1
	v_add_f32_dpp v164, v164, v164 row_shr:8 row_mask:0xf bank_mask:0xf bound_ctrl:1
	v_add_f32_dpp v165, v165, v165 row_shr:8 row_mask:0xf bank_mask:0xf bound_ctrl:1
	v_add_f32_dpp v162, v162, v162 row_bcast:15 row_mask:0xa bank_mask:0xf
	v_add_f32_dpp v163, v163, v163 row_bcast:15 row_mask:0xa bank_mask:0xf
	v_add_f32_dpp v164, v164, v164 row_bcast:15 row_mask:0xa bank_mask:0xf
	v_add_f32_dpp v165, v165, v165 row_bcast:15 row_mask:0xa bank_mask:0xf
	s_nop 1
	v_readlane_b32 s46, v162, 31
	v_readlane_b32 s47, v162, 63
	v_readlane_b32 s48, v163, 31
	v_readlane_b32 s49, v163, 63
	v_readlane_b32 s50, v164, 31
	v_readlane_b32 s51, v164, 63
	v_readlane_b32 s52, v165, 31
	v_readlane_b32 s53, v165, 63
	v_writelane_b32 v166, s46, 40
	s_nop 1
	v_writelane_b32 v166, s47, 41
	v_writelane_b32 v166, s48, 42
	v_writelane_b32 v166, s49, 43
	v_writelane_b32 v166, s50, 44
	v_writelane_b32 v166, s51, 45
	v_writelane_b32 v166, s52, 46
	v_writelane_b32 v166, s53, 47
	v_readlane_b32 s54, v90, 0
	v_readlane_b32 s55, v90, 1
	s_mul_i32 s0, s54, 0x300
	s_mul_i32 s1, s55, 0x300
	v_add_u32_e32 v167, s0, v195
	s_and_saveexec_b64 s[98:99], s[40:41]
	v_add_u32_e32 v167, s1, v195
	s_mov_b64 exec, s[98:99]
	s_waitcnt vmcnt(14)
; __device__ void peer_gather_phase(const Params& P, int l, bool do_store) {
;     ...
;         const int ea = __builtin_amdgcn_readlane(evs, kb + 2 * pr), eb = __builtin_amdgcn_readlane(evs, kb + 2 * pr + 1);
;         const uint2* up = (const uint2*)(U + (size_t)(uphi ? eb : ea) * 768);
;         u6[3 * pr] = up[0]; u6[3 * pr + 1] = up[1]; u6[3 * pr + 2] = up[2];
;         v8[2 * pr] = *(const uint2*)(V + (size_t)ea * 512);
;         v8[2 * pr + 1] = *(const uint2*)(V + (size_t)eb * 512);
;       }
;     };
;     auto compute_batch = [&](const uint2 (&u6)[12], const uint2 (&v8)[8], int bt) {
;       const int kb = (bt & 7) * 8;
;       float dvec = 0.f;
; #pragma unroll
;       for (int pr = 0; pr < 4; ++pr) {
;         v6u_t qv; qv[0] = u6[3 * pr].x; qv[1] = u6[3 * pr].y; qv[2] = u6[3 * pr + 1].x; qv[3] = u6[3 * pr + 1].y; qv[4] = u6[3 * pr + 2].x; qv[5] = u6[3 * pr + 2].y;
;         const v32f_t wv = __builtin_amdgcn_cvt_scalef32_pk32_f32_fp6(qv, 1.0f);
;         f32x2 a2 = f32x2{0.f, 0.f};
; #pragma unroll
;         for (int i = 0; i < 16; ++i) a2 += f32x2{wv[2 * i], wv[2 * i + 1]} * xu[i];
;         float hs = a2.x + a2.y;
;         hs += dpp_row_shr(hs, 1); hs += dpp_row_shr(hs, 2); hs += dpp_row_shr(hs, 4); hs += dpp_row_shr(hs, 8);
;         hs += __builtin_bit_cast(float, __builtin_amdgcn_update_dpp(0, __builtin_bit_cast(int, hs), 0x142, 0xa, 0xf, false));
;         const float da = __builtin_bit_cast(float, __builtin_amdgcn_readlane(__builtin_bit_cast(int, hs), 31));
;         const float db = __builtin_bit_cast(float, __builtin_amdgcn_readlane(__builtin_bit_cast(int, hs), 63));
;         dvec = (lane == kb + 2 * pr) ? da : dvec;
;         dvec = (lane == kb + 2 * pr + 1) ? db : dvec;
;       }
	v_cvt_scalef32_pk32_f32_fp6 v[0:31], v[50:55], 1.0
	global_load_dwordx2 v[54:55], v167, s[62:63] offset:16
	global_load_dwordx4 v[50:53], v167, s[62:63]
	v_pk_mul_f32 v[246:247], v[0:1], v[96:97]
	v_pk_mul_f32 v[254:255], v[2:3], v[98:99]
	v_pk_mul_f32 v[160:161], v[4:5], v[100:101]
	v_pk_fma_f32 v[246:247], v[6:7], v[102:103], v[246:247]
	v_pk_fma_f32 v[254:255], v[8:9], v[104:105], v[254:255]
	v_pk_fma_f32 v[160:161], v[10:11], v[106:107], v[160:161]
	v_pk_fma_f32 v[246:247], v[12:13], v[108:109], v[246:247]
	v_pk_fma_f32 v[254:255], v[14:15], v[110:111], v[254:255]
	v_pk_fma_f32 v[160:161], v[16:17], v[112:113], v[160:161]
	v_pk_fma_f32 v[246:247], v[18:19], v[114:115], v[246:247]
	v_pk_fma_f32 v[254:255], v[20:21], v[116:117], v[254:255]
	v_pk_fma_f32 v[160:161], v[22:23], v[118:119], v[160:161]
	v_pk_fma_f32 v[246:247], v[24:25], v[120:121], v[246:247]
	v_pk_fma_f32 v[254:255], v[26:27], v[122:123], v[254:255]
	v_pk_fma_f32 v[160:161], v[28:29], v[124:125], v[160:161]
	v_pk_fma_f32 v[246:247], v[30:31], v[126:127], v[246:247]
	v_pk_add_f32 v[254:255], v[254:255], v[160:161]
	s_nop 0
	v_pk_add_f32 v[246:247], v[246:247], v[254:255]
	s_nop 0
	v_add_f32_e32 v162, v246, v247
	v_readlane_b32 s54, v90, 2
	v_readlane_b32 s55, v90, 3
	s_mul_i32 s0, s54, 0x300
	s_mul_i32 s1, s55, 0x300
	v_add_u32_e32 v167, s0, v195
	s_and_saveexec_b64 s[98:99], s[40:41]
	v_add_u32_e32 v167, s1, v195
	s_mov_b64 exec, s[98:99]
	s_waitcnt vmcnt(14)
	v_cvt_scalef32_pk32_f32_fp6 v[0:31], v[44:49], 1.0
	global_load_dwordx2 v[48:49], v167, s[62:63] offset:16
	global_load_dwordx4 v[44:47], v167, s[62:63]
	v_pk_mul_f32 v[246:247], v[0:1], v[96:97]
	v_pk_mul_f32 v[254:255], v[2:3], v[98:99]
	v_pk_mul_f32 v[160:161], v[4:5], v[100:101]
	v_pk_fma_f32 v[246:247], v[6:7], v[102:103], v[246:247]
	v_pk_fma_f32 v[254:255], v[8:9], v[104:105], v[254:255]
	v_pk_fma_f32 v[160:161], v[10:11], v[106:107], v[160:161]
	v_pk_fma_f32 v[246:247], v[12:13], v[108:109], v[246:247]
	v_pk_fma_f32 v[254:255], v[14:15], v[110:111], v[254:255]
	v_pk_fma_f32 v[160:161], v[16:17], v[112:113], v[160:161]
	v_pk_fma_f32 v[246:247], v[18:19], v[114:115], v[246:247]
	v_pk_fma_f32 v[254:255], v[20:21], v[116:117], v[254:255]
	v_pk_fma_f32 v[160:161], v[22:23], v[118:119], v[160:161]
	v_pk_fma_f32 v[246:247], v[24:25], v[120:121], v[246:247]
	v_pk_fma_f32 v[254:255], v[26:27], v[122:123], v[254:255]
	v_pk_fma_f32 v[160:161], v[28:29], v[124:125], v[160:161]
	v_pk_fma_f32 v[246:247], v[30:31], v[126:127], v[246:247]
	v_pk_add_f32 v[254:255], v[254:255], v[160:161]
	s_nop 0
	v_pk_add_f32 v[246:247], v[246:247], v[254:255]
	s_nop 0
	v_add_f32_e32 v163, v246, v247
	v_readlane_b32 s54, v90, 4
	v_readlane_b32 s55, v90, 5
	s_mul_i32 s0, s54, 0x300
	s_mul_i32 s1, s55, 0x300
	v_add_u32_e32 v167, s0, v195
	s_and_saveexec_b64 s[98:99], s[40:41]
	v_add_u32_e32 v167, s1, v195
	s_mov_b64 exec, s[98:99]
	s_waitcnt vmcnt(14)
	v_cvt_scalef32_pk32_f32_fp6 v[0:31], v[38:43], 1.0
	global_load_dwordx2 v[42:43], v167, s[62:63] offset:16
	global_load_dwordx4 v[38:41], v167, s[62:63]
	v_pk_mul_f32 v[246:247], v[0:1], v[96:97]
	v_pk_mul_f32 v[254:255], v[2:3], v[98:99]
	v_pk_mul_f32 v[160:161], v[4:5], v[100:101]
	v_pk_fma_f32 v[246:247], v[6:7], v[102:103], v[246:247]
	v_pk_fma_f32 v[254:255], v[8:9], v[104:105], v[254:255]
	v_pk_fma_f32 v[160:161], v[10:11], v[106:107], v[160:161]
	v_pk_fma_f32 v[246:247], v[12:13], v[108:109], v[246:247]
	v_pk_fma_f32 v[254:255], v[14:15], v[110:111], v[254:255]
	v_pk_fma_f32 v[160:161], v[16:17], v[112:113], v[160:161]
	v_pk_fma_f32 v[246:247], v[18:19], v[114:115], v[246:247]
	v_pk_fma_f32 v[254:255], v[20:21], v[116:117], v[254:255]
	v_pk_fma_f32 v[160:161], v[22:23], v[118:119], v[160:161]
	v_pk_fma_f32 v[246:247], v[24:25], v[120:121], v[246:247]
	v_pk_fma_f32 v[254:255], v[26:27], v[122:123], v[254:255]
	v_pk_fma_f32 v[160:161], v[28:29], v[124:125], v[160:161]
	v_pk_fma_f32 v[246:247], v[30:31], v[126:127], v[246:247]
	v_pk_add_f32 v[254:255], v[254:255], v[160:161]
	s_nop 0
	v_pk_add_f32 v[246:247], v[246:247], v[254:255]
	s_nop 0
	v_add_f32_e32 v164, v246, v247
	v_readlane_b32 s54, v90, 6
	v_readlane_b32 s55, v90, 7
	s_mul_i32 s0, s54, 0x300
	s_mul_i32 s1, s55, 0x300
	v_add_u32_e32 v167, s0, v195
	s_and_saveexec_b64 s[98:99], s[40:41]
	v_add_u32_e32 v167, s1, v195
	s_mov_b64 exec, s[98:99]
	s_waitcnt vmcnt(14)
; __device__ void peer_gather_phase(const Params& P, int l, bool do_store) {
;     ...
;         const int ea = __builtin_amdgcn_readlane(evs, kb + 2 * pr), eb = __builtin_amdgcn_readlane(evs, kb + 2 * pr + 1);
;         const uint2* up = (const uint2*)(U + (size_t)(uphi ? eb : ea) * 768);
;         u6[3 * pr] = up[0]; u6[3 * pr + 1] = up[1]; u6[3 * pr + 2] = up[2];
;         v8[2 * pr] = *(const uint2*)(V + (size_t)ea * 512);
;         v8[2 * pr + 1] = *(const uint2*)(V + (size_t)eb * 512);
;       }
;     };
;     auto compute_batch = [&](const uint2 (&u6)[12], const uint2 (&v8)[8], int bt) {
;       const int kb = (bt & 7) * 8;
;       float dvec = 0.f;
; #pragma unroll
;       for (int pr = 0; pr < 4; ++pr) {
;         v6u_t qv; qv[0] = u6[3 * pr].x; qv[1] = u6[3 * pr].y; qv[2] = u6[3 * pr + 1].x; qv[3] = u6[3 * pr + 1].y; qv[4] = u6[3 * pr + 2].x; qv[5] = u6[3 * pr + 2].y;
;         const v32f_t wv = __builtin_amdgcn_cvt_scalef32_pk32_f32_fp6(qv, 1.0f);
;         f32x2 a2 = f32x2{0.f, 0.f};
; #pragma unroll
;         for (int i = 0; i < 16; ++i) a2 += f32x2{wv[2 * i], wv[2 * i + 1]} * xu[i];
;         float hs = a2.x + a2.y;
;         hs += dpp_row_shr(hs, 1); hs += dpp_row_shr(hs, 2); hs += dpp_row_shr(hs, 4); hs += dpp_row_shr(hs, 8);
;         hs += __builtin_bit_cast(float, __builtin_amdgcn_update_dpp(0, __builtin_bit_cast(int, hs), 0x142, 0xa, 0xf, false));
;         const float da = __builtin_bit_cast(float, __builtin_amdgcn_readlane(__builtin_bit_cast(int, hs), 31));
;         const float db = __builtin_bit_cast(float, __builtin_amdgcn_readlane(__builtin_bit_cast(int, hs), 63));
;         dvec = (lane == kb + 2 * pr) ? da : dvec;
;         dvec = (lane == kb + 2 * pr + 1) ? db : dvec;
;       }
	v_cvt_scalef32_pk32_f32_fp6 v[0:31], v[32:37], 1.0
	global_load_dwordx2 v[36:37], v167, s[62:63] offset:16
	global_load_dwordx4 v[32:35], v167, s[62:63]
	v_pk_mul_f32 v[246:247], v[0:1], v[96:97]
	v_pk_mul_f32 v[254:255], v[2:3], v[98:99]
	v_pk_mul_f32 v[160:161], v[4:5], v[100:101]
	v_pk_fma_f32 v[246:247], v[6:7], v[102:103], v[246:247]
	v_pk_fma_f32 v[254:255], v[8:9], v[104:105], v[254:255]
	v_pk_fma_f32 v[160:161], v[10:11], v[106:107], v[160:161]
	v_pk_fma_f32 v[246:247], v[12:13], v[108:109], v[246:247]
	v_pk_fma_f32 v[254:255], v[14:15], v[110:111], v[254:255]
	v_pk_fma_f32 v[160:161], v[16:17], v[112:113], v[160:161]
	v_pk_fma_f32 v[246:247], v[18:19], v[114:115], v[246:247]
	v_pk_fma_f32 v[254:255], v[20:21], v[116:117], v[254:255]
	v_pk_fma_f32 v[160:161], v[22:23], v[118:119], v[160:161]
	v_pk_fma_f32 v[246:247], v[24:25], v[120:121], v[246:247]
	v_pk_fma_f32 v[254:255], v[26:27], v[122:123], v[254:255]
	v_pk_fma_f32 v[160:161], v[28:29], v[124:125], v[160:161]
	v_pk_fma_f32 v[246:247], v[30:31], v[126:127], v[246:247]
	v_pk_add_f32 v[254:255], v[254:255], v[160:161]
	s_nop 0
	v_pk_add_f32 v[246:247], v[246:247], v[254:255]
	s_nop 0
	v_add_f32_e32 v165, v246, v247
	v_add_f32_dpp v162, v162, v162 row_shr:1 row_mask:0xf bank_mask:0xf bound_ctrl:1
	v_add_f32_dpp v163, v163, v163 row_shr:1 row_mask:0xf bank_mask:0xf bound_ctrl:1
	v_add_f32_dpp v164, v164, v164 row_shr:1 row_mask:0xf bank_mask:0xf bound_ctrl:1
	v_add_f32_dpp v165, v165, v165 row_shr:1 row_mask:0xf bank_mask:0xf bound_ctrl:1
	v_add_f32_dpp v162, v162, v162 row_shr:2 row_mask:0xf bank_mask:0xf bound_ctrl:1
	v_add_f32_dpp v163, v163, v163 row_shr:2 row_mask:0xf bank_mask:0xf bound_ctrl:1
	v_add_f32_dpp v164, v164, v164 row_shr:2 row_mask:0xf bank_mask:0xf bound_ctrl:1
	v_add_f32_dpp v165, v165, v165 row_shr:2 row_mask:0xf bank_mask:0xf bound_ctrl:1
	v_add_f32_dpp v162, v162, v162 row_shr:4 row_mask:0xf bank_mask:0xf bound_ctrl:1
	v_add_f32_dpp v163, v163, v163 row_shr:4 row_mask:0xf bank_mask:0xf bound_ctrl:1
	v_add_f32_dpp v164, v164, v164 row_shr:4 row_mask:0xf bank_mask:0xf bound_ctrl:1
	v_add_f32_dpp v165, v165, v165 row_shr:4 row_mask:0xf bank_mask:0xf bound_ctrl:1
	v_add_f32_dpp v162, v162, v162 row_shr:8 row_mask:0xf bank_mask:0xf bound_ctrl:1
	v_add_f32_dpp v163, v163, v163 row_shr:8 row_mask:0xf bank_mask:0xf bound_ctrl:1
	v_add_f32_dpp v164, v164, v164 row_shr:8 row_mask:0xf bank_mask:0xf bound_ctrl:1
	v_add_f32_dpp v165, v165, v165 row_shr:8 row_mask:0xf bank_mask:0xf bound_ctrl:1
	v_add_f32_dpp v162, v162, v162 row_bcast:15 row_mask:0xa bank_mask:0xf
	v_add_f32_dpp v163, v163, v163 row_bcast:15 row_mask:0xa bank_mask:0xf
	v_add_f32_dpp v164, v164, v164 row_bcast:15 row_mask:0xa bank_mask:0xf
	v_add_f32_dpp v165, v165, v165 row_bcast:15 row_mask:0xa bank_mask:0xf
	s_nop 1
	v_readlane_b32 s46, v162, 31
	v_readlane_b32 s47, v162, 63
	v_readlane_b32 s48, v163, 31
	v_readlane_b32 s49, v163, 63
	v_readlane_b32 s50, v164, 31
	v_readlane_b32 s51, v164, 63
	v_readlane_b32 s52, v165, 31
	v_readlane_b32 s53, v165, 63
	v_writelane_b32 v166, s46, 48
	s_nop 1
	v_writelane_b32 v166, s47, 49
	v_writelane_b32 v166, s48, 50
	v_writelane_b32 v166, s49, 51
	v_writelane_b32 v166, s50, 52
	v_writelane_b32 v166, s51, 53
	v_writelane_b32 v166, s52, 54
	v_writelane_b32 v166, s53, 55
	v_readlane_b32 s54, v90, 8
	v_readlane_b32 s55, v90, 9
	s_mul_i32 s0, s54, 0x300
	s_mul_i32 s1, s55, 0x300
	v_add_u32_e32 v167, s0, v195
	s_and_saveexec_b64 s[98:99], s[40:41]
	v_add_u32_e32 v167, s1, v195
	s_mov_b64 exec, s[98:99]
	s_waitcnt vmcnt(14)
	v_cvt_scalef32_pk32_f32_fp6 v[0:31], v[196:201], 1.0
	global_load_dwordx2 v[200:201], v167, s[62:63] offset:16
	global_load_dwordx4 v[196:199], v167, s[62:63]
	v_pk_mul_f32 v[246:247], v[0:1], v[96:97]
	v_pk_mul_f32 v[254:255], v[2:3], v[98:99]
	v_pk_mul_f32 v[160:161], v[4:5], v[100:101]
	v_pk_fma_f32 v[246:247], v[6:7], v[102:103], v[246:247]
	v_pk_fma_f32 v[254:255], v[8:9], v[104:105], v[254:255]
	v_pk_fma_f32 v[160:161], v[10:11], v[106:107], v[160:161]
	v_pk_fma_f32 v[246:247], v[12:13], v[108:109], v[246:247]
	v_pk_fma_f32 v[254:255], v[14:15], v[110:111], v[254:255]
	v_pk_fma_f32 v[160:161], v[16:17], v[112:113], v[160:161]
	v_pk_fma_f32 v[246:247], v[18:19], v[114:115], v[246:247]
	v_pk_fma_f32 v[254:255], v[20:21], v[116:117], v[254:255]
	v_pk_fma_f32 v[160:161], v[22:23], v[118:119], v[160:161]
	v_pk_fma_f32 v[246:247], v[24:25], v[120:121], v[246:247]
	v_pk_fma_f32 v[254:255], v[26:27], v[122:123], v[254:255]
	v_pk_fma_f32 v[160:161], v[28:29], v[124:125], v[160:161]
	v_pk_fma_f32 v[246:247], v[30:31], v[126:127], v[246:247]
	v_pk_add_f32 v[254:255], v[254:255], v[160:161]
	s_nop 0
	v_pk_add_f32 v[246:247], v[246:247], v[254:255]
	s_nop 0
	v_add_f32_e32 v162, v246, v247
	v_readlane_b32 s54, v90, 10
	v_readlane_b32 s55, v90, 11
	s_mul_i32 s0, s54, 0x300
	s_mul_i32 s1, s55, 0x300
	v_add_u32_e32 v167, s0, v195
	s_and_saveexec_b64 s[98:99], s[40:41]
	v_add_u32_e32 v167, s1, v195
	s_mov_b64 exec, s[98:99]
	s_waitcnt vmcnt(14)
; __device__ void peer_gather_phase(const Params& P, int l, bool do_store) {
;     ...
;         hs += dpp_row_shr(hs, 1); hs += dpp_row_shr(hs, 2); hs += dpp_row_shr(hs, 4); hs += dpp_row_shr(hs, 8);
;         hs += __builtin_bit_cast(float, __builtin_amdgcn_update_dpp(0, __builtin_bit_cast(int, hs), 0x142, 0xa, 0xf, false));
;         const float da = __builtin_bit_cast(float, __builtin_amdgcn_readlane(__builtin_bit_cast(int, hs), 31));
;         const float db = __builtin_bit_cast(float, __builtin_amdgcn_readlane(__builtin_bit_cast(int, hs), 63));
;         dvec = (lane == kb + 2 * pr) ? da : dvec;
;         dvec = (lane == kb + 2 * pr + 1) ? db : dvec;
;       }
;       const float sux = (bt < 8) ? sux0 : sux1;
;       const float gsx = (bt < 8) ? gsx0 : gsx1;
;       const float avec = gelu_t(dvec * sux) * gsx;
	v_cvt_scalef32_pk32_f32_fp6 v[0:31], v[228:233], 1.0
	global_load_dwordx2 v[232:233], v167, s[62:63] offset:16
	global_load_dwordx4 v[228:231], v167, s[62:63]
	v_pk_mul_f32 v[246:247], v[0:1], v[96:97]
	v_pk_mul_f32 v[254:255], v[2:3], v[98:99]
	v_pk_mul_f32 v[160:161], v[4:5], v[100:101]
	v_pk_fma_f32 v[246:247], v[6:7], v[102:103], v[246:247]
	v_pk_fma_f32 v[254:255], v[8:9], v[104:105], v[254:255]
	v_pk_fma_f32 v[160:161], v[10:11], v[106:107], v[160:161]
	v_pk_fma_f32 v[246:247], v[12:13], v[108:109], v[246:247]
	v_pk_fma_f32 v[254:255], v[14:15], v[110:111], v[254:255]
	v_pk_fma_f32 v[160:161], v[16:17], v[112:113], v[160:161]
	v_pk_fma_f32 v[246:247], v[18:19], v[114:115], v[246:247]
	v_pk_fma_f32 v[254:255], v[20:21], v[116:117], v[254:255]
	v_pk_fma_f32 v[160:161], v[22:23], v[118:119], v[160:161]
	v_pk_fma_f32 v[246:247], v[24:25], v[120:121], v[246:247]
	v_pk_fma_f32 v[254:255], v[26:27], v[122:123], v[254:255]
	v_pk_fma_f32 v[160:161], v[28:29], v[124:125], v[160:161]
	v_pk_fma_f32 v[246:247], v[30:31], v[126:127], v[246:247]
	v_pk_add_f32 v[254:255], v[254:255], v[160:161]
	s_nop 0
	v_pk_add_f32 v[246:247], v[246:247], v[254:255]
	s_nop 0
	v_add_f32_e32 v163, v246, v247
	v_readlane_b32 s54, v90, 12
	v_readlane_b32 s55, v90, 13
	s_mul_i32 s0, s54, 0x300
	s_mul_i32 s1, s55, 0x300
	v_add_u32_e32 v167, s0, v195
	s_and_saveexec_b64 s[98:99], s[40:41]
	v_add_u32_e32 v167, s1, v195
	s_mov_b64 exec, s[98:99]
	s_waitcnt vmcnt(14)
	v_cvt_scalef32_pk32_f32_fp6 v[0:31], v[234:239], 1.0
	global_load_dwordx2 v[238:239], v167, s[62:63] offset:16
	global_load_dwordx4 v[234:237], v167, s[62:63]
	v_pk_mul_f32 v[246:247], v[0:1], v[96:97]
	v_pk_mul_f32 v[254:255], v[2:3], v[98:99]
	v_pk_mul_f32 v[160:161], v[4:5], v[100:101]
	v_pk_fma_f32 v[246:247], v[6:7], v[102:103], v[246:247]
	v_pk_fma_f32 v[254:255], v[8:9], v[104:105], v[254:255]
	v_pk_fma_f32 v[160:161], v[10:11], v[106:107], v[160:161]
	v_pk_fma_f32 v[246:247], v[12:13], v[108:109], v[246:247]
	v_pk_fma_f32 v[254:255], v[14:15], v[110:111], v[254:255]
	v_pk_fma_f32 v[160:161], v[16:17], v[112:113], v[160:161]
	v_pk_fma_f32 v[246:247], v[18:19], v[114:115], v[246:247]
	v_pk_fma_f32 v[254:255], v[20:21], v[116:117], v[254:255]
	v_pk_fma_f32 v[160:161], v[22:23], v[118:119], v[160:161]
	v_pk_fma_f32 v[246:247], v[24:25], v[120:121], v[246:247]
	v_pk_fma_f32 v[254:255], v[26:27], v[122:123], v[254:255]
	v_pk_fma_f32 v[160:161], v[28:29], v[124:125], v[160:161]
	v_pk_fma_f32 v[246:247], v[30:31], v[126:127], v[246:247]
	v_pk_add_f32 v[254:255], v[254:255], v[160:161]
	s_nop 0
	v_pk_add_f32 v[246:247], v[246:247], v[254:255]
	s_nop 0
	v_add_f32_e32 v164, v246, v247
	v_readlane_b32 s54, v90, 14
	v_readlane_b32 s55, v90, 15
	s_mul_i32 s0, s54, 0x300
	s_mul_i32 s1, s55, 0x300
	v_add_u32_e32 v167, s0, v195
	s_and_saveexec_b64 s[98:99], s[40:41]
	v_add_u32_e32 v167, s1, v195
	s_mov_b64 exec, s[98:99]
	s_waitcnt vmcnt(14)
	v_cvt_scalef32_pk32_f32_fp6 v[0:31], v[240:245], 1.0
	global_load_dwordx2 v[244:245], v167, s[62:63] offset:16
	global_load_dwordx4 v[240:243], v167, s[62:63]
	v_pk_mul_f32 v[246:247], v[0:1], v[96:97]
	v_pk_mul_f32 v[254:255], v[2:3], v[98:99]
	v_pk_mul_f32 v[160:161], v[4:5], v[100:101]
	v_pk_fma_f32 v[246:247], v[6:7], v[102:103], v[246:247]
	v_pk_fma_f32 v[254:255], v[8:9], v[104:105], v[254:255]
	v_pk_fma_f32 v[160:161], v[10:11], v[106:107], v[160:161]
	v_pk_fma_f32 v[246:247], v[12:13], v[108:109], v[246:247]
	v_pk_fma_f32 v[254:255], v[14:15], v[110:111], v[254:255]
	v_pk_fma_f32 v[160:161], v[16:17], v[112:113], v[160:161]
	v_pk_fma_f32 v[246:247], v[18:19], v[114:115], v[246:247]
	v_pk_fma_f32 v[254:255], v[20:21], v[116:117], v[254:255]
	v_pk_fma_f32 v[160:161], v[22:23], v[118:119], v[160:161]
	v_pk_fma_f32 v[246:247], v[24:25], v[120:121], v[246:247]
	v_pk_fma_f32 v[254:255], v[26:27], v[122:123], v[254:255]
	v_pk_fma_f32 v[160:161], v[28:29], v[124:125], v[160:161]
	v_pk_fma_f32 v[246:247], v[30:31], v[126:127], v[246:247]
	v_pk_add_f32 v[254:255], v[254:255], v[160:161]
	s_nop 0
	v_pk_add_f32 v[246:247], v[246:247], v[254:255]
	s_nop 0
	v_add_f32_e32 v165, v246, v247
	v_add_f32_dpp v162, v162, v162 row_shr:1 row_mask:0xf bank_mask:0xf bound_ctrl:1
	v_add_f32_dpp v163, v163, v163 row_shr:1 row_mask:0xf bank_mask:0xf bound_ctrl:1
	v_add_f32_dpp v164, v164, v164 row_shr:1 row_mask:0xf bank_mask:0xf bound_ctrl:1
	v_add_f32_dpp v165, v165, v165 row_shr:1 row_mask:0xf bank_mask:0xf bound_ctrl:1
	v_add_f32_dpp v162, v162, v162 row_shr:2 row_mask:0xf bank_mask:0xf bound_ctrl:1
	v_add_f32_dpp v163, v163, v163 row_shr:2 row_mask:0xf bank_mask:0xf bound_ctrl:1
	v_add_f32_dpp v164, v164, v164 row_shr:2 row_mask:0xf bank_mask:0xf bound_ctrl:1
	v_add_f32_dpp v165, v165, v165 row_shr:2 row_mask:0xf bank_mask:0xf bound_ctrl:1
	v_add_f32_dpp v162, v162, v162 row_shr:4 row_mask:0xf bank_mask:0xf bound_ctrl:1
	v_add_f32_dpp v163, v163, v163 row_shr:4 row_mask:0xf bank_mask:0xf bound_ctrl:1
	v_add_f32_dpp v164, v164, v164 row_shr:4 row_mask:0xf bank_mask:0xf bound_ctrl:1
	v_add_f32_dpp v165, v165, v165 row_shr:4 row_mask:0xf bank_mask:0xf bound_ctrl:1
	v_add_f32_dpp v162, v162, v162 row_shr:8 row_mask:0xf bank_mask:0xf bound_ctrl:1
	v_add_f32_dpp v163, v163, v163 row_shr:8 row_mask:0xf bank_mask:0xf bound_ctrl:1
	v_add_f32_dpp v164, v164, v164 row_shr:8 row_mask:0xf bank_mask:0xf bound_ctrl:1
	v_add_f32_dpp v165, v165, v165 row_shr:8 row_mask:0xf bank_mask:0xf bound_ctrl:1
	v_add_f32_dpp v162, v162, v162 row_bcast:15 row_mask:0xa bank_mask:0xf
	v_add_f32_dpp v163, v163, v163 row_bcast:15 row_mask:0xa bank_mask:0xf
	v_add_f32_dpp v164, v164, v164 row_bcast:15 row_mask:0xa bank_mask:0xf
	v_add_f32_dpp v165, v165, v165 row_bcast:15 row_mask:0xa bank_mask:0xf
	s_nop 1
	v_readlane_b32 s46, v162, 31
	v_readlane_b32 s47, v162, 63
	v_readlane_b32 s48, v163, 31
	v_readlane_b32 s49, v163, 63
	v_readlane_b32 s50, v164, 31
	v_readlane_b32 s51, v164, 63
	v_readlane_b32 s52, v165, 31
	v_readlane_b32 s53, v165, 63
	v_writelane_b32 v166, s46, 56
	s_nop 1
	v_writelane_b32 v166, s47, 57
	v_writelane_b32 v166, s48, 58
	v_writelane_b32 v166, s49, 59
	v_writelane_b32 v166, s50, 60
	v_writelane_b32 v166, s51, 61
	v_writelane_b32 v166, s52, 62
	v_writelane_b32 v166, s53, 63
	s_nop 1
	v_mul_f32_e32 v0, v189, v166
	v_mul_f32_e32 v1, 0x3d372713, v0
	v_mul_f32_e32 v1, v0, v1
	v_fma_f32 v1, v0, v1, v0
	v_mul_f32_e32 v1, 0x3f4c422a, v1
	v_add_f32_e32 v1, v1, v1
	v_mul_f32_e32 v1, 0x3fb8aa3b, v1
	v_exp_f32_e32 v1, v1
	v_mul_f32_e32 v0, 0.5, v0
	v_add_f32_e32 v1, 1.0, v1
	v_div_scale_f32 v2, s[0:1], v1, v1, 2.0
	v_rcp_f32_e32 v3, v2
	s_nop 0
	v_fma_f32 v4, -v2, v3, 1.0
	v_fmac_f32_e32 v3, v4, v3
	v_div_scale_f32 v4, vcc, 2.0, v1, 2.0
	v_mul_f32_e32 v5, v4, v3
	v_fma_f32 v6, -v2, v5, v4
	v_fmac_f32_e32 v5, v6, v3
	v_fma_f32 v2, -v2, v5, v4
	v_div_fmas_f32 v2, v2, v3, v5
	v_div_fixup_f32 v1, v2, v1, 2.0
	v_sub_f32_e32 v1, 1.0, v1
	v_add_f32_e32 v1, 1.0, v1
	v_mul_f32_e32 v0, v0, v1
	v_mul_f32_e32 v167, v191, v0
	s_nop 1
	v_readlane_b32 s0, v167, 0
	s_waitcnt vmcnt(48)
; __device__ void peer_gather_phase(const Params& P, int l, bool do_store) {
;     ...
;         const int ea = __builtin_amdgcn_readlane(evs, kb + 2 * pr), eb = __builtin_amdgcn_readlane(evs, kb + 2 * pr + 1);
;         const uint2* up = (const uint2*)(U + (size_t)(uphi ? eb : ea) * 768);
;         u6[3 * pr] = up[0]; u6[3 * pr + 1] = up[1]; u6[3 * pr + 2] = up[2];
;         v8[2 * pr] = *(const uint2*)(V + (size_t)ea * 512);
;         v8[2 * pr + 1] = *(const uint2*)(V + (size_t)eb * 512);
;     ...
; #pragma unroll
;       for (int j = 0; j < 8; ++j) {
;         const float a = __builtin_bit_cast(float, __builtin_amdgcn_readlane(__builtin_bit_cast(int, avec), kb + j));
;         const f32x2 aa = f32x2{a, a};
;         y[0] += aa * __builtin_amdgcn_cvt_scalef32_pk_f32_fp4(v8[j].x, 1.0f, 0); y[1] += aa * __builtin_amdgcn_cvt_scalef32_pk_f32_fp4(v8[j].x, 1.0f, 1);
;         y[2] += aa * __builtin_amdgcn_cvt_scalef32_pk_f32_fp4(v8[j].x, 1.0f, 2); y[3] += aa * __builtin_amdgcn_cvt_scalef32_pk_f32_fp4(v8[j].x, 1.0f, 3);
;         y[4] += aa * __builtin_amdgcn_cvt_scalef32_pk_f32_fp4(v8[j].y, 1.0f, 0); y[5] += aa * __builtin_amdgcn_cvt_scalef32_pk_f32_fp4(v8[j].y, 1.0f, 1);
;         y[6] += aa * __builtin_amdgcn_cvt_scalef32_pk_f32_fp4(v8[j].y, 1.0f, 2); y[7] += aa * __builtin_amdgcn_cvt_scalef32_pk_f32_fp4(v8[j].y, 1.0f, 3);
;       }
	v_cvt_scalef32_pk_f32_fp4 v[0:1], v144, 1.0
	v_cvt_scalef32_pk_f32_fp4 v[2:3], v144, 1.0 op_sel:[1,0,0]
	v_cvt_scalef32_pk_f32_fp4 v[4:5], v144, 1.0 op_sel:[0,1,0]
	v_cvt_scalef32_pk_f32_fp4 v[6:7], v144, 1.0 op_sel:[1,1,0]
	v_cvt_scalef32_pk_f32_fp4 v[8:9], v145, 1.0
	v_cvt_scalef32_pk_f32_fp4 v[10:11], v145, 1.0 op_sel:[1,0,0]
	v_cvt_scalef32_pk_f32_fp4 v[12:13], v145, 1.0 op_sel:[0,1,0]
	v_cvt_scalef32_pk_f32_fp4 v[14:15], v145, 1.0 op_sel:[1,1,0]
	v_readlane_b32 s54, v92, 16
	s_lshl_b32 s56, s54, 9
	s_add_u32 s56, s64, s56
	s_addc_u32 s57, s65, 0
	global_load_dwordx2 v[144:145], v227, s[56:57]
	v_pk_fma_f32 v[130:131], v[0:1], s[0:1], v[130:131] op_sel_hi:[1,0,1]
	v_pk_fma_f32 v[138:139], v[2:3], s[0:1], v[138:139] op_sel_hi:[1,0,1]
	v_pk_fma_f32 v[140:141], v[4:5], s[0:1], v[140:141] op_sel_hi:[1,0,1]
	v_pk_fma_f32 v[142:143], v[6:7], s[0:1], v[142:143] op_sel_hi:[1,0,1]
	v_pk_fma_f32 v[128:129], v[8:9], s[0:1], v[128:129] op_sel_hi:[1,0,1]
	v_pk_fma_f32 v[132:133], v[10:11], s[0:1], v[132:133] op_sel_hi:[1,0,1]
	v_pk_fma_f32 v[134:135], v[12:13], s[0:1], v[134:135] op_sel_hi:[1,0,1]
	v_pk_fma_f32 v[136:137], v[14:15], s[0:1], v[136:137] op_sel_hi:[1,0,1]
	v_readlane_b32 s0, v167, 1
	s_waitcnt vmcnt(48)
	v_cvt_scalef32_pk_f32_fp4 v[0:1], v146, 1.0
	v_cvt_scalef32_pk_f32_fp4 v[2:3], v146, 1.0 op_sel:[1,0,0]
	v_cvt_scalef32_pk_f32_fp4 v[4:5], v146, 1.0 op_sel:[0,1,0]
	v_cvt_scalef32_pk_f32_fp4 v[6:7], v146, 1.0 op_sel:[1,1,0]
	v_cvt_scalef32_pk_f32_fp4 v[8:9], v147, 1.0
	v_cvt_scalef32_pk_f32_fp4 v[10:11], v147, 1.0 op_sel:[1,0,0]
	v_cvt_scalef32_pk_f32_fp4 v[12:13], v147, 1.0 op_sel:[0,1,0]
	v_cvt_scalef32_pk_f32_fp4 v[14:15], v147, 1.0 op_sel:[1,1,0]
	v_readlane_b32 s54, v92, 17
	s_lshl_b32 s56, s54, 9
	s_add_u32 s56, s64, s56
	s_addc_u32 s57, s65, 0
	global_load_dwordx2 v[146:147], v227, s[56:57]
	v_pk_fma_f32 v[130:131], v[0:1], s[0:1], v[130:131] op_sel_hi:[1,0,1]
	v_pk_fma_f32 v[138:139], v[2:3], s[0:1], v[138:139] op_sel_hi:[1,0,1]
	v_pk_fma_f32 v[140:141], v[4:5], s[0:1], v[140:141] op_sel_hi:[1,0,1]
	v_pk_fma_f32 v[142:143], v[6:7], s[0:1], v[142:143] op_sel_hi:[1,0,1]
	v_pk_fma_f32 v[128:129], v[8:9], s[0:1], v[128:129] op_sel_hi:[1,0,1]
	v_pk_fma_f32 v[132:133], v[10:11], s[0:1], v[132:133] op_sel_hi:[1,0,1]
	v_pk_fma_f32 v[134:135], v[12:13], s[0:1], v[134:135] op_sel_hi:[1,0,1]
	v_pk_fma_f32 v[136:137], v[14:15], s[0:1], v[136:137] op_sel_hi:[1,0,1]
	v_readlane_b32 s0, v167, 2
	s_waitcnt vmcnt(48)
	v_cvt_scalef32_pk_f32_fp4 v[0:1], v148, 1.0
	v_cvt_scalef32_pk_f32_fp4 v[2:3], v148, 1.0 op_sel:[1,0,0]
	v_cvt_scalef32_pk_f32_fp4 v[4:5], v148, 1.0 op_sel:[0,1,0]
	v_cvt_scalef32_pk_f32_fp4 v[6:7], v148, 1.0 op_sel:[1,1,0]
	v_cvt_scalef32_pk_f32_fp4 v[8:9], v149, 1.0
	v_cvt_scalef32_pk_f32_fp4 v[10:11], v149, 1.0 op_sel:[1,0,0]
	v_cvt_scalef32_pk_f32_fp4 v[12:13], v149, 1.0 op_sel:[0,1,0]
	v_cvt_scalef32_pk_f32_fp4 v[14:15], v149, 1.0 op_sel:[1,1,0]
	v_readlane_b32 s54, v92, 18
	s_lshl_b32 s56, s54, 9
	s_add_u32 s56, s64, s56
	s_addc_u32 s57, s65, 0
	global_load_dwordx2 v[148:149], v227, s[56:57]
	v_pk_fma_f32 v[130:131], v[0:1], s[0:1], v[130:131] op_sel_hi:[1,0,1]
	v_pk_fma_f32 v[138:139], v[2:3], s[0:1], v[138:139] op_sel_hi:[1,0,1]
	v_pk_fma_f32 v[140:141], v[4:5], s[0:1], v[140:141] op_sel_hi:[1,0,1]
	v_pk_fma_f32 v[142:143], v[6:7], s[0:1], v[142:143] op_sel_hi:[1,0,1]
	v_pk_fma_f32 v[128:129], v[8:9], s[0:1], v[128:129] op_sel_hi:[1,0,1]
	v_pk_fma_f32 v[132:133], v[10:11], s[0:1], v[132:133] op_sel_hi:[1,0,1]
	v_pk_fma_f32 v[134:135], v[12:13], s[0:1], v[134:135] op_sel_hi:[1,0,1]
	v_pk_fma_f32 v[136:137], v[14:15], s[0:1], v[136:137] op_sel_hi:[1,0,1]
	v_readlane_b32 s0, v167, 3
	s_waitcnt vmcnt(48)
	v_cvt_scalef32_pk_f32_fp4 v[0:1], v150, 1.0
	v_cvt_scalef32_pk_f32_fp4 v[2:3], v150, 1.0 op_sel:[1,0,0]
	v_cvt_scalef32_pk_f32_fp4 v[4:5], v150, 1.0 op_sel:[0,1,0]
	v_cvt_scalef32_pk_f32_fp4 v[6:7], v150, 1.0 op_sel:[1,1,0]
	v_cvt_scalef32_pk_f32_fp4 v[8:9], v151, 1.0
	v_cvt_scalef32_pk_f32_fp4 v[10:11], v151, 1.0 op_sel:[1,0,0]
	v_cvt_scalef32_pk_f32_fp4 v[12:13], v151, 1.0 op_sel:[0,1,0]
	v_cvt_scalef32_pk_f32_fp4 v[14:15], v151, 1.0 op_sel:[1,1,0]
	v_readlane_b32 s54, v92, 19
	s_lshl_b32 s56, s54, 9
	s_add_u32 s56, s64, s56
	s_addc_u32 s57, s65, 0
	global_load_dwordx2 v[150:151], v227, s[56:57]
	v_pk_fma_f32 v[130:131], v[0:1], s[0:1], v[130:131] op_sel_hi:[1,0,1]
	v_pk_fma_f32 v[138:139], v[2:3], s[0:1], v[138:139] op_sel_hi:[1,0,1]
	v_pk_fma_f32 v[140:141], v[4:5], s[0:1], v[140:141] op_sel_hi:[1,0,1]
	v_pk_fma_f32 v[142:143], v[6:7], s[0:1], v[142:143] op_sel_hi:[1,0,1]
	v_pk_fma_f32 v[128:129], v[8:9], s[0:1], v[128:129] op_sel_hi:[1,0,1]
	v_pk_fma_f32 v[132:133], v[10:11], s[0:1], v[132:133] op_sel_hi:[1,0,1]
	v_pk_fma_f32 v[134:135], v[12:13], s[0:1], v[134:135] op_sel_hi:[1,0,1]
	v_pk_fma_f32 v[136:137], v[14:15], s[0:1], v[136:137] op_sel_hi:[1,0,1]
	v_readlane_b32 s0, v167, 4
	s_waitcnt vmcnt(48)
	v_cvt_scalef32_pk_f32_fp4 v[0:1], v152, 1.0
	v_cvt_scalef32_pk_f32_fp4 v[2:3], v152, 1.0 op_sel:[1,0,0]
	v_cvt_scalef32_pk_f32_fp4 v[4:5], v152, 1.0 op_sel:[0,1,0]
	v_cvt_scalef32_pk_f32_fp4 v[6:7], v152, 1.0 op_sel:[1,1,0]
	v_cvt_scalef32_pk_f32_fp4 v[8:9], v153, 1.0
	v_cvt_scalef32_pk_f32_fp4 v[10:11], v153, 1.0 op_sel:[1,0,0]
	v_cvt_scalef32_pk_f32_fp4 v[12:13], v153, 1.0 op_sel:[0,1,0]
	v_cvt_scalef32_pk_f32_fp4 v[14:15], v153, 1.0 op_sel:[1,1,0]
	v_readlane_b32 s54, v92, 20
	s_lshl_b32 s56, s54, 9
	s_add_u32 s56, s64, s56
	s_addc_u32 s57, s65, 0
	global_load_dwordx2 v[152:153], v227, s[56:57]
	v_pk_fma_f32 v[130:131], v[0:1], s[0:1], v[130:131] op_sel_hi:[1,0,1]
	v_pk_fma_f32 v[138:139], v[2:3], s[0:1], v[138:139] op_sel_hi:[1,0,1]
	v_pk_fma_f32 v[140:141], v[4:5], s[0:1], v[140:141] op_sel_hi:[1,0,1]
	v_pk_fma_f32 v[142:143], v[6:7], s[0:1], v[142:143] op_sel_hi:[1,0,1]
	v_pk_fma_f32 v[128:129], v[8:9], s[0:1], v[128:129] op_sel_hi:[1,0,1]
	v_pk_fma_f32 v[132:133], v[10:11], s[0:1], v[132:133] op_sel_hi:[1,0,1]
	v_pk_fma_f32 v[134:135], v[12:13], s[0:1], v[134:135] op_sel_hi:[1,0,1]
	v_pk_fma_f32 v[136:137], v[14:15], s[0:1], v[136:137] op_sel_hi:[1,0,1]
	v_readlane_b32 s0, v167, 5
	s_waitcnt vmcnt(48)
; __device__ void peer_gather_phase(const Params& P, int l, bool do_store) {
;     ...
;         const int ea = __builtin_amdgcn_readlane(evs, kb + 2 * pr), eb = __builtin_amdgcn_readlane(evs, kb + 2 * pr + 1);
;         const uint2* up = (const uint2*)(U + (size_t)(uphi ? eb : ea) * 768);
;         u6[3 * pr] = up[0]; u6[3 * pr + 1] = up[1]; u6[3 * pr + 2] = up[2];
;         v8[2 * pr] = *(const uint2*)(V + (size_t)ea * 512);
;         v8[2 * pr + 1] = *(const uint2*)(V + (size_t)eb * 512);
;     ...
; #pragma unroll
;       for (int j = 0; j < 8; ++j) {
;         const float a = __builtin_bit_cast(float, __builtin_amdgcn_readlane(__builtin_bit_cast(int, avec), kb + j));
;         const f32x2 aa = f32x2{a, a};
;         y[0] += aa * __builtin_amdgcn_cvt_scalef32_pk_f32_fp4(v8[j].x, 1.0f, 0); y[1] += aa * __builtin_amdgcn_cvt_scalef32_pk_f32_fp4(v8[j].x, 1.0f, 1);
;         y[2] += aa * __builtin_amdgcn_cvt_scalef32_pk_f32_fp4(v8[j].x, 1.0f, 2); y[3] += aa * __builtin_amdgcn_cvt_scalef32_pk_f32_fp4(v8[j].x, 1.0f, 3);
;         y[4] += aa * __builtin_amdgcn_cvt_scalef32_pk_f32_fp4(v8[j].y, 1.0f, 0); y[5] += aa * __builtin_amdgcn_cvt_scalef32_pk_f32_fp4(v8[j].y, 1.0f, 1);
;         y[6] += aa * __builtin_amdgcn_cvt_scalef32_pk_f32_fp4(v8[j].y, 1.0f, 2); y[7] += aa * __builtin_amdgcn_cvt_scalef32_pk_f32_fp4(v8[j].y, 1.0f, 3);
;       }
	v_cvt_scalef32_pk_f32_fp4 v[0:1], v154, 1.0
	v_cvt_scalef32_pk_f32_fp4 v[2:3], v154, 1.0 op_sel:[1,0,0]
	v_cvt_scalef32_pk_f32_fp4 v[4:5], v154, 1.0 op_sel:[0,1,0]
	v_cvt_scalef32_pk_f32_fp4 v[6:7], v154, 1.0 op_sel:[1,1,0]
	v_cvt_scalef32_pk_f32_fp4 v[8:9], v155, 1.0
	v_cvt_scalef32_pk_f32_fp4 v[10:11], v155, 1.0 op_sel:[1,0,0]
	v_cvt_scalef32_pk_f32_fp4 v[12:13], v155, 1.0 op_sel:[0,1,0]
	v_cvt_scalef32_pk_f32_fp4 v[14:15], v155, 1.0 op_sel:[1,1,0]
	v_readlane_b32 s54, v92, 21
	s_lshl_b32 s56, s54, 9
	s_add_u32 s56, s64, s56
	s_addc_u32 s57, s65, 0
	global_load_dwordx2 v[154:155], v227, s[56:57]
	v_pk_fma_f32 v[130:131], v[0:1], s[0:1], v[130:131] op_sel_hi:[1,0,1]
	v_pk_fma_f32 v[138:139], v[2:3], s[0:1], v[138:139] op_sel_hi:[1,0,1]
	v_pk_fma_f32 v[140:141], v[4:5], s[0:1], v[140:141] op_sel_hi:[1,0,1]
	v_pk_fma_f32 v[142:143], v[6:7], s[0:1], v[142:143] op_sel_hi:[1,0,1]
	v_pk_fma_f32 v[128:129], v[8:9], s[0:1], v[128:129] op_sel_hi:[1,0,1]
	v_pk_fma_f32 v[132:133], v[10:11], s[0:1], v[132:133] op_sel_hi:[1,0,1]
	v_pk_fma_f32 v[134:135], v[12:13], s[0:1], v[134:135] op_sel_hi:[1,0,1]
	v_pk_fma_f32 v[136:137], v[14:15], s[0:1], v[136:137] op_sel_hi:[1,0,1]
	v_readlane_b32 s0, v167, 6
	s_waitcnt vmcnt(48)
	v_cvt_scalef32_pk_f32_fp4 v[0:1], v156, 1.0
	v_cvt_scalef32_pk_f32_fp4 v[2:3], v156, 1.0 op_sel:[1,0,0]
	v_cvt_scalef32_pk_f32_fp4 v[4:5], v156, 1.0 op_sel:[0,1,0]
	v_cvt_scalef32_pk_f32_fp4 v[6:7], v156, 1.0 op_sel:[1,1,0]
	v_cvt_scalef32_pk_f32_fp4 v[8:9], v157, 1.0
	v_cvt_scalef32_pk_f32_fp4 v[10:11], v157, 1.0 op_sel:[1,0,0]
	v_cvt_scalef32_pk_f32_fp4 v[12:13], v157, 1.0 op_sel:[0,1,0]
	v_cvt_scalef32_pk_f32_fp4 v[14:15], v157, 1.0 op_sel:[1,1,0]
	v_readlane_b32 s54, v92, 22
	s_lshl_b32 s56, s54, 9
	s_add_u32 s56, s64, s56
	s_addc_u32 s57, s65, 0
	global_load_dwordx2 v[156:157], v227, s[56:57]
	v_pk_fma_f32 v[130:131], v[0:1], s[0:1], v[130:131] op_sel_hi:[1,0,1]
	v_pk_fma_f32 v[138:139], v[2:3], s[0:1], v[138:139] op_sel_hi:[1,0,1]
	v_pk_fma_f32 v[140:141], v[4:5], s[0:1], v[140:141] op_sel_hi:[1,0,1]
	v_pk_fma_f32 v[142:143], v[6:7], s[0:1], v[142:143] op_sel_hi:[1,0,1]
	v_pk_fma_f32 v[128:129], v[8:9], s[0:1], v[128:129] op_sel_hi:[1,0,1]
	v_pk_fma_f32 v[132:133], v[10:11], s[0:1], v[132:133] op_sel_hi:[1,0,1]
	v_pk_fma_f32 v[134:135], v[12:13], s[0:1], v[134:135] op_sel_hi:[1,0,1]
	v_pk_fma_f32 v[136:137], v[14:15], s[0:1], v[136:137] op_sel_hi:[1,0,1]
	v_readlane_b32 s0, v167, 7
	s_waitcnt vmcnt(48)
	v_cvt_scalef32_pk_f32_fp4 v[0:1], v158, 1.0
	v_cvt_scalef32_pk_f32_fp4 v[2:3], v158, 1.0 op_sel:[1,0,0]
	v_cvt_scalef32_pk_f32_fp4 v[4:5], v158, 1.0 op_sel:[0,1,0]
	v_cvt_scalef32_pk_f32_fp4 v[6:7], v158, 1.0 op_sel:[1,1,0]
	v_cvt_scalef32_pk_f32_fp4 v[8:9], v159, 1.0
	v_cvt_scalef32_pk_f32_fp4 v[10:11], v159, 1.0 op_sel:[1,0,0]
	v_cvt_scalef32_pk_f32_fp4 v[12:13], v159, 1.0 op_sel:[0,1,0]
	v_cvt_scalef32_pk_f32_fp4 v[14:15], v159, 1.0 op_sel:[1,1,0]
	v_readlane_b32 s54, v92, 23
	s_lshl_b32 s56, s54, 9
	s_add_u32 s56, s64, s56
	s_addc_u32 s57, s65, 0
	global_load_dwordx2 v[158:159], v227, s[56:57]
	v_pk_fma_f32 v[130:131], v[0:1], s[0:1], v[130:131] op_sel_hi:[1,0,1]
	v_pk_fma_f32 v[138:139], v[2:3], s[0:1], v[138:139] op_sel_hi:[1,0,1]
	v_pk_fma_f32 v[140:141], v[4:5], s[0:1], v[140:141] op_sel_hi:[1,0,1]
	v_pk_fma_f32 v[142:143], v[6:7], s[0:1], v[142:143] op_sel_hi:[1,0,1]
	v_pk_fma_f32 v[128:129], v[8:9], s[0:1], v[128:129] op_sel_hi:[1,0,1]
	v_pk_fma_f32 v[132:133], v[10:11], s[0:1], v[132:133] op_sel_hi:[1,0,1]
	v_pk_fma_f32 v[134:135], v[12:13], s[0:1], v[134:135] op_sel_hi:[1,0,1]
	v_pk_fma_f32 v[136:137], v[14:15], s[0:1], v[136:137] op_sel_hi:[1,0,1]
	v_readlane_b32 s0, v167, 8
	s_waitcnt vmcnt(48)
	v_cvt_scalef32_pk_f32_fp4 v[0:1], v168, 1.0
	v_cvt_scalef32_pk_f32_fp4 v[2:3], v168, 1.0 op_sel:[1,0,0]
	v_cvt_scalef32_pk_f32_fp4 v[4:5], v168, 1.0 op_sel:[0,1,0]
	v_cvt_scalef32_pk_f32_fp4 v[6:7], v168, 1.0 op_sel:[1,1,0]
	v_cvt_scalef32_pk_f32_fp4 v[8:9], v169, 1.0
	v_cvt_scalef32_pk_f32_fp4 v[10:11], v169, 1.0 op_sel:[1,0,0]
	v_cvt_scalef32_pk_f32_fp4 v[12:13], v169, 1.0 op_sel:[0,1,0]
	v_cvt_scalef32_pk_f32_fp4 v[14:15], v169, 1.0 op_sel:[1,1,0]
	v_readlane_b32 s54, v92, 24
	s_lshl_b32 s56, s54, 9
	s_add_u32 s56, s64, s56
	s_addc_u32 s57, s65, 0
	global_load_dwordx2 v[168:169], v227, s[56:57]
	v_pk_fma_f32 v[130:131], v[0:1], s[0:1], v[130:131] op_sel_hi:[1,0,1]
	v_pk_fma_f32 v[138:139], v[2:3], s[0:1], v[138:139] op_sel_hi:[1,0,1]
	v_pk_fma_f32 v[140:141], v[4:5], s[0:1], v[140:141] op_sel_hi:[1,0,1]
	v_pk_fma_f32 v[142:143], v[6:7], s[0:1], v[142:143] op_sel_hi:[1,0,1]
	v_pk_fma_f32 v[128:129], v[8:9], s[0:1], v[128:129] op_sel_hi:[1,0,1]
	v_pk_fma_f32 v[132:133], v[10:11], s[0:1], v[132:133] op_sel_hi:[1,0,1]
	v_pk_fma_f32 v[134:135], v[12:13], s[0:1], v[134:135] op_sel_hi:[1,0,1]
	v_pk_fma_f32 v[136:137], v[14:15], s[0:1], v[136:137] op_sel_hi:[1,0,1]
	v_readlane_b32 s0, v167, 9
	s_waitcnt vmcnt(48)
	v_cvt_scalef32_pk_f32_fp4 v[0:1], v170, 1.0
	v_cvt_scalef32_pk_f32_fp4 v[2:3], v170, 1.0 op_sel:[1,0,0]
	v_cvt_scalef32_pk_f32_fp4 v[4:5], v170, 1.0 op_sel:[0,1,0]
	v_cvt_scalef32_pk_f32_fp4 v[6:7], v170, 1.0 op_sel:[1,1,0]
	v_cvt_scalef32_pk_f32_fp4 v[8:9], v171, 1.0
	v_cvt_scalef32_pk_f32_fp4 v[10:11], v171, 1.0 op_sel:[1,0,0]
	v_cvt_scalef32_pk_f32_fp4 v[12:13], v171, 1.0 op_sel:[0,1,0]
	v_cvt_scalef32_pk_f32_fp4 v[14:15], v171, 1.0 op_sel:[1,1,0]
	v_readlane_b32 s54, v92, 25
	s_lshl_b32 s56, s54, 9
	s_add_u32 s56, s64, s56
	s_addc_u32 s57, s65, 0
	global_load_dwordx2 v[170:171], v227, s[56:57]
	v_pk_fma_f32 v[130:131], v[0:1], s[0:1], v[130:131] op_sel_hi:[1,0,1]
	v_pk_fma_f32 v[138:139], v[2:3], s[0:1], v[138:139] op_sel_hi:[1,0,1]
	v_pk_fma_f32 v[140:141], v[4:5], s[0:1], v[140:141] op_sel_hi:[1,0,1]
	v_pk_fma_f32 v[142:143], v[6:7], s[0:1], v[142:143] op_sel_hi:[1,0,1]
	v_pk_fma_f32 v[128:129], v[8:9], s[0:1], v[128:129] op_sel_hi:[1,0,1]
	v_pk_fma_f32 v[132:133], v[10:11], s[0:1], v[132:133] op_sel_hi:[1,0,1]
	v_pk_fma_f32 v[134:135], v[12:13], s[0:1], v[134:135] op_sel_hi:[1,0,1]
	v_pk_fma_f32 v[136:137], v[14:15], s[0:1], v[136:137] op_sel_hi:[1,0,1]
	v_readlane_b32 s0, v167, 10
	s_waitcnt vmcnt(48)
; __device__ void peer_gather_phase(const Params& P, int l, bool do_store) {
;     ...
;         const int ea = __builtin_amdgcn_readlane(evs, kb + 2 * pr), eb = __builtin_amdgcn_readlane(evs, kb + 2 * pr + 1);
;         const uint2* up = (const uint2*)(U + (size_t)(uphi ? eb : ea) * 768);
;         u6[3 * pr] = up[0]; u6[3 * pr + 1] = up[1]; u6[3 * pr + 2] = up[2];
;         v8[2 * pr] = *(const uint2*)(V + (size_t)ea * 512);
;         v8[2 * pr + 1] = *(const uint2*)(V + (size_t)eb * 512);
;     ...
; #pragma unroll
;       for (int j = 0; j < 8; ++j) {
;         const float a = __builtin_bit_cast(float, __builtin_amdgcn_readlane(__builtin_bit_cast(int, avec), kb + j));
;         const f32x2 aa = f32x2{a, a};
;         y[0] += aa * __builtin_amdgcn_cvt_scalef32_pk_f32_fp4(v8[j].x, 1.0f, 0); y[1] += aa * __builtin_amdgcn_cvt_scalef32_pk_f32_fp4(v8[j].x, 1.0f, 1);
;         y[2] += aa * __builtin_amdgcn_cvt_scalef32_pk_f32_fp4(v8[j].x, 1.0f, 2); y[3] += aa * __builtin_amdgcn_cvt_scalef32_pk_f32_fp4(v8[j].x, 1.0f, 3);
;         y[4] += aa * __builtin_amdgcn_cvt_scalef32_pk_f32_fp4(v8[j].y, 1.0f, 0); y[5] += aa * __builtin_amdgcn_cvt_scalef32_pk_f32_fp4(v8[j].y, 1.0f, 1);
;         y[6] += aa * __builtin_amdgcn_cvt_scalef32_pk_f32_fp4(v8[j].y, 1.0f, 2); y[7] += aa * __builtin_amdgcn_cvt_scalef32_pk_f32_fp4(v8[j].y, 1.0f, 3);
;       }
	v_cvt_scalef32_pk_f32_fp4 v[0:1], v172, 1.0
	v_cvt_scalef32_pk_f32_fp4 v[2:3], v172, 1.0 op_sel:[1,0,0]
	v_cvt_scalef32_pk_f32_fp4 v[4:5], v172, 1.0 op_sel:[0,1,0]
	v_cvt_scalef32_pk_f32_fp4 v[6:7], v172, 1.0 op_sel:[1,1,0]
	v_cvt_scalef32_pk_f32_fp4 v[8:9], v173, 1.0
	v_cvt_scalef32_pk_f32_fp4 v[10:11], v173, 1.0 op_sel:[1,0,0]
	v_cvt_scalef32_pk_f32_fp4 v[12:13], v173, 1.0 op_sel:[0,1,0]
	v_cvt_scalef32_pk_f32_fp4 v[14:15], v173, 1.0 op_sel:[1,1,0]
	v_readlane_b32 s54, v92, 26
	s_lshl_b32 s56, s54, 9
	s_add_u32 s56, s64, s56
	s_addc_u32 s57, s65, 0
	global_load_dwordx2 v[172:173], v227, s[56:57]
	v_pk_fma_f32 v[130:131], v[0:1], s[0:1], v[130:131] op_sel_hi:[1,0,1]
	v_pk_fma_f32 v[138:139], v[2:3], s[0:1], v[138:139] op_sel_hi:[1,0,1]
	v_pk_fma_f32 v[140:141], v[4:5], s[0:1], v[140:141] op_sel_hi:[1,0,1]
	v_pk_fma_f32 v[142:143], v[6:7], s[0:1], v[142:143] op_sel_hi:[1,0,1]
	v_pk_fma_f32 v[128:129], v[8:9], s[0:1], v[128:129] op_sel_hi:[1,0,1]
	v_pk_fma_f32 v[132:133], v[10:11], s[0:1], v[132:133] op_sel_hi:[1,0,1]
	v_pk_fma_f32 v[134:135], v[12:13], s[0:1], v[134:135] op_sel_hi:[1,0,1]
	v_pk_fma_f32 v[136:137], v[14:15], s[0:1], v[136:137] op_sel_hi:[1,0,1]
	v_readlane_b32 s0, v167, 11
	s_waitcnt vmcnt(48)
	v_cvt_scalef32_pk_f32_fp4 v[0:1], v174, 1.0
	v_cvt_scalef32_pk_f32_fp4 v[2:3], v174, 1.0 op_sel:[1,0,0]
	v_cvt_scalef32_pk_f32_fp4 v[4:5], v174, 1.0 op_sel:[0,1,0]
	v_cvt_scalef32_pk_f32_fp4 v[6:7], v174, 1.0 op_sel:[1,1,0]
	v_cvt_scalef32_pk_f32_fp4 v[8:9], v175, 1.0
	v_cvt_scalef32_pk_f32_fp4 v[10:11], v175, 1.0 op_sel:[1,0,0]
	v_cvt_scalef32_pk_f32_fp4 v[12:13], v175, 1.0 op_sel:[0,1,0]
	v_cvt_scalef32_pk_f32_fp4 v[14:15], v175, 1.0 op_sel:[1,1,0]
	v_readlane_b32 s54, v92, 27
	s_lshl_b32 s56, s54, 9
	s_add_u32 s56, s64, s56
	s_addc_u32 s57, s65, 0
	global_load_dwordx2 v[174:175], v227, s[56:57]
	v_pk_fma_f32 v[130:131], v[0:1], s[0:1], v[130:131] op_sel_hi:[1,0,1]
	v_pk_fma_f32 v[138:139], v[2:3], s[0:1], v[138:139] op_sel_hi:[1,0,1]
	v_pk_fma_f32 v[140:141], v[4:5], s[0:1], v[140:141] op_sel_hi:[1,0,1]
	v_pk_fma_f32 v[142:143], v[6:7], s[0:1], v[142:143] op_sel_hi:[1,0,1]
	v_pk_fma_f32 v[128:129], v[8:9], s[0:1], v[128:129] op_sel_hi:[1,0,1]
	v_pk_fma_f32 v[132:133], v[10:11], s[0:1], v[132:133] op_sel_hi:[1,0,1]
	v_pk_fma_f32 v[134:135], v[12:13], s[0:1], v[134:135] op_sel_hi:[1,0,1]
	v_pk_fma_f32 v[136:137], v[14:15], s[0:1], v[136:137] op_sel_hi:[1,0,1]
	v_readlane_b32 s0, v167, 12
	s_waitcnt vmcnt(48)
	v_cvt_scalef32_pk_f32_fp4 v[0:1], v180, 1.0
	v_cvt_scalef32_pk_f32_fp4 v[2:3], v180, 1.0 op_sel:[1,0,0]
	v_cvt_scalef32_pk_f32_fp4 v[4:5], v180, 1.0 op_sel:[0,1,0]
	v_cvt_scalef32_pk_f32_fp4 v[6:7], v180, 1.0 op_sel:[1,1,0]
	v_cvt_scalef32_pk_f32_fp4 v[8:9], v181, 1.0
	v_cvt_scalef32_pk_f32_fp4 v[10:11], v181, 1.0 op_sel:[1,0,0]
	v_cvt_scalef32_pk_f32_fp4 v[12:13], v181, 1.0 op_sel:[0,1,0]
	v_cvt_scalef32_pk_f32_fp4 v[14:15], v181, 1.0 op_sel:[1,1,0]
	v_readlane_b32 s54, v92, 28
	s_lshl_b32 s56, s54, 9
	s_add_u32 s56, s64, s56
	s_addc_u32 s57, s65, 0
	global_load_dwordx2 v[180:181], v227, s[56:57]
	v_pk_fma_f32 v[130:131], v[0:1], s[0:1], v[130:131] op_sel_hi:[1,0,1]
	v_pk_fma_f32 v[138:139], v[2:3], s[0:1], v[138:139] op_sel_hi:[1,0,1]
	v_pk_fma_f32 v[140:141], v[4:5], s[0:1], v[140:141] op_sel_hi:[1,0,1]
	v_pk_fma_f32 v[142:143], v[6:7], s[0:1], v[142:143] op_sel_hi:[1,0,1]
	v_pk_fma_f32 v[128:129], v[8:9], s[0:1], v[128:129] op_sel_hi:[1,0,1]
	v_pk_fma_f32 v[132:133], v[10:11], s[0:1], v[132:133] op_sel_hi:[1,0,1]
	v_pk_fma_f32 v[134:135], v[12:13], s[0:1], v[134:135] op_sel_hi:[1,0,1]
	v_pk_fma_f32 v[136:137], v[14:15], s[0:1], v[136:137] op_sel_hi:[1,0,1]
	v_readlane_b32 s0, v167, 13
	s_waitcnt vmcnt(48)
	v_cvt_scalef32_pk_f32_fp4 v[0:1], v182, 1.0
	v_cvt_scalef32_pk_f32_fp4 v[2:3], v182, 1.0 op_sel:[1,0,0]
	v_cvt_scalef32_pk_f32_fp4 v[4:5], v182, 1.0 op_sel:[0,1,0]
	v_cvt_scalef32_pk_f32_fp4 v[6:7], v182, 1.0 op_sel:[1,1,0]
	v_cvt_scalef32_pk_f32_fp4 v[8:9], v183, 1.0
	v_cvt_scalef32_pk_f32_fp4 v[10:11], v183, 1.0 op_sel:[1,0,0]
	v_cvt_scalef32_pk_f32_fp4 v[12:13], v183, 1.0 op_sel:[0,1,0]
	v_cvt_scalef32_pk_f32_fp4 v[14:15], v183, 1.0 op_sel:[1,1,0]
	v_readlane_b32 s54, v92, 29
	s_lshl_b32 s56, s54, 9
	s_add_u32 s56, s64, s56
	s_addc_u32 s57, s65, 0
	global_load_dwordx2 v[182:183], v227, s[56:57]
	v_pk_fma_f32 v[130:131], v[0:1], s[0:1], v[130:131] op_sel_hi:[1,0,1]
	v_pk_fma_f32 v[138:139], v[2:3], s[0:1], v[138:139] op_sel_hi:[1,0,1]
	v_pk_fma_f32 v[140:141], v[4:5], s[0:1], v[140:141] op_sel_hi:[1,0,1]
	v_pk_fma_f32 v[142:143], v[6:7], s[0:1], v[142:143] op_sel_hi:[1,0,1]
	v_pk_fma_f32 v[128:129], v[8:9], s[0:1], v[128:129] op_sel_hi:[1,0,1]
	v_pk_fma_f32 v[132:133], v[10:11], s[0:1], v[132:133] op_sel_hi:[1,0,1]
	v_pk_fma_f32 v[134:135], v[12:13], s[0:1], v[134:135] op_sel_hi:[1,0,1]
	v_pk_fma_f32 v[136:137], v[14:15], s[0:1], v[136:137] op_sel_hi:[1,0,1]
	v_readlane_b32 s0, v167, 14
	s_waitcnt vmcnt(48)
	v_cvt_scalef32_pk_f32_fp4 v[0:1], v184, 1.0
	v_cvt_scalef32_pk_f32_fp4 v[2:3], v184, 1.0 op_sel:[1,0,0]
	v_cvt_scalef32_pk_f32_fp4 v[4:5], v184, 1.0 op_sel:[0,1,0]
	v_cvt_scalef32_pk_f32_fp4 v[6:7], v184, 1.0 op_sel:[1,1,0]
	v_cvt_scalef32_pk_f32_fp4 v[8:9], v185, 1.0
	v_cvt_scalef32_pk_f32_fp4 v[10:11], v185, 1.0 op_sel:[1,0,0]
	v_cvt_scalef32_pk_f32_fp4 v[12:13], v185, 1.0 op_sel:[0,1,0]
	v_cvt_scalef32_pk_f32_fp4 v[14:15], v185, 1.0 op_sel:[1,1,0]
	v_readlane_b32 s54, v92, 30
	s_lshl_b32 s56, s54, 9
	s_add_u32 s56, s64, s56
	s_addc_u32 s57, s65, 0
	global_load_dwordx2 v[184:185], v227, s[56:57]
	v_pk_fma_f32 v[130:131], v[0:1], s[0:1], v[130:131] op_sel_hi:[1,0,1]
	v_pk_fma_f32 v[138:139], v[2:3], s[0:1], v[138:139] op_sel_hi:[1,0,1]
	v_pk_fma_f32 v[140:141], v[4:5], s[0:1], v[140:141] op_sel_hi:[1,0,1]
	v_pk_fma_f32 v[142:143], v[6:7], s[0:1], v[142:143] op_sel_hi:[1,0,1]
	v_pk_fma_f32 v[128:129], v[8:9], s[0:1], v[128:129] op_sel_hi:[1,0,1]
	v_pk_fma_f32 v[132:133], v[10:11], s[0:1], v[132:133] op_sel_hi:[1,0,1]
	v_pk_fma_f32 v[134:135], v[12:13], s[0:1], v[134:135] op_sel_hi:[1,0,1]
	v_pk_fma_f32 v[136:137], v[14:15], s[0:1], v[136:137] op_sel_hi:[1,0,1]
	v_readlane_b32 s0, v167, 15
	s_waitcnt vmcnt(48)
; __device__ void peer_gather_phase(const Params& P, int l, bool do_store) {
;     ...
;         const int ea = __builtin_amdgcn_readlane(evs, kb + 2 * pr), eb = __builtin_amdgcn_readlane(evs, kb + 2 * pr + 1);
;         const uint2* up = (const uint2*)(U + (size_t)(uphi ? eb : ea) * 768);
;         u6[3 * pr] = up[0]; u6[3 * pr + 1] = up[1]; u6[3 * pr + 2] = up[2];
;         v8[2 * pr] = *(const uint2*)(V + (size_t)ea * 512);
;         v8[2 * pr + 1] = *(const uint2*)(V + (size_t)eb * 512);
;     ...
; #pragma unroll
;       for (int j = 0; j < 8; ++j) {
;         const float a = __builtin_bit_cast(float, __builtin_amdgcn_readlane(__builtin_bit_cast(int, avec), kb + j));
;         const f32x2 aa = f32x2{a, a};
;         y[0] += aa * __builtin_amdgcn_cvt_scalef32_pk_f32_fp4(v8[j].x, 1.0f, 0); y[1] += aa * __builtin_amdgcn_cvt_scalef32_pk_f32_fp4(v8[j].x, 1.0f, 1);
;         y[2] += aa * __builtin_amdgcn_cvt_scalef32_pk_f32_fp4(v8[j].x, 1.0f, 2); y[3] += aa * __builtin_amdgcn_cvt_scalef32_pk_f32_fp4(v8[j].x, 1.0f, 3);
;         y[4] += aa * __builtin_amdgcn_cvt_scalef32_pk_f32_fp4(v8[j].y, 1.0f, 0); y[5] += aa * __builtin_amdgcn_cvt_scalef32_pk_f32_fp4(v8[j].y, 1.0f, 1);
;         y[6] += aa * __builtin_amdgcn_cvt_scalef32_pk_f32_fp4(v8[j].y, 1.0f, 2); y[7] += aa * __builtin_amdgcn_cvt_scalef32_pk_f32_fp4(v8[j].y, 1.0f, 3);
;       }
	v_cvt_scalef32_pk_f32_fp4 v[0:1], v186, 1.0
	v_cvt_scalef32_pk_f32_fp4 v[2:3], v186, 1.0 op_sel:[1,0,0]
	v_cvt_scalef32_pk_f32_fp4 v[4:5], v186, 1.0 op_sel:[0,1,0]
	v_cvt_scalef32_pk_f32_fp4 v[6:7], v186, 1.0 op_sel:[1,1,0]
	v_cvt_scalef32_pk_f32_fp4 v[8:9], v187, 1.0
	v_cvt_scalef32_pk_f32_fp4 v[10:11], v187, 1.0 op_sel:[1,0,0]
	v_cvt_scalef32_pk_f32_fp4 v[12:13], v187, 1.0 op_sel:[0,1,0]
	v_cvt_scalef32_pk_f32_fp4 v[14:15], v187, 1.0 op_sel:[1,1,0]
	v_readlane_b32 s54, v92, 31
	s_lshl_b32 s56, s54, 9
	s_add_u32 s56, s64, s56
	s_addc_u32 s57, s65, 0
	global_load_dwordx2 v[186:187], v227, s[56:57]
	v_pk_fma_f32 v[130:131], v[0:1], s[0:1], v[130:131] op_sel_hi:[1,0,1]
	v_pk_fma_f32 v[138:139], v[2:3], s[0:1], v[138:139] op_sel_hi:[1,0,1]
	v_pk_fma_f32 v[140:141], v[4:5], s[0:1], v[140:141] op_sel_hi:[1,0,1]
	v_pk_fma_f32 v[142:143], v[6:7], s[0:1], v[142:143] op_sel_hi:[1,0,1]
	v_pk_fma_f32 v[128:129], v[8:9], s[0:1], v[128:129] op_sel_hi:[1,0,1]
	v_pk_fma_f32 v[132:133], v[10:11], s[0:1], v[132:133] op_sel_hi:[1,0,1]
	v_pk_fma_f32 v[134:135], v[12:13], s[0:1], v[134:135] op_sel_hi:[1,0,1]
	v_pk_fma_f32 v[136:137], v[14:15], s[0:1], v[136:137] op_sel_hi:[1,0,1]
	v_readlane_b32 s0, v167, 16
	s_waitcnt vmcnt(15)
	v_cvt_scalef32_pk_f32_fp4 v[0:1], v144, 1.0
	v_cvt_scalef32_pk_f32_fp4 v[2:3], v144, 1.0 op_sel:[1,0,0]
	v_cvt_scalef32_pk_f32_fp4 v[4:5], v144, 1.0 op_sel:[0,1,0]
	v_cvt_scalef32_pk_f32_fp4 v[6:7], v144, 1.0 op_sel:[1,1,0]
	v_cvt_scalef32_pk_f32_fp4 v[8:9], v145, 1.0
	v_cvt_scalef32_pk_f32_fp4 v[10:11], v145, 1.0 op_sel:[1,0,0]
	v_cvt_scalef32_pk_f32_fp4 v[12:13], v145, 1.0 op_sel:[0,1,0]
	v_cvt_scalef32_pk_f32_fp4 v[14:15], v145, 1.0 op_sel:[1,1,0]
	v_readlane_b32 s54, v92, 32
	s_lshl_b32 s56, s54, 9
	s_add_u32 s56, s64, s56
	s_addc_u32 s57, s65, 0
	global_load_dwordx2 v[144:145], v227, s[56:57]
	v_pk_fma_f32 v[130:131], v[0:1], s[0:1], v[130:131] op_sel_hi:[1,0,1]
	v_pk_fma_f32 v[138:139], v[2:3], s[0:1], v[138:139] op_sel_hi:[1,0,1]
	v_pk_fma_f32 v[140:141], v[4:5], s[0:1], v[140:141] op_sel_hi:[1,0,1]
	v_pk_fma_f32 v[142:143], v[6:7], s[0:1], v[142:143] op_sel_hi:[1,0,1]
	v_pk_fma_f32 v[128:129], v[8:9], s[0:1], v[128:129] op_sel_hi:[1,0,1]
	v_pk_fma_f32 v[132:133], v[10:11], s[0:1], v[132:133] op_sel_hi:[1,0,1]
	v_pk_fma_f32 v[134:135], v[12:13], s[0:1], v[134:135] op_sel_hi:[1,0,1]
	v_pk_fma_f32 v[136:137], v[14:15], s[0:1], v[136:137] op_sel_hi:[1,0,1]
	v_readlane_b32 s0, v167, 17
	s_waitcnt vmcnt(15)
	v_cvt_scalef32_pk_f32_fp4 v[0:1], v146, 1.0
	v_cvt_scalef32_pk_f32_fp4 v[2:3], v146, 1.0 op_sel:[1,0,0]
	v_cvt_scalef32_pk_f32_fp4 v[4:5], v146, 1.0 op_sel:[0,1,0]
	v_cvt_scalef32_pk_f32_fp4 v[6:7], v146, 1.0 op_sel:[1,1,0]
	v_cvt_scalef32_pk_f32_fp4 v[8:9], v147, 1.0
	v_cvt_scalef32_pk_f32_fp4 v[10:11], v147, 1.0 op_sel:[1,0,0]
	v_cvt_scalef32_pk_f32_fp4 v[12:13], v147, 1.0 op_sel:[0,1,0]
	v_cvt_scalef32_pk_f32_fp4 v[14:15], v147, 1.0 op_sel:[1,1,0]
	v_readlane_b32 s54, v92, 33
	s_lshl_b32 s56, s54, 9
	s_add_u32 s56, s64, s56
	s_addc_u32 s57, s65, 0
	global_load_dwordx2 v[146:147], v227, s[56:57]
	v_pk_fma_f32 v[130:131], v[0:1], s[0:1], v[130:131] op_sel_hi:[1,0,1]
	v_pk_fma_f32 v[138:139], v[2:3], s[0:1], v[138:139] op_sel_hi:[1,0,1]
	v_pk_fma_f32 v[140:141], v[4:5], s[0:1], v[140:141] op_sel_hi:[1,0,1]
	v_pk_fma_f32 v[142:143], v[6:7], s[0:1], v[142:143] op_sel_hi:[1,0,1]
	v_pk_fma_f32 v[128:129], v[8:9], s[0:1], v[128:129] op_sel_hi:[1,0,1]
	v_pk_fma_f32 v[132:133], v[10:11], s[0:1], v[132:133] op_sel_hi:[1,0,1]
	v_pk_fma_f32 v[134:135], v[12:13], s[0:1], v[134:135] op_sel_hi:[1,0,1]
	v_pk_fma_f32 v[136:137], v[14:15], s[0:1], v[136:137] op_sel_hi:[1,0,1]
	v_readlane_b32 s0, v167, 18
	s_waitcnt vmcnt(15)
	v_cvt_scalef32_pk_f32_fp4 v[0:1], v148, 1.0
	v_cvt_scalef32_pk_f32_fp4 v[2:3], v148, 1.0 op_sel:[1,0,0]
	v_cvt_scalef32_pk_f32_fp4 v[4:5], v148, 1.0 op_sel:[0,1,0]
	v_cvt_scalef32_pk_f32_fp4 v[6:7], v148, 1.0 op_sel:[1,1,0]
	v_cvt_scalef32_pk_f32_fp4 v[8:9], v149, 1.0
	v_cvt_scalef32_pk_f32_fp4 v[10:11], v149, 1.0 op_sel:[1,0,0]
	v_cvt_scalef32_pk_f32_fp4 v[12:13], v149, 1.0 op_sel:[0,1,0]
	v_cvt_scalef32_pk_f32_fp4 v[14:15], v149, 1.0 op_sel:[1,1,0]
	v_readlane_b32 s54, v92, 34
	s_lshl_b32 s56, s54, 9
	s_add_u32 s56, s64, s56
	s_addc_u32 s57, s65, 0
	global_load_dwordx2 v[148:149], v227, s[56:57]
	v_pk_fma_f32 v[130:131], v[0:1], s[0:1], v[130:131] op_sel_hi:[1,0,1]
	v_pk_fma_f32 v[138:139], v[2:3], s[0:1], v[138:139] op_sel_hi:[1,0,1]
	v_pk_fma_f32 v[140:141], v[4:5], s[0:1], v[140:141] op_sel_hi:[1,0,1]
	v_pk_fma_f32 v[142:143], v[6:7], s[0:1], v[142:143] op_sel_hi:[1,0,1]
	v_pk_fma_f32 v[128:129], v[8:9], s[0:1], v[128:129] op_sel_hi:[1,0,1]
	v_pk_fma_f32 v[132:133], v[10:11], s[0:1], v[132:133] op_sel_hi:[1,0,1]
	v_pk_fma_f32 v[134:135], v[12:13], s[0:1], v[134:135] op_sel_hi:[1,0,1]
	v_pk_fma_f32 v[136:137], v[14:15], s[0:1], v[136:137] op_sel_hi:[1,0,1]
	v_readlane_b32 s0, v167, 19
	s_waitcnt vmcnt(15)
	v_cvt_scalef32_pk_f32_fp4 v[0:1], v150, 1.0
	v_cvt_scalef32_pk_f32_fp4 v[2:3], v150, 1.0 op_sel:[1,0,0]
	v_cvt_scalef32_pk_f32_fp4 v[4:5], v150, 1.0 op_sel:[0,1,0]
	v_cvt_scalef32_pk_f32_fp4 v[6:7], v150, 1.0 op_sel:[1,1,0]
	v_cvt_scalef32_pk_f32_fp4 v[8:9], v151, 1.0
	v_cvt_scalef32_pk_f32_fp4 v[10:11], v151, 1.0 op_sel:[1,0,0]
	v_cvt_scalef32_pk_f32_fp4 v[12:13], v151, 1.0 op_sel:[0,1,0]
	v_cvt_scalef32_pk_f32_fp4 v[14:15], v151, 1.0 op_sel:[1,1,0]
	v_readlane_b32 s54, v92, 35
	s_lshl_b32 s56, s54, 9
	s_add_u32 s56, s64, s56
	s_addc_u32 s57, s65, 0
	global_load_dwordx2 v[150:151], v227, s[56:57]
	v_pk_fma_f32 v[130:131], v[0:1], s[0:1], v[130:131] op_sel_hi:[1,0,1]
	v_pk_fma_f32 v[138:139], v[2:3], s[0:1], v[138:139] op_sel_hi:[1,0,1]
	v_pk_fma_f32 v[140:141], v[4:5], s[0:1], v[140:141] op_sel_hi:[1,0,1]
	v_pk_fma_f32 v[142:143], v[6:7], s[0:1], v[142:143] op_sel_hi:[1,0,1]
	v_pk_fma_f32 v[128:129], v[8:9], s[0:1], v[128:129] op_sel_hi:[1,0,1]
	v_pk_fma_f32 v[132:133], v[10:11], s[0:1], v[132:133] op_sel_hi:[1,0,1]
	v_pk_fma_f32 v[134:135], v[12:13], s[0:1], v[134:135] op_sel_hi:[1,0,1]
	v_pk_fma_f32 v[136:137], v[14:15], s[0:1], v[136:137] op_sel_hi:[1,0,1]
	v_readlane_b32 s0, v167, 20
	s_waitcnt vmcnt(15)
; __device__ void peer_gather_phase(const Params& P, int l, bool do_store) {
;     ...
;         const int ea = __builtin_amdgcn_readlane(evs, kb + 2 * pr), eb = __builtin_amdgcn_readlane(evs, kb + 2 * pr + 1);
;         const uint2* up = (const uint2*)(U + (size_t)(uphi ? eb : ea) * 768);
;         u6[3 * pr] = up[0]; u6[3 * pr + 1] = up[1]; u6[3 * pr + 2] = up[2];
;         v8[2 * pr] = *(const uint2*)(V + (size_t)ea * 512);
;         v8[2 * pr + 1] = *(const uint2*)(V + (size_t)eb * 512);
;     ...
; #pragma unroll
;       for (int j = 0; j < 8; ++j) {
;         const float a = __builtin_bit_cast(float, __builtin_amdgcn_readlane(__builtin_bit_cast(int, avec), kb + j));
;         const f32x2 aa = f32x2{a, a};
;         y[0] += aa * __builtin_amdgcn_cvt_scalef32_pk_f32_fp4(v8[j].x, 1.0f, 0); y[1] += aa * __builtin_amdgcn_cvt_scalef32_pk_f32_fp4(v8[j].x, 1.0f, 1);
;         y[2] += aa * __builtin_amdgcn_cvt_scalef32_pk_f32_fp4(v8[j].x, 1.0f, 2); y[3] += aa * __builtin_amdgcn_cvt_scalef32_pk_f32_fp4(v8[j].x, 1.0f, 3);
;         y[4] += aa * __builtin_amdgcn_cvt_scalef32_pk_f32_fp4(v8[j].y, 1.0f, 0); y[5] += aa * __builtin_amdgcn_cvt_scalef32_pk_f32_fp4(v8[j].y, 1.0f, 1);
;         y[6] += aa * __builtin_amdgcn_cvt_scalef32_pk_f32_fp4(v8[j].y, 1.0f, 2); y[7] += aa * __builtin_amdgcn_cvt_scalef32_pk_f32_fp4(v8[j].y, 1.0f, 3);
;       }
	v_cvt_scalef32_pk_f32_fp4 v[0:1], v152, 1.0
	v_cvt_scalef32_pk_f32_fp4 v[2:3], v152, 1.0 op_sel:[1,0,0]
	v_cvt_scalef32_pk_f32_fp4 v[4:5], v152, 1.0 op_sel:[0,1,0]
	v_cvt_scalef32_pk_f32_fp4 v[6:7], v152, 1.0 op_sel:[1,1,0]
	v_cvt_scalef32_pk_f32_fp4 v[8:9], v153, 1.0
	v_cvt_scalef32_pk_f32_fp4 v[10:11], v153, 1.0 op_sel:[1,0,0]
	v_cvt_scalef32_pk_f32_fp4 v[12:13], v153, 1.0 op_sel:[0,1,0]
	v_cvt_scalef32_pk_f32_fp4 v[14:15], v153, 1.0 op_sel:[1,1,0]
	v_readlane_b32 s54, v92, 36
	s_lshl_b32 s56, s54, 9
	s_add_u32 s56, s64, s56
	s_addc_u32 s57, s65, 0
	global_load_dwordx2 v[152:153], v227, s[56:57]
	v_pk_fma_f32 v[130:131], v[0:1], s[0:1], v[130:131] op_sel_hi:[1,0,1]
	v_pk_fma_f32 v[138:139], v[2:3], s[0:1], v[138:139] op_sel_hi:[1,0,1]
	v_pk_fma_f32 v[140:141], v[4:5], s[0:1], v[140:141] op_sel_hi:[1,0,1]
	v_pk_fma_f32 v[142:143], v[6:7], s[0:1], v[142:143] op_sel_hi:[1,0,1]
	v_pk_fma_f32 v[128:129], v[8:9], s[0:1], v[128:129] op_sel_hi:[1,0,1]
	v_pk_fma_f32 v[132:133], v[10:11], s[0:1], v[132:133] op_sel_hi:[1,0,1]
	v_pk_fma_f32 v[134:135], v[12:13], s[0:1], v[134:135] op_sel_hi:[1,0,1]
	v_pk_fma_f32 v[136:137], v[14:15], s[0:1], v[136:137] op_sel_hi:[1,0,1]
	v_readlane_b32 s0, v167, 21
	s_waitcnt vmcnt(15)
	v_cvt_scalef32_pk_f32_fp4 v[0:1], v154, 1.0
	v_cvt_scalef32_pk_f32_fp4 v[2:3], v154, 1.0 op_sel:[1,0,0]
	v_cvt_scalef32_pk_f32_fp4 v[4:5], v154, 1.0 op_sel:[0,1,0]
	v_cvt_scalef32_pk_f32_fp4 v[6:7], v154, 1.0 op_sel:[1,1,0]
	v_cvt_scalef32_pk_f32_fp4 v[8:9], v155, 1.0
	v_cvt_scalef32_pk_f32_fp4 v[10:11], v155, 1.0 op_sel:[1,0,0]
	v_cvt_scalef32_pk_f32_fp4 v[12:13], v155, 1.0 op_sel:[0,1,0]
	v_cvt_scalef32_pk_f32_fp4 v[14:15], v155, 1.0 op_sel:[1,1,0]
	v_readlane_b32 s54, v92, 37
	s_lshl_b32 s56, s54, 9
	s_add_u32 s56, s64, s56
	s_addc_u32 s57, s65, 0
	global_load_dwordx2 v[154:155], v227, s[56:57]
	v_pk_fma_f32 v[130:131], v[0:1], s[0:1], v[130:131] op_sel_hi:[1,0,1]
	v_pk_fma_f32 v[138:139], v[2:3], s[0:1], v[138:139] op_sel_hi:[1,0,1]
	v_pk_fma_f32 v[140:141], v[4:5], s[0:1], v[140:141] op_sel_hi:[1,0,1]
	v_pk_fma_f32 v[142:143], v[6:7], s[0:1], v[142:143] op_sel_hi:[1,0,1]
	v_pk_fma_f32 v[128:129], v[8:9], s[0:1], v[128:129] op_sel_hi:[1,0,1]
	v_pk_fma_f32 v[132:133], v[10:11], s[0:1], v[132:133] op_sel_hi:[1,0,1]
	v_pk_fma_f32 v[134:135], v[12:13], s[0:1], v[134:135] op_sel_hi:[1,0,1]
	v_pk_fma_f32 v[136:137], v[14:15], s[0:1], v[136:137] op_sel_hi:[1,0,1]
	v_readlane_b32 s0, v167, 22
	s_waitcnt vmcnt(15)
	v_cvt_scalef32_pk_f32_fp4 v[0:1], v156, 1.0
	v_cvt_scalef32_pk_f32_fp4 v[2:3], v156, 1.0 op_sel:[1,0,0]
	v_cvt_scalef32_pk_f32_fp4 v[4:5], v156, 1.0 op_sel:[0,1,0]
	v_cvt_scalef32_pk_f32_fp4 v[6:7], v156, 1.0 op_sel:[1,1,0]
	v_cvt_scalef32_pk_f32_fp4 v[8:9], v157, 1.0
	v_cvt_scalef32_pk_f32_fp4 v[10:11], v157, 1.0 op_sel:[1,0,0]
	v_cvt_scalef32_pk_f32_fp4 v[12:13], v157, 1.0 op_sel:[0,1,0]
	v_cvt_scalef32_pk_f32_fp4 v[14:15], v157, 1.0 op_sel:[1,1,0]
	v_readlane_b32 s54, v92, 38
	s_lshl_b32 s56, s54, 9
	s_add_u32 s56, s64, s56
	s_addc_u32 s57, s65, 0
	global_load_dwordx2 v[156:157], v227, s[56:57]
	v_pk_fma_f32 v[130:131], v[0:1], s[0:1], v[130:131] op_sel_hi:[1,0,1]
	v_pk_fma_f32 v[138:139], v[2:3], s[0:1], v[138:139] op_sel_hi:[1,0,1]
	v_pk_fma_f32 v[140:141], v[4:5], s[0:1], v[140:141] op_sel_hi:[1,0,1]
	v_pk_fma_f32 v[142:143], v[6:7], s[0:1], v[142:143] op_sel_hi:[1,0,1]
	v_pk_fma_f32 v[128:129], v[8:9], s[0:1], v[128:129] op_sel_hi:[1,0,1]
	v_pk_fma_f32 v[132:133], v[10:11], s[0:1], v[132:133] op_sel_hi:[1,0,1]
	v_pk_fma_f32 v[134:135], v[12:13], s[0:1], v[134:135] op_sel_hi:[1,0,1]
	v_pk_fma_f32 v[136:137], v[14:15], s[0:1], v[136:137] op_sel_hi:[1,0,1]
	v_readlane_b32 s0, v167, 23
	s_waitcnt vmcnt(15)
	v_cvt_scalef32_pk_f32_fp4 v[0:1], v158, 1.0
	v_cvt_scalef32_pk_f32_fp4 v[2:3], v158, 1.0 op_sel:[1,0,0]
	v_cvt_scalef32_pk_f32_fp4 v[4:5], v158, 1.0 op_sel:[0,1,0]
	v_cvt_scalef32_pk_f32_fp4 v[6:7], v158, 1.0 op_sel:[1,1,0]
	v_cvt_scalef32_pk_f32_fp4 v[8:9], v159, 1.0
	v_cvt_scalef32_pk_f32_fp4 v[10:11], v159, 1.0 op_sel:[1,0,0]
	v_cvt_scalef32_pk_f32_fp4 v[12:13], v159, 1.0 op_sel:[0,1,0]
	v_cvt_scalef32_pk_f32_fp4 v[14:15], v159, 1.0 op_sel:[1,1,0]
	v_readlane_b32 s54, v92, 39
	s_lshl_b32 s56, s54, 9
	s_add_u32 s56, s64, s56
	s_addc_u32 s57, s65, 0
	global_load_dwordx2 v[158:159], v227, s[56:57]
	v_pk_fma_f32 v[130:131], v[0:1], s[0:1], v[130:131] op_sel_hi:[1,0,1]
	v_pk_fma_f32 v[138:139], v[2:3], s[0:1], v[138:139] op_sel_hi:[1,0,1]
	v_pk_fma_f32 v[140:141], v[4:5], s[0:1], v[140:141] op_sel_hi:[1,0,1]
	v_pk_fma_f32 v[142:143], v[6:7], s[0:1], v[142:143] op_sel_hi:[1,0,1]
	v_pk_fma_f32 v[128:129], v[8:9], s[0:1], v[128:129] op_sel_hi:[1,0,1]
	v_pk_fma_f32 v[132:133], v[10:11], s[0:1], v[132:133] op_sel_hi:[1,0,1]
	v_pk_fma_f32 v[134:135], v[12:13], s[0:1], v[134:135] op_sel_hi:[1,0,1]
	v_pk_fma_f32 v[136:137], v[14:15], s[0:1], v[136:137] op_sel_hi:[1,0,1]
	v_readlane_b32 s0, v167, 24
	s_waitcnt vmcnt(15)
	v_cvt_scalef32_pk_f32_fp4 v[0:1], v168, 1.0
	v_cvt_scalef32_pk_f32_fp4 v[2:3], v168, 1.0 op_sel:[1,0,0]
	v_cvt_scalef32_pk_f32_fp4 v[4:5], v168, 1.0 op_sel:[0,1,0]
	v_cvt_scalef32_pk_f32_fp4 v[6:7], v168, 1.0 op_sel:[1,1,0]
	v_cvt_scalef32_pk_f32_fp4 v[8:9], v169, 1.0
	v_cvt_scalef32_pk_f32_fp4 v[10:11], v169, 1.0 op_sel:[1,0,0]
	v_cvt_scalef32_pk_f32_fp4 v[12:13], v169, 1.0 op_sel:[0,1,0]
	v_cvt_scalef32_pk_f32_fp4 v[14:15], v169, 1.0 op_sel:[1,1,0]
	v_readlane_b32 s54, v92, 40
	s_lshl_b32 s56, s54, 9
	s_add_u32 s56, s64, s56
	s_addc_u32 s57, s65, 0
	global_load_dwordx2 v[168:169], v227, s[56:57]
	v_pk_fma_f32 v[130:131], v[0:1], s[0:1], v[130:131] op_sel_hi:[1,0,1]
	v_pk_fma_f32 v[138:139], v[2:3], s[0:1], v[138:139] op_sel_hi:[1,0,1]
	v_pk_fma_f32 v[140:141], v[4:5], s[0:1], v[140:141] op_sel_hi:[1,0,1]
	v_pk_fma_f32 v[142:143], v[6:7], s[0:1], v[142:143] op_sel_hi:[1,0,1]
	v_pk_fma_f32 v[128:129], v[8:9], s[0:1], v[128:129] op_sel_hi:[1,0,1]
	v_pk_fma_f32 v[132:133], v[10:11], s[0:1], v[132:133] op_sel_hi:[1,0,1]
	v_pk_fma_f32 v[134:135], v[12:13], s[0:1], v[134:135] op_sel_hi:[1,0,1]
	v_pk_fma_f32 v[136:137], v[14:15], s[0:1], v[136:137] op_sel_hi:[1,0,1]
	v_readlane_b32 s0, v167, 25
	s_waitcnt vmcnt(15)
; __device__ void peer_gather_phase(const Params& P, int l, bool do_store) {
;     ...
;         const int ea = __builtin_amdgcn_readlane(evs, kb + 2 * pr), eb = __builtin_amdgcn_readlane(evs, kb + 2 * pr + 1);
;         const uint2* up = (const uint2*)(U + (size_t)(uphi ? eb : ea) * 768);
;         u6[3 * pr] = up[0]; u6[3 * pr + 1] = up[1]; u6[3 * pr + 2] = up[2];
;         v8[2 * pr] = *(const uint2*)(V + (size_t)ea * 512);
;         v8[2 * pr + 1] = *(const uint2*)(V + (size_t)eb * 512);
;     ...
; #pragma unroll
;       for (int j = 0; j < 8; ++j) {
;         const float a = __builtin_bit_cast(float, __builtin_amdgcn_readlane(__builtin_bit_cast(int, avec), kb + j));
;         const f32x2 aa = f32x2{a, a};
;         y[0] += aa * __builtin_amdgcn_cvt_scalef32_pk_f32_fp4(v8[j].x, 1.0f, 0); y[1] += aa * __builtin_amdgcn_cvt_scalef32_pk_f32_fp4(v8[j].x, 1.0f, 1);
;         y[2] += aa * __builtin_amdgcn_cvt_scalef32_pk_f32_fp4(v8[j].x, 1.0f, 2); y[3] += aa * __builtin_amdgcn_cvt_scalef32_pk_f32_fp4(v8[j].x, 1.0f, 3);
;         y[4] += aa * __builtin_amdgcn_cvt_scalef32_pk_f32_fp4(v8[j].y, 1.0f, 0); y[5] += aa * __builtin_amdgcn_cvt_scalef32_pk_f32_fp4(v8[j].y, 1.0f, 1);
;         y[6] += aa * __builtin_amdgcn_cvt_scalef32_pk_f32_fp4(v8[j].y, 1.0f, 2); y[7] += aa * __builtin_amdgcn_cvt_scalef32_pk_f32_fp4(v8[j].y, 1.0f, 3);
;       }
	v_cvt_scalef32_pk_f32_fp4 v[0:1], v170, 1.0
	v_cvt_scalef32_pk_f32_fp4 v[2:3], v170, 1.0 op_sel:[1,0,0]
	v_cvt_scalef32_pk_f32_fp4 v[4:5], v170, 1.0 op_sel:[0,1,0]
	v_cvt_scalef32_pk_f32_fp4 v[6:7], v170, 1.0 op_sel:[1,1,0]
	v_cvt_scalef32_pk_f32_fp4 v[8:9], v171, 1.0
	v_cvt_scalef32_pk_f32_fp4 v[10:11], v171, 1.0 op_sel:[1,0,0]
	v_cvt_scalef32_pk_f32_fp4 v[12:13], v171, 1.0 op_sel:[0,1,0]
	v_cvt_scalef32_pk_f32_fp4 v[14:15], v171, 1.0 op_sel:[1,1,0]
	v_readlane_b32 s54, v92, 41
	s_lshl_b32 s56, s54, 9
	s_add_u32 s56, s64, s56
	s_addc_u32 s57, s65, 0
	global_load_dwordx2 v[170:171], v227, s[56:57]
	v_pk_fma_f32 v[130:131], v[0:1], s[0:1], v[130:131] op_sel_hi:[1,0,1]
	v_pk_fma_f32 v[138:139], v[2:3], s[0:1], v[138:139] op_sel_hi:[1,0,1]
	v_pk_fma_f32 v[140:141], v[4:5], s[0:1], v[140:141] op_sel_hi:[1,0,1]
	v_pk_fma_f32 v[142:143], v[6:7], s[0:1], v[142:143] op_sel_hi:[1,0,1]
	v_pk_fma_f32 v[128:129], v[8:9], s[0:1], v[128:129] op_sel_hi:[1,0,1]
	v_pk_fma_f32 v[132:133], v[10:11], s[0:1], v[132:133] op_sel_hi:[1,0,1]
	v_pk_fma_f32 v[134:135], v[12:13], s[0:1], v[134:135] op_sel_hi:[1,0,1]
	v_pk_fma_f32 v[136:137], v[14:15], s[0:1], v[136:137] op_sel_hi:[1,0,1]
	v_readlane_b32 s0, v167, 26
	s_waitcnt vmcnt(15)
	v_cvt_scalef32_pk_f32_fp4 v[0:1], v172, 1.0
	v_cvt_scalef32_pk_f32_fp4 v[2:3], v172, 1.0 op_sel:[1,0,0]
	v_cvt_scalef32_pk_f32_fp4 v[4:5], v172, 1.0 op_sel:[0,1,0]
	v_cvt_scalef32_pk_f32_fp4 v[6:7], v172, 1.0 op_sel:[1,1,0]
	v_cvt_scalef32_pk_f32_fp4 v[8:9], v173, 1.0
	v_cvt_scalef32_pk_f32_fp4 v[10:11], v173, 1.0 op_sel:[1,0,0]
	v_cvt_scalef32_pk_f32_fp4 v[12:13], v173, 1.0 op_sel:[0,1,0]
	v_cvt_scalef32_pk_f32_fp4 v[14:15], v173, 1.0 op_sel:[1,1,0]
	v_readlane_b32 s54, v92, 42
	s_lshl_b32 s56, s54, 9
	s_add_u32 s56, s64, s56
	s_addc_u32 s57, s65, 0
	global_load_dwordx2 v[172:173], v227, s[56:57]
	v_pk_fma_f32 v[130:131], v[0:1], s[0:1], v[130:131] op_sel_hi:[1,0,1]
	v_pk_fma_f32 v[138:139], v[2:3], s[0:1], v[138:139] op_sel_hi:[1,0,1]
	v_pk_fma_f32 v[140:141], v[4:5], s[0:1], v[140:141] op_sel_hi:[1,0,1]
	v_pk_fma_f32 v[142:143], v[6:7], s[0:1], v[142:143] op_sel_hi:[1,0,1]
	v_pk_fma_f32 v[128:129], v[8:9], s[0:1], v[128:129] op_sel_hi:[1,0,1]
	v_pk_fma_f32 v[132:133], v[10:11], s[0:1], v[132:133] op_sel_hi:[1,0,1]
	v_pk_fma_f32 v[134:135], v[12:13], s[0:1], v[134:135] op_sel_hi:[1,0,1]
	v_pk_fma_f32 v[136:137], v[14:15], s[0:1], v[136:137] op_sel_hi:[1,0,1]
	v_readlane_b32 s0, v167, 27
	s_waitcnt vmcnt(15)
	v_cvt_scalef32_pk_f32_fp4 v[0:1], v174, 1.0
	v_cvt_scalef32_pk_f32_fp4 v[2:3], v174, 1.0 op_sel:[1,0,0]
	v_cvt_scalef32_pk_f32_fp4 v[4:5], v174, 1.0 op_sel:[0,1,0]
	v_cvt_scalef32_pk_f32_fp4 v[6:7], v174, 1.0 op_sel:[1,1,0]
	v_cvt_scalef32_pk_f32_fp4 v[8:9], v175, 1.0
	v_cvt_scalef32_pk_f32_fp4 v[10:11], v175, 1.0 op_sel:[1,0,0]
	v_cvt_scalef32_pk_f32_fp4 v[12:13], v175, 1.0 op_sel:[0,1,0]
	v_cvt_scalef32_pk_f32_fp4 v[14:15], v175, 1.0 op_sel:[1,1,0]
	v_readlane_b32 s54, v92, 43
	s_lshl_b32 s56, s54, 9
	s_add_u32 s56, s64, s56
	s_addc_u32 s57, s65, 0
	global_load_dwordx2 v[174:175], v227, s[56:57]
	v_pk_fma_f32 v[130:131], v[0:1], s[0:1], v[130:131] op_sel_hi:[1,0,1]
	v_pk_fma_f32 v[138:139], v[2:3], s[0:1], v[138:139] op_sel_hi:[1,0,1]
	v_pk_fma_f32 v[140:141], v[4:5], s[0:1], v[140:141] op_sel_hi:[1,0,1]
	v_pk_fma_f32 v[142:143], v[6:7], s[0:1], v[142:143] op_sel_hi:[1,0,1]
	v_pk_fma_f32 v[128:129], v[8:9], s[0:1], v[128:129] op_sel_hi:[1,0,1]
	v_pk_fma_f32 v[132:133], v[10:11], s[0:1], v[132:133] op_sel_hi:[1,0,1]
	v_pk_fma_f32 v[134:135], v[12:13], s[0:1], v[134:135] op_sel_hi:[1,0,1]
	v_pk_fma_f32 v[136:137], v[14:15], s[0:1], v[136:137] op_sel_hi:[1,0,1]
	v_readlane_b32 s0, v167, 28
	s_waitcnt vmcnt(15)
	v_cvt_scalef32_pk_f32_fp4 v[0:1], v180, 1.0
	v_cvt_scalef32_pk_f32_fp4 v[2:3], v180, 1.0 op_sel:[1,0,0]
	v_cvt_scalef32_pk_f32_fp4 v[4:5], v180, 1.0 op_sel:[0,1,0]
	v_cvt_scalef32_pk_f32_fp4 v[6:7], v180, 1.0 op_sel:[1,1,0]
	v_cvt_scalef32_pk_f32_fp4 v[8:9], v181, 1.0
	v_cvt_scalef32_pk_f32_fp4 v[10:11], v181, 1.0 op_sel:[1,0,0]
	v_cvt_scalef32_pk_f32_fp4 v[12:13], v181, 1.0 op_sel:[0,1,0]
	v_cvt_scalef32_pk_f32_fp4 v[14:15], v181, 1.0 op_sel:[1,1,0]
	v_readlane_b32 s54, v92, 44
	s_lshl_b32 s56, s54, 9
	s_add_u32 s56, s64, s56
	s_addc_u32 s57, s65, 0
	global_load_dwordx2 v[180:181], v227, s[56:57]
	v_pk_fma_f32 v[130:131], v[0:1], s[0:1], v[130:131] op_sel_hi:[1,0,1]
	v_pk_fma_f32 v[138:139], v[2:3], s[0:1], v[138:139] op_sel_hi:[1,0,1]
	v_pk_fma_f32 v[140:141], v[4:5], s[0:1], v[140:141] op_sel_hi:[1,0,1]
	v_pk_fma_f32 v[142:143], v[6:7], s[0:1], v[142:143] op_sel_hi:[1,0,1]
	v_pk_fma_f32 v[128:129], v[8:9], s[0:1], v[128:129] op_sel_hi:[1,0,1]
	v_pk_fma_f32 v[132:133], v[10:11], s[0:1], v[132:133] op_sel_hi:[1,0,1]
	v_pk_fma_f32 v[134:135], v[12:13], s[0:1], v[134:135] op_sel_hi:[1,0,1]
	v_pk_fma_f32 v[136:137], v[14:15], s[0:1], v[136:137] op_sel_hi:[1,0,1]
	v_readlane_b32 s0, v167, 29
	s_waitcnt vmcnt(15)
	v_cvt_scalef32_pk_f32_fp4 v[0:1], v182, 1.0
	v_cvt_scalef32_pk_f32_fp4 v[2:3], v182, 1.0 op_sel:[1,0,0]
	v_cvt_scalef32_pk_f32_fp4 v[4:5], v182, 1.0 op_sel:[0,1,0]
	v_cvt_scalef32_pk_f32_fp4 v[6:7], v182, 1.0 op_sel:[1,1,0]
	v_cvt_scalef32_pk_f32_fp4 v[8:9], v183, 1.0
	v_cvt_scalef32_pk_f32_fp4 v[10:11], v183, 1.0 op_sel:[1,0,0]
	v_cvt_scalef32_pk_f32_fp4 v[12:13], v183, 1.0 op_sel:[0,1,0]
	v_cvt_scalef32_pk_f32_fp4 v[14:15], v183, 1.0 op_sel:[1,1,0]
	v_readlane_b32 s54, v92, 45
	s_lshl_b32 s56, s54, 9
	s_add_u32 s56, s64, s56
	s_addc_u32 s57, s65, 0
	global_load_dwordx2 v[182:183], v227, s[56:57]
	v_pk_fma_f32 v[130:131], v[0:1], s[0:1], v[130:131] op_sel_hi:[1,0,1]
	v_pk_fma_f32 v[138:139], v[2:3], s[0:1], v[138:139] op_sel_hi:[1,0,1]
	v_pk_fma_f32 v[140:141], v[4:5], s[0:1], v[140:141] op_sel_hi:[1,0,1]
	v_pk_fma_f32 v[142:143], v[6:7], s[0:1], v[142:143] op_sel_hi:[1,0,1]
	v_pk_fma_f32 v[128:129], v[8:9], s[0:1], v[128:129] op_sel_hi:[1,0,1]
	v_pk_fma_f32 v[132:133], v[10:11], s[0:1], v[132:133] op_sel_hi:[1,0,1]
	v_pk_fma_f32 v[134:135], v[12:13], s[0:1], v[134:135] op_sel_hi:[1,0,1]
	v_pk_fma_f32 v[136:137], v[14:15], s[0:1], v[136:137] op_sel_hi:[1,0,1]
	v_readlane_b32 s0, v167, 30
	s_waitcnt vmcnt(15)
; __device__ void peer_gather_phase(const Params& P, int l, bool do_store) {
;     ...
;         const int ea = __builtin_amdgcn_readlane(evs, kb + 2 * pr), eb = __builtin_amdgcn_readlane(evs, kb + 2 * pr + 1);
;         const uint2* up = (const uint2*)(U + (size_t)(uphi ? eb : ea) * 768);
;         u6[3 * pr] = up[0]; u6[3 * pr + 1] = up[1]; u6[3 * pr + 2] = up[2];
;         v8[2 * pr] = *(const uint2*)(V + (size_t)ea * 512);
;         v8[2 * pr + 1] = *(const uint2*)(V + (size_t)eb * 512);
;     ...
; #pragma unroll
;       for (int j = 0; j < 8; ++j) {
;         const float a = __builtin_bit_cast(float, __builtin_amdgcn_readlane(__builtin_bit_cast(int, avec), kb + j));
;         const f32x2 aa = f32x2{a, a};
;         y[0] += aa * __builtin_amdgcn_cvt_scalef32_pk_f32_fp4(v8[j].x, 1.0f, 0); y[1] += aa * __builtin_amdgcn_cvt_scalef32_pk_f32_fp4(v8[j].x, 1.0f, 1);
;         y[2] += aa * __builtin_amdgcn_cvt_scalef32_pk_f32_fp4(v8[j].x, 1.0f, 2); y[3] += aa * __builtin_amdgcn_cvt_scalef32_pk_f32_fp4(v8[j].x, 1.0f, 3);
;         y[4] += aa * __builtin_amdgcn_cvt_scalef32_pk_f32_fp4(v8[j].y, 1.0f, 0); y[5] += aa * __builtin_amdgcn_cvt_scalef32_pk_f32_fp4(v8[j].y, 1.0f, 1);
;         y[6] += aa * __builtin_amdgcn_cvt_scalef32_pk_f32_fp4(v8[j].y, 1.0f, 2); y[7] += aa * __builtin_amdgcn_cvt_scalef32_pk_f32_fp4(v8[j].y, 1.0f, 3);
;       }
	v_cvt_scalef32_pk_f32_fp4 v[0:1], v184, 1.0
	v_cvt_scalef32_pk_f32_fp4 v[2:3], v184, 1.0 op_sel:[1,0,0]
	v_cvt_scalef32_pk_f32_fp4 v[4:5], v184, 1.0 op_sel:[0,1,0]
	v_cvt_scalef32_pk_f32_fp4 v[6:7], v184, 1.0 op_sel:[1,1,0]
	v_cvt_scalef32_pk_f32_fp4 v[8:9], v185, 1.0
	v_cvt_scalef32_pk_f32_fp4 v[10:11], v185, 1.0 op_sel:[1,0,0]
	v_cvt_scalef32_pk_f32_fp4 v[12:13], v185, 1.0 op_sel:[0,1,0]
	v_cvt_scalef32_pk_f32_fp4 v[14:15], v185, 1.0 op_sel:[1,1,0]
	v_readlane_b32 s54, v92, 46
	s_lshl_b32 s56, s54, 9
	s_add_u32 s56, s64, s56
	s_addc_u32 s57, s65, 0
	global_load_dwordx2 v[184:185], v227, s[56:57]
	v_pk_fma_f32 v[130:131], v[0:1], s[0:1], v[130:131] op_sel_hi:[1,0,1]
	v_pk_fma_f32 v[138:139], v[2:3], s[0:1], v[138:139] op_sel_hi:[1,0,1]
	v_pk_fma_f32 v[140:141], v[4:5], s[0:1], v[140:141] op_sel_hi:[1,0,1]
	v_pk_fma_f32 v[142:143], v[6:7], s[0:1], v[142:143] op_sel_hi:[1,0,1]
	v_pk_fma_f32 v[128:129], v[8:9], s[0:1], v[128:129] op_sel_hi:[1,0,1]
	v_pk_fma_f32 v[132:133], v[10:11], s[0:1], v[132:133] op_sel_hi:[1,0,1]
	v_pk_fma_f32 v[134:135], v[12:13], s[0:1], v[134:135] op_sel_hi:[1,0,1]
	v_pk_fma_f32 v[136:137], v[14:15], s[0:1], v[136:137] op_sel_hi:[1,0,1]
	v_readlane_b32 s0, v167, 31
	s_waitcnt vmcnt(15)
	v_cvt_scalef32_pk_f32_fp4 v[0:1], v186, 1.0
	v_cvt_scalef32_pk_f32_fp4 v[2:3], v186, 1.0 op_sel:[1,0,0]
	v_cvt_scalef32_pk_f32_fp4 v[4:5], v186, 1.0 op_sel:[0,1,0]
	v_cvt_scalef32_pk_f32_fp4 v[6:7], v186, 1.0 op_sel:[1,1,0]
	v_cvt_scalef32_pk_f32_fp4 v[8:9], v187, 1.0
	v_cvt_scalef32_pk_f32_fp4 v[10:11], v187, 1.0 op_sel:[1,0,0]
	v_cvt_scalef32_pk_f32_fp4 v[12:13], v187, 1.0 op_sel:[0,1,0]
	v_cvt_scalef32_pk_f32_fp4 v[14:15], v187, 1.0 op_sel:[1,1,0]
	v_readlane_b32 s54, v92, 47
	s_lshl_b32 s56, s54, 9
	s_add_u32 s56, s64, s56
	s_addc_u32 s57, s65, 0
	global_load_dwordx2 v[186:187], v227, s[56:57]
	v_pk_fma_f32 v[130:131], v[0:1], s[0:1], v[130:131] op_sel_hi:[1,0,1]
	v_pk_fma_f32 v[138:139], v[2:3], s[0:1], v[138:139] op_sel_hi:[1,0,1]
	v_pk_fma_f32 v[140:141], v[4:5], s[0:1], v[140:141] op_sel_hi:[1,0,1]
	v_pk_fma_f32 v[142:143], v[6:7], s[0:1], v[142:143] op_sel_hi:[1,0,1]
	v_pk_fma_f32 v[128:129], v[8:9], s[0:1], v[128:129] op_sel_hi:[1,0,1]
	v_pk_fma_f32 v[132:133], v[10:11], s[0:1], v[132:133] op_sel_hi:[1,0,1]
	v_pk_fma_f32 v[134:135], v[12:13], s[0:1], v[134:135] op_sel_hi:[1,0,1]
	v_pk_fma_f32 v[136:137], v[14:15], s[0:1], v[136:137] op_sel_hi:[1,0,1]
	v_readlane_b32 s0, v167, 32
	s_waitcnt vmcnt(15)
	v_cvt_scalef32_pk_f32_fp4 v[0:1], v144, 1.0
	v_cvt_scalef32_pk_f32_fp4 v[2:3], v144, 1.0 op_sel:[1,0,0]
	v_cvt_scalef32_pk_f32_fp4 v[4:5], v144, 1.0 op_sel:[0,1,0]
	v_cvt_scalef32_pk_f32_fp4 v[6:7], v144, 1.0 op_sel:[1,1,0]
	v_cvt_scalef32_pk_f32_fp4 v[8:9], v145, 1.0
	v_cvt_scalef32_pk_f32_fp4 v[10:11], v145, 1.0 op_sel:[1,0,0]
	v_cvt_scalef32_pk_f32_fp4 v[12:13], v145, 1.0 op_sel:[0,1,0]
	v_cvt_scalef32_pk_f32_fp4 v[14:15], v145, 1.0 op_sel:[1,1,0]
	v_readlane_b32 s54, v92, 48
	s_lshl_b32 s56, s54, 9
	s_add_u32 s56, s64, s56
	s_addc_u32 s57, s65, 0
	global_load_dwordx2 v[144:145], v227, s[56:57]
	v_pk_fma_f32 v[130:131], v[0:1], s[0:1], v[130:131] op_sel_hi:[1,0,1]
	v_pk_fma_f32 v[138:139], v[2:3], s[0:1], v[138:139] op_sel_hi:[1,0,1]
	v_pk_fma_f32 v[140:141], v[4:5], s[0:1], v[140:141] op_sel_hi:[1,0,1]
	v_pk_fma_f32 v[142:143], v[6:7], s[0:1], v[142:143] op_sel_hi:[1,0,1]
	v_pk_fma_f32 v[128:129], v[8:9], s[0:1], v[128:129] op_sel_hi:[1,0,1]
	v_pk_fma_f32 v[132:133], v[10:11], s[0:1], v[132:133] op_sel_hi:[1,0,1]
	v_pk_fma_f32 v[134:135], v[12:13], s[0:1], v[134:135] op_sel_hi:[1,0,1]
	v_pk_fma_f32 v[136:137], v[14:15], s[0:1], v[136:137] op_sel_hi:[1,0,1]
	v_readlane_b32 s0, v167, 33
	s_waitcnt vmcnt(15)
	v_cvt_scalef32_pk_f32_fp4 v[0:1], v146, 1.0
	v_cvt_scalef32_pk_f32_fp4 v[2:3], v146, 1.0 op_sel:[1,0,0]
	v_cvt_scalef32_pk_f32_fp4 v[4:5], v146, 1.0 op_sel:[0,1,0]
	v_cvt_scalef32_pk_f32_fp4 v[6:7], v146, 1.0 op_sel:[1,1,0]
	v_cvt_scalef32_pk_f32_fp4 v[8:9], v147, 1.0
	v_cvt_scalef32_pk_f32_fp4 v[10:11], v147, 1.0 op_sel:[1,0,0]
	v_cvt_scalef32_pk_f32_fp4 v[12:13], v147, 1.0 op_sel:[0,1,0]
	v_cvt_scalef32_pk_f32_fp4 v[14:15], v147, 1.0 op_sel:[1,1,0]
	v_readlane_b32 s54, v92, 49
	s_lshl_b32 s56, s54, 9
	s_add_u32 s56, s64, s56
	s_addc_u32 s57, s65, 0
	global_load_dwordx2 v[146:147], v227, s[56:57]
	v_pk_fma_f32 v[130:131], v[0:1], s[0:1], v[130:131] op_sel_hi:[1,0,1]
	v_pk_fma_f32 v[138:139], v[2:3], s[0:1], v[138:139] op_sel_hi:[1,0,1]
	v_pk_fma_f32 v[140:141], v[4:5], s[0:1], v[140:141] op_sel_hi:[1,0,1]
	v_pk_fma_f32 v[142:143], v[6:7], s[0:1], v[142:143] op_sel_hi:[1,0,1]
	v_pk_fma_f32 v[128:129], v[8:9], s[0:1], v[128:129] op_sel_hi:[1,0,1]
	v_pk_fma_f32 v[132:133], v[10:11], s[0:1], v[132:133] op_sel_hi:[1,0,1]
	v_pk_fma_f32 v[134:135], v[12:13], s[0:1], v[134:135] op_sel_hi:[1,0,1]
	v_pk_fma_f32 v[136:137], v[14:15], s[0:1], v[136:137] op_sel_hi:[1,0,1]
	v_readlane_b32 s0, v167, 34
	s_waitcnt vmcnt(15)
	v_cvt_scalef32_pk_f32_fp4 v[0:1], v148, 1.0
	v_cvt_scalef32_pk_f32_fp4 v[2:3], v148, 1.0 op_sel:[1,0,0]
	v_cvt_scalef32_pk_f32_fp4 v[4:5], v148, 1.0 op_sel:[0,1,0]
	v_cvt_scalef32_pk_f32_fp4 v[6:7], v148, 1.0 op_sel:[1,1,0]
	v_cvt_scalef32_pk_f32_fp4 v[8:9], v149, 1.0
	v_cvt_scalef32_pk_f32_fp4 v[10:11], v149, 1.0 op_sel:[1,0,0]
	v_cvt_scalef32_pk_f32_fp4 v[12:13], v149, 1.0 op_sel:[0,1,0]
	v_cvt_scalef32_pk_f32_fp4 v[14:15], v149, 1.0 op_sel:[1,1,0]
	v_readlane_b32 s54, v92, 50
	s_lshl_b32 s56, s54, 9
	s_add_u32 s56, s64, s56
	s_addc_u32 s57, s65, 0
	global_load_dwordx2 v[148:149], v227, s[56:57]
	v_pk_fma_f32 v[130:131], v[0:1], s[0:1], v[130:131] op_sel_hi:[1,0,1]
	v_pk_fma_f32 v[138:139], v[2:3], s[0:1], v[138:139] op_sel_hi:[1,0,1]
	v_pk_fma_f32 v[140:141], v[4:5], s[0:1], v[140:141] op_sel_hi:[1,0,1]
	v_pk_fma_f32 v[142:143], v[6:7], s[0:1], v[142:143] op_sel_hi:[1,0,1]
	v_pk_fma_f32 v[128:129], v[8:9], s[0:1], v[128:129] op_sel_hi:[1,0,1]
	v_pk_fma_f32 v[132:133], v[10:11], s[0:1], v[132:133] op_sel_hi:[1,0,1]
	v_pk_fma_f32 v[134:135], v[12:13], s[0:1], v[134:135] op_sel_hi:[1,0,1]
	v_pk_fma_f32 v[136:137], v[14:15], s[0:1], v[136:137] op_sel_hi:[1,0,1]
	v_readlane_b32 s0, v167, 35
	s_waitcnt vmcnt(15)
; __device__ void peer_gather_phase(const Params& P, int l, bool do_store) {
;     ...
;         const uint2* up = (const uint2*)(U + (size_t)(uphi ? eb : ea) * 768);
;         u6[3 * pr] = up[0]; u6[3 * pr + 1] = up[1]; u6[3 * pr + 2] = up[2];
;         v8[2 * pr] = *(const uint2*)(V + (size_t)ea * 512);
;         v8[2 * pr + 1] = *(const uint2*)(V + (size_t)eb * 512);
;     ...
; #pragma unroll
;       for (int j = 0; j < 8; ++j) {
;         const float a = __builtin_bit_cast(float, __builtin_amdgcn_readlane(__builtin_bit_cast(int, avec), kb + j));
;         const f32x2 aa = f32x2{a, a};
;         y[0] += aa * __builtin_amdgcn_cvt_scalef32_pk_f32_fp4(v8[j].x, 1.0f, 0); y[1] += aa * __builtin_amdgcn_cvt_scalef32_pk_f32_fp4(v8[j].x, 1.0f, 1);
;         y[2] += aa * __builtin_amdgcn_cvt_scalef32_pk_f32_fp4(v8[j].x, 1.0f, 2); y[3] += aa * __builtin_amdgcn_cvt_scalef32_pk_f32_fp4(v8[j].x, 1.0f, 3);
;         y[4] += aa * __builtin_amdgcn_cvt_scalef32_pk_f32_fp4(v8[j].y, 1.0f, 0); y[5] += aa * __builtin_amdgcn_cvt_scalef32_pk_f32_fp4(v8[j].y, 1.0f, 1);
;         y[6] += aa * __builtin_amdgcn_cvt_scalef32_pk_f32_fp4(v8[j].y, 1.0f, 2); y[7] += aa * __builtin_amdgcn_cvt_scalef32_pk_f32_fp4(v8[j].y, 1.0f, 3);
;       }
	v_cvt_scalef32_pk_f32_fp4 v[0:1], v150, 1.0
	v_cvt_scalef32_pk_f32_fp4 v[2:3], v150, 1.0 op_sel:[1,0,0]
	v_cvt_scalef32_pk_f32_fp4 v[4:5], v150, 1.0 op_sel:[0,1,0]
	v_cvt_scalef32_pk_f32_fp4 v[6:7], v150, 1.0 op_sel:[1,1,0]
	v_cvt_scalef32_pk_f32_fp4 v[8:9], v151, 1.0
	v_cvt_scalef32_pk_f32_fp4 v[10:11], v151, 1.0 op_sel:[1,0,0]
	v_cvt_scalef32_pk_f32_fp4 v[12:13], v151, 1.0 op_sel:[0,1,0]
	v_cvt_scalef32_pk_f32_fp4 v[14:15], v151, 1.0 op_sel:[1,1,0]
	v_readlane_b32 s54, v92, 51
	s_lshl_b32 s56, s54, 9
	s_add_u32 s56, s64, s56
	s_addc_u32 s57, s65, 0
	global_load_dwordx2 v[150:151], v227, s[56:57]
	v_pk_fma_f32 v[130:131], v[0:1], s[0:1], v[130:131] op_sel_hi:[1,0,1]
	v_pk_fma_f32 v[138:139], v[2:3], s[0:1], v[138:139] op_sel_hi:[1,0,1]
	v_pk_fma_f32 v[140:141], v[4:5], s[0:1], v[140:141] op_sel_hi:[1,0,1]
	v_pk_fma_f32 v[142:143], v[6:7], s[0:1], v[142:143] op_sel_hi:[1,0,1]
	v_pk_fma_f32 v[128:129], v[8:9], s[0:1], v[128:129] op_sel_hi:[1,0,1]
	v_pk_fma_f32 v[132:133], v[10:11], s[0:1], v[132:133] op_sel_hi:[1,0,1]
	v_pk_fma_f32 v[134:135], v[12:13], s[0:1], v[134:135] op_sel_hi:[1,0,1]
	v_pk_fma_f32 v[136:137], v[14:15], s[0:1], v[136:137] op_sel_hi:[1,0,1]
	v_readlane_b32 s0, v167, 36
	s_waitcnt vmcnt(15)
	v_cvt_scalef32_pk_f32_fp4 v[0:1], v152, 1.0
	v_cvt_scalef32_pk_f32_fp4 v[2:3], v152, 1.0 op_sel:[1,0,0]
	v_cvt_scalef32_pk_f32_fp4 v[4:5], v152, 1.0 op_sel:[0,1,0]
	v_cvt_scalef32_pk_f32_fp4 v[6:7], v152, 1.0 op_sel:[1,1,0]
	v_cvt_scalef32_pk_f32_fp4 v[8:9], v153, 1.0
	v_cvt_scalef32_pk_f32_fp4 v[10:11], v153, 1.0 op_sel:[1,0,0]
	v_cvt_scalef32_pk_f32_fp4 v[12:13], v153, 1.0 op_sel:[0,1,0]
	v_cvt_scalef32_pk_f32_fp4 v[14:15], v153, 1.0 op_sel:[1,1,0]
	v_readlane_b32 s54, v92, 52
	s_lshl_b32 s56, s54, 9
	s_add_u32 s56, s64, s56
	s_addc_u32 s57, s65, 0
	global_load_dwordx2 v[152:153], v227, s[56:57]
	v_pk_fma_f32 v[130:131], v[0:1], s[0:1], v[130:131] op_sel_hi:[1,0,1]
	v_pk_fma_f32 v[138:139], v[2:3], s[0:1], v[138:139] op_sel_hi:[1,0,1]
	v_pk_fma_f32 v[140:141], v[4:5], s[0:1], v[140:141] op_sel_hi:[1,0,1]
	v_pk_fma_f32 v[142:143], v[6:7], s[0:1], v[142:143] op_sel_hi:[1,0,1]
	v_pk_fma_f32 v[128:129], v[8:9], s[0:1], v[128:129] op_sel_hi:[1,0,1]
	v_pk_fma_f32 v[132:133], v[10:11], s[0:1], v[132:133] op_sel_hi:[1,0,1]
	v_pk_fma_f32 v[134:135], v[12:13], s[0:1], v[134:135] op_sel_hi:[1,0,1]
	v_pk_fma_f32 v[136:137], v[14:15], s[0:1], v[136:137] op_sel_hi:[1,0,1]
	v_readlane_b32 s0, v167, 37
	s_waitcnt vmcnt(15)
	v_cvt_scalef32_pk_f32_fp4 v[0:1], v154, 1.0
	v_cvt_scalef32_pk_f32_fp4 v[2:3], v154, 1.0 op_sel:[1,0,0]
	v_cvt_scalef32_pk_f32_fp4 v[4:5], v154, 1.0 op_sel:[0,1,0]
	v_cvt_scalef32_pk_f32_fp4 v[6:7], v154, 1.0 op_sel:[1,1,0]
	v_cvt_scalef32_pk_f32_fp4 v[8:9], v155, 1.0
	v_cvt_scalef32_pk_f32_fp4 v[10:11], v155, 1.0 op_sel:[1,0,0]
	v_cvt_scalef32_pk_f32_fp4 v[12:13], v155, 1.0 op_sel:[0,1,0]
	v_cvt_scalef32_pk_f32_fp4 v[14:15], v155, 1.0 op_sel:[1,1,0]
	v_readlane_b32 s54, v92, 53
	s_lshl_b32 s56, s54, 9
	s_add_u32 s56, s64, s56
	s_addc_u32 s57, s65, 0
	global_load_dwordx2 v[154:155], v227, s[56:57]
	v_pk_fma_f32 v[130:131], v[0:1], s[0:1], v[130:131] op_sel_hi:[1,0,1]
	v_pk_fma_f32 v[138:139], v[2:3], s[0:1], v[138:139] op_sel_hi:[1,0,1]
	v_pk_fma_f32 v[140:141], v[4:5], s[0:1], v[140:141] op_sel_hi:[1,0,1]
	v_pk_fma_f32 v[142:143], v[6:7], s[0:1], v[142:143] op_sel_hi:[1,0,1]
	v_pk_fma_f32 v[128:129], v[8:9], s[0:1], v[128:129] op_sel_hi:[1,0,1]
	v_pk_fma_f32 v[132:133], v[10:11], s[0:1], v[132:133] op_sel_hi:[1,0,1]
	v_pk_fma_f32 v[134:135], v[12:13], s[0:1], v[134:135] op_sel_hi:[1,0,1]
	v_pk_fma_f32 v[136:137], v[14:15], s[0:1], v[136:137] op_sel_hi:[1,0,1]
	v_readlane_b32 s0, v167, 38
	s_waitcnt vmcnt(15)
	v_cvt_scalef32_pk_f32_fp4 v[0:1], v156, 1.0
	v_cvt_scalef32_pk_f32_fp4 v[2:3], v156, 1.0 op_sel:[1,0,0]
	v_cvt_scalef32_pk_f32_fp4 v[4:5], v156, 1.0 op_sel:[0,1,0]
	v_cvt_scalef32_pk_f32_fp4 v[6:7], v156, 1.0 op_sel:[1,1,0]
	v_cvt_scalef32_pk_f32_fp4 v[8:9], v157, 1.0
	v_cvt_scalef32_pk_f32_fp4 v[10:11], v157, 1.0 op_sel:[1,0,0]
	v_cvt_scalef32_pk_f32_fp4 v[12:13], v157, 1.0 op_sel:[0,1,0]
	v_cvt_scalef32_pk_f32_fp4 v[14:15], v157, 1.0 op_sel:[1,1,0]
	v_readlane_b32 s54, v92, 54
	s_lshl_b32 s56, s54, 9
	s_add_u32 s56, s64, s56
	s_addc_u32 s57, s65, 0
	global_load_dwordx2 v[156:157], v227, s[56:57]
	v_pk_fma_f32 v[130:131], v[0:1], s[0:1], v[130:131] op_sel_hi:[1,0,1]
	v_pk_fma_f32 v[138:139], v[2:3], s[0:1], v[138:139] op_sel_hi:[1,0,1]
	v_pk_fma_f32 v[140:141], v[4:5], s[0:1], v[140:141] op_sel_hi:[1,0,1]
	v_pk_fma_f32 v[142:143], v[6:7], s[0:1], v[142:143] op_sel_hi:[1,0,1]
	v_pk_fma_f32 v[128:129], v[8:9], s[0:1], v[128:129] op_sel_hi:[1,0,1]
	v_pk_fma_f32 v[132:133], v[10:11], s[0:1], v[132:133] op_sel_hi:[1,0,1]
	v_pk_fma_f32 v[134:135], v[12:13], s[0:1], v[134:135] op_sel_hi:[1,0,1]
	v_pk_fma_f32 v[136:137], v[14:15], s[0:1], v[136:137] op_sel_hi:[1,0,1]
	v_readlane_b32 s0, v167, 39
	s_waitcnt vmcnt(15)
	v_cvt_scalef32_pk_f32_fp4 v[0:1], v158, 1.0
	v_cvt_scalef32_pk_f32_fp4 v[2:3], v158, 1.0 op_sel:[1,0,0]
	v_cvt_scalef32_pk_f32_fp4 v[4:5], v158, 1.0 op_sel:[0,1,0]
	v_cvt_scalef32_pk_f32_fp4 v[6:7], v158, 1.0 op_sel:[1,1,0]
	v_cvt_scalef32_pk_f32_fp4 v[8:9], v159, 1.0
	v_cvt_scalef32_pk_f32_fp4 v[10:11], v159, 1.0 op_sel:[1,0,0]
	v_cvt_scalef32_pk_f32_fp4 v[12:13], v159, 1.0 op_sel:[0,1,0]
	v_cvt_scalef32_pk_f32_fp4 v[14:15], v159, 1.0 op_sel:[1,1,0]
	v_readlane_b32 s54, v92, 55
	s_lshl_b32 s56, s54, 9
	s_add_u32 s56, s64, s56
	s_addc_u32 s57, s65, 0
	global_load_dwordx2 v[158:159], v227, s[56:57]
	v_pk_fma_f32 v[130:131], v[0:1], s[0:1], v[130:131] op_sel_hi:[1,0,1]
	v_pk_fma_f32 v[138:139], v[2:3], s[0:1], v[138:139] op_sel_hi:[1,0,1]
	v_pk_fma_f32 v[140:141], v[4:5], s[0:1], v[140:141] op_sel_hi:[1,0,1]
	v_pk_fma_f32 v[142:143], v[6:7], s[0:1], v[142:143] op_sel_hi:[1,0,1]
	v_pk_fma_f32 v[128:129], v[8:9], s[0:1], v[128:129] op_sel_hi:[1,0,1]
	v_pk_fma_f32 v[132:133], v[10:11], s[0:1], v[132:133] op_sel_hi:[1,0,1]
	v_pk_fma_f32 v[134:135], v[12:13], s[0:1], v[134:135] op_sel_hi:[1,0,1]
	v_pk_fma_f32 v[136:137], v[14:15], s[0:1], v[136:137] op_sel_hi:[1,0,1]
	v_readlane_b32 s0, v167, 40
	s_waitcnt vmcnt(15)
; __device__ void peer_gather_phase(const Params& P, int l, bool do_store) {
;     ...
;         const uint2* up = (const uint2*)(U + (size_t)(uphi ? eb : ea) * 768);
;         u6[3 * pr] = up[0]; u6[3 * pr + 1] = up[1]; u6[3 * pr + 2] = up[2];
;         v8[2 * pr] = *(const uint2*)(V + (size_t)ea * 512);
;         v8[2 * pr + 1] = *(const uint2*)(V + (size_t)eb * 512);
;     ...
; #pragma unroll
;       for (int j = 0; j < 8; ++j) {
;         const float a = __builtin_bit_cast(float, __builtin_amdgcn_readlane(__builtin_bit_cast(int, avec), kb + j));
;         const f32x2 aa = f32x2{a, a};
;         y[0] += aa * __builtin_amdgcn_cvt_scalef32_pk_f32_fp4(v8[j].x, 1.0f, 0); y[1] += aa * __builtin_amdgcn_cvt_scalef32_pk_f32_fp4(v8[j].x, 1.0f, 1);
;         y[2] += aa * __builtin_amdgcn_cvt_scalef32_pk_f32_fp4(v8[j].x, 1.0f, 2); y[3] += aa * __builtin_amdgcn_cvt_scalef32_pk_f32_fp4(v8[j].x, 1.0f, 3);
;         y[4] += aa * __builtin_amdgcn_cvt_scalef32_pk_f32_fp4(v8[j].y, 1.0f, 0); y[5] += aa * __builtin_amdgcn_cvt_scalef32_pk_f32_fp4(v8[j].y, 1.0f, 1);
;         y[6] += aa * __builtin_amdgcn_cvt_scalef32_pk_f32_fp4(v8[j].y, 1.0f, 2); y[7] += aa * __builtin_amdgcn_cvt_scalef32_pk_f32_fp4(v8[j].y, 1.0f, 3);
;       }
	v_cvt_scalef32_pk_f32_fp4 v[0:1], v168, 1.0
	v_cvt_scalef32_pk_f32_fp4 v[2:3], v168, 1.0 op_sel:[1,0,0]
	v_cvt_scalef32_pk_f32_fp4 v[4:5], v168, 1.0 op_sel:[0,1,0]
	v_cvt_scalef32_pk_f32_fp4 v[6:7], v168, 1.0 op_sel:[1,1,0]
	v_cvt_scalef32_pk_f32_fp4 v[8:9], v169, 1.0
	v_cvt_scalef32_pk_f32_fp4 v[10:11], v169, 1.0 op_sel:[1,0,0]
	v_cvt_scalef32_pk_f32_fp4 v[12:13], v169, 1.0 op_sel:[0,1,0]
	v_cvt_scalef32_pk_f32_fp4 v[14:15], v169, 1.0 op_sel:[1,1,0]
	v_readlane_b32 s54, v92, 56
	s_lshl_b32 s56, s54, 9
	s_add_u32 s56, s64, s56
	s_addc_u32 s57, s65, 0
	global_load_dwordx2 v[168:169], v227, s[56:57]
	v_pk_fma_f32 v[130:131], v[0:1], s[0:1], v[130:131] op_sel_hi:[1,0,1]
	v_pk_fma_f32 v[138:139], v[2:3], s[0:1], v[138:139] op_sel_hi:[1,0,1]
	v_pk_fma_f32 v[140:141], v[4:5], s[0:1], v[140:141] op_sel_hi:[1,0,1]
	v_pk_fma_f32 v[142:143], v[6:7], s[0:1], v[142:143] op_sel_hi:[1,0,1]
	v_pk_fma_f32 v[128:129], v[8:9], s[0:1], v[128:129] op_sel_hi:[1,0,1]
	v_pk_fma_f32 v[132:133], v[10:11], s[0:1], v[132:133] op_sel_hi:[1,0,1]
	v_pk_fma_f32 v[134:135], v[12:13], s[0:1], v[134:135] op_sel_hi:[1,0,1]
	v_pk_fma_f32 v[136:137], v[14:15], s[0:1], v[136:137] op_sel_hi:[1,0,1]
	v_readlane_b32 s0, v167, 41
	s_waitcnt vmcnt(15)
	v_cvt_scalef32_pk_f32_fp4 v[0:1], v170, 1.0
	v_cvt_scalef32_pk_f32_fp4 v[2:3], v170, 1.0 op_sel:[1,0,0]
	v_cvt_scalef32_pk_f32_fp4 v[4:5], v170, 1.0 op_sel:[0,1,0]
	v_cvt_scalef32_pk_f32_fp4 v[6:7], v170, 1.0 op_sel:[1,1,0]
	v_cvt_scalef32_pk_f32_fp4 v[8:9], v171, 1.0
	v_cvt_scalef32_pk_f32_fp4 v[10:11], v171, 1.0 op_sel:[1,0,0]
	v_cvt_scalef32_pk_f32_fp4 v[12:13], v171, 1.0 op_sel:[0,1,0]
	v_cvt_scalef32_pk_f32_fp4 v[14:15], v171, 1.0 op_sel:[1,1,0]
	v_readlane_b32 s54, v92, 57
	s_lshl_b32 s56, s54, 9
	s_add_u32 s56, s64, s56
	s_addc_u32 s57, s65, 0
	global_load_dwordx2 v[170:171], v227, s[56:57]
	v_pk_fma_f32 v[130:131], v[0:1], s[0:1], v[130:131] op_sel_hi:[1,0,1]
	v_pk_fma_f32 v[138:139], v[2:3], s[0:1], v[138:139] op_sel_hi:[1,0,1]
	v_pk_fma_f32 v[140:141], v[4:5], s[0:1], v[140:141] op_sel_hi:[1,0,1]
	v_pk_fma_f32 v[142:143], v[6:7], s[0:1], v[142:143] op_sel_hi:[1,0,1]
	v_pk_fma_f32 v[128:129], v[8:9], s[0:1], v[128:129] op_sel_hi:[1,0,1]
	v_pk_fma_f32 v[132:133], v[10:11], s[0:1], v[132:133] op_sel_hi:[1,0,1]
	v_pk_fma_f32 v[134:135], v[12:13], s[0:1], v[134:135] op_sel_hi:[1,0,1]
	v_pk_fma_f32 v[136:137], v[14:15], s[0:1], v[136:137] op_sel_hi:[1,0,1]
	v_readlane_b32 s0, v167, 42
	s_waitcnt vmcnt(15)
	v_cvt_scalef32_pk_f32_fp4 v[0:1], v172, 1.0
	v_cvt_scalef32_pk_f32_fp4 v[2:3], v172, 1.0 op_sel:[1,0,0]
	v_cvt_scalef32_pk_f32_fp4 v[4:5], v172, 1.0 op_sel:[0,1,0]
	v_cvt_scalef32_pk_f32_fp4 v[6:7], v172, 1.0 op_sel:[1,1,0]
	v_cvt_scalef32_pk_f32_fp4 v[8:9], v173, 1.0
	v_cvt_scalef32_pk_f32_fp4 v[10:11], v173, 1.0 op_sel:[1,0,0]
	v_cvt_scalef32_pk_f32_fp4 v[12:13], v173, 1.0 op_sel:[0,1,0]
	v_cvt_scalef32_pk_f32_fp4 v[14:15], v173, 1.0 op_sel:[1,1,0]
	v_readlane_b32 s54, v92, 58
	s_lshl_b32 s56, s54, 9
	s_add_u32 s56, s64, s56
	s_addc_u32 s57, s65, 0
	global_load_dwordx2 v[172:173], v227, s[56:57]
	v_pk_fma_f32 v[130:131], v[0:1], s[0:1], v[130:131] op_sel_hi:[1,0,1]
	v_pk_fma_f32 v[138:139], v[2:3], s[0:1], v[138:139] op_sel_hi:[1,0,1]
	v_pk_fma_f32 v[140:141], v[4:5], s[0:1], v[140:141] op_sel_hi:[1,0,1]
	v_pk_fma_f32 v[142:143], v[6:7], s[0:1], v[142:143] op_sel_hi:[1,0,1]
	v_pk_fma_f32 v[128:129], v[8:9], s[0:1], v[128:129] op_sel_hi:[1,0,1]
	v_pk_fma_f32 v[132:133], v[10:11], s[0:1], v[132:133] op_sel_hi:[1,0,1]
	v_pk_fma_f32 v[134:135], v[12:13], s[0:1], v[134:135] op_sel_hi:[1,0,1]
	v_pk_fma_f32 v[136:137], v[14:15], s[0:1], v[136:137] op_sel_hi:[1,0,1]
	v_readlane_b32 s0, v167, 43
	s_waitcnt vmcnt(15)
	v_cvt_scalef32_pk_f32_fp4 v[0:1], v174, 1.0
	v_cvt_scalef32_pk_f32_fp4 v[2:3], v174, 1.0 op_sel:[1,0,0]
	v_cvt_scalef32_pk_f32_fp4 v[4:5], v174, 1.0 op_sel:[0,1,0]
	v_cvt_scalef32_pk_f32_fp4 v[6:7], v174, 1.0 op_sel:[1,1,0]
	v_cvt_scalef32_pk_f32_fp4 v[8:9], v175, 1.0
	v_cvt_scalef32_pk_f32_fp4 v[10:11], v175, 1.0 op_sel:[1,0,0]
	v_cvt_scalef32_pk_f32_fp4 v[12:13], v175, 1.0 op_sel:[0,1,0]
	v_cvt_scalef32_pk_f32_fp4 v[14:15], v175, 1.0 op_sel:[1,1,0]
	v_readlane_b32 s54, v92, 59
	s_lshl_b32 s56, s54, 9
	s_add_u32 s56, s64, s56
	s_addc_u32 s57, s65, 0
	global_load_dwordx2 v[174:175], v227, s[56:57]
	v_pk_fma_f32 v[130:131], v[0:1], s[0:1], v[130:131] op_sel_hi:[1,0,1]
	v_pk_fma_f32 v[138:139], v[2:3], s[0:1], v[138:139] op_sel_hi:[1,0,1]
	v_pk_fma_f32 v[140:141], v[4:5], s[0:1], v[140:141] op_sel_hi:[1,0,1]
	v_pk_fma_f32 v[142:143], v[6:7], s[0:1], v[142:143] op_sel_hi:[1,0,1]
	v_pk_fma_f32 v[128:129], v[8:9], s[0:1], v[128:129] op_sel_hi:[1,0,1]
	v_pk_fma_f32 v[132:133], v[10:11], s[0:1], v[132:133] op_sel_hi:[1,0,1]
	v_pk_fma_f32 v[134:135], v[12:13], s[0:1], v[134:135] op_sel_hi:[1,0,1]
	v_pk_fma_f32 v[136:137], v[14:15], s[0:1], v[136:137] op_sel_hi:[1,0,1]
	v_readlane_b32 s0, v167, 44
	s_waitcnt vmcnt(15)
	v_cvt_scalef32_pk_f32_fp4 v[0:1], v180, 1.0
	v_cvt_scalef32_pk_f32_fp4 v[2:3], v180, 1.0 op_sel:[1,0,0]
	v_cvt_scalef32_pk_f32_fp4 v[4:5], v180, 1.0 op_sel:[0,1,0]
	v_cvt_scalef32_pk_f32_fp4 v[6:7], v180, 1.0 op_sel:[1,1,0]
	v_cvt_scalef32_pk_f32_fp4 v[8:9], v181, 1.0
	v_cvt_scalef32_pk_f32_fp4 v[10:11], v181, 1.0 op_sel:[1,0,0]
	v_cvt_scalef32_pk_f32_fp4 v[12:13], v181, 1.0 op_sel:[0,1,0]
	v_cvt_scalef32_pk_f32_fp4 v[14:15], v181, 1.0 op_sel:[1,1,0]
	v_readlane_b32 s54, v92, 60
	s_lshl_b32 s56, s54, 9
	s_add_u32 s56, s64, s56
	s_addc_u32 s57, s65, 0
	global_load_dwordx2 v[180:181], v227, s[56:57]
	v_pk_fma_f32 v[130:131], v[0:1], s[0:1], v[130:131] op_sel_hi:[1,0,1]
	v_pk_fma_f32 v[138:139], v[2:3], s[0:1], v[138:139] op_sel_hi:[1,0,1]
	v_pk_fma_f32 v[140:141], v[4:5], s[0:1], v[140:141] op_sel_hi:[1,0,1]
	v_pk_fma_f32 v[142:143], v[6:7], s[0:1], v[142:143] op_sel_hi:[1,0,1]
	v_pk_fma_f32 v[128:129], v[8:9], s[0:1], v[128:129] op_sel_hi:[1,0,1]
	v_pk_fma_f32 v[132:133], v[10:11], s[0:1], v[132:133] op_sel_hi:[1,0,1]
	v_pk_fma_f32 v[134:135], v[12:13], s[0:1], v[134:135] op_sel_hi:[1,0,1]
	v_pk_fma_f32 v[136:137], v[14:15], s[0:1], v[136:137] op_sel_hi:[1,0,1]
	v_readlane_b32 s0, v167, 45
	s_waitcnt vmcnt(15)
; __device__ void peer_gather_phase(const Params& P, int l, bool do_store) {
;     ...
;         const uint2* up = (const uint2*)(U + (size_t)(uphi ? eb : ea) * 768);
;         u6[3 * pr] = up[0]; u6[3 * pr + 1] = up[1]; u6[3 * pr + 2] = up[2];
;         v8[2 * pr] = *(const uint2*)(V + (size_t)ea * 512);
;         v8[2 * pr + 1] = *(const uint2*)(V + (size_t)eb * 512);
;     ...
; #pragma unroll
;       for (int j = 0; j < 8; ++j) {
;         const float a = __builtin_bit_cast(float, __builtin_amdgcn_readlane(__builtin_bit_cast(int, avec), kb + j));
;         const f32x2 aa = f32x2{a, a};
;         y[0] += aa * __builtin_amdgcn_cvt_scalef32_pk_f32_fp4(v8[j].x, 1.0f, 0); y[1] += aa * __builtin_amdgcn_cvt_scalef32_pk_f32_fp4(v8[j].x, 1.0f, 1);
;         y[2] += aa * __builtin_amdgcn_cvt_scalef32_pk_f32_fp4(v8[j].x, 1.0f, 2); y[3] += aa * __builtin_amdgcn_cvt_scalef32_pk_f32_fp4(v8[j].x, 1.0f, 3);
;         y[4] += aa * __builtin_amdgcn_cvt_scalef32_pk_f32_fp4(v8[j].y, 1.0f, 0); y[5] += aa * __builtin_amdgcn_cvt_scalef32_pk_f32_fp4(v8[j].y, 1.0f, 1);
;         y[6] += aa * __builtin_amdgcn_cvt_scalef32_pk_f32_fp4(v8[j].y, 1.0f, 2); y[7] += aa * __builtin_amdgcn_cvt_scalef32_pk_f32_fp4(v8[j].y, 1.0f, 3);
;       }
	v_cvt_scalef32_pk_f32_fp4 v[0:1], v182, 1.0
	v_cvt_scalef32_pk_f32_fp4 v[2:3], v182, 1.0 op_sel:[1,0,0]
	v_cvt_scalef32_pk_f32_fp4 v[4:5], v182, 1.0 op_sel:[0,1,0]
	v_cvt_scalef32_pk_f32_fp4 v[6:7], v182, 1.0 op_sel:[1,1,0]
	v_cvt_scalef32_pk_f32_fp4 v[8:9], v183, 1.0
	v_cvt_scalef32_pk_f32_fp4 v[10:11], v183, 1.0 op_sel:[1,0,0]
	v_cvt_scalef32_pk_f32_fp4 v[12:13], v183, 1.0 op_sel:[0,1,0]
	v_cvt_scalef32_pk_f32_fp4 v[14:15], v183, 1.0 op_sel:[1,1,0]
	v_readlane_b32 s54, v92, 61
	s_lshl_b32 s56, s54, 9
	s_add_u32 s56, s64, s56
	s_addc_u32 s57, s65, 0
	global_load_dwordx2 v[182:183], v227, s[56:57]
	v_pk_fma_f32 v[130:131], v[0:1], s[0:1], v[130:131] op_sel_hi:[1,0,1]
	v_pk_fma_f32 v[138:139], v[2:3], s[0:1], v[138:139] op_sel_hi:[1,0,1]
	v_pk_fma_f32 v[140:141], v[4:5], s[0:1], v[140:141] op_sel_hi:[1,0,1]
	v_pk_fma_f32 v[142:143], v[6:7], s[0:1], v[142:143] op_sel_hi:[1,0,1]
	v_pk_fma_f32 v[128:129], v[8:9], s[0:1], v[128:129] op_sel_hi:[1,0,1]
	v_pk_fma_f32 v[132:133], v[10:11], s[0:1], v[132:133] op_sel_hi:[1,0,1]
	v_pk_fma_f32 v[134:135], v[12:13], s[0:1], v[134:135] op_sel_hi:[1,0,1]
	v_pk_fma_f32 v[136:137], v[14:15], s[0:1], v[136:137] op_sel_hi:[1,0,1]
	v_readlane_b32 s0, v167, 46
	s_waitcnt vmcnt(15)
	v_cvt_scalef32_pk_f32_fp4 v[0:1], v184, 1.0
	v_cvt_scalef32_pk_f32_fp4 v[2:3], v184, 1.0 op_sel:[1,0,0]
	v_cvt_scalef32_pk_f32_fp4 v[4:5], v184, 1.0 op_sel:[0,1,0]
	v_cvt_scalef32_pk_f32_fp4 v[6:7], v184, 1.0 op_sel:[1,1,0]
	v_cvt_scalef32_pk_f32_fp4 v[8:9], v185, 1.0
	v_cvt_scalef32_pk_f32_fp4 v[10:11], v185, 1.0 op_sel:[1,0,0]
	v_cvt_scalef32_pk_f32_fp4 v[12:13], v185, 1.0 op_sel:[0,1,0]
	v_cvt_scalef32_pk_f32_fp4 v[14:15], v185, 1.0 op_sel:[1,1,0]
	v_readlane_b32 s54, v92, 62
	s_lshl_b32 s56, s54, 9
	s_add_u32 s56, s64, s56
	s_addc_u32 s57, s65, 0
	global_load_dwordx2 v[184:185], v227, s[56:57]
	v_pk_fma_f32 v[130:131], v[0:1], s[0:1], v[130:131] op_sel_hi:[1,0,1]
	v_pk_fma_f32 v[138:139], v[2:3], s[0:1], v[138:139] op_sel_hi:[1,0,1]
	v_pk_fma_f32 v[140:141], v[4:5], s[0:1], v[140:141] op_sel_hi:[1,0,1]
	v_pk_fma_f32 v[142:143], v[6:7], s[0:1], v[142:143] op_sel_hi:[1,0,1]
	v_pk_fma_f32 v[128:129], v[8:9], s[0:1], v[128:129] op_sel_hi:[1,0,1]
	v_pk_fma_f32 v[132:133], v[10:11], s[0:1], v[132:133] op_sel_hi:[1,0,1]
	v_pk_fma_f32 v[134:135], v[12:13], s[0:1], v[134:135] op_sel_hi:[1,0,1]
	v_pk_fma_f32 v[136:137], v[14:15], s[0:1], v[136:137] op_sel_hi:[1,0,1]
	v_readlane_b32 s0, v167, 47
	s_waitcnt vmcnt(15)
	v_cvt_scalef32_pk_f32_fp4 v[0:1], v186, 1.0
	v_cvt_scalef32_pk_f32_fp4 v[2:3], v186, 1.0 op_sel:[1,0,0]
	v_cvt_scalef32_pk_f32_fp4 v[4:5], v186, 1.0 op_sel:[0,1,0]
	v_cvt_scalef32_pk_f32_fp4 v[6:7], v186, 1.0 op_sel:[1,1,0]
	v_cvt_scalef32_pk_f32_fp4 v[8:9], v187, 1.0
	v_cvt_scalef32_pk_f32_fp4 v[10:11], v187, 1.0 op_sel:[1,0,0]
	v_cvt_scalef32_pk_f32_fp4 v[12:13], v187, 1.0 op_sel:[0,1,0]
	v_cvt_scalef32_pk_f32_fp4 v[14:15], v187, 1.0 op_sel:[1,1,0]
	v_readlane_b32 s54, v92, 63
	s_lshl_b32 s56, s54, 9
	s_add_u32 s56, s64, s56
	s_addc_u32 s57, s65, 0
	global_load_dwordx2 v[186:187], v227, s[56:57]
	v_pk_fma_f32 v[130:131], v[0:1], s[0:1], v[130:131] op_sel_hi:[1,0,1]
	v_pk_fma_f32 v[138:139], v[2:3], s[0:1], v[138:139] op_sel_hi:[1,0,1]
	v_pk_fma_f32 v[140:141], v[4:5], s[0:1], v[140:141] op_sel_hi:[1,0,1]
	v_pk_fma_f32 v[142:143], v[6:7], s[0:1], v[142:143] op_sel_hi:[1,0,1]
	v_pk_fma_f32 v[128:129], v[8:9], s[0:1], v[128:129] op_sel_hi:[1,0,1]
	v_pk_fma_f32 v[132:133], v[10:11], s[0:1], v[132:133] op_sel_hi:[1,0,1]
	v_pk_fma_f32 v[134:135], v[12:13], s[0:1], v[134:135] op_sel_hi:[1,0,1]
	v_pk_fma_f32 v[136:137], v[14:15], s[0:1], v[136:137] op_sel_hi:[1,0,1]
	v_readlane_b32 s0, v167, 48
	s_waitcnt vmcnt(15)
	v_cvt_scalef32_pk_f32_fp4 v[0:1], v144, 1.0
	v_cvt_scalef32_pk_f32_fp4 v[2:3], v144, 1.0 op_sel:[1,0,0]
	v_cvt_scalef32_pk_f32_fp4 v[4:5], v144, 1.0 op_sel:[0,1,0]
	v_cvt_scalef32_pk_f32_fp4 v[6:7], v144, 1.0 op_sel:[1,1,0]
	v_cvt_scalef32_pk_f32_fp4 v[8:9], v145, 1.0
	v_cvt_scalef32_pk_f32_fp4 v[10:11], v145, 1.0 op_sel:[1,0,0]
	v_cvt_scalef32_pk_f32_fp4 v[12:13], v145, 1.0 op_sel:[0,1,0]
	v_cvt_scalef32_pk_f32_fp4 v[14:15], v145, 1.0 op_sel:[1,1,0]
	v_readlane_b32 s54, v90, 0
	s_lshl_b32 s56, s54, 9
	s_add_u32 s56, s64, s56
	s_addc_u32 s57, s65, 0
	global_load_dwordx2 v[144:145], v227, s[56:57]
	v_pk_fma_f32 v[130:131], v[0:1], s[0:1], v[130:131] op_sel_hi:[1,0,1]
	v_pk_fma_f32 v[138:139], v[2:3], s[0:1], v[138:139] op_sel_hi:[1,0,1]
	v_pk_fma_f32 v[140:141], v[4:5], s[0:1], v[140:141] op_sel_hi:[1,0,1]
	v_pk_fma_f32 v[142:143], v[6:7], s[0:1], v[142:143] op_sel_hi:[1,0,1]
	v_pk_fma_f32 v[128:129], v[8:9], s[0:1], v[128:129] op_sel_hi:[1,0,1]
	v_pk_fma_f32 v[132:133], v[10:11], s[0:1], v[132:133] op_sel_hi:[1,0,1]
	v_pk_fma_f32 v[134:135], v[12:13], s[0:1], v[134:135] op_sel_hi:[1,0,1]
	v_pk_fma_f32 v[136:137], v[14:15], s[0:1], v[136:137] op_sel_hi:[1,0,1]
	v_readlane_b32 s0, v167, 49
	s_waitcnt vmcnt(15)
	v_cvt_scalef32_pk_f32_fp4 v[0:1], v146, 1.0
	v_cvt_scalef32_pk_f32_fp4 v[2:3], v146, 1.0 op_sel:[1,0,0]
	v_cvt_scalef32_pk_f32_fp4 v[4:5], v146, 1.0 op_sel:[0,1,0]
	v_cvt_scalef32_pk_f32_fp4 v[6:7], v146, 1.0 op_sel:[1,1,0]
	v_cvt_scalef32_pk_f32_fp4 v[8:9], v147, 1.0
	v_cvt_scalef32_pk_f32_fp4 v[10:11], v147, 1.0 op_sel:[1,0,0]
	v_cvt_scalef32_pk_f32_fp4 v[12:13], v147, 1.0 op_sel:[0,1,0]
	v_cvt_scalef32_pk_f32_fp4 v[14:15], v147, 1.0 op_sel:[1,1,0]
	v_readlane_b32 s54, v90, 1
	s_lshl_b32 s56, s54, 9
	s_add_u32 s56, s64, s56
	s_addc_u32 s57, s65, 0
	global_load_dwordx2 v[146:147], v227, s[56:57]
	v_pk_fma_f32 v[130:131], v[0:1], s[0:1], v[130:131] op_sel_hi:[1,0,1]
	v_pk_fma_f32 v[138:139], v[2:3], s[0:1], v[138:139] op_sel_hi:[1,0,1]
	v_pk_fma_f32 v[140:141], v[4:5], s[0:1], v[140:141] op_sel_hi:[1,0,1]
	v_pk_fma_f32 v[142:143], v[6:7], s[0:1], v[142:143] op_sel_hi:[1,0,1]
	v_pk_fma_f32 v[128:129], v[8:9], s[0:1], v[128:129] op_sel_hi:[1,0,1]
	v_pk_fma_f32 v[132:133], v[10:11], s[0:1], v[132:133] op_sel_hi:[1,0,1]
	v_pk_fma_f32 v[134:135], v[12:13], s[0:1], v[134:135] op_sel_hi:[1,0,1]
	v_pk_fma_f32 v[136:137], v[14:15], s[0:1], v[136:137] op_sel_hi:[1,0,1]
	v_readlane_b32 s0, v167, 50
	s_waitcnt vmcnt(15)
; __device__ void peer_gather_phase(const Params& P, int l, bool do_store) {
;     ...
;         const uint2* up = (const uint2*)(U + (size_t)(uphi ? eb : ea) * 768);
;         u6[3 * pr] = up[0]; u6[3 * pr + 1] = up[1]; u6[3 * pr + 2] = up[2];
;         v8[2 * pr] = *(const uint2*)(V + (size_t)ea * 512);
;         v8[2 * pr + 1] = *(const uint2*)(V + (size_t)eb * 512);
;     ...
; #pragma unroll
;       for (int j = 0; j < 8; ++j) {
;         const float a = __builtin_bit_cast(float, __builtin_amdgcn_readlane(__builtin_bit_cast(int, avec), kb + j));
;         const f32x2 aa = f32x2{a, a};
;         y[0] += aa * __builtin_amdgcn_cvt_scalef32_pk_f32_fp4(v8[j].x, 1.0f, 0); y[1] += aa * __builtin_amdgcn_cvt_scalef32_pk_f32_fp4(v8[j].x, 1.0f, 1);
;         y[2] += aa * __builtin_amdgcn_cvt_scalef32_pk_f32_fp4(v8[j].x, 1.0f, 2); y[3] += aa * __builtin_amdgcn_cvt_scalef32_pk_f32_fp4(v8[j].x, 1.0f, 3);
;         y[4] += aa * __builtin_amdgcn_cvt_scalef32_pk_f32_fp4(v8[j].y, 1.0f, 0); y[5] += aa * __builtin_amdgcn_cvt_scalef32_pk_f32_fp4(v8[j].y, 1.0f, 1);
;         y[6] += aa * __builtin_amdgcn_cvt_scalef32_pk_f32_fp4(v8[j].y, 1.0f, 2); y[7] += aa * __builtin_amdgcn_cvt_scalef32_pk_f32_fp4(v8[j].y, 1.0f, 3);
;       }
	v_cvt_scalef32_pk_f32_fp4 v[0:1], v148, 1.0
	v_cvt_scalef32_pk_f32_fp4 v[2:3], v148, 1.0 op_sel:[1,0,0]
	v_cvt_scalef32_pk_f32_fp4 v[4:5], v148, 1.0 op_sel:[0,1,0]
	v_cvt_scalef32_pk_f32_fp4 v[6:7], v148, 1.0 op_sel:[1,1,0]
	v_cvt_scalef32_pk_f32_fp4 v[8:9], v149, 1.0
	v_cvt_scalef32_pk_f32_fp4 v[10:11], v149, 1.0 op_sel:[1,0,0]
	v_cvt_scalef32_pk_f32_fp4 v[12:13], v149, 1.0 op_sel:[0,1,0]
	v_cvt_scalef32_pk_f32_fp4 v[14:15], v149, 1.0 op_sel:[1,1,0]
	v_readlane_b32 s54, v90, 2
	s_lshl_b32 s56, s54, 9
	s_add_u32 s56, s64, s56
	s_addc_u32 s57, s65, 0
	global_load_dwordx2 v[148:149], v227, s[56:57]
	v_pk_fma_f32 v[130:131], v[0:1], s[0:1], v[130:131] op_sel_hi:[1,0,1]
	v_pk_fma_f32 v[138:139], v[2:3], s[0:1], v[138:139] op_sel_hi:[1,0,1]
	v_pk_fma_f32 v[140:141], v[4:5], s[0:1], v[140:141] op_sel_hi:[1,0,1]
	v_pk_fma_f32 v[142:143], v[6:7], s[0:1], v[142:143] op_sel_hi:[1,0,1]
	v_pk_fma_f32 v[128:129], v[8:9], s[0:1], v[128:129] op_sel_hi:[1,0,1]
	v_pk_fma_f32 v[132:133], v[10:11], s[0:1], v[132:133] op_sel_hi:[1,0,1]
	v_pk_fma_f32 v[134:135], v[12:13], s[0:1], v[134:135] op_sel_hi:[1,0,1]
	v_pk_fma_f32 v[136:137], v[14:15], s[0:1], v[136:137] op_sel_hi:[1,0,1]
	v_readlane_b32 s0, v167, 51
	s_waitcnt vmcnt(15)
	v_cvt_scalef32_pk_f32_fp4 v[0:1], v150, 1.0
	v_cvt_scalef32_pk_f32_fp4 v[2:3], v150, 1.0 op_sel:[1,0,0]
	v_cvt_scalef32_pk_f32_fp4 v[4:5], v150, 1.0 op_sel:[0,1,0]
	v_cvt_scalef32_pk_f32_fp4 v[6:7], v150, 1.0 op_sel:[1,1,0]
	v_cvt_scalef32_pk_f32_fp4 v[8:9], v151, 1.0
	v_cvt_scalef32_pk_f32_fp4 v[10:11], v151, 1.0 op_sel:[1,0,0]
	v_cvt_scalef32_pk_f32_fp4 v[12:13], v151, 1.0 op_sel:[0,1,0]
	v_cvt_scalef32_pk_f32_fp4 v[14:15], v151, 1.0 op_sel:[1,1,0]
	v_readlane_b32 s54, v90, 3
	s_lshl_b32 s56, s54, 9
	s_add_u32 s56, s64, s56
	s_addc_u32 s57, s65, 0
	global_load_dwordx2 v[150:151], v227, s[56:57]
	v_pk_fma_f32 v[130:131], v[0:1], s[0:1], v[130:131] op_sel_hi:[1,0,1]
	v_pk_fma_f32 v[138:139], v[2:3], s[0:1], v[138:139] op_sel_hi:[1,0,1]
	v_pk_fma_f32 v[140:141], v[4:5], s[0:1], v[140:141] op_sel_hi:[1,0,1]
	v_pk_fma_f32 v[142:143], v[6:7], s[0:1], v[142:143] op_sel_hi:[1,0,1]
	v_pk_fma_f32 v[128:129], v[8:9], s[0:1], v[128:129] op_sel_hi:[1,0,1]
	v_pk_fma_f32 v[132:133], v[10:11], s[0:1], v[132:133] op_sel_hi:[1,0,1]
	v_pk_fma_f32 v[134:135], v[12:13], s[0:1], v[134:135] op_sel_hi:[1,0,1]
	v_pk_fma_f32 v[136:137], v[14:15], s[0:1], v[136:137] op_sel_hi:[1,0,1]
	v_readlane_b32 s0, v167, 52
	s_waitcnt vmcnt(15)
	v_cvt_scalef32_pk_f32_fp4 v[0:1], v152, 1.0
	v_cvt_scalef32_pk_f32_fp4 v[2:3], v152, 1.0 op_sel:[1,0,0]
	v_cvt_scalef32_pk_f32_fp4 v[4:5], v152, 1.0 op_sel:[0,1,0]
	v_cvt_scalef32_pk_f32_fp4 v[6:7], v152, 1.0 op_sel:[1,1,0]
	v_cvt_scalef32_pk_f32_fp4 v[8:9], v153, 1.0
	v_cvt_scalef32_pk_f32_fp4 v[10:11], v153, 1.0 op_sel:[1,0,0]
	v_cvt_scalef32_pk_f32_fp4 v[12:13], v153, 1.0 op_sel:[0,1,0]
	v_cvt_scalef32_pk_f32_fp4 v[14:15], v153, 1.0 op_sel:[1,1,0]
	v_readlane_b32 s54, v90, 4
	s_lshl_b32 s56, s54, 9
	s_add_u32 s56, s64, s56
	s_addc_u32 s57, s65, 0
	global_load_dwordx2 v[152:153], v227, s[56:57]
	v_pk_fma_f32 v[130:131], v[0:1], s[0:1], v[130:131] op_sel_hi:[1,0,1]
	v_pk_fma_f32 v[138:139], v[2:3], s[0:1], v[138:139] op_sel_hi:[1,0,1]
	v_pk_fma_f32 v[140:141], v[4:5], s[0:1], v[140:141] op_sel_hi:[1,0,1]
	v_pk_fma_f32 v[142:143], v[6:7], s[0:1], v[142:143] op_sel_hi:[1,0,1]
	v_pk_fma_f32 v[128:129], v[8:9], s[0:1], v[128:129] op_sel_hi:[1,0,1]
	v_pk_fma_f32 v[132:133], v[10:11], s[0:1], v[132:133] op_sel_hi:[1,0,1]
	v_pk_fma_f32 v[134:135], v[12:13], s[0:1], v[134:135] op_sel_hi:[1,0,1]
	v_pk_fma_f32 v[136:137], v[14:15], s[0:1], v[136:137] op_sel_hi:[1,0,1]
	v_readlane_b32 s0, v167, 53
	s_waitcnt vmcnt(15)
	v_cvt_scalef32_pk_f32_fp4 v[0:1], v154, 1.0
	v_cvt_scalef32_pk_f32_fp4 v[2:3], v154, 1.0 op_sel:[1,0,0]
	v_cvt_scalef32_pk_f32_fp4 v[4:5], v154, 1.0 op_sel:[0,1,0]
	v_cvt_scalef32_pk_f32_fp4 v[6:7], v154, 1.0 op_sel:[1,1,0]
	v_cvt_scalef32_pk_f32_fp4 v[8:9], v155, 1.0
	v_cvt_scalef32_pk_f32_fp4 v[10:11], v155, 1.0 op_sel:[1,0,0]
	v_cvt_scalef32_pk_f32_fp4 v[12:13], v155, 1.0 op_sel:[0,1,0]
	v_cvt_scalef32_pk_f32_fp4 v[14:15], v155, 1.0 op_sel:[1,1,0]
	v_readlane_b32 s54, v90, 5
	s_lshl_b32 s56, s54, 9
	s_add_u32 s56, s64, s56
	s_addc_u32 s57, s65, 0
	global_load_dwordx2 v[154:155], v227, s[56:57]
	v_pk_fma_f32 v[130:131], v[0:1], s[0:1], v[130:131] op_sel_hi:[1,0,1]
	v_pk_fma_f32 v[138:139], v[2:3], s[0:1], v[138:139] op_sel_hi:[1,0,1]
	v_pk_fma_f32 v[140:141], v[4:5], s[0:1], v[140:141] op_sel_hi:[1,0,1]
	v_pk_fma_f32 v[142:143], v[6:7], s[0:1], v[142:143] op_sel_hi:[1,0,1]
	v_pk_fma_f32 v[128:129], v[8:9], s[0:1], v[128:129] op_sel_hi:[1,0,1]
	v_pk_fma_f32 v[132:133], v[10:11], s[0:1], v[132:133] op_sel_hi:[1,0,1]
	v_pk_fma_f32 v[134:135], v[12:13], s[0:1], v[134:135] op_sel_hi:[1,0,1]
	v_pk_fma_f32 v[136:137], v[14:15], s[0:1], v[136:137] op_sel_hi:[1,0,1]
	v_readlane_b32 s0, v167, 54
	s_waitcnt vmcnt(15)
	v_cvt_scalef32_pk_f32_fp4 v[0:1], v156, 1.0
	v_cvt_scalef32_pk_f32_fp4 v[2:3], v156, 1.0 op_sel:[1,0,0]
	v_cvt_scalef32_pk_f32_fp4 v[4:5], v156, 1.0 op_sel:[0,1,0]
	v_cvt_scalef32_pk_f32_fp4 v[6:7], v156, 1.0 op_sel:[1,1,0]
	v_cvt_scalef32_pk_f32_fp4 v[8:9], v157, 1.0
	v_cvt_scalef32_pk_f32_fp4 v[10:11], v157, 1.0 op_sel:[1,0,0]
	v_cvt_scalef32_pk_f32_fp4 v[12:13], v157, 1.0 op_sel:[0,1,0]
	v_cvt_scalef32_pk_f32_fp4 v[14:15], v157, 1.0 op_sel:[1,1,0]
	v_readlane_b32 s54, v90, 6
	s_lshl_b32 s56, s54, 9
	s_add_u32 s56, s64, s56
	s_addc_u32 s57, s65, 0
	global_load_dwordx2 v[156:157], v227, s[56:57]
	v_pk_fma_f32 v[130:131], v[0:1], s[0:1], v[130:131] op_sel_hi:[1,0,1]
	v_pk_fma_f32 v[138:139], v[2:3], s[0:1], v[138:139] op_sel_hi:[1,0,1]
	v_pk_fma_f32 v[140:141], v[4:5], s[0:1], v[140:141] op_sel_hi:[1,0,1]
	v_pk_fma_f32 v[142:143], v[6:7], s[0:1], v[142:143] op_sel_hi:[1,0,1]
	v_pk_fma_f32 v[128:129], v[8:9], s[0:1], v[128:129] op_sel_hi:[1,0,1]
	v_pk_fma_f32 v[132:133], v[10:11], s[0:1], v[132:133] op_sel_hi:[1,0,1]
	v_pk_fma_f32 v[134:135], v[12:13], s[0:1], v[134:135] op_sel_hi:[1,0,1]
	v_pk_fma_f32 v[136:137], v[14:15], s[0:1], v[136:137] op_sel_hi:[1,0,1]
	v_readlane_b32 s0, v167, 55
	s_waitcnt vmcnt(15)
; __device__ void peer_gather_phase(const Params& P, int l, bool do_store) {
;     ...
;         const uint2* up = (const uint2*)(U + (size_t)(uphi ? eb : ea) * 768);
;         u6[3 * pr] = up[0]; u6[3 * pr + 1] = up[1]; u6[3 * pr + 2] = up[2];
;         v8[2 * pr] = *(const uint2*)(V + (size_t)ea * 512);
;         v8[2 * pr + 1] = *(const uint2*)(V + (size_t)eb * 512);
;     ...
; #pragma unroll
;       for (int j = 0; j < 8; ++j) {
;         const float a = __builtin_bit_cast(float, __builtin_amdgcn_readlane(__builtin_bit_cast(int, avec), kb + j));
;         const f32x2 aa = f32x2{a, a};
;         y[0] += aa * __builtin_amdgcn_cvt_scalef32_pk_f32_fp4(v8[j].x, 1.0f, 0); y[1] += aa * __builtin_amdgcn_cvt_scalef32_pk_f32_fp4(v8[j].x, 1.0f, 1);
;         y[2] += aa * __builtin_amdgcn_cvt_scalef32_pk_f32_fp4(v8[j].x, 1.0f, 2); y[3] += aa * __builtin_amdgcn_cvt_scalef32_pk_f32_fp4(v8[j].x, 1.0f, 3);
;         y[4] += aa * __builtin_amdgcn_cvt_scalef32_pk_f32_fp4(v8[j].y, 1.0f, 0); y[5] += aa * __builtin_amdgcn_cvt_scalef32_pk_f32_fp4(v8[j].y, 1.0f, 1);
;         y[6] += aa * __builtin_amdgcn_cvt_scalef32_pk_f32_fp4(v8[j].y, 1.0f, 2); y[7] += aa * __builtin_amdgcn_cvt_scalef32_pk_f32_fp4(v8[j].y, 1.0f, 3);
;       }
	v_cvt_scalef32_pk_f32_fp4 v[0:1], v158, 1.0
	v_cvt_scalef32_pk_f32_fp4 v[2:3], v158, 1.0 op_sel:[1,0,0]
	v_cvt_scalef32_pk_f32_fp4 v[4:5], v158, 1.0 op_sel:[0,1,0]
	v_cvt_scalef32_pk_f32_fp4 v[6:7], v158, 1.0 op_sel:[1,1,0]
	v_cvt_scalef32_pk_f32_fp4 v[8:9], v159, 1.0
	v_cvt_scalef32_pk_f32_fp4 v[10:11], v159, 1.0 op_sel:[1,0,0]
	v_cvt_scalef32_pk_f32_fp4 v[12:13], v159, 1.0 op_sel:[0,1,0]
	v_cvt_scalef32_pk_f32_fp4 v[14:15], v159, 1.0 op_sel:[1,1,0]
	v_readlane_b32 s54, v90, 7
	s_lshl_b32 s56, s54, 9
	s_add_u32 s56, s64, s56
	s_addc_u32 s57, s65, 0
	global_load_dwordx2 v[158:159], v227, s[56:57]
	v_pk_fma_f32 v[130:131], v[0:1], s[0:1], v[130:131] op_sel_hi:[1,0,1]
	v_pk_fma_f32 v[138:139], v[2:3], s[0:1], v[138:139] op_sel_hi:[1,0,1]
	v_pk_fma_f32 v[140:141], v[4:5], s[0:1], v[140:141] op_sel_hi:[1,0,1]
	v_pk_fma_f32 v[142:143], v[6:7], s[0:1], v[142:143] op_sel_hi:[1,0,1]
	v_pk_fma_f32 v[128:129], v[8:9], s[0:1], v[128:129] op_sel_hi:[1,0,1]
	v_pk_fma_f32 v[132:133], v[10:11], s[0:1], v[132:133] op_sel_hi:[1,0,1]
	v_pk_fma_f32 v[134:135], v[12:13], s[0:1], v[134:135] op_sel_hi:[1,0,1]
	v_pk_fma_f32 v[136:137], v[14:15], s[0:1], v[136:137] op_sel_hi:[1,0,1]
	v_readlane_b32 s0, v167, 56
	s_waitcnt vmcnt(15)
	v_cvt_scalef32_pk_f32_fp4 v[0:1], v168, 1.0
	v_cvt_scalef32_pk_f32_fp4 v[2:3], v168, 1.0 op_sel:[1,0,0]
	v_cvt_scalef32_pk_f32_fp4 v[4:5], v168, 1.0 op_sel:[0,1,0]
	v_cvt_scalef32_pk_f32_fp4 v[6:7], v168, 1.0 op_sel:[1,1,0]
	v_cvt_scalef32_pk_f32_fp4 v[8:9], v169, 1.0
	v_cvt_scalef32_pk_f32_fp4 v[10:11], v169, 1.0 op_sel:[1,0,0]
	v_cvt_scalef32_pk_f32_fp4 v[12:13], v169, 1.0 op_sel:[0,1,0]
	v_cvt_scalef32_pk_f32_fp4 v[14:15], v169, 1.0 op_sel:[1,1,0]
	v_readlane_b32 s54, v90, 8
	s_lshl_b32 s56, s54, 9
	s_add_u32 s56, s64, s56
	s_addc_u32 s57, s65, 0
	global_load_dwordx2 v[168:169], v227, s[56:57]
	v_pk_fma_f32 v[130:131], v[0:1], s[0:1], v[130:131] op_sel_hi:[1,0,1]
	v_pk_fma_f32 v[138:139], v[2:3], s[0:1], v[138:139] op_sel_hi:[1,0,1]
	v_pk_fma_f32 v[140:141], v[4:5], s[0:1], v[140:141] op_sel_hi:[1,0,1]
	v_pk_fma_f32 v[142:143], v[6:7], s[0:1], v[142:143] op_sel_hi:[1,0,1]
	v_pk_fma_f32 v[128:129], v[8:9], s[0:1], v[128:129] op_sel_hi:[1,0,1]
	v_pk_fma_f32 v[132:133], v[10:11], s[0:1], v[132:133] op_sel_hi:[1,0,1]
	v_pk_fma_f32 v[134:135], v[12:13], s[0:1], v[134:135] op_sel_hi:[1,0,1]
	v_pk_fma_f32 v[136:137], v[14:15], s[0:1], v[136:137] op_sel_hi:[1,0,1]
	v_readlane_b32 s0, v167, 57
	s_waitcnt vmcnt(15)
	v_cvt_scalef32_pk_f32_fp4 v[0:1], v170, 1.0
	v_cvt_scalef32_pk_f32_fp4 v[2:3], v170, 1.0 op_sel:[1,0,0]
	v_cvt_scalef32_pk_f32_fp4 v[4:5], v170, 1.0 op_sel:[0,1,0]
	v_cvt_scalef32_pk_f32_fp4 v[6:7], v170, 1.0 op_sel:[1,1,0]
	v_cvt_scalef32_pk_f32_fp4 v[8:9], v171, 1.0
	v_cvt_scalef32_pk_f32_fp4 v[10:11], v171, 1.0 op_sel:[1,0,0]
	v_cvt_scalef32_pk_f32_fp4 v[12:13], v171, 1.0 op_sel:[0,1,0]
	v_cvt_scalef32_pk_f32_fp4 v[14:15], v171, 1.0 op_sel:[1,1,0]
	v_readlane_b32 s54, v90, 9
	s_lshl_b32 s56, s54, 9
	s_add_u32 s56, s64, s56
	s_addc_u32 s57, s65, 0
	global_load_dwordx2 v[170:171], v227, s[56:57]
	v_pk_fma_f32 v[130:131], v[0:1], s[0:1], v[130:131] op_sel_hi:[1,0,1]
	v_pk_fma_f32 v[138:139], v[2:3], s[0:1], v[138:139] op_sel_hi:[1,0,1]
	v_pk_fma_f32 v[140:141], v[4:5], s[0:1], v[140:141] op_sel_hi:[1,0,1]
	v_pk_fma_f32 v[142:143], v[6:7], s[0:1], v[142:143] op_sel_hi:[1,0,1]
	v_pk_fma_f32 v[128:129], v[8:9], s[0:1], v[128:129] op_sel_hi:[1,0,1]
	v_pk_fma_f32 v[132:133], v[10:11], s[0:1], v[132:133] op_sel_hi:[1,0,1]
	v_pk_fma_f32 v[134:135], v[12:13], s[0:1], v[134:135] op_sel_hi:[1,0,1]
	v_pk_fma_f32 v[136:137], v[14:15], s[0:1], v[136:137] op_sel_hi:[1,0,1]
	v_readlane_b32 s0, v167, 58
	s_waitcnt vmcnt(15)
	v_cvt_scalef32_pk_f32_fp4 v[0:1], v172, 1.0
	v_cvt_scalef32_pk_f32_fp4 v[2:3], v172, 1.0 op_sel:[1,0,0]
	v_cvt_scalef32_pk_f32_fp4 v[4:5], v172, 1.0 op_sel:[0,1,0]
	v_cvt_scalef32_pk_f32_fp4 v[6:7], v172, 1.0 op_sel:[1,1,0]
	v_cvt_scalef32_pk_f32_fp4 v[8:9], v173, 1.0
	v_cvt_scalef32_pk_f32_fp4 v[10:11], v173, 1.0 op_sel:[1,0,0]
	v_cvt_scalef32_pk_f32_fp4 v[12:13], v173, 1.0 op_sel:[0,1,0]
	v_cvt_scalef32_pk_f32_fp4 v[14:15], v173, 1.0 op_sel:[1,1,0]
	v_readlane_b32 s54, v90, 10
	s_lshl_b32 s56, s54, 9
	s_add_u32 s56, s64, s56
	s_addc_u32 s57, s65, 0
	global_load_dwordx2 v[172:173], v227, s[56:57]
	v_pk_fma_f32 v[130:131], v[0:1], s[0:1], v[130:131] op_sel_hi:[1,0,1]
	v_pk_fma_f32 v[138:139], v[2:3], s[0:1], v[138:139] op_sel_hi:[1,0,1]
	v_pk_fma_f32 v[140:141], v[4:5], s[0:1], v[140:141] op_sel_hi:[1,0,1]
	v_pk_fma_f32 v[142:143], v[6:7], s[0:1], v[142:143] op_sel_hi:[1,0,1]
	v_pk_fma_f32 v[128:129], v[8:9], s[0:1], v[128:129] op_sel_hi:[1,0,1]
	v_pk_fma_f32 v[132:133], v[10:11], s[0:1], v[132:133] op_sel_hi:[1,0,1]
	v_pk_fma_f32 v[134:135], v[12:13], s[0:1], v[134:135] op_sel_hi:[1,0,1]
	v_pk_fma_f32 v[136:137], v[14:15], s[0:1], v[136:137] op_sel_hi:[1,0,1]
	v_readlane_b32 s0, v167, 59
	s_waitcnt vmcnt(15)
	v_cvt_scalef32_pk_f32_fp4 v[0:1], v174, 1.0
	v_cvt_scalef32_pk_f32_fp4 v[2:3], v174, 1.0 op_sel:[1,0,0]
	v_cvt_scalef32_pk_f32_fp4 v[4:5], v174, 1.0 op_sel:[0,1,0]
	v_cvt_scalef32_pk_f32_fp4 v[6:7], v174, 1.0 op_sel:[1,1,0]
	v_cvt_scalef32_pk_f32_fp4 v[8:9], v175, 1.0
	v_cvt_scalef32_pk_f32_fp4 v[10:11], v175, 1.0 op_sel:[1,0,0]
	v_cvt_scalef32_pk_f32_fp4 v[12:13], v175, 1.0 op_sel:[0,1,0]
	v_cvt_scalef32_pk_f32_fp4 v[14:15], v175, 1.0 op_sel:[1,1,0]
	v_readlane_b32 s54, v90, 11
	s_lshl_b32 s56, s54, 9
	s_add_u32 s56, s64, s56
	s_addc_u32 s57, s65, 0
	global_load_dwordx2 v[174:175], v227, s[56:57]
	v_pk_fma_f32 v[130:131], v[0:1], s[0:1], v[130:131] op_sel_hi:[1,0,1]
	v_pk_fma_f32 v[138:139], v[2:3], s[0:1], v[138:139] op_sel_hi:[1,0,1]
	v_pk_fma_f32 v[140:141], v[4:5], s[0:1], v[140:141] op_sel_hi:[1,0,1]
	v_pk_fma_f32 v[142:143], v[6:7], s[0:1], v[142:143] op_sel_hi:[1,0,1]
	v_pk_fma_f32 v[128:129], v[8:9], s[0:1], v[128:129] op_sel_hi:[1,0,1]
	v_pk_fma_f32 v[132:133], v[10:11], s[0:1], v[132:133] op_sel_hi:[1,0,1]
	v_pk_fma_f32 v[134:135], v[12:13], s[0:1], v[134:135] op_sel_hi:[1,0,1]
	v_pk_fma_f32 v[136:137], v[14:15], s[0:1], v[136:137] op_sel_hi:[1,0,1]
	v_readlane_b32 s0, v167, 60
	s_waitcnt vmcnt(15)
; __device__ void peer_gather_phase(const Params& P, int l, bool do_store) {
;     ...
;         const int ea = __builtin_amdgcn_readlane(evs, kb + 2 * pr), eb = __builtin_amdgcn_readlane(evs, kb + 2 * pr + 1);
;         const uint2* up = (const uint2*)(U + (size_t)(uphi ? eb : ea) * 768);
;         u6[3 * pr] = up[0]; u6[3 * pr + 1] = up[1]; u6[3 * pr + 2] = up[2];
;     ...
; #pragma unroll
;       for (int j = 0; j < 8; ++j) {
;         const float a = __builtin_bit_cast(float, __builtin_amdgcn_readlane(__builtin_bit_cast(int, avec), kb + j));
;         const f32x2 aa = f32x2{a, a};
;         y[0] += aa * __builtin_amdgcn_cvt_scalef32_pk_f32_fp4(v8[j].x, 1.0f, 0); y[1] += aa * __builtin_amdgcn_cvt_scalef32_pk_f32_fp4(v8[j].x, 1.0f, 1);
;         y[2] += aa * __builtin_amdgcn_cvt_scalef32_pk_f32_fp4(v8[j].x, 1.0f, 2); y[3] += aa * __builtin_amdgcn_cvt_scalef32_pk_f32_fp4(v8[j].x, 1.0f, 3);
;         y[4] += aa * __builtin_amdgcn_cvt_scalef32_pk_f32_fp4(v8[j].y, 1.0f, 0); y[5] += aa * __builtin_amdgcn_cvt_scalef32_pk_f32_fp4(v8[j].y, 1.0f, 1);
;         y[6] += aa * __builtin_amdgcn_cvt_scalef32_pk_f32_fp4(v8[j].y, 1.0f, 2); y[7] += aa * __builtin_amdgcn_cvt_scalef32_pk_f32_fp4(v8[j].y, 1.0f, 3);
;       }
	v_cvt_scalef32_pk_f32_fp4 v[0:1], v180, 1.0
	v_cvt_scalef32_pk_f32_fp4 v[2:3], v180, 1.0 op_sel:[1,0,0]
	v_cvt_scalef32_pk_f32_fp4 v[4:5], v180, 1.0 op_sel:[0,1,0]
	v_cvt_scalef32_pk_f32_fp4 v[6:7], v180, 1.0 op_sel:[1,1,0]
	v_cvt_scalef32_pk_f32_fp4 v[8:9], v181, 1.0
	v_cvt_scalef32_pk_f32_fp4 v[10:11], v181, 1.0 op_sel:[1,0,0]
	v_cvt_scalef32_pk_f32_fp4 v[12:13], v181, 1.0 op_sel:[0,1,0]
	v_cvt_scalef32_pk_f32_fp4 v[14:15], v181, 1.0 op_sel:[1,1,0]
	v_readlane_b32 s54, v90, 12
	s_lshl_b32 s56, s54, 9
	s_add_u32 s56, s64, s56
	s_addc_u32 s57, s65, 0
	global_load_dwordx2 v[180:181], v227, s[56:57]
	v_pk_fma_f32 v[130:131], v[0:1], s[0:1], v[130:131] op_sel_hi:[1,0,1]
	v_pk_fma_f32 v[138:139], v[2:3], s[0:1], v[138:139] op_sel_hi:[1,0,1]
	v_pk_fma_f32 v[140:141], v[4:5], s[0:1], v[140:141] op_sel_hi:[1,0,1]
	v_pk_fma_f32 v[142:143], v[6:7], s[0:1], v[142:143] op_sel_hi:[1,0,1]
	v_pk_fma_f32 v[128:129], v[8:9], s[0:1], v[128:129] op_sel_hi:[1,0,1]
	v_pk_fma_f32 v[132:133], v[10:11], s[0:1], v[132:133] op_sel_hi:[1,0,1]
	v_pk_fma_f32 v[134:135], v[12:13], s[0:1], v[134:135] op_sel_hi:[1,0,1]
	v_pk_fma_f32 v[136:137], v[14:15], s[0:1], v[136:137] op_sel_hi:[1,0,1]
	v_readlane_b32 s0, v167, 61
	s_waitcnt vmcnt(15)
	v_cvt_scalef32_pk_f32_fp4 v[0:1], v182, 1.0
	v_cvt_scalef32_pk_f32_fp4 v[2:3], v182, 1.0 op_sel:[1,0,0]
	v_cvt_scalef32_pk_f32_fp4 v[4:5], v182, 1.0 op_sel:[0,1,0]
	v_cvt_scalef32_pk_f32_fp4 v[6:7], v182, 1.0 op_sel:[1,1,0]
	v_cvt_scalef32_pk_f32_fp4 v[8:9], v183, 1.0
	v_cvt_scalef32_pk_f32_fp4 v[10:11], v183, 1.0 op_sel:[1,0,0]
	v_cvt_scalef32_pk_f32_fp4 v[12:13], v183, 1.0 op_sel:[0,1,0]
	v_cvt_scalef32_pk_f32_fp4 v[14:15], v183, 1.0 op_sel:[1,1,0]
	v_readlane_b32 s54, v90, 13
	s_lshl_b32 s56, s54, 9
	s_add_u32 s56, s64, s56
	s_addc_u32 s57, s65, 0
	global_load_dwordx2 v[182:183], v227, s[56:57]
	v_pk_fma_f32 v[130:131], v[0:1], s[0:1], v[130:131] op_sel_hi:[1,0,1]
	v_pk_fma_f32 v[138:139], v[2:3], s[0:1], v[138:139] op_sel_hi:[1,0,1]
	v_pk_fma_f32 v[140:141], v[4:5], s[0:1], v[140:141] op_sel_hi:[1,0,1]
	v_pk_fma_f32 v[142:143], v[6:7], s[0:1], v[142:143] op_sel_hi:[1,0,1]
	v_pk_fma_f32 v[128:129], v[8:9], s[0:1], v[128:129] op_sel_hi:[1,0,1]
	v_pk_fma_f32 v[132:133], v[10:11], s[0:1], v[132:133] op_sel_hi:[1,0,1]
	v_pk_fma_f32 v[134:135], v[12:13], s[0:1], v[134:135] op_sel_hi:[1,0,1]
	v_pk_fma_f32 v[136:137], v[14:15], s[0:1], v[136:137] op_sel_hi:[1,0,1]
	v_readlane_b32 s0, v167, 62
	s_waitcnt vmcnt(15)
	v_cvt_scalef32_pk_f32_fp4 v[0:1], v184, 1.0
	v_cvt_scalef32_pk_f32_fp4 v[2:3], v184, 1.0 op_sel:[1,0,0]
	v_cvt_scalef32_pk_f32_fp4 v[4:5], v184, 1.0 op_sel:[0,1,0]
	v_cvt_scalef32_pk_f32_fp4 v[6:7], v184, 1.0 op_sel:[1,1,0]
	v_cvt_scalef32_pk_f32_fp4 v[8:9], v185, 1.0
	v_cvt_scalef32_pk_f32_fp4 v[10:11], v185, 1.0 op_sel:[1,0,0]
	v_cvt_scalef32_pk_f32_fp4 v[12:13], v185, 1.0 op_sel:[0,1,0]
	v_cvt_scalef32_pk_f32_fp4 v[14:15], v185, 1.0 op_sel:[1,1,0]
	v_readlane_b32 s54, v90, 14
	s_lshl_b32 s56, s54, 9
	s_add_u32 s56, s64, s56
	s_addc_u32 s57, s65, 0
	global_load_dwordx2 v[184:185], v227, s[56:57]
	v_pk_fma_f32 v[130:131], v[0:1], s[0:1], v[130:131] op_sel_hi:[1,0,1]
	v_pk_fma_f32 v[138:139], v[2:3], s[0:1], v[138:139] op_sel_hi:[1,0,1]
	v_pk_fma_f32 v[140:141], v[4:5], s[0:1], v[140:141] op_sel_hi:[1,0,1]
	v_pk_fma_f32 v[142:143], v[6:7], s[0:1], v[142:143] op_sel_hi:[1,0,1]
	v_pk_fma_f32 v[128:129], v[8:9], s[0:1], v[128:129] op_sel_hi:[1,0,1]
	v_pk_fma_f32 v[132:133], v[10:11], s[0:1], v[132:133] op_sel_hi:[1,0,1]
	v_pk_fma_f32 v[134:135], v[12:13], s[0:1], v[134:135] op_sel_hi:[1,0,1]
	v_pk_fma_f32 v[136:137], v[14:15], s[0:1], v[136:137] op_sel_hi:[1,0,1]
	v_readlane_b32 s0, v167, 63
	s_waitcnt vmcnt(15)
	v_cvt_scalef32_pk_f32_fp4 v[0:1], v186, 1.0
	v_cvt_scalef32_pk_f32_fp4 v[2:3], v186, 1.0 op_sel:[1,0,0]
	v_cvt_scalef32_pk_f32_fp4 v[4:5], v186, 1.0 op_sel:[0,1,0]
	v_cvt_scalef32_pk_f32_fp4 v[6:7], v186, 1.0 op_sel:[1,1,0]
	v_cvt_scalef32_pk_f32_fp4 v[8:9], v187, 1.0
	v_cvt_scalef32_pk_f32_fp4 v[10:11], v187, 1.0 op_sel:[1,0,0]
	v_cvt_scalef32_pk_f32_fp4 v[12:13], v187, 1.0 op_sel:[0,1,0]
	v_cvt_scalef32_pk_f32_fp4 v[14:15], v187, 1.0 op_sel:[1,1,0]
	v_readlane_b32 s54, v90, 15
	s_lshl_b32 s56, s54, 9
	s_add_u32 s56, s64, s56
	s_addc_u32 s57, s65, 0
	global_load_dwordx2 v[186:187], v227, s[56:57]
	v_pk_fma_f32 v[130:131], v[0:1], s[0:1], v[130:131] op_sel_hi:[1,0,1]
	v_pk_fma_f32 v[138:139], v[2:3], s[0:1], v[138:139] op_sel_hi:[1,0,1]
	v_pk_fma_f32 v[140:141], v[4:5], s[0:1], v[140:141] op_sel_hi:[1,0,1]
	v_pk_fma_f32 v[142:143], v[6:7], s[0:1], v[142:143] op_sel_hi:[1,0,1]
	v_pk_fma_f32 v[128:129], v[8:9], s[0:1], v[128:129] op_sel_hi:[1,0,1]
	v_pk_fma_f32 v[132:133], v[10:11], s[0:1], v[132:133] op_sel_hi:[1,0,1]
	v_pk_fma_f32 v[134:135], v[12:13], s[0:1], v[134:135] op_sel_hi:[1,0,1]
	v_pk_fma_f32 v[136:137], v[14:15], s[0:1], v[136:137] op_sel_hi:[1,0,1]
	v_readlane_b32 s54, v90, 16
	v_readlane_b32 s55, v90, 17
	s_mul_i32 s0, s54, 0x300
	s_mul_i32 s1, s55, 0x300
	v_add_u32_e32 v167, s0, v195
	s_and_saveexec_b64 s[98:99], s[40:41]
	v_add_u32_e32 v167, s1, v195
	s_mov_b64 exec, s[98:99]
	s_waitcnt vmcnt(48)
; __device__ void peer_gather_phase(const Params& P, int l, bool do_store) {
;     ...
;         const int ea = __builtin_amdgcn_readlane(evs, kb + 2 * pr), eb = __builtin_amdgcn_readlane(evs, kb + 2 * pr + 1);
;         const uint2* up = (const uint2*)(U + (size_t)(uphi ? eb : ea) * 768);
;         u6[3 * pr] = up[0]; u6[3 * pr + 1] = up[1]; u6[3 * pr + 2] = up[2];
;     ...
;       for (int pr = 0; pr < 4; ++pr) {
;         v6u_t qv; qv[0] = u6[3 * pr].x; qv[1] = u6[3 * pr].y; qv[2] = u6[3 * pr + 1].x; qv[3] = u6[3 * pr + 1].y; qv[4] = u6[3 * pr + 2].x; qv[5] = u6[3 * pr + 2].y;
;         const v32f_t wv = __builtin_amdgcn_cvt_scalef32_pk32_f32_fp6(qv, 1.0f);
;         f32x2 a2 = f32x2{0.f, 0.f};
; #pragma unroll
;         for (int i = 0; i < 16; ++i) a2 += f32x2{wv[2 * i], wv[2 * i + 1]} * xu[i];
;         float hs = a2.x + a2.y;
	v_cvt_scalef32_pk32_f32_fp6 v[0:31], v[50:55], 1.0
	global_load_dwordx2 v[54:55], v167, s[62:63] offset:16
	global_load_dwordx4 v[50:53], v167, s[62:63]
	v_pk_mul_f32 v[246:247], v[0:1], v[96:97]
	v_pk_mul_f32 v[254:255], v[2:3], v[98:99]
	v_pk_mul_f32 v[160:161], v[4:5], v[100:101]
	v_pk_fma_f32 v[246:247], v[6:7], v[102:103], v[246:247]
	v_pk_fma_f32 v[254:255], v[8:9], v[104:105], v[254:255]
	v_pk_fma_f32 v[160:161], v[10:11], v[106:107], v[160:161]
	v_pk_fma_f32 v[246:247], v[12:13], v[108:109], v[246:247]
	v_pk_fma_f32 v[254:255], v[14:15], v[110:111], v[254:255]
	v_pk_fma_f32 v[160:161], v[16:17], v[112:113], v[160:161]
	v_pk_fma_f32 v[246:247], v[18:19], v[114:115], v[246:247]
	v_pk_fma_f32 v[254:255], v[20:21], v[116:117], v[254:255]
	v_pk_fma_f32 v[160:161], v[22:23], v[118:119], v[160:161]
	v_pk_fma_f32 v[246:247], v[24:25], v[120:121], v[246:247]
	v_pk_fma_f32 v[254:255], v[26:27], v[122:123], v[254:255]
	v_pk_fma_f32 v[160:161], v[28:29], v[124:125], v[160:161]
	v_pk_fma_f32 v[246:247], v[30:31], v[126:127], v[246:247]
	v_pk_add_f32 v[254:255], v[254:255], v[160:161]
	s_nop 0
	v_pk_add_f32 v[246:247], v[246:247], v[254:255]
	s_nop 0
	v_add_f32_e32 v162, v246, v247
	v_readlane_b32 s54, v90, 18
	v_readlane_b32 s55, v90, 19
	s_mul_i32 s0, s54, 0x300
	s_mul_i32 s1, s55, 0x300
	v_add_u32_e32 v167, s0, v195
	s_and_saveexec_b64 s[98:99], s[40:41]
	v_add_u32_e32 v167, s1, v195
	s_mov_b64 exec, s[98:99]
	s_waitcnt vmcnt(48)
	v_cvt_scalef32_pk32_f32_fp6 v[0:31], v[44:49], 1.0
	global_load_dwordx2 v[48:49], v167, s[62:63] offset:16
	global_load_dwordx4 v[44:47], v167, s[62:63]
	v_pk_mul_f32 v[246:247], v[0:1], v[96:97]
	v_pk_mul_f32 v[254:255], v[2:3], v[98:99]
	v_pk_mul_f32 v[160:161], v[4:5], v[100:101]
	v_pk_fma_f32 v[246:247], v[6:7], v[102:103], v[246:247]
	v_pk_fma_f32 v[254:255], v[8:9], v[104:105], v[254:255]
	v_pk_fma_f32 v[160:161], v[10:11], v[106:107], v[160:161]
	v_pk_fma_f32 v[246:247], v[12:13], v[108:109], v[246:247]
	v_pk_fma_f32 v[254:255], v[14:15], v[110:111], v[254:255]
	v_pk_fma_f32 v[160:161], v[16:17], v[112:113], v[160:161]
	v_pk_fma_f32 v[246:247], v[18:19], v[114:115], v[246:247]
	v_pk_fma_f32 v[254:255], v[20:21], v[116:117], v[254:255]
	v_pk_fma_f32 v[160:161], v[22:23], v[118:119], v[160:161]
	v_pk_fma_f32 v[246:247], v[24:25], v[120:121], v[246:247]
	v_pk_fma_f32 v[254:255], v[26:27], v[122:123], v[254:255]
	v_pk_fma_f32 v[160:161], v[28:29], v[124:125], v[160:161]
	v_pk_fma_f32 v[246:247], v[30:31], v[126:127], v[246:247]
	v_pk_add_f32 v[254:255], v[254:255], v[160:161]
	s_nop 0
	v_pk_add_f32 v[246:247], v[246:247], v[254:255]
	s_nop 0
	v_add_f32_e32 v163, v246, v247
	v_readlane_b32 s54, v90, 20
	v_readlane_b32 s55, v90, 21
	s_mul_i32 s0, s54, 0x300
	s_mul_i32 s1, s55, 0x300
	v_add_u32_e32 v167, s0, v195
	s_and_saveexec_b64 s[98:99], s[40:41]
	v_add_u32_e32 v167, s1, v195
	s_mov_b64 exec, s[98:99]
	s_waitcnt vmcnt(48)
	v_cvt_scalef32_pk32_f32_fp6 v[0:31], v[38:43], 1.0
	global_load_dwordx2 v[42:43], v167, s[62:63] offset:16
	global_load_dwordx4 v[38:41], v167, s[62:63]
	v_pk_mul_f32 v[246:247], v[0:1], v[96:97]
	v_pk_mul_f32 v[254:255], v[2:3], v[98:99]
	v_pk_mul_f32 v[160:161], v[4:5], v[100:101]
	v_pk_fma_f32 v[246:247], v[6:7], v[102:103], v[246:247]
	v_pk_fma_f32 v[254:255], v[8:9], v[104:105], v[254:255]
	v_pk_fma_f32 v[160:161], v[10:11], v[106:107], v[160:161]
	v_pk_fma_f32 v[246:247], v[12:13], v[108:109], v[246:247]
	v_pk_fma_f32 v[254:255], v[14:15], v[110:111], v[254:255]
	v_pk_fma_f32 v[160:161], v[16:17], v[112:113], v[160:161]
	v_pk_fma_f32 v[246:247], v[18:19], v[114:115], v[246:247]
	v_pk_fma_f32 v[254:255], v[20:21], v[116:117], v[254:255]
	v_pk_fma_f32 v[160:161], v[22:23], v[118:119], v[160:161]
	v_pk_fma_f32 v[246:247], v[24:25], v[120:121], v[246:247]
	v_pk_fma_f32 v[254:255], v[26:27], v[122:123], v[254:255]
	v_pk_fma_f32 v[160:161], v[28:29], v[124:125], v[160:161]
	v_pk_fma_f32 v[246:247], v[30:31], v[126:127], v[246:247]
	v_pk_add_f32 v[254:255], v[254:255], v[160:161]
	s_nop 0
	v_pk_add_f32 v[246:247], v[246:247], v[254:255]
	s_nop 0
	v_add_f32_e32 v164, v246, v247
	v_readlane_b32 s54, v90, 22
	v_readlane_b32 s55, v90, 23
	s_mul_i32 s0, s54, 0x300
	s_mul_i32 s1, s55, 0x300
	v_add_u32_e32 v167, s0, v195
	s_and_saveexec_b64 s[98:99], s[40:41]
	v_add_u32_e32 v167, s1, v195
	s_mov_b64 exec, s[98:99]
	s_waitcnt vmcnt(48)
; __device__ void peer_gather_phase(const Params& P, int l, bool do_store) {
;     ...
;       for (int pr = 0; pr < 4; ++pr) {
;         v6u_t qv; qv[0] = u6[3 * pr].x; qv[1] = u6[3 * pr].y; qv[2] = u6[3 * pr + 1].x; qv[3] = u6[3 * pr + 1].y; qv[4] = u6[3 * pr + 2].x; qv[5] = u6[3 * pr + 2].y;
;         const v32f_t wv = __builtin_amdgcn_cvt_scalef32_pk32_f32_fp6(qv, 1.0f);
;         f32x2 a2 = f32x2{0.f, 0.f};
; #pragma unroll
;         for (int i = 0; i < 16; ++i) a2 += f32x2{wv[2 * i], wv[2 * i + 1]} * xu[i];
;         float hs = a2.x + a2.y;
;         hs += dpp_row_shr(hs, 1); hs += dpp_row_shr(hs, 2); hs += dpp_row_shr(hs, 4); hs += dpp_row_shr(hs, 8);
;         hs += __builtin_bit_cast(float, __builtin_amdgcn_update_dpp(0, __builtin_bit_cast(int, hs), 0x142, 0xa, 0xf, false));
;         const float da = __builtin_bit_cast(float, __builtin_amdgcn_readlane(__builtin_bit_cast(int, hs), 31));
;         const float db = __builtin_bit_cast(float, __builtin_amdgcn_readlane(__builtin_bit_cast(int, hs), 63));
;         dvec = (lane == kb + 2 * pr) ? da : dvec;
;         dvec = (lane == kb + 2 * pr + 1) ? db : dvec;
;       }
	v_cvt_scalef32_pk32_f32_fp6 v[0:31], v[32:37], 1.0
	global_load_dwordx2 v[36:37], v167, s[62:63] offset:16
	global_load_dwordx4 v[32:35], v167, s[62:63]
	v_pk_mul_f32 v[246:247], v[0:1], v[96:97]
	v_pk_mul_f32 v[254:255], v[2:3], v[98:99]
	v_pk_mul_f32 v[160:161], v[4:5], v[100:101]
	v_pk_fma_f32 v[246:247], v[6:7], v[102:103], v[246:247]
	v_pk_fma_f32 v[254:255], v[8:9], v[104:105], v[254:255]
	v_pk_fma_f32 v[160:161], v[10:11], v[106:107], v[160:161]
	v_pk_fma_f32 v[246:247], v[12:13], v[108:109], v[246:247]
	v_pk_fma_f32 v[254:255], v[14:15], v[110:111], v[254:255]
	v_pk_fma_f32 v[160:161], v[16:17], v[112:113], v[160:161]
	v_pk_fma_f32 v[246:247], v[18:19], v[114:115], v[246:247]
	v_pk_fma_f32 v[254:255], v[20:21], v[116:117], v[254:255]
	v_pk_fma_f32 v[160:161], v[22:23], v[118:119], v[160:161]
	v_pk_fma_f32 v[246:247], v[24:25], v[120:121], v[246:247]
	v_pk_fma_f32 v[254:255], v[26:27], v[122:123], v[254:255]
	v_pk_fma_f32 v[160:161], v[28:29], v[124:125], v[160:161]
	v_pk_fma_f32 v[246:247], v[30:31], v[126:127], v[246:247]
	v_pk_add_f32 v[254:255], v[254:255], v[160:161]
	s_nop 0
	v_pk_add_f32 v[246:247], v[246:247], v[254:255]
	s_nop 0
	v_add_f32_e32 v165, v246, v247
	v_add_f32_dpp v162, v162, v162 row_shr:1 row_mask:0xf bank_mask:0xf bound_ctrl:1
	v_add_f32_dpp v163, v163, v163 row_shr:1 row_mask:0xf bank_mask:0xf bound_ctrl:1
	v_add_f32_dpp v164, v164, v164 row_shr:1 row_mask:0xf bank_mask:0xf bound_ctrl:1
	v_add_f32_dpp v165, v165, v165 row_shr:1 row_mask:0xf bank_mask:0xf bound_ctrl:1
	v_add_f32_dpp v162, v162, v162 row_shr:2 row_mask:0xf bank_mask:0xf bound_ctrl:1
	v_add_f32_dpp v163, v163, v163 row_shr:2 row_mask:0xf bank_mask:0xf bound_ctrl:1
	v_add_f32_dpp v164, v164, v164 row_shr:2 row_mask:0xf bank_mask:0xf bound_ctrl:1
	v_add_f32_dpp v165, v165, v165 row_shr:2 row_mask:0xf bank_mask:0xf bound_ctrl:1
	v_add_f32_dpp v162, v162, v162 row_shr:4 row_mask:0xf bank_mask:0xf bound_ctrl:1
	v_add_f32_dpp v163, v163, v163 row_shr:4 row_mask:0xf bank_mask:0xf bound_ctrl:1
	v_add_f32_dpp v164, v164, v164 row_shr:4 row_mask:0xf bank_mask:0xf bound_ctrl:1
	v_add_f32_dpp v165, v165, v165 row_shr:4 row_mask:0xf bank_mask:0xf bound_ctrl:1
	v_add_f32_dpp v162, v162, v162 row_shr:8 row_mask:0xf bank_mask:0xf bound_ctrl:1
	v_add_f32_dpp v163, v163, v163 row_shr:8 row_mask:0xf bank_mask:0xf bound_ctrl:1
	v_add_f32_dpp v164, v164, v164 row_shr:8 row_mask:0xf bank_mask:0xf bound_ctrl:1
	v_add_f32_dpp v165, v165, v165 row_shr:8 row_mask:0xf bank_mask:0xf bound_ctrl:1
	v_add_f32_dpp v162, v162, v162 row_bcast:15 row_mask:0xa bank_mask:0xf
	v_add_f32_dpp v163, v163, v163 row_bcast:15 row_mask:0xa bank_mask:0xf
	v_add_f32_dpp v164, v164, v164 row_bcast:15 row_mask:0xa bank_mask:0xf
	v_add_f32_dpp v165, v165, v165 row_bcast:15 row_mask:0xa bank_mask:0xf
	s_nop 1
	v_readlane_b32 s46, v162, 31
	v_readlane_b32 s47, v162, 63
	v_readlane_b32 s48, v163, 31
	v_readlane_b32 s49, v163, 63
	v_readlane_b32 s50, v164, 31
	v_readlane_b32 s51, v164, 63
	v_readlane_b32 s52, v165, 31
	v_readlane_b32 s53, v165, 63
	v_writelane_b32 v166, s46, 0
	s_nop 1
	v_writelane_b32 v166, s47, 1
	v_writelane_b32 v166, s48, 2
	v_writelane_b32 v166, s49, 3
	v_writelane_b32 v166, s50, 4
	v_writelane_b32 v166, s51, 5
	v_writelane_b32 v166, s52, 6
	v_writelane_b32 v166, s53, 7
	v_readlane_b32 s54, v90, 24
	v_readlane_b32 s55, v90, 25
	s_mul_i32 s0, s54, 0x300
	s_mul_i32 s1, s55, 0x300
	v_add_u32_e32 v167, s0, v195
	s_and_saveexec_b64 s[98:99], s[40:41]
	v_add_u32_e32 v167, s1, v195
	s_mov_b64 exec, s[98:99]
	s_waitcnt vmcnt(48)
	v_cvt_scalef32_pk32_f32_fp6 v[0:31], v[196:201], 1.0
	global_load_dwordx2 v[200:201], v167, s[62:63] offset:16
	global_load_dwordx4 v[196:199], v167, s[62:63]
	v_pk_mul_f32 v[246:247], v[0:1], v[96:97]
	v_pk_mul_f32 v[254:255], v[2:3], v[98:99]
	v_pk_mul_f32 v[160:161], v[4:5], v[100:101]
	v_pk_fma_f32 v[246:247], v[6:7], v[102:103], v[246:247]
	v_pk_fma_f32 v[254:255], v[8:9], v[104:105], v[254:255]
	v_pk_fma_f32 v[160:161], v[10:11], v[106:107], v[160:161]
	v_pk_fma_f32 v[246:247], v[12:13], v[108:109], v[246:247]
	v_pk_fma_f32 v[254:255], v[14:15], v[110:111], v[254:255]
	v_pk_fma_f32 v[160:161], v[16:17], v[112:113], v[160:161]
	v_pk_fma_f32 v[246:247], v[18:19], v[114:115], v[246:247]
	v_pk_fma_f32 v[254:255], v[20:21], v[116:117], v[254:255]
	v_pk_fma_f32 v[160:161], v[22:23], v[118:119], v[160:161]
	v_pk_fma_f32 v[246:247], v[24:25], v[120:121], v[246:247]
	v_pk_fma_f32 v[254:255], v[26:27], v[122:123], v[254:255]
	v_pk_fma_f32 v[160:161], v[28:29], v[124:125], v[160:161]
	v_pk_fma_f32 v[246:247], v[30:31], v[126:127], v[246:247]
	v_pk_add_f32 v[254:255], v[254:255], v[160:161]
	s_nop 0
	v_pk_add_f32 v[246:247], v[246:247], v[254:255]
	s_nop 0
	v_add_f32_e32 v162, v246, v247
	v_readlane_b32 s54, v90, 26
	v_readlane_b32 s55, v90, 27
	s_mul_i32 s0, s54, 0x300
	s_mul_i32 s1, s55, 0x300
	v_add_u32_e32 v167, s0, v195
	s_and_saveexec_b64 s[98:99], s[40:41]
	v_add_u32_e32 v167, s1, v195
	s_mov_b64 exec, s[98:99]
	s_waitcnt vmcnt(48)
; __device__ void peer_gather_phase(const Params& P, int l, bool do_store) {
;     ...
;         const int ea = __builtin_amdgcn_readlane(evs, kb + 2 * pr), eb = __builtin_amdgcn_readlane(evs, kb + 2 * pr + 1);
;         const uint2* up = (const uint2*)(U + (size_t)(uphi ? eb : ea) * 768);
;         u6[3 * pr] = up[0]; u6[3 * pr + 1] = up[1]; u6[3 * pr + 2] = up[2];
;     ...
;       for (int pr = 0; pr < 4; ++pr) {
;         v6u_t qv; qv[0] = u6[3 * pr].x; qv[1] = u6[3 * pr].y; qv[2] = u6[3 * pr + 1].x; qv[3] = u6[3 * pr + 1].y; qv[4] = u6[3 * pr + 2].x; qv[5] = u6[3 * pr + 2].y;
;         const v32f_t wv = __builtin_amdgcn_cvt_scalef32_pk32_f32_fp6(qv, 1.0f);
;         f32x2 a2 = f32x2{0.f, 0.f};
; #pragma unroll
;         for (int i = 0; i < 16; ++i) a2 += f32x2{wv[2 * i], wv[2 * i + 1]} * xu[i];
;         float hs = a2.x + a2.y;
;         hs += dpp_row_shr(hs, 1); hs += dpp_row_shr(hs, 2); hs += dpp_row_shr(hs, 4); hs += dpp_row_shr(hs, 8);
;         hs += __builtin_bit_cast(float, __builtin_amdgcn_update_dpp(0, __builtin_bit_cast(int, hs), 0x142, 0xa, 0xf, false));
;         const float da = __builtin_bit_cast(float, __builtin_amdgcn_readlane(__builtin_bit_cast(int, hs), 31));
;         const float db = __builtin_bit_cast(float, __builtin_amdgcn_readlane(__builtin_bit_cast(int, hs), 63));
;         dvec = (lane == kb + 2 * pr) ? da : dvec;
;         dvec = (lane == kb + 2 * pr + 1) ? db : dvec;
;       }
	v_cvt_scalef32_pk32_f32_fp6 v[0:31], v[228:233], 1.0
	global_load_dwordx2 v[232:233], v167, s[62:63] offset:16
	global_load_dwordx4 v[228:231], v167, s[62:63]
	v_pk_mul_f32 v[246:247], v[0:1], v[96:97]
	v_pk_mul_f32 v[254:255], v[2:3], v[98:99]
	v_pk_mul_f32 v[160:161], v[4:5], v[100:101]
	v_pk_fma_f32 v[246:247], v[6:7], v[102:103], v[246:247]
	v_pk_fma_f32 v[254:255], v[8:9], v[104:105], v[254:255]
	v_pk_fma_f32 v[160:161], v[10:11], v[106:107], v[160:161]
	v_pk_fma_f32 v[246:247], v[12:13], v[108:109], v[246:247]
	v_pk_fma_f32 v[254:255], v[14:15], v[110:111], v[254:255]
	v_pk_fma_f32 v[160:161], v[16:17], v[112:113], v[160:161]
	v_pk_fma_f32 v[246:247], v[18:19], v[114:115], v[246:247]
	v_pk_fma_f32 v[254:255], v[20:21], v[116:117], v[254:255]
	v_pk_fma_f32 v[160:161], v[22:23], v[118:119], v[160:161]
	v_pk_fma_f32 v[246:247], v[24:25], v[120:121], v[246:247]
	v_pk_fma_f32 v[254:255], v[26:27], v[122:123], v[254:255]
	v_pk_fma_f32 v[160:161], v[28:29], v[124:125], v[160:161]
	v_pk_fma_f32 v[246:247], v[30:31], v[126:127], v[246:247]
	v_pk_add_f32 v[254:255], v[254:255], v[160:161]
	s_nop 0
	v_pk_add_f32 v[246:247], v[246:247], v[254:255]
	s_nop 0
	v_add_f32_e32 v163, v246, v247
	v_readlane_b32 s54, v90, 28
	v_readlane_b32 s55, v90, 29
	s_mul_i32 s0, s54, 0x300
	s_mul_i32 s1, s55, 0x300
	v_add_u32_e32 v167, s0, v195
	s_and_saveexec_b64 s[98:99], s[40:41]
	v_add_u32_e32 v167, s1, v195
	s_mov_b64 exec, s[98:99]
	s_waitcnt vmcnt(48)
	v_cvt_scalef32_pk32_f32_fp6 v[0:31], v[234:239], 1.0
	global_load_dwordx2 v[238:239], v167, s[62:63] offset:16
	global_load_dwordx4 v[234:237], v167, s[62:63]
	v_pk_mul_f32 v[246:247], v[0:1], v[96:97]
	v_pk_mul_f32 v[254:255], v[2:3], v[98:99]
	v_pk_mul_f32 v[160:161], v[4:5], v[100:101]
	v_pk_fma_f32 v[246:247], v[6:7], v[102:103], v[246:247]
	v_pk_fma_f32 v[254:255], v[8:9], v[104:105], v[254:255]
	v_pk_fma_f32 v[160:161], v[10:11], v[106:107], v[160:161]
	v_pk_fma_f32 v[246:247], v[12:13], v[108:109], v[246:247]
	v_pk_fma_f32 v[254:255], v[14:15], v[110:111], v[254:255]
	v_pk_fma_f32 v[160:161], v[16:17], v[112:113], v[160:161]
	v_pk_fma_f32 v[246:247], v[18:19], v[114:115], v[246:247]
	v_pk_fma_f32 v[254:255], v[20:21], v[116:117], v[254:255]
	v_pk_fma_f32 v[160:161], v[22:23], v[118:119], v[160:161]
	v_pk_fma_f32 v[246:247], v[24:25], v[120:121], v[246:247]
	v_pk_fma_f32 v[254:255], v[26:27], v[122:123], v[254:255]
	v_pk_fma_f32 v[160:161], v[28:29], v[124:125], v[160:161]
	v_pk_fma_f32 v[246:247], v[30:31], v[126:127], v[246:247]
	v_pk_add_f32 v[254:255], v[254:255], v[160:161]
	s_nop 0
	v_pk_add_f32 v[246:247], v[246:247], v[254:255]
	s_nop 0
	v_add_f32_e32 v164, v246, v247
	v_readlane_b32 s54, v90, 30
	v_readlane_b32 s55, v90, 31
	s_mul_i32 s0, s54, 0x300
	s_mul_i32 s1, s55, 0x300
	v_add_u32_e32 v167, s0, v195
	s_and_saveexec_b64 s[98:99], s[40:41]
	v_add_u32_e32 v167, s1, v195
	s_mov_b64 exec, s[98:99]
	s_waitcnt vmcnt(48)
	v_cvt_scalef32_pk32_f32_fp6 v[0:31], v[240:245], 1.0
	global_load_dwordx2 v[244:245], v167, s[62:63] offset:16
	global_load_dwordx4 v[240:243], v167, s[62:63]
	v_pk_mul_f32 v[246:247], v[0:1], v[96:97]
	v_pk_mul_f32 v[254:255], v[2:3], v[98:99]
	v_pk_mul_f32 v[160:161], v[4:5], v[100:101]
	v_pk_fma_f32 v[246:247], v[6:7], v[102:103], v[246:247]
	v_pk_fma_f32 v[254:255], v[8:9], v[104:105], v[254:255]
	v_pk_fma_f32 v[160:161], v[10:11], v[106:107], v[160:161]
	v_pk_fma_f32 v[246:247], v[12:13], v[108:109], v[246:247]
	v_pk_fma_f32 v[254:255], v[14:15], v[110:111], v[254:255]
	v_pk_fma_f32 v[160:161], v[16:17], v[112:113], v[160:161]
	v_pk_fma_f32 v[246:247], v[18:19], v[114:115], v[246:247]
	v_pk_fma_f32 v[254:255], v[20:21], v[116:117], v[254:255]
	v_pk_fma_f32 v[160:161], v[22:23], v[118:119], v[160:161]
	v_pk_fma_f32 v[246:247], v[24:25], v[120:121], v[246:247]
	v_pk_fma_f32 v[254:255], v[26:27], v[122:123], v[254:255]
	v_pk_fma_f32 v[160:161], v[28:29], v[124:125], v[160:161]
	v_pk_fma_f32 v[246:247], v[30:31], v[126:127], v[246:247]
	v_pk_add_f32 v[254:255], v[254:255], v[160:161]
	s_nop 0
	v_pk_add_f32 v[246:247], v[246:247], v[254:255]
	s_nop 0
	v_add_f32_e32 v165, v246, v247
	v_add_f32_dpp v162, v162, v162 row_shr:1 row_mask:0xf bank_mask:0xf bound_ctrl:1
	v_add_f32_dpp v163, v163, v163 row_shr:1 row_mask:0xf bank_mask:0xf bound_ctrl:1
	v_add_f32_dpp v164, v164, v164 row_shr:1 row_mask:0xf bank_mask:0xf bound_ctrl:1
	v_add_f32_dpp v165, v165, v165 row_shr:1 row_mask:0xf bank_mask:0xf bound_ctrl:1
	v_add_f32_dpp v162, v162, v162 row_shr:2 row_mask:0xf bank_mask:0xf bound_ctrl:1
	v_add_f32_dpp v163, v163, v163 row_shr:2 row_mask:0xf bank_mask:0xf bound_ctrl:1
	v_add_f32_dpp v164, v164, v164 row_shr:2 row_mask:0xf bank_mask:0xf bound_ctrl:1
	v_add_f32_dpp v165, v165, v165 row_shr:2 row_mask:0xf bank_mask:0xf bound_ctrl:1
	v_add_f32_dpp v162, v162, v162 row_shr:4 row_mask:0xf bank_mask:0xf bound_ctrl:1
	v_add_f32_dpp v163, v163, v163 row_shr:4 row_mask:0xf bank_mask:0xf bound_ctrl:1
	v_add_f32_dpp v164, v164, v164 row_shr:4 row_mask:0xf bank_mask:0xf bound_ctrl:1
	v_add_f32_dpp v165, v165, v165 row_shr:4 row_mask:0xf bank_mask:0xf bound_ctrl:1
	v_add_f32_dpp v162, v162, v162 row_shr:8 row_mask:0xf bank_mask:0xf bound_ctrl:1
	v_add_f32_dpp v163, v163, v163 row_shr:8 row_mask:0xf bank_mask:0xf bound_ctrl:1
	v_add_f32_dpp v164, v164, v164 row_shr:8 row_mask:0xf bank_mask:0xf bound_ctrl:1
	v_add_f32_dpp v165, v165, v165 row_shr:8 row_mask:0xf bank_mask:0xf bound_ctrl:1
	v_add_f32_dpp v162, v162, v162 row_bcast:15 row_mask:0xa bank_mask:0xf
	v_add_f32_dpp v163, v163, v163 row_bcast:15 row_mask:0xa bank_mask:0xf
	v_add_f32_dpp v164, v164, v164 row_bcast:15 row_mask:0xa bank_mask:0xf
	v_add_f32_dpp v165, v165, v165 row_bcast:15 row_mask:0xa bank_mask:0xf
	s_nop 1
	v_readlane_b32 s46, v162, 31
	v_readlane_b32 s47, v162, 63
	v_readlane_b32 s48, v163, 31
	v_readlane_b32 s49, v163, 63
	v_readlane_b32 s50, v164, 31
	v_readlane_b32 s51, v164, 63
	v_readlane_b32 s52, v165, 31
	v_readlane_b32 s53, v165, 63
	v_writelane_b32 v166, s46, 8
	s_nop 1
	v_writelane_b32 v166, s47, 9
	v_writelane_b32 v166, s48, 10
	v_writelane_b32 v166, s49, 11
	v_writelane_b32 v166, s50, 12
	v_writelane_b32 v166, s51, 13
	v_writelane_b32 v166, s52, 14
	v_writelane_b32 v166, s53, 15
	v_readlane_b32 s54, v90, 32
	v_readlane_b32 s55, v90, 33
	s_mul_i32 s0, s54, 0x300
	s_mul_i32 s1, s55, 0x300
	v_add_u32_e32 v167, s0, v195
	s_and_saveexec_b64 s[98:99], s[40:41]
	v_add_u32_e32 v167, s1, v195
	s_mov_b64 exec, s[98:99]
	s_waitcnt vmcnt(14)
; __device__ void peer_gather_phase(const Params& P, int l, bool do_store) {
;     ...
;         const int ea = __builtin_amdgcn_readlane(evs, kb + 2 * pr), eb = __builtin_amdgcn_readlane(evs, kb + 2 * pr + 1);
;         const uint2* up = (const uint2*)(U + (size_t)(uphi ? eb : ea) * 768);
;         u6[3 * pr] = up[0]; u6[3 * pr + 1] = up[1]; u6[3 * pr + 2] = up[2];
;     ...
;       for (int pr = 0; pr < 4; ++pr) {
;         v6u_t qv; qv[0] = u6[3 * pr].x; qv[1] = u6[3 * pr].y; qv[2] = u6[3 * pr + 1].x; qv[3] = u6[3 * pr + 1].y; qv[4] = u6[3 * pr + 2].x; qv[5] = u6[3 * pr + 2].y;
;         const v32f_t wv = __builtin_amdgcn_cvt_scalef32_pk32_f32_fp6(qv, 1.0f);
;         f32x2 a2 = f32x2{0.f, 0.f};
; #pragma unroll
;         for (int i = 0; i < 16; ++i) a2 += f32x2{wv[2 * i], wv[2 * i + 1]} * xu[i];
;         float hs = a2.x + a2.y;
	v_cvt_scalef32_pk32_f32_fp6 v[0:31], v[50:55], 1.0
	global_load_dwordx2 v[54:55], v167, s[62:63] offset:16
	global_load_dwordx4 v[50:53], v167, s[62:63]
	v_pk_mul_f32 v[246:247], v[0:1], v[96:97]
	v_pk_mul_f32 v[254:255], v[2:3], v[98:99]
	v_pk_mul_f32 v[160:161], v[4:5], v[100:101]
	v_pk_fma_f32 v[246:247], v[6:7], v[102:103], v[246:247]
	v_pk_fma_f32 v[254:255], v[8:9], v[104:105], v[254:255]
	v_pk_fma_f32 v[160:161], v[10:11], v[106:107], v[160:161]
	v_pk_fma_f32 v[246:247], v[12:13], v[108:109], v[246:247]
	v_pk_fma_f32 v[254:255], v[14:15], v[110:111], v[254:255]
	v_pk_fma_f32 v[160:161], v[16:17], v[112:113], v[160:161]
	v_pk_fma_f32 v[246:247], v[18:19], v[114:115], v[246:247]
	v_pk_fma_f32 v[254:255], v[20:21], v[116:117], v[254:255]
	v_pk_fma_f32 v[160:161], v[22:23], v[118:119], v[160:161]
	v_pk_fma_f32 v[246:247], v[24:25], v[120:121], v[246:247]
	v_pk_fma_f32 v[254:255], v[26:27], v[122:123], v[254:255]
	v_pk_fma_f32 v[160:161], v[28:29], v[124:125], v[160:161]
	v_pk_fma_f32 v[246:247], v[30:31], v[126:127], v[246:247]
	v_pk_add_f32 v[254:255], v[254:255], v[160:161]
	s_nop 0
	v_pk_add_f32 v[246:247], v[246:247], v[254:255]
	s_nop 0
	v_add_f32_e32 v162, v246, v247
	v_readlane_b32 s54, v90, 34
	v_readlane_b32 s55, v90, 35
	s_mul_i32 s0, s54, 0x300
	s_mul_i32 s1, s55, 0x300
	v_add_u32_e32 v167, s0, v195
	s_and_saveexec_b64 s[98:99], s[40:41]
	v_add_u32_e32 v167, s1, v195
	s_mov_b64 exec, s[98:99]
	s_waitcnt vmcnt(14)
	v_cvt_scalef32_pk32_f32_fp6 v[0:31], v[44:49], 1.0
	global_load_dwordx2 v[48:49], v167, s[62:63] offset:16
	global_load_dwordx4 v[44:47], v167, s[62:63]
	v_pk_mul_f32 v[246:247], v[0:1], v[96:97]
	v_pk_mul_f32 v[254:255], v[2:3], v[98:99]
	v_pk_mul_f32 v[160:161], v[4:5], v[100:101]
	v_pk_fma_f32 v[246:247], v[6:7], v[102:103], v[246:247]
	v_pk_fma_f32 v[254:255], v[8:9], v[104:105], v[254:255]
	v_pk_fma_f32 v[160:161], v[10:11], v[106:107], v[160:161]
	v_pk_fma_f32 v[246:247], v[12:13], v[108:109], v[246:247]
	v_pk_fma_f32 v[254:255], v[14:15], v[110:111], v[254:255]
	v_pk_fma_f32 v[160:161], v[16:17], v[112:113], v[160:161]
	v_pk_fma_f32 v[246:247], v[18:19], v[114:115], v[246:247]
	v_pk_fma_f32 v[254:255], v[20:21], v[116:117], v[254:255]
	v_pk_fma_f32 v[160:161], v[22:23], v[118:119], v[160:161]
	v_pk_fma_f32 v[246:247], v[24:25], v[120:121], v[246:247]
	v_pk_fma_f32 v[254:255], v[26:27], v[122:123], v[254:255]
	v_pk_fma_f32 v[160:161], v[28:29], v[124:125], v[160:161]
	v_pk_fma_f32 v[246:247], v[30:31], v[126:127], v[246:247]
	v_pk_add_f32 v[254:255], v[254:255], v[160:161]
	s_nop 0
	v_pk_add_f32 v[246:247], v[246:247], v[254:255]
	s_nop 0
	v_add_f32_e32 v163, v246, v247
	v_readlane_b32 s54, v90, 36
	v_readlane_b32 s55, v90, 37
	s_mul_i32 s0, s54, 0x300
	s_mul_i32 s1, s55, 0x300
	v_add_u32_e32 v167, s0, v195
	s_and_saveexec_b64 s[98:99], s[40:41]
	v_add_u32_e32 v167, s1, v195
	s_mov_b64 exec, s[98:99]
	s_waitcnt vmcnt(14)
	v_cvt_scalef32_pk32_f32_fp6 v[0:31], v[38:43], 1.0
	global_load_dwordx2 v[42:43], v167, s[62:63] offset:16
	global_load_dwordx4 v[38:41], v167, s[62:63]
	v_pk_mul_f32 v[246:247], v[0:1], v[96:97]
	v_pk_mul_f32 v[254:255], v[2:3], v[98:99]
	v_pk_mul_f32 v[160:161], v[4:5], v[100:101]
	v_pk_fma_f32 v[246:247], v[6:7], v[102:103], v[246:247]
	v_pk_fma_f32 v[254:255], v[8:9], v[104:105], v[254:255]
	v_pk_fma_f32 v[160:161], v[10:11], v[106:107], v[160:161]
	v_pk_fma_f32 v[246:247], v[12:13], v[108:109], v[246:247]
	v_pk_fma_f32 v[254:255], v[14:15], v[110:111], v[254:255]
	v_pk_fma_f32 v[160:161], v[16:17], v[112:113], v[160:161]
	v_pk_fma_f32 v[246:247], v[18:19], v[114:115], v[246:247]
	v_pk_fma_f32 v[254:255], v[20:21], v[116:117], v[254:255]
	v_pk_fma_f32 v[160:161], v[22:23], v[118:119], v[160:161]
	v_pk_fma_f32 v[246:247], v[24:25], v[120:121], v[246:247]
	v_pk_fma_f32 v[254:255], v[26:27], v[122:123], v[254:255]
	v_pk_fma_f32 v[160:161], v[28:29], v[124:125], v[160:161]
	v_pk_fma_f32 v[246:247], v[30:31], v[126:127], v[246:247]
	v_pk_add_f32 v[254:255], v[254:255], v[160:161]
	s_nop 0
	v_pk_add_f32 v[246:247], v[246:247], v[254:255]
	s_nop 0
	v_add_f32_e32 v164, v246, v247
	v_readlane_b32 s54, v90, 38
	v_readlane_b32 s55, v90, 39
	s_mul_i32 s0, s54, 0x300
	s_mul_i32 s1, s55, 0x300
	v_add_u32_e32 v167, s0, v195
	s_and_saveexec_b64 s[98:99], s[40:41]
	v_add_u32_e32 v167, s1, v195
	s_mov_b64 exec, s[98:99]
	s_waitcnt vmcnt(14)
; __device__ void peer_gather_phase(const Params& P, int l, bool do_store) {
;     ...
;       for (int pr = 0; pr < 4; ++pr) {
;         v6u_t qv; qv[0] = u6[3 * pr].x; qv[1] = u6[3 * pr].y; qv[2] = u6[3 * pr + 1].x; qv[3] = u6[3 * pr + 1].y; qv[4] = u6[3 * pr + 2].x; qv[5] = u6[3 * pr + 2].y;
;         const v32f_t wv = __builtin_amdgcn_cvt_scalef32_pk32_f32_fp6(qv, 1.0f);
;         f32x2 a2 = f32x2{0.f, 0.f};
; #pragma unroll
;         for (int i = 0; i < 16; ++i) a2 += f32x2{wv[2 * i], wv[2 * i + 1]} * xu[i];
;         float hs = a2.x + a2.y;
;         hs += dpp_row_shr(hs, 1); hs += dpp_row_shr(hs, 2); hs += dpp_row_shr(hs, 4); hs += dpp_row_shr(hs, 8);
;         hs += __builtin_bit_cast(float, __builtin_amdgcn_update_dpp(0, __builtin_bit_cast(int, hs), 0x142, 0xa, 0xf, false));
;         const float da = __builtin_bit_cast(float, __builtin_amdgcn_readlane(__builtin_bit_cast(int, hs), 31));
;         const float db = __builtin_bit_cast(float, __builtin_amdgcn_readlane(__builtin_bit_cast(int, hs), 63));
;         dvec = (lane == kb + 2 * pr) ? da : dvec;
;         dvec = (lane == kb + 2 * pr + 1) ? db : dvec;
;       }
	v_cvt_scalef32_pk32_f32_fp6 v[0:31], v[32:37], 1.0
	global_load_dwordx2 v[36:37], v167, s[62:63] offset:16
	global_load_dwordx4 v[32:35], v167, s[62:63]
	v_pk_mul_f32 v[246:247], v[0:1], v[96:97]
	v_pk_mul_f32 v[254:255], v[2:3], v[98:99]
	v_pk_mul_f32 v[160:161], v[4:5], v[100:101]
	v_pk_fma_f32 v[246:247], v[6:7], v[102:103], v[246:247]
	v_pk_fma_f32 v[254:255], v[8:9], v[104:105], v[254:255]
	v_pk_fma_f32 v[160:161], v[10:11], v[106:107], v[160:161]
	v_pk_fma_f32 v[246:247], v[12:13], v[108:109], v[246:247]
	v_pk_fma_f32 v[254:255], v[14:15], v[110:111], v[254:255]
	v_pk_fma_f32 v[160:161], v[16:17], v[112:113], v[160:161]
	v_pk_fma_f32 v[246:247], v[18:19], v[114:115], v[246:247]
	v_pk_fma_f32 v[254:255], v[20:21], v[116:117], v[254:255]
	v_pk_fma_f32 v[160:161], v[22:23], v[118:119], v[160:161]
	v_pk_fma_f32 v[246:247], v[24:25], v[120:121], v[246:247]
	v_pk_fma_f32 v[254:255], v[26:27], v[122:123], v[254:255]
	v_pk_fma_f32 v[160:161], v[28:29], v[124:125], v[160:161]
	v_pk_fma_f32 v[246:247], v[30:31], v[126:127], v[246:247]
	v_pk_add_f32 v[254:255], v[254:255], v[160:161]
	s_nop 0
	v_pk_add_f32 v[246:247], v[246:247], v[254:255]
	s_nop 0
	v_add_f32_e32 v165, v246, v247
	v_add_f32_dpp v162, v162, v162 row_shr:1 row_mask:0xf bank_mask:0xf bound_ctrl:1
	v_add_f32_dpp v163, v163, v163 row_shr:1 row_mask:0xf bank_mask:0xf bound_ctrl:1
	v_add_f32_dpp v164, v164, v164 row_shr:1 row_mask:0xf bank_mask:0xf bound_ctrl:1
	v_add_f32_dpp v165, v165, v165 row_shr:1 row_mask:0xf bank_mask:0xf bound_ctrl:1
	v_add_f32_dpp v162, v162, v162 row_shr:2 row_mask:0xf bank_mask:0xf bound_ctrl:1
	v_add_f32_dpp v163, v163, v163 row_shr:2 row_mask:0xf bank_mask:0xf bound_ctrl:1
	v_add_f32_dpp v164, v164, v164 row_shr:2 row_mask:0xf bank_mask:0xf bound_ctrl:1
	v_add_f32_dpp v165, v165, v165 row_shr:2 row_mask:0xf bank_mask:0xf bound_ctrl:1
	v_add_f32_dpp v162, v162, v162 row_shr:4 row_mask:0xf bank_mask:0xf bound_ctrl:1
	v_add_f32_dpp v163, v163, v163 row_shr:4 row_mask:0xf bank_mask:0xf bound_ctrl:1
	v_add_f32_dpp v164, v164, v164 row_shr:4 row_mask:0xf bank_mask:0xf bound_ctrl:1
	v_add_f32_dpp v165, v165, v165 row_shr:4 row_mask:0xf bank_mask:0xf bound_ctrl:1
	v_add_f32_dpp v162, v162, v162 row_shr:8 row_mask:0xf bank_mask:0xf bound_ctrl:1
	v_add_f32_dpp v163, v163, v163 row_shr:8 row_mask:0xf bank_mask:0xf bound_ctrl:1
	v_add_f32_dpp v164, v164, v164 row_shr:8 row_mask:0xf bank_mask:0xf bound_ctrl:1
	v_add_f32_dpp v165, v165, v165 row_shr:8 row_mask:0xf bank_mask:0xf bound_ctrl:1
	v_add_f32_dpp v162, v162, v162 row_bcast:15 row_mask:0xa bank_mask:0xf
	v_add_f32_dpp v163, v163, v163 row_bcast:15 row_mask:0xa bank_mask:0xf
	v_add_f32_dpp v164, v164, v164 row_bcast:15 row_mask:0xa bank_mask:0xf
	v_add_f32_dpp v165, v165, v165 row_bcast:15 row_mask:0xa bank_mask:0xf
	s_nop 1
	v_readlane_b32 s46, v162, 31
	v_readlane_b32 s47, v162, 63
	v_readlane_b32 s48, v163, 31
	v_readlane_b32 s49, v163, 63
	v_readlane_b32 s50, v164, 31
	v_readlane_b32 s51, v164, 63
	v_readlane_b32 s52, v165, 31
	v_readlane_b32 s53, v165, 63
	v_writelane_b32 v166, s46, 16
	s_nop 1
	v_writelane_b32 v166, s47, 17
	v_writelane_b32 v166, s48, 18
	v_writelane_b32 v166, s49, 19
	v_writelane_b32 v166, s50, 20
	v_writelane_b32 v166, s51, 21
	v_writelane_b32 v166, s52, 22
	v_writelane_b32 v166, s53, 23
	v_readlane_b32 s54, v90, 40
	v_readlane_b32 s55, v90, 41
	s_mul_i32 s0, s54, 0x300
	s_mul_i32 s1, s55, 0x300
	v_add_u32_e32 v167, s0, v195
	s_and_saveexec_b64 s[98:99], s[40:41]
	v_add_u32_e32 v167, s1, v195
	s_mov_b64 exec, s[98:99]
	s_waitcnt vmcnt(14)
	v_cvt_scalef32_pk32_f32_fp6 v[0:31], v[196:201], 1.0
	global_load_dwordx2 v[200:201], v167, s[62:63] offset:16
	global_load_dwordx4 v[196:199], v167, s[62:63]
	v_pk_mul_f32 v[246:247], v[0:1], v[96:97]
	v_pk_mul_f32 v[254:255], v[2:3], v[98:99]
	v_pk_mul_f32 v[160:161], v[4:5], v[100:101]
	v_pk_fma_f32 v[246:247], v[6:7], v[102:103], v[246:247]
	v_pk_fma_f32 v[254:255], v[8:9], v[104:105], v[254:255]
	v_pk_fma_f32 v[160:161], v[10:11], v[106:107], v[160:161]
	v_pk_fma_f32 v[246:247], v[12:13], v[108:109], v[246:247]
	v_pk_fma_f32 v[254:255], v[14:15], v[110:111], v[254:255]
	v_pk_fma_f32 v[160:161], v[16:17], v[112:113], v[160:161]
	v_pk_fma_f32 v[246:247], v[18:19], v[114:115], v[246:247]
	v_pk_fma_f32 v[254:255], v[20:21], v[116:117], v[254:255]
	v_pk_fma_f32 v[160:161], v[22:23], v[118:119], v[160:161]
	v_pk_fma_f32 v[246:247], v[24:25], v[120:121], v[246:247]
	v_pk_fma_f32 v[254:255], v[26:27], v[122:123], v[254:255]
	v_pk_fma_f32 v[160:161], v[28:29], v[124:125], v[160:161]
	v_pk_fma_f32 v[246:247], v[30:31], v[126:127], v[246:247]
	v_pk_add_f32 v[254:255], v[254:255], v[160:161]
	s_nop 0
	v_pk_add_f32 v[246:247], v[246:247], v[254:255]
	s_nop 0
	v_add_f32_e32 v162, v246, v247
	v_readlane_b32 s54, v90, 42
	v_readlane_b32 s55, v90, 43
	s_mul_i32 s0, s54, 0x300
	s_mul_i32 s1, s55, 0x300
	v_add_u32_e32 v167, s0, v195
	s_and_saveexec_b64 s[98:99], s[40:41]
	v_add_u32_e32 v167, s1, v195
	s_mov_b64 exec, s[98:99]
	s_waitcnt vmcnt(14)
; __device__ void peer_gather_phase(const Params& P, int l, bool do_store) {
;     ...
;       for (int pr = 0; pr < 4; ++pr) {
;         v6u_t qv; qv[0] = u6[3 * pr].x; qv[1] = u6[3 * pr].y; qv[2] = u6[3 * pr + 1].x; qv[3] = u6[3 * pr + 1].y; qv[4] = u6[3 * pr + 2].x; qv[5] = u6[3 * pr + 2].y;
;         const v32f_t wv = __builtin_amdgcn_cvt_scalef32_pk32_f32_fp6(qv, 1.0f);
;         f32x2 a2 = f32x2{0.f, 0.f};
; #pragma unroll
;         for (int i = 0; i < 16; ++i) a2 += f32x2{wv[2 * i], wv[2 * i + 1]} * xu[i];
;         float hs = a2.x + a2.y;
;         hs += dpp_row_shr(hs, 1); hs += dpp_row_shr(hs, 2); hs += dpp_row_shr(hs, 4); hs += dpp_row_shr(hs, 8);
;         hs += __builtin_bit_cast(float, __builtin_amdgcn_update_dpp(0, __builtin_bit_cast(int, hs), 0x142, 0xa, 0xf, false));
;         const float da = __builtin_bit_cast(float, __builtin_amdgcn_readlane(__builtin_bit_cast(int, hs), 31));
;         const float db = __builtin_bit_cast(float, __builtin_amdgcn_readlane(__builtin_bit_cast(int, hs), 63));
;         dvec = (lane == kb + 2 * pr) ? da : dvec;
;         dvec = (lane == kb + 2 * pr + 1) ? db : dvec;
;       }
	v_cvt_scalef32_pk32_f32_fp6 v[0:31], v[228:233], 1.0
	global_load_dwordx2 v[232:233], v167, s[62:63] offset:16
	global_load_dwordx4 v[228:231], v167, s[62:63]
	v_pk_mul_f32 v[246:247], v[0:1], v[96:97]
	v_pk_mul_f32 v[254:255], v[2:3], v[98:99]
	v_pk_mul_f32 v[160:161], v[4:5], v[100:101]
	v_pk_fma_f32 v[246:247], v[6:7], v[102:103], v[246:247]
	v_pk_fma_f32 v[254:255], v[8:9], v[104:105], v[254:255]
	v_pk_fma_f32 v[160:161], v[10:11], v[106:107], v[160:161]
	v_pk_fma_f32 v[246:247], v[12:13], v[108:109], v[246:247]
	v_pk_fma_f32 v[254:255], v[14:15], v[110:111], v[254:255]
	v_pk_fma_f32 v[160:161], v[16:17], v[112:113], v[160:161]
	v_pk_fma_f32 v[246:247], v[18:19], v[114:115], v[246:247]
	v_pk_fma_f32 v[254:255], v[20:21], v[116:117], v[254:255]
	v_pk_fma_f32 v[160:161], v[22:23], v[118:119], v[160:161]
	v_pk_fma_f32 v[246:247], v[24:25], v[120:121], v[246:247]
	v_pk_fma_f32 v[254:255], v[26:27], v[122:123], v[254:255]
	v_pk_fma_f32 v[160:161], v[28:29], v[124:125], v[160:161]
	v_pk_fma_f32 v[246:247], v[30:31], v[126:127], v[246:247]
	v_pk_add_f32 v[254:255], v[254:255], v[160:161]
	s_nop 0
	v_pk_add_f32 v[246:247], v[246:247], v[254:255]
	s_nop 0
	v_add_f32_e32 v163, v246, v247
	v_readlane_b32 s54, v90, 44
	v_readlane_b32 s55, v90, 45
	s_mul_i32 s0, s54, 0x300
	s_mul_i32 s1, s55, 0x300
	v_add_u32_e32 v167, s0, v195
	s_and_saveexec_b64 s[98:99], s[40:41]
	v_add_u32_e32 v167, s1, v195
	s_mov_b64 exec, s[98:99]
	s_waitcnt vmcnt(14)
	v_cvt_scalef32_pk32_f32_fp6 v[0:31], v[234:239], 1.0
	global_load_dwordx2 v[238:239], v167, s[62:63] offset:16
	global_load_dwordx4 v[234:237], v167, s[62:63]
	v_pk_mul_f32 v[246:247], v[0:1], v[96:97]
	v_pk_mul_f32 v[254:255], v[2:3], v[98:99]
	v_pk_mul_f32 v[160:161], v[4:5], v[100:101]
	v_pk_fma_f32 v[246:247], v[6:7], v[102:103], v[246:247]
	v_pk_fma_f32 v[254:255], v[8:9], v[104:105], v[254:255]
	v_pk_fma_f32 v[160:161], v[10:11], v[106:107], v[160:161]
	v_pk_fma_f32 v[246:247], v[12:13], v[108:109], v[246:247]
	v_pk_fma_f32 v[254:255], v[14:15], v[110:111], v[254:255]
	v_pk_fma_f32 v[160:161], v[16:17], v[112:113], v[160:161]
	v_pk_fma_f32 v[246:247], v[18:19], v[114:115], v[246:247]
	v_pk_fma_f32 v[254:255], v[20:21], v[116:117], v[254:255]
	v_pk_fma_f32 v[160:161], v[22:23], v[118:119], v[160:161]
	v_pk_fma_f32 v[246:247], v[24:25], v[120:121], v[246:247]
	v_pk_fma_f32 v[254:255], v[26:27], v[122:123], v[254:255]
	v_pk_fma_f32 v[160:161], v[28:29], v[124:125], v[160:161]
	v_pk_fma_f32 v[246:247], v[30:31], v[126:127], v[246:247]
	v_pk_add_f32 v[254:255], v[254:255], v[160:161]
	s_nop 0
	v_pk_add_f32 v[246:247], v[246:247], v[254:255]
	s_nop 0
	v_add_f32_e32 v164, v246, v247
	v_readlane_b32 s54, v90, 46
	v_readlane_b32 s55, v90, 47
	s_mul_i32 s0, s54, 0x300
	s_mul_i32 s1, s55, 0x300
	v_add_u32_e32 v167, s0, v195
	s_and_saveexec_b64 s[98:99], s[40:41]
	v_add_u32_e32 v167, s1, v195
	s_mov_b64 exec, s[98:99]
	s_waitcnt vmcnt(14)
	v_cvt_scalef32_pk32_f32_fp6 v[0:31], v[240:245], 1.0
	global_load_dwordx2 v[244:245], v167, s[62:63] offset:16
	global_load_dwordx4 v[240:243], v167, s[62:63]
	v_pk_mul_f32 v[246:247], v[0:1], v[96:97]
	v_pk_mul_f32 v[254:255], v[2:3], v[98:99]
	v_pk_mul_f32 v[160:161], v[4:5], v[100:101]
	v_pk_fma_f32 v[246:247], v[6:7], v[102:103], v[246:247]
	v_pk_fma_f32 v[254:255], v[8:9], v[104:105], v[254:255]
	v_pk_fma_f32 v[160:161], v[10:11], v[106:107], v[160:161]
	v_pk_fma_f32 v[246:247], v[12:13], v[108:109], v[246:247]
	v_pk_fma_f32 v[254:255], v[14:15], v[110:111], v[254:255]
	v_pk_fma_f32 v[160:161], v[16:17], v[112:113], v[160:161]
	v_pk_fma_f32 v[246:247], v[18:19], v[114:115], v[246:247]
	v_pk_fma_f32 v[254:255], v[20:21], v[116:117], v[254:255]
	v_pk_fma_f32 v[160:161], v[22:23], v[118:119], v[160:161]
	v_pk_fma_f32 v[246:247], v[24:25], v[120:121], v[246:247]
	v_pk_fma_f32 v[254:255], v[26:27], v[122:123], v[254:255]
	v_pk_fma_f32 v[160:161], v[28:29], v[124:125], v[160:161]
	v_pk_fma_f32 v[246:247], v[30:31], v[126:127], v[246:247]
	v_pk_add_f32 v[254:255], v[254:255], v[160:161]
	s_nop 0
	v_pk_add_f32 v[246:247], v[246:247], v[254:255]
	s_nop 0
	v_add_f32_e32 v165, v246, v247
	v_add_f32_dpp v162, v162, v162 row_shr:1 row_mask:0xf bank_mask:0xf bound_ctrl:1
	v_add_f32_dpp v163, v163, v163 row_shr:1 row_mask:0xf bank_mask:0xf bound_ctrl:1
	v_add_f32_dpp v164, v164, v164 row_shr:1 row_mask:0xf bank_mask:0xf bound_ctrl:1
	v_add_f32_dpp v165, v165, v165 row_shr:1 row_mask:0xf bank_mask:0xf bound_ctrl:1
	v_add_f32_dpp v162, v162, v162 row_shr:2 row_mask:0xf bank_mask:0xf bound_ctrl:1
	v_add_f32_dpp v163, v163, v163 row_shr:2 row_mask:0xf bank_mask:0xf bound_ctrl:1
	v_add_f32_dpp v164, v164, v164 row_shr:2 row_mask:0xf bank_mask:0xf bound_ctrl:1
	v_add_f32_dpp v165, v165, v165 row_shr:2 row_mask:0xf bank_mask:0xf bound_ctrl:1
	v_add_f32_dpp v162, v162, v162 row_shr:4 row_mask:0xf bank_mask:0xf bound_ctrl:1
	v_add_f32_dpp v163, v163, v163 row_shr:4 row_mask:0xf bank_mask:0xf bound_ctrl:1
	v_add_f32_dpp v164, v164, v164 row_shr:4 row_mask:0xf bank_mask:0xf bound_ctrl:1
	v_add_f32_dpp v165, v165, v165 row_shr:4 row_mask:0xf bank_mask:0xf bound_ctrl:1
	v_add_f32_dpp v162, v162, v162 row_shr:8 row_mask:0xf bank_mask:0xf bound_ctrl:1
	v_add_f32_dpp v163, v163, v163 row_shr:8 row_mask:0xf bank_mask:0xf bound_ctrl:1
	v_add_f32_dpp v164, v164, v164 row_shr:8 row_mask:0xf bank_mask:0xf bound_ctrl:1
	v_add_f32_dpp v165, v165, v165 row_shr:8 row_mask:0xf bank_mask:0xf bound_ctrl:1
	v_add_f32_dpp v162, v162, v162 row_bcast:15 row_mask:0xa bank_mask:0xf
	v_add_f32_dpp v163, v163, v163 row_bcast:15 row_mask:0xa bank_mask:0xf
	v_add_f32_dpp v164, v164, v164 row_bcast:15 row_mask:0xa bank_mask:0xf
	v_add_f32_dpp v165, v165, v165 row_bcast:15 row_mask:0xa bank_mask:0xf
	s_nop 1
	v_readlane_b32 s46, v162, 31
	v_readlane_b32 s47, v162, 63
	v_readlane_b32 s48, v163, 31
	v_readlane_b32 s49, v163, 63
	v_readlane_b32 s50, v164, 31
	v_readlane_b32 s51, v164, 63
	v_readlane_b32 s52, v165, 31
	v_readlane_b32 s53, v165, 63
	v_writelane_b32 v166, s46, 24
	s_nop 1
	v_writelane_b32 v166, s47, 25
	v_writelane_b32 v166, s48, 26
	v_writelane_b32 v166, s49, 27
	v_writelane_b32 v166, s50, 28
	v_writelane_b32 v166, s51, 29
	v_writelane_b32 v166, s52, 30
	v_writelane_b32 v166, s53, 31
	v_readlane_b32 s54, v90, 48
	v_readlane_b32 s55, v90, 49
	s_mul_i32 s0, s54, 0x300
	s_mul_i32 s1, s55, 0x300
	v_add_u32_e32 v167, s0, v195
	s_and_saveexec_b64 s[98:99], s[40:41]
	v_add_u32_e32 v167, s1, v195
	s_mov_b64 exec, s[98:99]
	s_waitcnt vmcnt(14)
; __device__ void peer_gather_phase(const Params& P, int l, bool do_store) {
;     ...
;         const int ea = __builtin_amdgcn_readlane(evs, kb + 2 * pr), eb = __builtin_amdgcn_readlane(evs, kb + 2 * pr + 1);
;         const uint2* up = (const uint2*)(U + (size_t)(uphi ? eb : ea) * 768);
;         u6[3 * pr] = up[0]; u6[3 * pr + 1] = up[1]; u6[3 * pr + 2] = up[2];
;     ...
;       for (int pr = 0; pr < 4; ++pr) {
;         v6u_t qv; qv[0] = u6[3 * pr].x; qv[1] = u6[3 * pr].y; qv[2] = u6[3 * pr + 1].x; qv[3] = u6[3 * pr + 1].y; qv[4] = u6[3 * pr + 2].x; qv[5] = u6[3 * pr + 2].y;
;         const v32f_t wv = __builtin_amdgcn_cvt_scalef32_pk32_f32_fp6(qv, 1.0f);
;         f32x2 a2 = f32x2{0.f, 0.f};
; #pragma unroll
;         for (int i = 0; i < 16; ++i) a2 += f32x2{wv[2 * i], wv[2 * i + 1]} * xu[i];
;         float hs = a2.x + a2.y;
	v_cvt_scalef32_pk32_f32_fp6 v[0:31], v[50:55], 1.0
	global_load_dwordx2 v[54:55], v167, s[62:63] offset:16
	global_load_dwordx4 v[50:53], v167, s[62:63]
	v_pk_mul_f32 v[246:247], v[0:1], v[96:97]
	v_pk_mul_f32 v[254:255], v[2:3], v[98:99]
	v_pk_mul_f32 v[160:161], v[4:5], v[100:101]
	v_pk_fma_f32 v[246:247], v[6:7], v[102:103], v[246:247]
	v_pk_fma_f32 v[254:255], v[8:9], v[104:105], v[254:255]
	v_pk_fma_f32 v[160:161], v[10:11], v[106:107], v[160:161]
	v_pk_fma_f32 v[246:247], v[12:13], v[108:109], v[246:247]
	v_pk_fma_f32 v[254:255], v[14:15], v[110:111], v[254:255]
	v_pk_fma_f32 v[160:161], v[16:17], v[112:113], v[160:161]
	v_pk_fma_f32 v[246:247], v[18:19], v[114:115], v[246:247]
	v_pk_fma_f32 v[254:255], v[20:21], v[116:117], v[254:255]
	v_pk_fma_f32 v[160:161], v[22:23], v[118:119], v[160:161]
	v_pk_fma_f32 v[246:247], v[24:25], v[120:121], v[246:247]
	v_pk_fma_f32 v[254:255], v[26:27], v[122:123], v[254:255]
	v_pk_fma_f32 v[160:161], v[28:29], v[124:125], v[160:161]
	v_pk_fma_f32 v[246:247], v[30:31], v[126:127], v[246:247]
	v_pk_add_f32 v[254:255], v[254:255], v[160:161]
	s_nop 0
	v_pk_add_f32 v[246:247], v[246:247], v[254:255]
	s_nop 0
	v_add_f32_e32 v162, v246, v247
	v_readlane_b32 s54, v90, 50
	v_readlane_b32 s55, v90, 51
	s_mul_i32 s0, s54, 0x300
	s_mul_i32 s1, s55, 0x300
	v_add_u32_e32 v167, s0, v195
	s_and_saveexec_b64 s[98:99], s[40:41]
	v_add_u32_e32 v167, s1, v195
	s_mov_b64 exec, s[98:99]
	s_waitcnt vmcnt(14)
	v_cvt_scalef32_pk32_f32_fp6 v[0:31], v[44:49], 1.0
	global_load_dwordx2 v[48:49], v167, s[62:63] offset:16
	global_load_dwordx4 v[44:47], v167, s[62:63]
	v_pk_mul_f32 v[246:247], v[0:1], v[96:97]
	v_pk_mul_f32 v[254:255], v[2:3], v[98:99]
	v_pk_mul_f32 v[160:161], v[4:5], v[100:101]
	v_pk_fma_f32 v[246:247], v[6:7], v[102:103], v[246:247]
	v_pk_fma_f32 v[254:255], v[8:9], v[104:105], v[254:255]
	v_pk_fma_f32 v[160:161], v[10:11], v[106:107], v[160:161]
	v_pk_fma_f32 v[246:247], v[12:13], v[108:109], v[246:247]
	v_pk_fma_f32 v[254:255], v[14:15], v[110:111], v[254:255]
	v_pk_fma_f32 v[160:161], v[16:17], v[112:113], v[160:161]
	v_pk_fma_f32 v[246:247], v[18:19], v[114:115], v[246:247]
	v_pk_fma_f32 v[254:255], v[20:21], v[116:117], v[254:255]
	v_pk_fma_f32 v[160:161], v[22:23], v[118:119], v[160:161]
	v_pk_fma_f32 v[246:247], v[24:25], v[120:121], v[246:247]
	v_pk_fma_f32 v[254:255], v[26:27], v[122:123], v[254:255]
	v_pk_fma_f32 v[160:161], v[28:29], v[124:125], v[160:161]
	v_pk_fma_f32 v[246:247], v[30:31], v[126:127], v[246:247]
	v_pk_add_f32 v[254:255], v[254:255], v[160:161]
	s_nop 0
	v_pk_add_f32 v[246:247], v[246:247], v[254:255]
	s_nop 0
	v_add_f32_e32 v163, v246, v247
	v_readlane_b32 s54, v90, 52
	v_readlane_b32 s55, v90, 53
	s_mul_i32 s0, s54, 0x300
	s_mul_i32 s1, s55, 0x300
	v_add_u32_e32 v167, s0, v195
	s_and_saveexec_b64 s[98:99], s[40:41]
	v_add_u32_e32 v167, s1, v195
	s_mov_b64 exec, s[98:99]
	s_waitcnt vmcnt(14)
	v_cvt_scalef32_pk32_f32_fp6 v[0:31], v[38:43], 1.0
	global_load_dwordx2 v[42:43], v167, s[62:63] offset:16
	global_load_dwordx4 v[38:41], v167, s[62:63]
	v_pk_mul_f32 v[246:247], v[0:1], v[96:97]
	v_pk_mul_f32 v[254:255], v[2:3], v[98:99]
	v_pk_mul_f32 v[160:161], v[4:5], v[100:101]
	v_pk_fma_f32 v[246:247], v[6:7], v[102:103], v[246:247]
	v_pk_fma_f32 v[254:255], v[8:9], v[104:105], v[254:255]
	v_pk_fma_f32 v[160:161], v[10:11], v[106:107], v[160:161]
	v_pk_fma_f32 v[246:247], v[12:13], v[108:109], v[246:247]
	v_pk_fma_f32 v[254:255], v[14:15], v[110:111], v[254:255]
	v_pk_fma_f32 v[160:161], v[16:17], v[112:113], v[160:161]
	v_pk_fma_f32 v[246:247], v[18:19], v[114:115], v[246:247]
	v_pk_fma_f32 v[254:255], v[20:21], v[116:117], v[254:255]
	v_pk_fma_f32 v[160:161], v[22:23], v[118:119], v[160:161]
	v_pk_fma_f32 v[246:247], v[24:25], v[120:121], v[246:247]
	v_pk_fma_f32 v[254:255], v[26:27], v[122:123], v[254:255]
	v_pk_fma_f32 v[160:161], v[28:29], v[124:125], v[160:161]
	v_pk_fma_f32 v[246:247], v[30:31], v[126:127], v[246:247]
	v_pk_add_f32 v[254:255], v[254:255], v[160:161]
	s_nop 0
	v_pk_add_f32 v[246:247], v[246:247], v[254:255]
	s_nop 0
	v_add_f32_e32 v164, v246, v247
	v_readlane_b32 s54, v90, 54
	v_readlane_b32 s55, v90, 55
	s_mul_i32 s0, s54, 0x300
	s_mul_i32 s1, s55, 0x300
	v_add_u32_e32 v167, s0, v195
	s_and_saveexec_b64 s[98:99], s[40:41]
	v_add_u32_e32 v167, s1, v195
	s_mov_b64 exec, s[98:99]
	s_waitcnt vmcnt(14)
; __device__ void peer_gather_phase(const Params& P, int l, bool do_store) {
;     ...
;       for (int pr = 0; pr < 4; ++pr) {
;         v6u_t qv; qv[0] = u6[3 * pr].x; qv[1] = u6[3 * pr].y; qv[2] = u6[3 * pr + 1].x; qv[3] = u6[3 * pr + 1].y; qv[4] = u6[3 * pr + 2].x; qv[5] = u6[3 * pr + 2].y;
;         const v32f_t wv = __builtin_amdgcn_cvt_scalef32_pk32_f32_fp6(qv, 1.0f);
;         f32x2 a2 = f32x2{0.f, 0.f};
; #pragma unroll
;         for (int i = 0; i < 16; ++i) a2 += f32x2{wv[2 * i], wv[2 * i + 1]} * xu[i];
;         float hs = a2.x + a2.y;
;         hs += dpp_row_shr(hs, 1); hs += dpp_row_shr(hs, 2); hs += dpp_row_shr(hs, 4); hs += dpp_row_shr(hs, 8);
;         hs += __builtin_bit_cast(float, __builtin_amdgcn_update_dpp(0, __builtin_bit_cast(int, hs), 0x142, 0xa, 0xf, false));
;         const float da = __builtin_bit_cast(float, __builtin_amdgcn_readlane(__builtin_bit_cast(int, hs), 31));
;         const float db = __builtin_bit_cast(float, __builtin_amdgcn_readlane(__builtin_bit_cast(int, hs), 63));
;         dvec = (lane == kb + 2 * pr) ? da : dvec;
;         dvec = (lane == kb + 2 * pr + 1) ? db : dvec;
;       }
	v_cvt_scalef32_pk32_f32_fp6 v[0:31], v[32:37], 1.0
	global_load_dwordx2 v[36:37], v167, s[62:63] offset:16
	global_load_dwordx4 v[32:35], v167, s[62:63]
	v_pk_mul_f32 v[246:247], v[0:1], v[96:97]
	v_pk_mul_f32 v[254:255], v[2:3], v[98:99]
	v_pk_mul_f32 v[160:161], v[4:5], v[100:101]
	v_pk_fma_f32 v[246:247], v[6:7], v[102:103], v[246:247]
	v_pk_fma_f32 v[254:255], v[8:9], v[104:105], v[254:255]
	v_pk_fma_f32 v[160:161], v[10:11], v[106:107], v[160:161]
	v_pk_fma_f32 v[246:247], v[12:13], v[108:109], v[246:247]
	v_pk_fma_f32 v[254:255], v[14:15], v[110:111], v[254:255]
	v_pk_fma_f32 v[160:161], v[16:17], v[112:113], v[160:161]
	v_pk_fma_f32 v[246:247], v[18:19], v[114:115], v[246:247]
	v_pk_fma_f32 v[254:255], v[20:21], v[116:117], v[254:255]
	v_pk_fma_f32 v[160:161], v[22:23], v[118:119], v[160:161]
	v_pk_fma_f32 v[246:247], v[24:25], v[120:121], v[246:247]
	v_pk_fma_f32 v[254:255], v[26:27], v[122:123], v[254:255]
	v_pk_fma_f32 v[160:161], v[28:29], v[124:125], v[160:161]
	v_pk_fma_f32 v[246:247], v[30:31], v[126:127], v[246:247]
	v_pk_add_f32 v[254:255], v[254:255], v[160:161]
	s_nop 0
	v_pk_add_f32 v[246:247], v[246:247], v[254:255]
	s_nop 0
	v_add_f32_e32 v165, v246, v247
	v_add_f32_dpp v162, v162, v162 row_shr:1 row_mask:0xf bank_mask:0xf bound_ctrl:1
	v_add_f32_dpp v163, v163, v163 row_shr:1 row_mask:0xf bank_mask:0xf bound_ctrl:1
	v_add_f32_dpp v164, v164, v164 row_shr:1 row_mask:0xf bank_mask:0xf bound_ctrl:1
	v_add_f32_dpp v165, v165, v165 row_shr:1 row_mask:0xf bank_mask:0xf bound_ctrl:1
	v_add_f32_dpp v162, v162, v162 row_shr:2 row_mask:0xf bank_mask:0xf bound_ctrl:1
	v_add_f32_dpp v163, v163, v163 row_shr:2 row_mask:0xf bank_mask:0xf bound_ctrl:1
	v_add_f32_dpp v164, v164, v164 row_shr:2 row_mask:0xf bank_mask:0xf bound_ctrl:1
	v_add_f32_dpp v165, v165, v165 row_shr:2 row_mask:0xf bank_mask:0xf bound_ctrl:1
	v_add_f32_dpp v162, v162, v162 row_shr:4 row_mask:0xf bank_mask:0xf bound_ctrl:1
	v_add_f32_dpp v163, v163, v163 row_shr:4 row_mask:0xf bank_mask:0xf bound_ctrl:1
	v_add_f32_dpp v164, v164, v164 row_shr:4 row_mask:0xf bank_mask:0xf bound_ctrl:1
	v_add_f32_dpp v165, v165, v165 row_shr:4 row_mask:0xf bank_mask:0xf bound_ctrl:1
	v_add_f32_dpp v162, v162, v162 row_shr:8 row_mask:0xf bank_mask:0xf bound_ctrl:1
	v_add_f32_dpp v163, v163, v163 row_shr:8 row_mask:0xf bank_mask:0xf bound_ctrl:1
	v_add_f32_dpp v164, v164, v164 row_shr:8 row_mask:0xf bank_mask:0xf bound_ctrl:1
	v_add_f32_dpp v165, v165, v165 row_shr:8 row_mask:0xf bank_mask:0xf bound_ctrl:1
	v_add_f32_dpp v162, v162, v162 row_bcast:15 row_mask:0xa bank_mask:0xf
	v_add_f32_dpp v163, v163, v163 row_bcast:15 row_mask:0xa bank_mask:0xf
	v_add_f32_dpp v164, v164, v164 row_bcast:15 row_mask:0xa bank_mask:0xf
	v_add_f32_dpp v165, v165, v165 row_bcast:15 row_mask:0xa bank_mask:0xf
	s_nop 1
	v_readlane_b32 s46, v162, 31
	v_readlane_b32 s47, v162, 63
	v_readlane_b32 s48, v163, 31
	v_readlane_b32 s49, v163, 63
	v_readlane_b32 s50, v164, 31
	v_readlane_b32 s51, v164, 63
	v_readlane_b32 s52, v165, 31
	v_readlane_b32 s53, v165, 63
	v_writelane_b32 v166, s46, 32
	s_nop 1
	v_writelane_b32 v166, s47, 33
	v_writelane_b32 v166, s48, 34
	v_writelane_b32 v166, s49, 35
	v_writelane_b32 v166, s50, 36
	v_writelane_b32 v166, s51, 37
	v_writelane_b32 v166, s52, 38
	v_writelane_b32 v166, s53, 39
	v_readlane_b32 s54, v90, 56
	v_readlane_b32 s55, v90, 57
	s_mul_i32 s0, s54, 0x300
	s_mul_i32 s1, s55, 0x300
	v_add_u32_e32 v167, s0, v195
	s_and_saveexec_b64 s[98:99], s[40:41]
	v_add_u32_e32 v167, s1, v195
	s_mov_b64 exec, s[98:99]
	s_waitcnt vmcnt(14)
	v_cvt_scalef32_pk32_f32_fp6 v[0:31], v[196:201], 1.0
	global_load_dwordx2 v[200:201], v167, s[62:63] offset:16
	global_load_dwordx4 v[196:199], v167, s[62:63]
	v_pk_mul_f32 v[246:247], v[0:1], v[96:97]
	v_pk_mul_f32 v[254:255], v[2:3], v[98:99]
	v_pk_mul_f32 v[160:161], v[4:5], v[100:101]
	v_pk_fma_f32 v[246:247], v[6:7], v[102:103], v[246:247]
	v_pk_fma_f32 v[254:255], v[8:9], v[104:105], v[254:255]
	v_pk_fma_f32 v[160:161], v[10:11], v[106:107], v[160:161]
	v_pk_fma_f32 v[246:247], v[12:13], v[108:109], v[246:247]
	v_pk_fma_f32 v[254:255], v[14:15], v[110:111], v[254:255]
	v_pk_fma_f32 v[160:161], v[16:17], v[112:113], v[160:161]
	v_pk_fma_f32 v[246:247], v[18:19], v[114:115], v[246:247]
	v_pk_fma_f32 v[254:255], v[20:21], v[116:117], v[254:255]
	v_pk_fma_f32 v[160:161], v[22:23], v[118:119], v[160:161]
	v_pk_fma_f32 v[246:247], v[24:25], v[120:121], v[246:247]
	v_pk_fma_f32 v[254:255], v[26:27], v[122:123], v[254:255]
	v_pk_fma_f32 v[160:161], v[28:29], v[124:125], v[160:161]
	v_pk_fma_f32 v[246:247], v[30:31], v[126:127], v[246:247]
	v_pk_add_f32 v[254:255], v[254:255], v[160:161]
	s_nop 0
	v_pk_add_f32 v[246:247], v[246:247], v[254:255]
	s_nop 0
	v_add_f32_e32 v162, v246, v247
	v_readlane_b32 s54, v90, 58
	v_readlane_b32 s55, v90, 59
	s_mul_i32 s0, s54, 0x300
	s_mul_i32 s1, s55, 0x300
	v_add_u32_e32 v167, s0, v195
	s_and_saveexec_b64 s[98:99], s[40:41]
	v_add_u32_e32 v167, s1, v195
	s_mov_b64 exec, s[98:99]
	s_waitcnt vmcnt(14)
; __device__ void peer_gather_phase(const Params& P, int l, bool do_store) {
;     ...
;       for (int pr = 0; pr < 4; ++pr) {
;         v6u_t qv; qv[0] = u6[3 * pr].x; qv[1] = u6[3 * pr].y; qv[2] = u6[3 * pr + 1].x; qv[3] = u6[3 * pr + 1].y; qv[4] = u6[3 * pr + 2].x; qv[5] = u6[3 * pr + 2].y;
;         const v32f_t wv = __builtin_amdgcn_cvt_scalef32_pk32_f32_fp6(qv, 1.0f);
;         f32x2 a2 = f32x2{0.f, 0.f};
; #pragma unroll
;         for (int i = 0; i < 16; ++i) a2 += f32x2{wv[2 * i], wv[2 * i + 1]} * xu[i];
;         float hs = a2.x + a2.y;
;         hs += dpp_row_shr(hs, 1); hs += dpp_row_shr(hs, 2); hs += dpp_row_shr(hs, 4); hs += dpp_row_shr(hs, 8);
;         hs += __builtin_bit_cast(float, __builtin_amdgcn_update_dpp(0, __builtin_bit_cast(int, hs), 0x142, 0xa, 0xf, false));
;         const float da = __builtin_bit_cast(float, __builtin_amdgcn_readlane(__builtin_bit_cast(int, hs), 31));
;         const float db = __builtin_bit_cast(float, __builtin_amdgcn_readlane(__builtin_bit_cast(int, hs), 63));
;         dvec = (lane == kb + 2 * pr) ? da : dvec;
;         dvec = (lane == kb + 2 * pr + 1) ? db : dvec;
;       }
	v_cvt_scalef32_pk32_f32_fp6 v[0:31], v[228:233], 1.0
	global_load_dwordx2 v[232:233], v167, s[62:63] offset:16
	global_load_dwordx4 v[228:231], v167, s[62:63]
	v_pk_mul_f32 v[246:247], v[0:1], v[96:97]
	v_pk_mul_f32 v[254:255], v[2:3], v[98:99]
	v_pk_mul_f32 v[160:161], v[4:5], v[100:101]
	v_pk_fma_f32 v[246:247], v[6:7], v[102:103], v[246:247]
	v_pk_fma_f32 v[254:255], v[8:9], v[104:105], v[254:255]
	v_pk_fma_f32 v[160:161], v[10:11], v[106:107], v[160:161]
	v_pk_fma_f32 v[246:247], v[12:13], v[108:109], v[246:247]
	v_pk_fma_f32 v[254:255], v[14:15], v[110:111], v[254:255]
	v_pk_fma_f32 v[160:161], v[16:17], v[112:113], v[160:161]
	v_pk_fma_f32 v[246:247], v[18:19], v[114:115], v[246:247]
	v_pk_fma_f32 v[254:255], v[20:21], v[116:117], v[254:255]
	v_pk_fma_f32 v[160:161], v[22:23], v[118:119], v[160:161]
	v_pk_fma_f32 v[246:247], v[24:25], v[120:121], v[246:247]
	v_pk_fma_f32 v[254:255], v[26:27], v[122:123], v[254:255]
	v_pk_fma_f32 v[160:161], v[28:29], v[124:125], v[160:161]
	v_pk_fma_f32 v[246:247], v[30:31], v[126:127], v[246:247]
	v_pk_add_f32 v[254:255], v[254:255], v[160:161]
	s_nop 0
	v_pk_add_f32 v[246:247], v[246:247], v[254:255]
	s_nop 0
	v_add_f32_e32 v163, v246, v247
	v_readlane_b32 s54, v90, 60
	v_readlane_b32 s55, v90, 61
	s_mul_i32 s0, s54, 0x300
	s_mul_i32 s1, s55, 0x300
	v_add_u32_e32 v167, s0, v195
	s_and_saveexec_b64 s[98:99], s[40:41]
	v_add_u32_e32 v167, s1, v195
	s_mov_b64 exec, s[98:99]
	s_waitcnt vmcnt(14)
	v_cvt_scalef32_pk32_f32_fp6 v[0:31], v[234:239], 1.0
	global_load_dwordx2 v[238:239], v167, s[62:63] offset:16
	global_load_dwordx4 v[234:237], v167, s[62:63]
	v_pk_mul_f32 v[246:247], v[0:1], v[96:97]
	v_pk_mul_f32 v[254:255], v[2:3], v[98:99]
	v_pk_mul_f32 v[160:161], v[4:5], v[100:101]
	v_pk_fma_f32 v[246:247], v[6:7], v[102:103], v[246:247]
	v_pk_fma_f32 v[254:255], v[8:9], v[104:105], v[254:255]
	v_pk_fma_f32 v[160:161], v[10:11], v[106:107], v[160:161]
	v_pk_fma_f32 v[246:247], v[12:13], v[108:109], v[246:247]
	v_pk_fma_f32 v[254:255], v[14:15], v[110:111], v[254:255]
	v_pk_fma_f32 v[160:161], v[16:17], v[112:113], v[160:161]
	v_pk_fma_f32 v[246:247], v[18:19], v[114:115], v[246:247]
	v_pk_fma_f32 v[254:255], v[20:21], v[116:117], v[254:255]
	v_pk_fma_f32 v[160:161], v[22:23], v[118:119], v[160:161]
	v_pk_fma_f32 v[246:247], v[24:25], v[120:121], v[246:247]
	v_pk_fma_f32 v[254:255], v[26:27], v[122:123], v[254:255]
	v_pk_fma_f32 v[160:161], v[28:29], v[124:125], v[160:161]
	v_pk_fma_f32 v[246:247], v[30:31], v[126:127], v[246:247]
	v_pk_add_f32 v[254:255], v[254:255], v[160:161]
	s_nop 0
	v_pk_add_f32 v[246:247], v[246:247], v[254:255]
	s_nop 0
	v_add_f32_e32 v164, v246, v247
	v_readlane_b32 s54, v90, 62
	v_readlane_b32 s55, v90, 63
	s_mul_i32 s0, s54, 0x300
	s_mul_i32 s1, s55, 0x300
	v_add_u32_e32 v167, s0, v195
	s_and_saveexec_b64 s[98:99], s[40:41]
	v_add_u32_e32 v167, s1, v195
	s_mov_b64 exec, s[98:99]
	s_waitcnt vmcnt(14)
	v_cvt_scalef32_pk32_f32_fp6 v[0:31], v[240:245], 1.0
	global_load_dwordx2 v[244:245], v167, s[62:63] offset:16
	global_load_dwordx4 v[240:243], v167, s[62:63]
	v_pk_mul_f32 v[246:247], v[0:1], v[96:97]
	v_pk_mul_f32 v[254:255], v[2:3], v[98:99]
	v_pk_mul_f32 v[160:161], v[4:5], v[100:101]
	v_pk_fma_f32 v[246:247], v[6:7], v[102:103], v[246:247]
	v_pk_fma_f32 v[254:255], v[8:9], v[104:105], v[254:255]
	v_pk_fma_f32 v[160:161], v[10:11], v[106:107], v[160:161]
	v_pk_fma_f32 v[246:247], v[12:13], v[108:109], v[246:247]
	v_pk_fma_f32 v[254:255], v[14:15], v[110:111], v[254:255]
	v_pk_fma_f32 v[160:161], v[16:17], v[112:113], v[160:161]
	v_pk_fma_f32 v[246:247], v[18:19], v[114:115], v[246:247]
	v_pk_fma_f32 v[254:255], v[20:21], v[116:117], v[254:255]
	v_pk_fma_f32 v[160:161], v[22:23], v[118:119], v[160:161]
	v_pk_fma_f32 v[246:247], v[24:25], v[120:121], v[246:247]
	v_pk_fma_f32 v[254:255], v[26:27], v[122:123], v[254:255]
	v_pk_fma_f32 v[160:161], v[28:29], v[124:125], v[160:161]
	v_pk_fma_f32 v[246:247], v[30:31], v[126:127], v[246:247]
	v_pk_add_f32 v[254:255], v[254:255], v[160:161]
	s_nop 0
	v_pk_add_f32 v[246:247], v[246:247], v[254:255]
	s_nop 0
	v_add_f32_e32 v165, v246, v247
	v_add_f32_dpp v162, v162, v162 row_shr:1 row_mask:0xf bank_mask:0xf bound_ctrl:1
	v_add_f32_dpp v163, v163, v163 row_shr:1 row_mask:0xf bank_mask:0xf bound_ctrl:1
	v_add_f32_dpp v164, v164, v164 row_shr:1 row_mask:0xf bank_mask:0xf bound_ctrl:1
	v_add_f32_dpp v165, v165, v165 row_shr:1 row_mask:0xf bank_mask:0xf bound_ctrl:1
	v_add_f32_dpp v162, v162, v162 row_shr:2 row_mask:0xf bank_mask:0xf bound_ctrl:1
	v_add_f32_dpp v163, v163, v163 row_shr:2 row_mask:0xf bank_mask:0xf bound_ctrl:1
	v_add_f32_dpp v164, v164, v164 row_shr:2 row_mask:0xf bank_mask:0xf bound_ctrl:1
	v_add_f32_dpp v165, v165, v165 row_shr:2 row_mask:0xf bank_mask:0xf bound_ctrl:1
	v_add_f32_dpp v162, v162, v162 row_shr:4 row_mask:0xf bank_mask:0xf bound_ctrl:1
	v_add_f32_dpp v163, v163, v163 row_shr:4 row_mask:0xf bank_mask:0xf bound_ctrl:1
	v_add_f32_dpp v164, v164, v164 row_shr:4 row_mask:0xf bank_mask:0xf bound_ctrl:1
	v_add_f32_dpp v165, v165, v165 row_shr:4 row_mask:0xf bank_mask:0xf bound_ctrl:1
	v_add_f32_dpp v162, v162, v162 row_shr:8 row_mask:0xf bank_mask:0xf bound_ctrl:1
	v_add_f32_dpp v163, v163, v163 row_shr:8 row_mask:0xf bank_mask:0xf bound_ctrl:1
	v_add_f32_dpp v164, v164, v164 row_shr:8 row_mask:0xf bank_mask:0xf bound_ctrl:1
	v_add_f32_dpp v165, v165, v165 row_shr:8 row_mask:0xf bank_mask:0xf bound_ctrl:1
	v_add_f32_dpp v162, v162, v162 row_bcast:15 row_mask:0xa bank_mask:0xf
	v_add_f32_dpp v163, v163, v163 row_bcast:15 row_mask:0xa bank_mask:0xf
	v_add_f32_dpp v164, v164, v164 row_bcast:15 row_mask:0xa bank_mask:0xf
	v_add_f32_dpp v165, v165, v165 row_bcast:15 row_mask:0xa bank_mask:0xf
	s_nop 1
	v_readlane_b32 s46, v162, 31
	v_readlane_b32 s47, v162, 63
	v_readlane_b32 s48, v163, 31
	v_readlane_b32 s49, v163, 63
	v_readlane_b32 s50, v164, 31
	v_readlane_b32 s51, v164, 63
	v_readlane_b32 s52, v165, 31
	v_readlane_b32 s53, v165, 63
	v_writelane_b32 v166, s46, 40
	s_nop 1
	v_writelane_b32 v166, s47, 41
	v_writelane_b32 v166, s48, 42
	v_writelane_b32 v166, s49, 43
	v_writelane_b32 v166, s50, 44
	v_writelane_b32 v166, s51, 45
	v_writelane_b32 v166, s52, 46
	v_writelane_b32 v166, s53, 47
	s_waitcnt vmcnt(14)
; __device__ void peer_gather_phase(const Params& P, int l, bool do_store) {
;     ...
;       for (int pr = 0; pr < 4; ++pr) {
;         v6u_t qv; qv[0] = u6[3 * pr].x; qv[1] = u6[3 * pr].y; qv[2] = u6[3 * pr + 1].x; qv[3] = u6[3 * pr + 1].y; qv[4] = u6[3 * pr + 2].x; qv[5] = u6[3 * pr + 2].y;
;         const v32f_t wv = __builtin_amdgcn_cvt_scalef32_pk32_f32_fp6(qv, 1.0f);
;         f32x2 a2 = f32x2{0.f, 0.f};
; #pragma unroll
;         for (int i = 0; i < 16; ++i) a2 += f32x2{wv[2 * i], wv[2 * i + 1]} * xu[i];
;         float hs = a2.x + a2.y;
;         hs += dpp_row_shr(hs, 1); hs += dpp_row_shr(hs, 2); hs += dpp_row_shr(hs, 4); hs += dpp_row_shr(hs, 8);
;         hs += __builtin_bit_cast(float, __builtin_amdgcn_update_dpp(0, __builtin_bit_cast(int, hs), 0x142, 0xa, 0xf, false));
;         const float da = __builtin_bit_cast(float, __builtin_amdgcn_readlane(__builtin_bit_cast(int, hs), 31));
;         const float db = __builtin_bit_cast(float, __builtin_amdgcn_readlane(__builtin_bit_cast(int, hs), 63));
;         dvec = (lane == kb + 2 * pr) ? da : dvec;
;         dvec = (lane == kb + 2 * pr + 1) ? db : dvec;
;       }
	v_cvt_scalef32_pk32_f32_fp6 v[0:31], v[50:55], 1.0
	v_pk_mul_f32 v[246:247], v[0:1], v[96:97]
	v_pk_mul_f32 v[254:255], v[2:3], v[98:99]
	v_pk_mul_f32 v[160:161], v[4:5], v[100:101]
	v_pk_fma_f32 v[246:247], v[6:7], v[102:103], v[246:247]
	v_pk_fma_f32 v[254:255], v[8:9], v[104:105], v[254:255]
	v_pk_fma_f32 v[160:161], v[10:11], v[106:107], v[160:161]
	v_pk_fma_f32 v[246:247], v[12:13], v[108:109], v[246:247]
	v_pk_fma_f32 v[254:255], v[14:15], v[110:111], v[254:255]
	v_pk_fma_f32 v[160:161], v[16:17], v[112:113], v[160:161]
	v_pk_fma_f32 v[246:247], v[18:19], v[114:115], v[246:247]
	v_pk_fma_f32 v[254:255], v[20:21], v[116:117], v[254:255]
	v_pk_fma_f32 v[160:161], v[22:23], v[118:119], v[160:161]
	v_pk_fma_f32 v[246:247], v[24:25], v[120:121], v[246:247]
	v_pk_fma_f32 v[254:255], v[26:27], v[122:123], v[254:255]
	v_pk_fma_f32 v[160:161], v[28:29], v[124:125], v[160:161]
	v_pk_fma_f32 v[246:247], v[30:31], v[126:127], v[246:247]
	v_pk_add_f32 v[254:255], v[254:255], v[160:161]
	s_nop 0
	v_pk_add_f32 v[246:247], v[246:247], v[254:255]
	s_nop 0
	v_add_f32_e32 v162, v246, v247
	s_waitcnt vmcnt(12)
	v_cvt_scalef32_pk32_f32_fp6 v[0:31], v[44:49], 1.0
	v_pk_mul_f32 v[246:247], v[0:1], v[96:97]
	v_pk_mul_f32 v[254:255], v[2:3], v[98:99]
	v_pk_mul_f32 v[160:161], v[4:5], v[100:101]
	v_pk_fma_f32 v[246:247], v[6:7], v[102:103], v[246:247]
	v_pk_fma_f32 v[254:255], v[8:9], v[104:105], v[254:255]
	v_pk_fma_f32 v[160:161], v[10:11], v[106:107], v[160:161]
	v_pk_fma_f32 v[246:247], v[12:13], v[108:109], v[246:247]
	v_pk_fma_f32 v[254:255], v[14:15], v[110:111], v[254:255]
	v_pk_fma_f32 v[160:161], v[16:17], v[112:113], v[160:161]
	v_pk_fma_f32 v[246:247], v[18:19], v[114:115], v[246:247]
	v_pk_fma_f32 v[254:255], v[20:21], v[116:117], v[254:255]
	v_pk_fma_f32 v[160:161], v[22:23], v[118:119], v[160:161]
	v_pk_fma_f32 v[246:247], v[24:25], v[120:121], v[246:247]
	v_pk_fma_f32 v[254:255], v[26:27], v[122:123], v[254:255]
	v_pk_fma_f32 v[160:161], v[28:29], v[124:125], v[160:161]
	v_pk_fma_f32 v[246:247], v[30:31], v[126:127], v[246:247]
	v_pk_add_f32 v[254:255], v[254:255], v[160:161]
	s_nop 0
	v_pk_add_f32 v[246:247], v[246:247], v[254:255]
	s_nop 0
	v_add_f32_e32 v163, v246, v247
	s_waitcnt vmcnt(10)
	v_cvt_scalef32_pk32_f32_fp6 v[0:31], v[38:43], 1.0
	v_pk_mul_f32 v[246:247], v[0:1], v[96:97]
	v_pk_mul_f32 v[254:255], v[2:3], v[98:99]
	v_pk_mul_f32 v[160:161], v[4:5], v[100:101]
	v_pk_fma_f32 v[246:247], v[6:7], v[102:103], v[246:247]
	v_pk_fma_f32 v[254:255], v[8:9], v[104:105], v[254:255]
	v_pk_fma_f32 v[160:161], v[10:11], v[106:107], v[160:161]
	v_pk_fma_f32 v[246:247], v[12:13], v[108:109], v[246:247]
	v_pk_fma_f32 v[254:255], v[14:15], v[110:111], v[254:255]
	v_pk_fma_f32 v[160:161], v[16:17], v[112:113], v[160:161]
	v_pk_fma_f32 v[246:247], v[18:19], v[114:115], v[246:247]
	v_pk_fma_f32 v[254:255], v[20:21], v[116:117], v[254:255]
	v_pk_fma_f32 v[160:161], v[22:23], v[118:119], v[160:161]
	v_pk_fma_f32 v[246:247], v[24:25], v[120:121], v[246:247]
	v_pk_fma_f32 v[254:255], v[26:27], v[122:123], v[254:255]
	v_pk_fma_f32 v[160:161], v[28:29], v[124:125], v[160:161]
	v_pk_fma_f32 v[246:247], v[30:31], v[126:127], v[246:247]
	v_pk_add_f32 v[254:255], v[254:255], v[160:161]
	s_nop 0
	v_pk_add_f32 v[246:247], v[246:247], v[254:255]
	s_nop 0
	v_add_f32_e32 v164, v246, v247
	s_waitcnt vmcnt(8)
	v_cvt_scalef32_pk32_f32_fp6 v[0:31], v[32:37], 1.0
	v_pk_mul_f32 v[246:247], v[0:1], v[96:97]
	v_pk_mul_f32 v[254:255], v[2:3], v[98:99]
	v_pk_mul_f32 v[160:161], v[4:5], v[100:101]
	v_pk_fma_f32 v[246:247], v[6:7], v[102:103], v[246:247]
	v_pk_fma_f32 v[254:255], v[8:9], v[104:105], v[254:255]
	v_pk_fma_f32 v[160:161], v[10:11], v[106:107], v[160:161]
	v_pk_fma_f32 v[246:247], v[12:13], v[108:109], v[246:247]
	v_pk_fma_f32 v[254:255], v[14:15], v[110:111], v[254:255]
	v_pk_fma_f32 v[160:161], v[16:17], v[112:113], v[160:161]
	v_pk_fma_f32 v[246:247], v[18:19], v[114:115], v[246:247]
	v_pk_fma_f32 v[254:255], v[20:21], v[116:117], v[254:255]
	v_pk_fma_f32 v[160:161], v[22:23], v[118:119], v[160:161]
	v_pk_fma_f32 v[246:247], v[24:25], v[120:121], v[246:247]
	v_pk_fma_f32 v[254:255], v[26:27], v[122:123], v[254:255]
	v_pk_fma_f32 v[160:161], v[28:29], v[124:125], v[160:161]
	v_pk_fma_f32 v[246:247], v[30:31], v[126:127], v[246:247]
	v_pk_add_f32 v[254:255], v[254:255], v[160:161]
	s_nop 0
	v_pk_add_f32 v[246:247], v[246:247], v[254:255]
	s_nop 0
	v_add_f32_e32 v165, v246, v247
	v_add_f32_dpp v162, v162, v162 row_shr:1 row_mask:0xf bank_mask:0xf bound_ctrl:1
	v_add_f32_dpp v163, v163, v163 row_shr:1 row_mask:0xf bank_mask:0xf bound_ctrl:1
	v_add_f32_dpp v164, v164, v164 row_shr:1 row_mask:0xf bank_mask:0xf bound_ctrl:1
	v_add_f32_dpp v165, v165, v165 row_shr:1 row_mask:0xf bank_mask:0xf bound_ctrl:1
	v_add_f32_dpp v162, v162, v162 row_shr:2 row_mask:0xf bank_mask:0xf bound_ctrl:1
	v_add_f32_dpp v163, v163, v163 row_shr:2 row_mask:0xf bank_mask:0xf bound_ctrl:1
	v_add_f32_dpp v164, v164, v164 row_shr:2 row_mask:0xf bank_mask:0xf bound_ctrl:1
	v_add_f32_dpp v165, v165, v165 row_shr:2 row_mask:0xf bank_mask:0xf bound_ctrl:1
	v_add_f32_dpp v162, v162, v162 row_shr:4 row_mask:0xf bank_mask:0xf bound_ctrl:1
	v_add_f32_dpp v163, v163, v163 row_shr:4 row_mask:0xf bank_mask:0xf bound_ctrl:1
	v_add_f32_dpp v164, v164, v164 row_shr:4 row_mask:0xf bank_mask:0xf bound_ctrl:1
	v_add_f32_dpp v165, v165, v165 row_shr:4 row_mask:0xf bank_mask:0xf bound_ctrl:1
	v_add_f32_dpp v162, v162, v162 row_shr:8 row_mask:0xf bank_mask:0xf bound_ctrl:1
	v_add_f32_dpp v163, v163, v163 row_shr:8 row_mask:0xf bank_mask:0xf bound_ctrl:1
	v_add_f32_dpp v164, v164, v164 row_shr:8 row_mask:0xf bank_mask:0xf bound_ctrl:1
	v_add_f32_dpp v165, v165, v165 row_shr:8 row_mask:0xf bank_mask:0xf bound_ctrl:1
	v_add_f32_dpp v162, v162, v162 row_bcast:15 row_mask:0xa bank_mask:0xf
	v_add_f32_dpp v163, v163, v163 row_bcast:15 row_mask:0xa bank_mask:0xf
	v_add_f32_dpp v164, v164, v164 row_bcast:15 row_mask:0xa bank_mask:0xf
	v_add_f32_dpp v165, v165, v165 row_bcast:15 row_mask:0xa bank_mask:0xf
	s_nop 1
	v_readlane_b32 s46, v162, 31
	v_readlane_b32 s47, v162, 63
	v_readlane_b32 s48, v163, 31
	v_readlane_b32 s49, v163, 63
	v_readlane_b32 s50, v164, 31
	v_readlane_b32 s51, v164, 63
	v_readlane_b32 s52, v165, 31
	v_readlane_b32 s53, v165, 63
	v_writelane_b32 v166, s46, 48
	s_nop 1
	v_writelane_b32 v166, s47, 49
	v_writelane_b32 v166, s48, 50
	v_writelane_b32 v166, s49, 51
	v_writelane_b32 v166, s50, 52
	v_writelane_b32 v166, s51, 53
	v_writelane_b32 v166, s52, 54
	v_writelane_b32 v166, s53, 55
	s_waitcnt vmcnt(6)
; __device__ void peer_gather_phase(const Params& P, int l, bool do_store) {
;     ...
;       for (int pr = 0; pr < 4; ++pr) {
;         v6u_t qv; qv[0] = u6[3 * pr].x; qv[1] = u6[3 * pr].y; qv[2] = u6[3 * pr + 1].x; qv[3] = u6[3 * pr + 1].y; qv[4] = u6[3 * pr + 2].x; qv[5] = u6[3 * pr + 2].y;
;         const v32f_t wv = __builtin_amdgcn_cvt_scalef32_pk32_f32_fp6(qv, 1.0f);
;         f32x2 a2 = f32x2{0.f, 0.f};
; #pragma unroll
;         for (int i = 0; i < 16; ++i) a2 += f32x2{wv[2 * i], wv[2 * i + 1]} * xu[i];
;         float hs = a2.x + a2.y;
;         hs += dpp_row_shr(hs, 1); hs += dpp_row_shr(hs, 2); hs += dpp_row_shr(hs, 4); hs += dpp_row_shr(hs, 8);
;         hs += __builtin_bit_cast(float, __builtin_amdgcn_update_dpp(0, __builtin_bit_cast(int, hs), 0x142, 0xa, 0xf, false));
;         const float da = __builtin_bit_cast(float, __builtin_amdgcn_readlane(__builtin_bit_cast(int, hs), 31));
;         const float db = __builtin_bit_cast(float, __builtin_amdgcn_readlane(__builtin_bit_cast(int, hs), 63));
;         dvec = (lane == kb + 2 * pr) ? da : dvec;
;         dvec = (lane == kb + 2 * pr + 1) ? db : dvec;
	v_cvt_scalef32_pk32_f32_fp6 v[0:31], v[196:201], 1.0
	v_pk_mul_f32 v[246:247], v[0:1], v[96:97]
	v_pk_mul_f32 v[254:255], v[2:3], v[98:99]
	v_pk_mul_f32 v[160:161], v[4:5], v[100:101]
	v_pk_fma_f32 v[246:247], v[6:7], v[102:103], v[246:247]
	v_pk_fma_f32 v[254:255], v[8:9], v[104:105], v[254:255]
	v_pk_fma_f32 v[160:161], v[10:11], v[106:107], v[160:161]
	v_pk_fma_f32 v[246:247], v[12:13], v[108:109], v[246:247]
	v_pk_fma_f32 v[254:255], v[14:15], v[110:111], v[254:255]
	v_pk_fma_f32 v[160:161], v[16:17], v[112:113], v[160:161]
	v_pk_fma_f32 v[246:247], v[18:19], v[114:115], v[246:247]
	v_pk_fma_f32 v[254:255], v[20:21], v[116:117], v[254:255]
	v_pk_fma_f32 v[160:161], v[22:23], v[118:119], v[160:161]
	v_pk_fma_f32 v[246:247], v[24:25], v[120:121], v[246:247]
	v_pk_fma_f32 v[254:255], v[26:27], v[122:123], v[254:255]
	v_pk_fma_f32 v[160:161], v[28:29], v[124:125], v[160:161]
	v_pk_fma_f32 v[246:247], v[30:31], v[126:127], v[246:247]
	v_pk_add_f32 v[254:255], v[254:255], v[160:161]
	s_nop 0
	v_pk_add_f32 v[246:247], v[246:247], v[254:255]
	s_nop 0
	v_add_f32_e32 v162, v246, v247
	s_waitcnt vmcnt(4)
	v_cvt_scalef32_pk32_f32_fp6 v[0:31], v[228:233], 1.0
	v_pk_mul_f32 v[246:247], v[0:1], v[96:97]
	v_pk_mul_f32 v[254:255], v[2:3], v[98:99]
	v_pk_mul_f32 v[160:161], v[4:5], v[100:101]
	v_pk_fma_f32 v[246:247], v[6:7], v[102:103], v[246:247]
	v_pk_fma_f32 v[254:255], v[8:9], v[104:105], v[254:255]
	v_pk_fma_f32 v[160:161], v[10:11], v[106:107], v[160:161]
	v_pk_fma_f32 v[246:247], v[12:13], v[108:109], v[246:247]
	v_pk_fma_f32 v[254:255], v[14:15], v[110:111], v[254:255]
	v_pk_fma_f32 v[160:161], v[16:17], v[112:113], v[160:161]
	v_pk_fma_f32 v[246:247], v[18:19], v[114:115], v[246:247]
	v_pk_fma_f32 v[254:255], v[20:21], v[116:117], v[254:255]
	v_pk_fma_f32 v[160:161], v[22:23], v[118:119], v[160:161]
	v_pk_fma_f32 v[246:247], v[24:25], v[120:121], v[246:247]
	v_pk_fma_f32 v[254:255], v[26:27], v[122:123], v[254:255]
	v_pk_fma_f32 v[160:161], v[28:29], v[124:125], v[160:161]
	v_pk_fma_f32 v[246:247], v[30:31], v[126:127], v[246:247]
	v_pk_add_f32 v[254:255], v[254:255], v[160:161]
	s_nop 0
	v_pk_add_f32 v[246:247], v[246:247], v[254:255]
	s_nop 0
	v_add_f32_e32 v163, v246, v247
	s_waitcnt vmcnt(2)
	v_cvt_scalef32_pk32_f32_fp6 v[0:31], v[234:239], 1.0
	v_pk_mul_f32 v[246:247], v[0:1], v[96:97]
	v_pk_mul_f32 v[254:255], v[2:3], v[98:99]
	v_pk_mul_f32 v[160:161], v[4:5], v[100:101]
	v_pk_fma_f32 v[246:247], v[6:7], v[102:103], v[246:247]
	v_pk_fma_f32 v[254:255], v[8:9], v[104:105], v[254:255]
	v_pk_fma_f32 v[160:161], v[10:11], v[106:107], v[160:161]
	v_pk_fma_f32 v[246:247], v[12:13], v[108:109], v[246:247]
	v_pk_fma_f32 v[254:255], v[14:15], v[110:111], v[254:255]
	v_pk_fma_f32 v[160:161], v[16:17], v[112:113], v[160:161]
	v_pk_fma_f32 v[246:247], v[18:19], v[114:115], v[246:247]
	v_pk_fma_f32 v[254:255], v[20:21], v[116:117], v[254:255]
	v_pk_fma_f32 v[160:161], v[22:23], v[118:119], v[160:161]
	v_pk_fma_f32 v[246:247], v[24:25], v[120:121], v[246:247]
	v_pk_fma_f32 v[254:255], v[26:27], v[122:123], v[254:255]
	v_pk_fma_f32 v[160:161], v[28:29], v[124:125], v[160:161]
	v_pk_fma_f32 v[246:247], v[30:31], v[126:127], v[246:247]
	v_pk_add_f32 v[254:255], v[254:255], v[160:161]
	s_nop 0
	v_pk_add_f32 v[246:247], v[246:247], v[254:255]
	s_nop 0
	v_add_f32_e32 v164, v246, v247
	s_waitcnt vmcnt(0)
	v_cvt_scalef32_pk32_f32_fp6 v[0:31], v[240:245], 1.0
	v_pk_mul_f32 v[246:247], v[0:1], v[96:97]
	v_pk_mul_f32 v[254:255], v[2:3], v[98:99]
	v_pk_mul_f32 v[160:161], v[4:5], v[100:101]
	v_pk_fma_f32 v[246:247], v[6:7], v[102:103], v[246:247]
	v_pk_fma_f32 v[254:255], v[8:9], v[104:105], v[254:255]
	v_pk_fma_f32 v[160:161], v[10:11], v[106:107], v[160:161]
	v_pk_fma_f32 v[246:247], v[12:13], v[108:109], v[246:247]
	v_pk_fma_f32 v[254:255], v[14:15], v[110:111], v[254:255]
	v_pk_fma_f32 v[160:161], v[16:17], v[112:113], v[160:161]
	v_pk_fma_f32 v[246:247], v[18:19], v[114:115], v[246:247]
	v_pk_fma_f32 v[254:255], v[20:21], v[116:117], v[254:255]
	v_pk_fma_f32 v[160:161], v[22:23], v[118:119], v[160:161]
	v_pk_fma_f32 v[246:247], v[24:25], v[120:121], v[246:247]
	v_pk_fma_f32 v[254:255], v[26:27], v[122:123], v[254:255]
	v_pk_fma_f32 v[160:161], v[28:29], v[124:125], v[160:161]
	v_pk_fma_f32 v[246:247], v[30:31], v[126:127], v[246:247]
	v_pk_add_f32 v[254:255], v[254:255], v[160:161]
	s_nop 0
	v_pk_add_f32 v[246:247], v[246:247], v[254:255]
	s_nop 0
	v_add_f32_e32 v165, v246, v247
	v_add_f32_dpp v162, v162, v162 row_shr:1 row_mask:0xf bank_mask:0xf bound_ctrl:1
	v_add_f32_dpp v163, v163, v163 row_shr:1 row_mask:0xf bank_mask:0xf bound_ctrl:1
	v_add_f32_dpp v164, v164, v164 row_shr:1 row_mask:0xf bank_mask:0xf bound_ctrl:1
	v_add_f32_dpp v165, v165, v165 row_shr:1 row_mask:0xf bank_mask:0xf bound_ctrl:1
	v_add_f32_dpp v162, v162, v162 row_shr:2 row_mask:0xf bank_mask:0xf bound_ctrl:1
	v_add_f32_dpp v163, v163, v163 row_shr:2 row_mask:0xf bank_mask:0xf bound_ctrl:1
	v_add_f32_dpp v164, v164, v164 row_shr:2 row_mask:0xf bank_mask:0xf bound_ctrl:1
	v_add_f32_dpp v165, v165, v165 row_shr:2 row_mask:0xf bank_mask:0xf bound_ctrl:1
	v_add_f32_dpp v162, v162, v162 row_shr:4 row_mask:0xf bank_mask:0xf bound_ctrl:1
	v_add_f32_dpp v163, v163, v163 row_shr:4 row_mask:0xf bank_mask:0xf bound_ctrl:1
	v_add_f32_dpp v164, v164, v164 row_shr:4 row_mask:0xf bank_mask:0xf bound_ctrl:1
	v_add_f32_dpp v165, v165, v165 row_shr:4 row_mask:0xf bank_mask:0xf bound_ctrl:1
	v_add_f32_dpp v162, v162, v162 row_shr:8 row_mask:0xf bank_mask:0xf bound_ctrl:1
	v_add_f32_dpp v163, v163, v163 row_shr:8 row_mask:0xf bank_mask:0xf bound_ctrl:1
	v_add_f32_dpp v164, v164, v164 row_shr:8 row_mask:0xf bank_mask:0xf bound_ctrl:1
; DEV float gelu_t(float x) {
;   float z = 0.7978845608028654f * (x + 0.044715f * x * x * x);
;   float e = __expf(2.f * z);
;   float th = 1.f - 2.f / (e + 1.f);
;   return 0.5f * x * (1.f + th);
; }
; __device__ void peer_gather_phase(const Params& P, int l, bool do_store) {
;     ...
;         hs += dpp_row_shr(hs, 1); hs += dpp_row_shr(hs, 2); hs += dpp_row_shr(hs, 4); hs += dpp_row_shr(hs, 8);
;         hs += __builtin_bit_cast(float, __builtin_amdgcn_update_dpp(0, __builtin_bit_cast(int, hs), 0x142, 0xa, 0xf, false));
;         const float da = __builtin_bit_cast(float, __builtin_amdgcn_readlane(__builtin_bit_cast(int, hs), 31));
;         const float db = __builtin_bit_cast(float, __builtin_amdgcn_readlane(__builtin_bit_cast(int, hs), 63));
;         dvec = (lane == kb + 2 * pr) ? da : dvec;
;         dvec = (lane == kb + 2 * pr + 1) ? db : dvec;
;       }
;       const float sux = (bt < 8) ? sux0 : sux1;
;       const float gsx = (bt < 8) ? gsx0 : gsx1;
;       const float avec = gelu_t(dvec * sux) * gsx;
; #pragma unroll
;       for (int j = 0; j < 8; ++j) {
;         const float a = __builtin_bit_cast(float, __builtin_amdgcn_readlane(__builtin_bit_cast(int, avec), kb + j));
;         const f32x2 aa = f32x2{a, a};
;         y[0] += aa * __builtin_amdgcn_cvt_scalef32_pk_f32_fp4(v8[j].x, 1.0f, 0); y[1] += aa * __builtin_amdgcn_cvt_scalef32_pk_f32_fp4(v8[j].x, 1.0f, 1);
;         y[2] += aa * __builtin_amdgcn_cvt_scalef32_pk_f32_fp4(v8[j].x, 1.0f, 2); y[3] += aa * __builtin_amdgcn_cvt_scalef32_pk_f32_fp4(v8[j].x, 1.0f, 3);
;         y[4] += aa * __builtin_amdgcn_cvt_scalef32_pk_f32_fp4(v8[j].y, 1.0f, 0); y[5] += aa * __builtin_amdgcn_cvt_scalef32_pk_f32_fp4(v8[j].y, 1.0f, 1);
;         y[6] += aa * __builtin_amdgcn_cvt_scalef32_pk_f32_fp4(v8[j].y, 1.0f, 2); y[7] += aa * __builtin_amdgcn_cvt_scalef32_pk_f32_fp4(v8[j].y, 1.0f, 3);
;       }
	v_add_f32_dpp v165, v165, v165 row_shr:8 row_mask:0xf bank_mask:0xf bound_ctrl:1
	v_add_f32_dpp v162, v162, v162 row_bcast:15 row_mask:0xa bank_mask:0xf
	v_add_f32_dpp v163, v163, v163 row_bcast:15 row_mask:0xa bank_mask:0xf
	v_add_f32_dpp v164, v164, v164 row_bcast:15 row_mask:0xa bank_mask:0xf
	v_add_f32_dpp v165, v165, v165 row_bcast:15 row_mask:0xa bank_mask:0xf
	s_nop 1
	v_readlane_b32 s46, v162, 31
	v_readlane_b32 s47, v162, 63
	v_readlane_b32 s48, v163, 31
	v_readlane_b32 s49, v163, 63
	v_readlane_b32 s50, v164, 31
	v_readlane_b32 s51, v164, 63
	v_readlane_b32 s52, v165, 31
	v_readlane_b32 s53, v165, 63
	v_writelane_b32 v166, s46, 56
	s_nop 1
	v_writelane_b32 v166, s47, 57
	v_writelane_b32 v166, s48, 58
	v_writelane_b32 v166, s49, 59
	v_writelane_b32 v166, s50, 60
	v_writelane_b32 v166, s51, 61
	v_writelane_b32 v166, s52, 62
	v_writelane_b32 v166, s53, 63
	s_nop 1
	v_mul_f32_e32 v0, v190, v166
	v_mul_f32_e32 v1, 0x3d372713, v0
	v_mul_f32_e32 v1, v0, v1
	v_fma_f32 v1, v0, v1, v0
	v_mul_f32_e32 v1, 0x3f4c422a, v1
	v_add_f32_e32 v1, v1, v1
	v_mul_f32_e32 v1, 0x3fb8aa3b, v1
	v_exp_f32_e32 v1, v1
	v_mul_f32_e32 v0, 0.5, v0
	v_add_f32_e32 v1, 1.0, v1
	v_div_scale_f32 v2, s[0:1], v1, v1, 2.0
	v_rcp_f32_e32 v3, v2
	s_nop 0
	v_fma_f32 v4, -v2, v3, 1.0
	v_fmac_f32_e32 v3, v4, v3
	v_div_scale_f32 v4, vcc, 2.0, v1, 2.0
	v_mul_f32_e32 v5, v4, v3
	v_fma_f32 v6, -v2, v5, v4
	v_fmac_f32_e32 v5, v6, v3
	v_fma_f32 v2, -v2, v5, v4
	v_div_fmas_f32 v2, v2, v3, v5
	v_div_fixup_f32 v1, v2, v1, 2.0
	v_sub_f32_e32 v1, 1.0, v1
	v_add_f32_e32 v1, 1.0, v1
	v_mul_f32_e32 v0, v0, v1
	v_mul_f32_e32 v167, v192, v0
	s_nop 1
	v_readlane_b32 s0, v167, 0
	s_waitcnt vmcnt(48)
	v_cvt_scalef32_pk_f32_fp4 v[0:1], v144, 1.0
	v_cvt_scalef32_pk_f32_fp4 v[2:3], v144, 1.0 op_sel:[1,0,0]
	v_cvt_scalef32_pk_f32_fp4 v[4:5], v144, 1.0 op_sel:[0,1,0]
	v_cvt_scalef32_pk_f32_fp4 v[6:7], v144, 1.0 op_sel:[1,1,0]
	v_cvt_scalef32_pk_f32_fp4 v[8:9], v145, 1.0
	v_cvt_scalef32_pk_f32_fp4 v[10:11], v145, 1.0 op_sel:[1,0,0]
	v_cvt_scalef32_pk_f32_fp4 v[12:13], v145, 1.0 op_sel:[0,1,0]
	v_cvt_scalef32_pk_f32_fp4 v[14:15], v145, 1.0 op_sel:[1,1,0]
	v_readlane_b32 s54, v90, 16
	s_lshl_b32 s56, s54, 9
	s_add_u32 s56, s64, s56
	s_addc_u32 s57, s65, 0
	global_load_dwordx2 v[144:145], v227, s[56:57]
	v_pk_fma_f32 v[130:131], v[0:1], s[0:1], v[130:131] op_sel_hi:[1,0,1]
	v_pk_fma_f32 v[138:139], v[2:3], s[0:1], v[138:139] op_sel_hi:[1,0,1]
	v_pk_fma_f32 v[140:141], v[4:5], s[0:1], v[140:141] op_sel_hi:[1,0,1]
	v_pk_fma_f32 v[142:143], v[6:7], s[0:1], v[142:143] op_sel_hi:[1,0,1]
	v_pk_fma_f32 v[128:129], v[8:9], s[0:1], v[128:129] op_sel_hi:[1,0,1]
	v_pk_fma_f32 v[132:133], v[10:11], s[0:1], v[132:133] op_sel_hi:[1,0,1]
	v_pk_fma_f32 v[134:135], v[12:13], s[0:1], v[134:135] op_sel_hi:[1,0,1]
	v_pk_fma_f32 v[136:137], v[14:15], s[0:1], v[136:137] op_sel_hi:[1,0,1]
	v_readlane_b32 s0, v167, 1
	s_waitcnt vmcnt(48)
	v_cvt_scalef32_pk_f32_fp4 v[0:1], v146, 1.0
	v_cvt_scalef32_pk_f32_fp4 v[2:3], v146, 1.0 op_sel:[1,0,0]
	v_cvt_scalef32_pk_f32_fp4 v[4:5], v146, 1.0 op_sel:[0,1,0]
	v_cvt_scalef32_pk_f32_fp4 v[6:7], v146, 1.0 op_sel:[1,1,0]
	v_cvt_scalef32_pk_f32_fp4 v[8:9], v147, 1.0
	v_cvt_scalef32_pk_f32_fp4 v[10:11], v147, 1.0 op_sel:[1,0,0]
	v_cvt_scalef32_pk_f32_fp4 v[12:13], v147, 1.0 op_sel:[0,1,0]
	v_cvt_scalef32_pk_f32_fp4 v[14:15], v147, 1.0 op_sel:[1,1,0]
	v_readlane_b32 s54, v90, 17
	s_lshl_b32 s56, s54, 9
	s_add_u32 s56, s64, s56
	s_addc_u32 s57, s65, 0
	global_load_dwordx2 v[146:147], v227, s[56:57]
	v_pk_fma_f32 v[130:131], v[0:1], s[0:1], v[130:131] op_sel_hi:[1,0,1]
	v_pk_fma_f32 v[138:139], v[2:3], s[0:1], v[138:139] op_sel_hi:[1,0,1]
	v_pk_fma_f32 v[140:141], v[4:5], s[0:1], v[140:141] op_sel_hi:[1,0,1]
	v_pk_fma_f32 v[142:143], v[6:7], s[0:1], v[142:143] op_sel_hi:[1,0,1]
	v_pk_fma_f32 v[128:129], v[8:9], s[0:1], v[128:129] op_sel_hi:[1,0,1]
	v_pk_fma_f32 v[132:133], v[10:11], s[0:1], v[132:133] op_sel_hi:[1,0,1]
	v_pk_fma_f32 v[134:135], v[12:13], s[0:1], v[134:135] op_sel_hi:[1,0,1]
	v_pk_fma_f32 v[136:137], v[14:15], s[0:1], v[136:137] op_sel_hi:[1,0,1]
	v_readlane_b32 s0, v167, 2
	s_waitcnt vmcnt(48)
	v_cvt_scalef32_pk_f32_fp4 v[0:1], v148, 1.0
	v_cvt_scalef32_pk_f32_fp4 v[2:3], v148, 1.0 op_sel:[1,0,0]
	v_cvt_scalef32_pk_f32_fp4 v[4:5], v148, 1.0 op_sel:[0,1,0]
	v_cvt_scalef32_pk_f32_fp4 v[6:7], v148, 1.0 op_sel:[1,1,0]
	v_cvt_scalef32_pk_f32_fp4 v[8:9], v149, 1.0
	v_cvt_scalef32_pk_f32_fp4 v[10:11], v149, 1.0 op_sel:[1,0,0]
	v_cvt_scalef32_pk_f32_fp4 v[12:13], v149, 1.0 op_sel:[0,1,0]
	v_cvt_scalef32_pk_f32_fp4 v[14:15], v149, 1.0 op_sel:[1,1,0]
	v_readlane_b32 s54, v90, 18
	s_lshl_b32 s56, s54, 9
	s_add_u32 s56, s64, s56
	s_addc_u32 s57, s65, 0
	global_load_dwordx2 v[148:149], v227, s[56:57]
	v_pk_fma_f32 v[130:131], v[0:1], s[0:1], v[130:131] op_sel_hi:[1,0,1]
	v_pk_fma_f32 v[138:139], v[2:3], s[0:1], v[138:139] op_sel_hi:[1,0,1]
	v_pk_fma_f32 v[140:141], v[4:5], s[0:1], v[140:141] op_sel_hi:[1,0,1]
	v_pk_fma_f32 v[142:143], v[6:7], s[0:1], v[142:143] op_sel_hi:[1,0,1]
	v_pk_fma_f32 v[128:129], v[8:9], s[0:1], v[128:129] op_sel_hi:[1,0,1]
	v_pk_fma_f32 v[132:133], v[10:11], s[0:1], v[132:133] op_sel_hi:[1,0,1]
	v_pk_fma_f32 v[134:135], v[12:13], s[0:1], v[134:135] op_sel_hi:[1,0,1]
	v_pk_fma_f32 v[136:137], v[14:15], s[0:1], v[136:137] op_sel_hi:[1,0,1]
	v_readlane_b32 s0, v167, 3
	s_waitcnt vmcnt(48)
; __device__ void peer_gather_phase(const Params& P, int l, bool do_store) {
;     ...
;         const uint2* up = (const uint2*)(U + (size_t)(uphi ? eb : ea) * 768);
;         u6[3 * pr] = up[0]; u6[3 * pr + 1] = up[1]; u6[3 * pr + 2] = up[2];
;         v8[2 * pr] = *(const uint2*)(V + (size_t)ea * 512);
;         v8[2 * pr + 1] = *(const uint2*)(V + (size_t)eb * 512);
;     ...
; #pragma unroll
;       for (int j = 0; j < 8; ++j) {
;         const float a = __builtin_bit_cast(float, __builtin_amdgcn_readlane(__builtin_bit_cast(int, avec), kb + j));
;         const f32x2 aa = f32x2{a, a};
;         y[0] += aa * __builtin_amdgcn_cvt_scalef32_pk_f32_fp4(v8[j].x, 1.0f, 0); y[1] += aa * __builtin_amdgcn_cvt_scalef32_pk_f32_fp4(v8[j].x, 1.0f, 1);
;         y[2] += aa * __builtin_amdgcn_cvt_scalef32_pk_f32_fp4(v8[j].x, 1.0f, 2); y[3] += aa * __builtin_amdgcn_cvt_scalef32_pk_f32_fp4(v8[j].x, 1.0f, 3);
;         y[4] += aa * __builtin_amdgcn_cvt_scalef32_pk_f32_fp4(v8[j].y, 1.0f, 0); y[5] += aa * __builtin_amdgcn_cvt_scalef32_pk_f32_fp4(v8[j].y, 1.0f, 1);
;         y[6] += aa * __builtin_amdgcn_cvt_scalef32_pk_f32_fp4(v8[j].y, 1.0f, 2); y[7] += aa * __builtin_amdgcn_cvt_scalef32_pk_f32_fp4(v8[j].y, 1.0f, 3);
;       }
	v_cvt_scalef32_pk_f32_fp4 v[0:1], v150, 1.0
	v_cvt_scalef32_pk_f32_fp4 v[2:3], v150, 1.0 op_sel:[1,0,0]
	v_cvt_scalef32_pk_f32_fp4 v[4:5], v150, 1.0 op_sel:[0,1,0]
	v_cvt_scalef32_pk_f32_fp4 v[6:7], v150, 1.0 op_sel:[1,1,0]
	v_cvt_scalef32_pk_f32_fp4 v[8:9], v151, 1.0
	v_cvt_scalef32_pk_f32_fp4 v[10:11], v151, 1.0 op_sel:[1,0,0]
	v_cvt_scalef32_pk_f32_fp4 v[12:13], v151, 1.0 op_sel:[0,1,0]
	v_cvt_scalef32_pk_f32_fp4 v[14:15], v151, 1.0 op_sel:[1,1,0]
	v_readlane_b32 s54, v90, 19
	s_lshl_b32 s56, s54, 9
	s_add_u32 s56, s64, s56
	s_addc_u32 s57, s65, 0
	global_load_dwordx2 v[150:151], v227, s[56:57]
	v_pk_fma_f32 v[130:131], v[0:1], s[0:1], v[130:131] op_sel_hi:[1,0,1]
	v_pk_fma_f32 v[138:139], v[2:3], s[0:1], v[138:139] op_sel_hi:[1,0,1]
	v_pk_fma_f32 v[140:141], v[4:5], s[0:1], v[140:141] op_sel_hi:[1,0,1]
	v_pk_fma_f32 v[142:143], v[6:7], s[0:1], v[142:143] op_sel_hi:[1,0,1]
	v_pk_fma_f32 v[128:129], v[8:9], s[0:1], v[128:129] op_sel_hi:[1,0,1]
	v_pk_fma_f32 v[132:133], v[10:11], s[0:1], v[132:133] op_sel_hi:[1,0,1]
	v_pk_fma_f32 v[134:135], v[12:13], s[0:1], v[134:135] op_sel_hi:[1,0,1]
	v_pk_fma_f32 v[136:137], v[14:15], s[0:1], v[136:137] op_sel_hi:[1,0,1]
	v_readlane_b32 s0, v167, 4
	s_waitcnt vmcnt(48)
	v_cvt_scalef32_pk_f32_fp4 v[0:1], v152, 1.0
	v_cvt_scalef32_pk_f32_fp4 v[2:3], v152, 1.0 op_sel:[1,0,0]
	v_cvt_scalef32_pk_f32_fp4 v[4:5], v152, 1.0 op_sel:[0,1,0]
	v_cvt_scalef32_pk_f32_fp4 v[6:7], v152, 1.0 op_sel:[1,1,0]
	v_cvt_scalef32_pk_f32_fp4 v[8:9], v153, 1.0
	v_cvt_scalef32_pk_f32_fp4 v[10:11], v153, 1.0 op_sel:[1,0,0]
	v_cvt_scalef32_pk_f32_fp4 v[12:13], v153, 1.0 op_sel:[0,1,0]
	v_cvt_scalef32_pk_f32_fp4 v[14:15], v153, 1.0 op_sel:[1,1,0]
	v_readlane_b32 s54, v90, 20
	s_lshl_b32 s56, s54, 9
	s_add_u32 s56, s64, s56
	s_addc_u32 s57, s65, 0
	global_load_dwordx2 v[152:153], v227, s[56:57]
	v_pk_fma_f32 v[130:131], v[0:1], s[0:1], v[130:131] op_sel_hi:[1,0,1]
	v_pk_fma_f32 v[138:139], v[2:3], s[0:1], v[138:139] op_sel_hi:[1,0,1]
	v_pk_fma_f32 v[140:141], v[4:5], s[0:1], v[140:141] op_sel_hi:[1,0,1]
	v_pk_fma_f32 v[142:143], v[6:7], s[0:1], v[142:143] op_sel_hi:[1,0,1]
	v_pk_fma_f32 v[128:129], v[8:9], s[0:1], v[128:129] op_sel_hi:[1,0,1]
	v_pk_fma_f32 v[132:133], v[10:11], s[0:1], v[132:133] op_sel_hi:[1,0,1]
	v_pk_fma_f32 v[134:135], v[12:13], s[0:1], v[134:135] op_sel_hi:[1,0,1]
	v_pk_fma_f32 v[136:137], v[14:15], s[0:1], v[136:137] op_sel_hi:[1,0,1]
	v_readlane_b32 s0, v167, 5
	s_waitcnt vmcnt(48)
	v_cvt_scalef32_pk_f32_fp4 v[0:1], v154, 1.0
	v_cvt_scalef32_pk_f32_fp4 v[2:3], v154, 1.0 op_sel:[1,0,0]
	v_cvt_scalef32_pk_f32_fp4 v[4:5], v154, 1.0 op_sel:[0,1,0]
	v_cvt_scalef32_pk_f32_fp4 v[6:7], v154, 1.0 op_sel:[1,1,0]
	v_cvt_scalef32_pk_f32_fp4 v[8:9], v155, 1.0
	v_cvt_scalef32_pk_f32_fp4 v[10:11], v155, 1.0 op_sel:[1,0,0]
	v_cvt_scalef32_pk_f32_fp4 v[12:13], v155, 1.0 op_sel:[0,1,0]
	v_cvt_scalef32_pk_f32_fp4 v[14:15], v155, 1.0 op_sel:[1,1,0]
	v_readlane_b32 s54, v90, 21
	s_lshl_b32 s56, s54, 9
	s_add_u32 s56, s64, s56
	s_addc_u32 s57, s65, 0
	global_load_dwordx2 v[154:155], v227, s[56:57]
	v_pk_fma_f32 v[130:131], v[0:1], s[0:1], v[130:131] op_sel_hi:[1,0,1]
	v_pk_fma_f32 v[138:139], v[2:3], s[0:1], v[138:139] op_sel_hi:[1,0,1]
	v_pk_fma_f32 v[140:141], v[4:5], s[0:1], v[140:141] op_sel_hi:[1,0,1]
	v_pk_fma_f32 v[142:143], v[6:7], s[0:1], v[142:143] op_sel_hi:[1,0,1]
	v_pk_fma_f32 v[128:129], v[8:9], s[0:1], v[128:129] op_sel_hi:[1,0,1]
	v_pk_fma_f32 v[132:133], v[10:11], s[0:1], v[132:133] op_sel_hi:[1,0,1]
	v_pk_fma_f32 v[134:135], v[12:13], s[0:1], v[134:135] op_sel_hi:[1,0,1]
	v_pk_fma_f32 v[136:137], v[14:15], s[0:1], v[136:137] op_sel_hi:[1,0,1]
	v_readlane_b32 s0, v167, 6
	s_waitcnt vmcnt(48)
	v_cvt_scalef32_pk_f32_fp4 v[0:1], v156, 1.0
	v_cvt_scalef32_pk_f32_fp4 v[2:3], v156, 1.0 op_sel:[1,0,0]
	v_cvt_scalef32_pk_f32_fp4 v[4:5], v156, 1.0 op_sel:[0,1,0]
	v_cvt_scalef32_pk_f32_fp4 v[6:7], v156, 1.0 op_sel:[1,1,0]
	v_cvt_scalef32_pk_f32_fp4 v[8:9], v157, 1.0
	v_cvt_scalef32_pk_f32_fp4 v[10:11], v157, 1.0 op_sel:[1,0,0]
	v_cvt_scalef32_pk_f32_fp4 v[12:13], v157, 1.0 op_sel:[0,1,0]
	v_cvt_scalef32_pk_f32_fp4 v[14:15], v157, 1.0 op_sel:[1,1,0]
	v_readlane_b32 s54, v90, 22
	s_lshl_b32 s56, s54, 9
	s_add_u32 s56, s64, s56
	s_addc_u32 s57, s65, 0
	global_load_dwordx2 v[156:157], v227, s[56:57]
	v_pk_fma_f32 v[130:131], v[0:1], s[0:1], v[130:131] op_sel_hi:[1,0,1]
	v_pk_fma_f32 v[138:139], v[2:3], s[0:1], v[138:139] op_sel_hi:[1,0,1]
	v_pk_fma_f32 v[140:141], v[4:5], s[0:1], v[140:141] op_sel_hi:[1,0,1]
	v_pk_fma_f32 v[142:143], v[6:7], s[0:1], v[142:143] op_sel_hi:[1,0,1]
	v_pk_fma_f32 v[128:129], v[8:9], s[0:1], v[128:129] op_sel_hi:[1,0,1]
	v_pk_fma_f32 v[132:133], v[10:11], s[0:1], v[132:133] op_sel_hi:[1,0,1]
	v_pk_fma_f32 v[134:135], v[12:13], s[0:1], v[134:135] op_sel_hi:[1,0,1]
	v_pk_fma_f32 v[136:137], v[14:15], s[0:1], v[136:137] op_sel_hi:[1,0,1]
	v_readlane_b32 s0, v167, 7
	s_waitcnt vmcnt(48)
	v_cvt_scalef32_pk_f32_fp4 v[0:1], v158, 1.0
	v_cvt_scalef32_pk_f32_fp4 v[2:3], v158, 1.0 op_sel:[1,0,0]
	v_cvt_scalef32_pk_f32_fp4 v[4:5], v158, 1.0 op_sel:[0,1,0]
	v_cvt_scalef32_pk_f32_fp4 v[6:7], v158, 1.0 op_sel:[1,1,0]
	v_cvt_scalef32_pk_f32_fp4 v[8:9], v159, 1.0
	v_cvt_scalef32_pk_f32_fp4 v[10:11], v159, 1.0 op_sel:[1,0,0]
	v_cvt_scalef32_pk_f32_fp4 v[12:13], v159, 1.0 op_sel:[0,1,0]
	v_cvt_scalef32_pk_f32_fp4 v[14:15], v159, 1.0 op_sel:[1,1,0]
	v_readlane_b32 s54, v90, 23
	s_lshl_b32 s56, s54, 9
	s_add_u32 s56, s64, s56
	s_addc_u32 s57, s65, 0
	global_load_dwordx2 v[158:159], v227, s[56:57]
	v_pk_fma_f32 v[130:131], v[0:1], s[0:1], v[130:131] op_sel_hi:[1,0,1]
	v_pk_fma_f32 v[138:139], v[2:3], s[0:1], v[138:139] op_sel_hi:[1,0,1]
	v_pk_fma_f32 v[140:141], v[4:5], s[0:1], v[140:141] op_sel_hi:[1,0,1]
	v_pk_fma_f32 v[142:143], v[6:7], s[0:1], v[142:143] op_sel_hi:[1,0,1]
	v_pk_fma_f32 v[128:129], v[8:9], s[0:1], v[128:129] op_sel_hi:[1,0,1]
	v_pk_fma_f32 v[132:133], v[10:11], s[0:1], v[132:133] op_sel_hi:[1,0,1]
	v_pk_fma_f32 v[134:135], v[12:13], s[0:1], v[134:135] op_sel_hi:[1,0,1]
	v_pk_fma_f32 v[136:137], v[14:15], s[0:1], v[136:137] op_sel_hi:[1,0,1]
	v_readlane_b32 s0, v167, 8
	s_waitcnt vmcnt(48)
; __device__ void peer_gather_phase(const Params& P, int l, bool do_store) {
;     ...
;         const uint2* up = (const uint2*)(U + (size_t)(uphi ? eb : ea) * 768);
;         u6[3 * pr] = up[0]; u6[3 * pr + 1] = up[1]; u6[3 * pr + 2] = up[2];
;         v8[2 * pr] = *(const uint2*)(V + (size_t)ea * 512);
;         v8[2 * pr + 1] = *(const uint2*)(V + (size_t)eb * 512);
;     ...
; #pragma unroll
;       for (int j = 0; j < 8; ++j) {
;         const float a = __builtin_bit_cast(float, __builtin_amdgcn_readlane(__builtin_bit_cast(int, avec), kb + j));
;         const f32x2 aa = f32x2{a, a};
;         y[0] += aa * __builtin_amdgcn_cvt_scalef32_pk_f32_fp4(v8[j].x, 1.0f, 0); y[1] += aa * __builtin_amdgcn_cvt_scalef32_pk_f32_fp4(v8[j].x, 1.0f, 1);
;         y[2] += aa * __builtin_amdgcn_cvt_scalef32_pk_f32_fp4(v8[j].x, 1.0f, 2); y[3] += aa * __builtin_amdgcn_cvt_scalef32_pk_f32_fp4(v8[j].x, 1.0f, 3);
;         y[4] += aa * __builtin_amdgcn_cvt_scalef32_pk_f32_fp4(v8[j].y, 1.0f, 0); y[5] += aa * __builtin_amdgcn_cvt_scalef32_pk_f32_fp4(v8[j].y, 1.0f, 1);
;         y[6] += aa * __builtin_amdgcn_cvt_scalef32_pk_f32_fp4(v8[j].y, 1.0f, 2); y[7] += aa * __builtin_amdgcn_cvt_scalef32_pk_f32_fp4(v8[j].y, 1.0f, 3);
;       }
	v_cvt_scalef32_pk_f32_fp4 v[0:1], v168, 1.0
	v_cvt_scalef32_pk_f32_fp4 v[2:3], v168, 1.0 op_sel:[1,0,0]
	v_cvt_scalef32_pk_f32_fp4 v[4:5], v168, 1.0 op_sel:[0,1,0]
	v_cvt_scalef32_pk_f32_fp4 v[6:7], v168, 1.0 op_sel:[1,1,0]
	v_cvt_scalef32_pk_f32_fp4 v[8:9], v169, 1.0
	v_cvt_scalef32_pk_f32_fp4 v[10:11], v169, 1.0 op_sel:[1,0,0]
	v_cvt_scalef32_pk_f32_fp4 v[12:13], v169, 1.0 op_sel:[0,1,0]
	v_cvt_scalef32_pk_f32_fp4 v[14:15], v169, 1.0 op_sel:[1,1,0]
	v_readlane_b32 s54, v90, 24
	s_lshl_b32 s56, s54, 9
	s_add_u32 s56, s64, s56
	s_addc_u32 s57, s65, 0
	global_load_dwordx2 v[168:169], v227, s[56:57]
	v_pk_fma_f32 v[130:131], v[0:1], s[0:1], v[130:131] op_sel_hi:[1,0,1]
	v_pk_fma_f32 v[138:139], v[2:3], s[0:1], v[138:139] op_sel_hi:[1,0,1]
	v_pk_fma_f32 v[140:141], v[4:5], s[0:1], v[140:141] op_sel_hi:[1,0,1]
	v_pk_fma_f32 v[142:143], v[6:7], s[0:1], v[142:143] op_sel_hi:[1,0,1]
	v_pk_fma_f32 v[128:129], v[8:9], s[0:1], v[128:129] op_sel_hi:[1,0,1]
	v_pk_fma_f32 v[132:133], v[10:11], s[0:1], v[132:133] op_sel_hi:[1,0,1]
	v_pk_fma_f32 v[134:135], v[12:13], s[0:1], v[134:135] op_sel_hi:[1,0,1]
	v_pk_fma_f32 v[136:137], v[14:15], s[0:1], v[136:137] op_sel_hi:[1,0,1]
	v_readlane_b32 s0, v167, 9
	s_waitcnt vmcnt(48)
	v_cvt_scalef32_pk_f32_fp4 v[0:1], v170, 1.0
	v_cvt_scalef32_pk_f32_fp4 v[2:3], v170, 1.0 op_sel:[1,0,0]
	v_cvt_scalef32_pk_f32_fp4 v[4:5], v170, 1.0 op_sel:[0,1,0]
	v_cvt_scalef32_pk_f32_fp4 v[6:7], v170, 1.0 op_sel:[1,1,0]
	v_cvt_scalef32_pk_f32_fp4 v[8:9], v171, 1.0
	v_cvt_scalef32_pk_f32_fp4 v[10:11], v171, 1.0 op_sel:[1,0,0]
	v_cvt_scalef32_pk_f32_fp4 v[12:13], v171, 1.0 op_sel:[0,1,0]
	v_cvt_scalef32_pk_f32_fp4 v[14:15], v171, 1.0 op_sel:[1,1,0]
	v_readlane_b32 s54, v90, 25
	s_lshl_b32 s56, s54, 9
	s_add_u32 s56, s64, s56
	s_addc_u32 s57, s65, 0
	global_load_dwordx2 v[170:171], v227, s[56:57]
	v_pk_fma_f32 v[130:131], v[0:1], s[0:1], v[130:131] op_sel_hi:[1,0,1]
	v_pk_fma_f32 v[138:139], v[2:3], s[0:1], v[138:139] op_sel_hi:[1,0,1]
	v_pk_fma_f32 v[140:141], v[4:5], s[0:1], v[140:141] op_sel_hi:[1,0,1]
	v_pk_fma_f32 v[142:143], v[6:7], s[0:1], v[142:143] op_sel_hi:[1,0,1]
	v_pk_fma_f32 v[128:129], v[8:9], s[0:1], v[128:129] op_sel_hi:[1,0,1]
	v_pk_fma_f32 v[132:133], v[10:11], s[0:1], v[132:133] op_sel_hi:[1,0,1]
	v_pk_fma_f32 v[134:135], v[12:13], s[0:1], v[134:135] op_sel_hi:[1,0,1]
	v_pk_fma_f32 v[136:137], v[14:15], s[0:1], v[136:137] op_sel_hi:[1,0,1]
	v_readlane_b32 s0, v167, 10
	s_waitcnt vmcnt(48)
	v_cvt_scalef32_pk_f32_fp4 v[0:1], v172, 1.0
	v_cvt_scalef32_pk_f32_fp4 v[2:3], v172, 1.0 op_sel:[1,0,0]
	v_cvt_scalef32_pk_f32_fp4 v[4:5], v172, 1.0 op_sel:[0,1,0]
	v_cvt_scalef32_pk_f32_fp4 v[6:7], v172, 1.0 op_sel:[1,1,0]
	v_cvt_scalef32_pk_f32_fp4 v[8:9], v173, 1.0
	v_cvt_scalef32_pk_f32_fp4 v[10:11], v173, 1.0 op_sel:[1,0,0]
	v_cvt_scalef32_pk_f32_fp4 v[12:13], v173, 1.0 op_sel:[0,1,0]
	v_cvt_scalef32_pk_f32_fp4 v[14:15], v173, 1.0 op_sel:[1,1,0]
	v_readlane_b32 s54, v90, 26
	s_lshl_b32 s56, s54, 9
	s_add_u32 s56, s64, s56
	s_addc_u32 s57, s65, 0
	global_load_dwordx2 v[172:173], v227, s[56:57]
	v_pk_fma_f32 v[130:131], v[0:1], s[0:1], v[130:131] op_sel_hi:[1,0,1]
	v_pk_fma_f32 v[138:139], v[2:3], s[0:1], v[138:139] op_sel_hi:[1,0,1]
	v_pk_fma_f32 v[140:141], v[4:5], s[0:1], v[140:141] op_sel_hi:[1,0,1]
	v_pk_fma_f32 v[142:143], v[6:7], s[0:1], v[142:143] op_sel_hi:[1,0,1]
	v_pk_fma_f32 v[128:129], v[8:9], s[0:1], v[128:129] op_sel_hi:[1,0,1]
	v_pk_fma_f32 v[132:133], v[10:11], s[0:1], v[132:133] op_sel_hi:[1,0,1]
	v_pk_fma_f32 v[134:135], v[12:13], s[0:1], v[134:135] op_sel_hi:[1,0,1]
	v_pk_fma_f32 v[136:137], v[14:15], s[0:1], v[136:137] op_sel_hi:[1,0,1]
	v_readlane_b32 s0, v167, 11
	s_waitcnt vmcnt(48)
	v_cvt_scalef32_pk_f32_fp4 v[0:1], v174, 1.0
	v_cvt_scalef32_pk_f32_fp4 v[2:3], v174, 1.0 op_sel:[1,0,0]
	v_cvt_scalef32_pk_f32_fp4 v[4:5], v174, 1.0 op_sel:[0,1,0]
	v_cvt_scalef32_pk_f32_fp4 v[6:7], v174, 1.0 op_sel:[1,1,0]
	v_cvt_scalef32_pk_f32_fp4 v[8:9], v175, 1.0
	v_cvt_scalef32_pk_f32_fp4 v[10:11], v175, 1.0 op_sel:[1,0,0]
	v_cvt_scalef32_pk_f32_fp4 v[12:13], v175, 1.0 op_sel:[0,1,0]
	v_cvt_scalef32_pk_f32_fp4 v[14:15], v175, 1.0 op_sel:[1,1,0]
	v_readlane_b32 s54, v90, 27
	s_lshl_b32 s56, s54, 9
	s_add_u32 s56, s64, s56
	s_addc_u32 s57, s65, 0
	global_load_dwordx2 v[174:175], v227, s[56:57]
	v_pk_fma_f32 v[130:131], v[0:1], s[0:1], v[130:131] op_sel_hi:[1,0,1]
	v_pk_fma_f32 v[138:139], v[2:3], s[0:1], v[138:139] op_sel_hi:[1,0,1]
	v_pk_fma_f32 v[140:141], v[4:5], s[0:1], v[140:141] op_sel_hi:[1,0,1]
	v_pk_fma_f32 v[142:143], v[6:7], s[0:1], v[142:143] op_sel_hi:[1,0,1]
	v_pk_fma_f32 v[128:129], v[8:9], s[0:1], v[128:129] op_sel_hi:[1,0,1]
	v_pk_fma_f32 v[132:133], v[10:11], s[0:1], v[132:133] op_sel_hi:[1,0,1]
	v_pk_fma_f32 v[134:135], v[12:13], s[0:1], v[134:135] op_sel_hi:[1,0,1]
	v_pk_fma_f32 v[136:137], v[14:15], s[0:1], v[136:137] op_sel_hi:[1,0,1]
	v_readlane_b32 s0, v167, 12
	s_waitcnt vmcnt(48)
	v_cvt_scalef32_pk_f32_fp4 v[0:1], v180, 1.0
	v_cvt_scalef32_pk_f32_fp4 v[2:3], v180, 1.0 op_sel:[1,0,0]
	v_cvt_scalef32_pk_f32_fp4 v[4:5], v180, 1.0 op_sel:[0,1,0]
	v_cvt_scalef32_pk_f32_fp4 v[6:7], v180, 1.0 op_sel:[1,1,0]
	v_cvt_scalef32_pk_f32_fp4 v[8:9], v181, 1.0
	v_cvt_scalef32_pk_f32_fp4 v[10:11], v181, 1.0 op_sel:[1,0,0]
	v_cvt_scalef32_pk_f32_fp4 v[12:13], v181, 1.0 op_sel:[0,1,0]
	v_cvt_scalef32_pk_f32_fp4 v[14:15], v181, 1.0 op_sel:[1,1,0]
	v_readlane_b32 s54, v90, 28
	s_lshl_b32 s56, s54, 9
	s_add_u32 s56, s64, s56
	s_addc_u32 s57, s65, 0
	global_load_dwordx2 v[180:181], v227, s[56:57]
	v_pk_fma_f32 v[130:131], v[0:1], s[0:1], v[130:131] op_sel_hi:[1,0,1]
	v_pk_fma_f32 v[138:139], v[2:3], s[0:1], v[138:139] op_sel_hi:[1,0,1]
	v_pk_fma_f32 v[140:141], v[4:5], s[0:1], v[140:141] op_sel_hi:[1,0,1]
	v_pk_fma_f32 v[142:143], v[6:7], s[0:1], v[142:143] op_sel_hi:[1,0,1]
	v_pk_fma_f32 v[128:129], v[8:9], s[0:1], v[128:129] op_sel_hi:[1,0,1]
	v_pk_fma_f32 v[132:133], v[10:11], s[0:1], v[132:133] op_sel_hi:[1,0,1]
	v_pk_fma_f32 v[134:135], v[12:13], s[0:1], v[134:135] op_sel_hi:[1,0,1]
	v_pk_fma_f32 v[136:137], v[14:15], s[0:1], v[136:137] op_sel_hi:[1,0,1]
	v_readlane_b32 s0, v167, 13
	s_waitcnt vmcnt(48)
; __device__ void peer_gather_phase(const Params& P, int l, bool do_store) {
;     ...
;         const uint2* up = (const uint2*)(U + (size_t)(uphi ? eb : ea) * 768);
;         u6[3 * pr] = up[0]; u6[3 * pr + 1] = up[1]; u6[3 * pr + 2] = up[2];
;         v8[2 * pr] = *(const uint2*)(V + (size_t)ea * 512);
;         v8[2 * pr + 1] = *(const uint2*)(V + (size_t)eb * 512);
;     ...
; #pragma unroll
;       for (int j = 0; j < 8; ++j) {
;         const float a = __builtin_bit_cast(float, __builtin_amdgcn_readlane(__builtin_bit_cast(int, avec), kb + j));
;         const f32x2 aa = f32x2{a, a};
;         y[0] += aa * __builtin_amdgcn_cvt_scalef32_pk_f32_fp4(v8[j].x, 1.0f, 0); y[1] += aa * __builtin_amdgcn_cvt_scalef32_pk_f32_fp4(v8[j].x, 1.0f, 1);
;         y[2] += aa * __builtin_amdgcn_cvt_scalef32_pk_f32_fp4(v8[j].x, 1.0f, 2); y[3] += aa * __builtin_amdgcn_cvt_scalef32_pk_f32_fp4(v8[j].x, 1.0f, 3);
;         y[4] += aa * __builtin_amdgcn_cvt_scalef32_pk_f32_fp4(v8[j].y, 1.0f, 0); y[5] += aa * __builtin_amdgcn_cvt_scalef32_pk_f32_fp4(v8[j].y, 1.0f, 1);
;         y[6] += aa * __builtin_amdgcn_cvt_scalef32_pk_f32_fp4(v8[j].y, 1.0f, 2); y[7] += aa * __builtin_amdgcn_cvt_scalef32_pk_f32_fp4(v8[j].y, 1.0f, 3);
;       }
	v_cvt_scalef32_pk_f32_fp4 v[0:1], v182, 1.0
	v_cvt_scalef32_pk_f32_fp4 v[2:3], v182, 1.0 op_sel:[1,0,0]
	v_cvt_scalef32_pk_f32_fp4 v[4:5], v182, 1.0 op_sel:[0,1,0]
	v_cvt_scalef32_pk_f32_fp4 v[6:7], v182, 1.0 op_sel:[1,1,0]
	v_cvt_scalef32_pk_f32_fp4 v[8:9], v183, 1.0
	v_cvt_scalef32_pk_f32_fp4 v[10:11], v183, 1.0 op_sel:[1,0,0]
	v_cvt_scalef32_pk_f32_fp4 v[12:13], v183, 1.0 op_sel:[0,1,0]
	v_cvt_scalef32_pk_f32_fp4 v[14:15], v183, 1.0 op_sel:[1,1,0]
	v_readlane_b32 s54, v90, 29
	s_lshl_b32 s56, s54, 9
	s_add_u32 s56, s64, s56
	s_addc_u32 s57, s65, 0
	global_load_dwordx2 v[182:183], v227, s[56:57]
	v_pk_fma_f32 v[130:131], v[0:1], s[0:1], v[130:131] op_sel_hi:[1,0,1]
	v_pk_fma_f32 v[138:139], v[2:3], s[0:1], v[138:139] op_sel_hi:[1,0,1]
	v_pk_fma_f32 v[140:141], v[4:5], s[0:1], v[140:141] op_sel_hi:[1,0,1]
	v_pk_fma_f32 v[142:143], v[6:7], s[0:1], v[142:143] op_sel_hi:[1,0,1]
	v_pk_fma_f32 v[128:129], v[8:9], s[0:1], v[128:129] op_sel_hi:[1,0,1]
	v_pk_fma_f32 v[132:133], v[10:11], s[0:1], v[132:133] op_sel_hi:[1,0,1]
	v_pk_fma_f32 v[134:135], v[12:13], s[0:1], v[134:135] op_sel_hi:[1,0,1]
	v_pk_fma_f32 v[136:137], v[14:15], s[0:1], v[136:137] op_sel_hi:[1,0,1]
	v_readlane_b32 s0, v167, 14
	s_waitcnt vmcnt(48)
	v_cvt_scalef32_pk_f32_fp4 v[0:1], v184, 1.0
	v_cvt_scalef32_pk_f32_fp4 v[2:3], v184, 1.0 op_sel:[1,0,0]
	v_cvt_scalef32_pk_f32_fp4 v[4:5], v184, 1.0 op_sel:[0,1,0]
	v_cvt_scalef32_pk_f32_fp4 v[6:7], v184, 1.0 op_sel:[1,1,0]
	v_cvt_scalef32_pk_f32_fp4 v[8:9], v185, 1.0
	v_cvt_scalef32_pk_f32_fp4 v[10:11], v185, 1.0 op_sel:[1,0,0]
	v_cvt_scalef32_pk_f32_fp4 v[12:13], v185, 1.0 op_sel:[0,1,0]
	v_cvt_scalef32_pk_f32_fp4 v[14:15], v185, 1.0 op_sel:[1,1,0]
	v_readlane_b32 s54, v90, 30
	s_lshl_b32 s56, s54, 9
	s_add_u32 s56, s64, s56
	s_addc_u32 s57, s65, 0
	global_load_dwordx2 v[184:185], v227, s[56:57]
	v_pk_fma_f32 v[130:131], v[0:1], s[0:1], v[130:131] op_sel_hi:[1,0,1]
	v_pk_fma_f32 v[138:139], v[2:3], s[0:1], v[138:139] op_sel_hi:[1,0,1]
	v_pk_fma_f32 v[140:141], v[4:5], s[0:1], v[140:141] op_sel_hi:[1,0,1]
	v_pk_fma_f32 v[142:143], v[6:7], s[0:1], v[142:143] op_sel_hi:[1,0,1]
	v_pk_fma_f32 v[128:129], v[8:9], s[0:1], v[128:129] op_sel_hi:[1,0,1]
	v_pk_fma_f32 v[132:133], v[10:11], s[0:1], v[132:133] op_sel_hi:[1,0,1]
	v_pk_fma_f32 v[134:135], v[12:13], s[0:1], v[134:135] op_sel_hi:[1,0,1]
	v_pk_fma_f32 v[136:137], v[14:15], s[0:1], v[136:137] op_sel_hi:[1,0,1]
	v_readlane_b32 s0, v167, 15
	s_waitcnt vmcnt(48)
	v_cvt_scalef32_pk_f32_fp4 v[0:1], v186, 1.0
	v_cvt_scalef32_pk_f32_fp4 v[2:3], v186, 1.0 op_sel:[1,0,0]
	v_cvt_scalef32_pk_f32_fp4 v[4:5], v186, 1.0 op_sel:[0,1,0]
	v_cvt_scalef32_pk_f32_fp4 v[6:7], v186, 1.0 op_sel:[1,1,0]
	v_cvt_scalef32_pk_f32_fp4 v[8:9], v187, 1.0
	v_cvt_scalef32_pk_f32_fp4 v[10:11], v187, 1.0 op_sel:[1,0,0]
	v_cvt_scalef32_pk_f32_fp4 v[12:13], v187, 1.0 op_sel:[0,1,0]
	v_cvt_scalef32_pk_f32_fp4 v[14:15], v187, 1.0 op_sel:[1,1,0]
	v_readlane_b32 s54, v90, 31
	s_lshl_b32 s56, s54, 9
	s_add_u32 s56, s64, s56
	s_addc_u32 s57, s65, 0
	global_load_dwordx2 v[186:187], v227, s[56:57]
	v_pk_fma_f32 v[130:131], v[0:1], s[0:1], v[130:131] op_sel_hi:[1,0,1]
	v_pk_fma_f32 v[138:139], v[2:3], s[0:1], v[138:139] op_sel_hi:[1,0,1]
	v_pk_fma_f32 v[140:141], v[4:5], s[0:1], v[140:141] op_sel_hi:[1,0,1]
	v_pk_fma_f32 v[142:143], v[6:7], s[0:1], v[142:143] op_sel_hi:[1,0,1]
	v_pk_fma_f32 v[128:129], v[8:9], s[0:1], v[128:129] op_sel_hi:[1,0,1]
	v_pk_fma_f32 v[132:133], v[10:11], s[0:1], v[132:133] op_sel_hi:[1,0,1]
	v_pk_fma_f32 v[134:135], v[12:13], s[0:1], v[134:135] op_sel_hi:[1,0,1]
	v_pk_fma_f32 v[136:137], v[14:15], s[0:1], v[136:137] op_sel_hi:[1,0,1]
	v_readlane_b32 s0, v167, 16
	s_waitcnt vmcnt(15)
	v_cvt_scalef32_pk_f32_fp4 v[0:1], v144, 1.0
	v_cvt_scalef32_pk_f32_fp4 v[2:3], v144, 1.0 op_sel:[1,0,0]
	v_cvt_scalef32_pk_f32_fp4 v[4:5], v144, 1.0 op_sel:[0,1,0]
	v_cvt_scalef32_pk_f32_fp4 v[6:7], v144, 1.0 op_sel:[1,1,0]
	v_cvt_scalef32_pk_f32_fp4 v[8:9], v145, 1.0
	v_cvt_scalef32_pk_f32_fp4 v[10:11], v145, 1.0 op_sel:[1,0,0]
	v_cvt_scalef32_pk_f32_fp4 v[12:13], v145, 1.0 op_sel:[0,1,0]
	v_cvt_scalef32_pk_f32_fp4 v[14:15], v145, 1.0 op_sel:[1,1,0]
	v_readlane_b32 s54, v90, 32
	s_lshl_b32 s56, s54, 9
	s_add_u32 s56, s64, s56
	s_addc_u32 s57, s65, 0
	global_load_dwordx2 v[144:145], v227, s[56:57]
	v_pk_fma_f32 v[130:131], v[0:1], s[0:1], v[130:131] op_sel_hi:[1,0,1]
	v_pk_fma_f32 v[138:139], v[2:3], s[0:1], v[138:139] op_sel_hi:[1,0,1]
	v_pk_fma_f32 v[140:141], v[4:5], s[0:1], v[140:141] op_sel_hi:[1,0,1]
	v_pk_fma_f32 v[142:143], v[6:7], s[0:1], v[142:143] op_sel_hi:[1,0,1]
	v_pk_fma_f32 v[128:129], v[8:9], s[0:1], v[128:129] op_sel_hi:[1,0,1]
	v_pk_fma_f32 v[132:133], v[10:11], s[0:1], v[132:133] op_sel_hi:[1,0,1]
	v_pk_fma_f32 v[134:135], v[12:13], s[0:1], v[134:135] op_sel_hi:[1,0,1]
	v_pk_fma_f32 v[136:137], v[14:15], s[0:1], v[136:137] op_sel_hi:[1,0,1]
	v_readlane_b32 s0, v167, 17
	s_waitcnt vmcnt(15)
	v_cvt_scalef32_pk_f32_fp4 v[0:1], v146, 1.0
	v_cvt_scalef32_pk_f32_fp4 v[2:3], v146, 1.0 op_sel:[1,0,0]
	v_cvt_scalef32_pk_f32_fp4 v[4:5], v146, 1.0 op_sel:[0,1,0]
	v_cvt_scalef32_pk_f32_fp4 v[6:7], v146, 1.0 op_sel:[1,1,0]
	v_cvt_scalef32_pk_f32_fp4 v[8:9], v147, 1.0
	v_cvt_scalef32_pk_f32_fp4 v[10:11], v147, 1.0 op_sel:[1,0,0]
	v_cvt_scalef32_pk_f32_fp4 v[12:13], v147, 1.0 op_sel:[0,1,0]
	v_cvt_scalef32_pk_f32_fp4 v[14:15], v147, 1.0 op_sel:[1,1,0]
	v_readlane_b32 s54, v90, 33
	s_lshl_b32 s56, s54, 9
	s_add_u32 s56, s64, s56
	s_addc_u32 s57, s65, 0
	global_load_dwordx2 v[146:147], v227, s[56:57]
	v_pk_fma_f32 v[130:131], v[0:1], s[0:1], v[130:131] op_sel_hi:[1,0,1]
	v_pk_fma_f32 v[138:139], v[2:3], s[0:1], v[138:139] op_sel_hi:[1,0,1]
	v_pk_fma_f32 v[140:141], v[4:5], s[0:1], v[140:141] op_sel_hi:[1,0,1]
	v_pk_fma_f32 v[142:143], v[6:7], s[0:1], v[142:143] op_sel_hi:[1,0,1]
	v_pk_fma_f32 v[128:129], v[8:9], s[0:1], v[128:129] op_sel_hi:[1,0,1]
	v_pk_fma_f32 v[132:133], v[10:11], s[0:1], v[132:133] op_sel_hi:[1,0,1]
	v_pk_fma_f32 v[134:135], v[12:13], s[0:1], v[134:135] op_sel_hi:[1,0,1]
	v_pk_fma_f32 v[136:137], v[14:15], s[0:1], v[136:137] op_sel_hi:[1,0,1]
	v_readlane_b32 s0, v167, 18
	s_waitcnt vmcnt(15)
; __device__ void peer_gather_phase(const Params& P, int l, bool do_store) {
;     ...
;         const int ea = __builtin_amdgcn_readlane(evs, kb + 2 * pr), eb = __builtin_amdgcn_readlane(evs, kb + 2 * pr + 1);
;         const uint2* up = (const uint2*)(U + (size_t)(uphi ? eb : ea) * 768);
;         u6[3 * pr] = up[0]; u6[3 * pr + 1] = up[1]; u6[3 * pr + 2] = up[2];
;         v8[2 * pr] = *(const uint2*)(V + (size_t)ea * 512);
;         v8[2 * pr + 1] = *(const uint2*)(V + (size_t)eb * 512);
;     ...
; #pragma unroll
;       for (int j = 0; j < 8; ++j) {
;         const float a = __builtin_bit_cast(float, __builtin_amdgcn_readlane(__builtin_bit_cast(int, avec), kb + j));
;         const f32x2 aa = f32x2{a, a};
;         y[0] += aa * __builtin_amdgcn_cvt_scalef32_pk_f32_fp4(v8[j].x, 1.0f, 0); y[1] += aa * __builtin_amdgcn_cvt_scalef32_pk_f32_fp4(v8[j].x, 1.0f, 1);
;         y[2] += aa * __builtin_amdgcn_cvt_scalef32_pk_f32_fp4(v8[j].x, 1.0f, 2); y[3] += aa * __builtin_amdgcn_cvt_scalef32_pk_f32_fp4(v8[j].x, 1.0f, 3);
;         y[4] += aa * __builtin_amdgcn_cvt_scalef32_pk_f32_fp4(v8[j].y, 1.0f, 0); y[5] += aa * __builtin_amdgcn_cvt_scalef32_pk_f32_fp4(v8[j].y, 1.0f, 1);
;         y[6] += aa * __builtin_amdgcn_cvt_scalef32_pk_f32_fp4(v8[j].y, 1.0f, 2); y[7] += aa * __builtin_amdgcn_cvt_scalef32_pk_f32_fp4(v8[j].y, 1.0f, 3);
;       }
	v_cvt_scalef32_pk_f32_fp4 v[0:1], v148, 1.0
	v_cvt_scalef32_pk_f32_fp4 v[2:3], v148, 1.0 op_sel:[1,0,0]
	v_cvt_scalef32_pk_f32_fp4 v[4:5], v148, 1.0 op_sel:[0,1,0]
	v_cvt_scalef32_pk_f32_fp4 v[6:7], v148, 1.0 op_sel:[1,1,0]
	v_cvt_scalef32_pk_f32_fp4 v[8:9], v149, 1.0
	v_cvt_scalef32_pk_f32_fp4 v[10:11], v149, 1.0 op_sel:[1,0,0]
	v_cvt_scalef32_pk_f32_fp4 v[12:13], v149, 1.0 op_sel:[0,1,0]
	v_cvt_scalef32_pk_f32_fp4 v[14:15], v149, 1.0 op_sel:[1,1,0]
	v_readlane_b32 s54, v90, 34
	s_lshl_b32 s56, s54, 9
	s_add_u32 s56, s64, s56
	s_addc_u32 s57, s65, 0
	global_load_dwordx2 v[148:149], v227, s[56:57]
	v_pk_fma_f32 v[130:131], v[0:1], s[0:1], v[130:131] op_sel_hi:[1,0,1]
	v_pk_fma_f32 v[138:139], v[2:3], s[0:1], v[138:139] op_sel_hi:[1,0,1]
	v_pk_fma_f32 v[140:141], v[4:5], s[0:1], v[140:141] op_sel_hi:[1,0,1]
	v_pk_fma_f32 v[142:143], v[6:7], s[0:1], v[142:143] op_sel_hi:[1,0,1]
	v_pk_fma_f32 v[128:129], v[8:9], s[0:1], v[128:129] op_sel_hi:[1,0,1]
	v_pk_fma_f32 v[132:133], v[10:11], s[0:1], v[132:133] op_sel_hi:[1,0,1]
	v_pk_fma_f32 v[134:135], v[12:13], s[0:1], v[134:135] op_sel_hi:[1,0,1]
	v_pk_fma_f32 v[136:137], v[14:15], s[0:1], v[136:137] op_sel_hi:[1,0,1]
	v_readlane_b32 s0, v167, 19
	s_waitcnt vmcnt(15)
	v_cvt_scalef32_pk_f32_fp4 v[0:1], v150, 1.0
	v_cvt_scalef32_pk_f32_fp4 v[2:3], v150, 1.0 op_sel:[1,0,0]
	v_cvt_scalef32_pk_f32_fp4 v[4:5], v150, 1.0 op_sel:[0,1,0]
	v_cvt_scalef32_pk_f32_fp4 v[6:7], v150, 1.0 op_sel:[1,1,0]
	v_cvt_scalef32_pk_f32_fp4 v[8:9], v151, 1.0
	v_cvt_scalef32_pk_f32_fp4 v[10:11], v151, 1.0 op_sel:[1,0,0]
	v_cvt_scalef32_pk_f32_fp4 v[12:13], v151, 1.0 op_sel:[0,1,0]
	v_cvt_scalef32_pk_f32_fp4 v[14:15], v151, 1.0 op_sel:[1,1,0]
	v_readlane_b32 s54, v90, 35
	s_lshl_b32 s56, s54, 9
	s_add_u32 s56, s64, s56
	s_addc_u32 s57, s65, 0
	global_load_dwordx2 v[150:151], v227, s[56:57]
	v_pk_fma_f32 v[130:131], v[0:1], s[0:1], v[130:131] op_sel_hi:[1,0,1]
	v_pk_fma_f32 v[138:139], v[2:3], s[0:1], v[138:139] op_sel_hi:[1,0,1]
	v_pk_fma_f32 v[140:141], v[4:5], s[0:1], v[140:141] op_sel_hi:[1,0,1]
	v_pk_fma_f32 v[142:143], v[6:7], s[0:1], v[142:143] op_sel_hi:[1,0,1]
	v_pk_fma_f32 v[128:129], v[8:9], s[0:1], v[128:129] op_sel_hi:[1,0,1]
	v_pk_fma_f32 v[132:133], v[10:11], s[0:1], v[132:133] op_sel_hi:[1,0,1]
	v_pk_fma_f32 v[134:135], v[12:13], s[0:1], v[134:135] op_sel_hi:[1,0,1]
	v_pk_fma_f32 v[136:137], v[14:15], s[0:1], v[136:137] op_sel_hi:[1,0,1]
	v_readlane_b32 s0, v167, 20
	s_waitcnt vmcnt(15)
	v_cvt_scalef32_pk_f32_fp4 v[0:1], v152, 1.0
	v_cvt_scalef32_pk_f32_fp4 v[2:3], v152, 1.0 op_sel:[1,0,0]
	v_cvt_scalef32_pk_f32_fp4 v[4:5], v152, 1.0 op_sel:[0,1,0]
	v_cvt_scalef32_pk_f32_fp4 v[6:7], v152, 1.0 op_sel:[1,1,0]
	v_cvt_scalef32_pk_f32_fp4 v[8:9], v153, 1.0
	v_cvt_scalef32_pk_f32_fp4 v[10:11], v153, 1.0 op_sel:[1,0,0]
	v_cvt_scalef32_pk_f32_fp4 v[12:13], v153, 1.0 op_sel:[0,1,0]
	v_cvt_scalef32_pk_f32_fp4 v[14:15], v153, 1.0 op_sel:[1,1,0]
	v_readlane_b32 s54, v90, 36
	s_lshl_b32 s56, s54, 9
	s_add_u32 s56, s64, s56
	s_addc_u32 s57, s65, 0
	global_load_dwordx2 v[152:153], v227, s[56:57]
	v_pk_fma_f32 v[130:131], v[0:1], s[0:1], v[130:131] op_sel_hi:[1,0,1]
	v_pk_fma_f32 v[138:139], v[2:3], s[0:1], v[138:139] op_sel_hi:[1,0,1]
	v_pk_fma_f32 v[140:141], v[4:5], s[0:1], v[140:141] op_sel_hi:[1,0,1]
	v_pk_fma_f32 v[142:143], v[6:7], s[0:1], v[142:143] op_sel_hi:[1,0,1]
	v_pk_fma_f32 v[128:129], v[8:9], s[0:1], v[128:129] op_sel_hi:[1,0,1]
	v_pk_fma_f32 v[132:133], v[10:11], s[0:1], v[132:133] op_sel_hi:[1,0,1]
	v_pk_fma_f32 v[134:135], v[12:13], s[0:1], v[134:135] op_sel_hi:[1,0,1]
	v_pk_fma_f32 v[136:137], v[14:15], s[0:1], v[136:137] op_sel_hi:[1,0,1]
	v_readlane_b32 s0, v167, 21
	s_waitcnt vmcnt(15)
	v_cvt_scalef32_pk_f32_fp4 v[0:1], v154, 1.0
	v_cvt_scalef32_pk_f32_fp4 v[2:3], v154, 1.0 op_sel:[1,0,0]
	v_cvt_scalef32_pk_f32_fp4 v[4:5], v154, 1.0 op_sel:[0,1,0]
	v_cvt_scalef32_pk_f32_fp4 v[6:7], v154, 1.0 op_sel:[1,1,0]
	v_cvt_scalef32_pk_f32_fp4 v[8:9], v155, 1.0
	v_cvt_scalef32_pk_f32_fp4 v[10:11], v155, 1.0 op_sel:[1,0,0]
	v_cvt_scalef32_pk_f32_fp4 v[12:13], v155, 1.0 op_sel:[0,1,0]
	v_cvt_scalef32_pk_f32_fp4 v[14:15], v155, 1.0 op_sel:[1,1,0]
	v_readlane_b32 s54, v90, 37
	s_lshl_b32 s56, s54, 9
	s_add_u32 s56, s64, s56
	s_addc_u32 s57, s65, 0
	global_load_dwordx2 v[154:155], v227, s[56:57]
	v_pk_fma_f32 v[130:131], v[0:1], s[0:1], v[130:131] op_sel_hi:[1,0,1]
	v_pk_fma_f32 v[138:139], v[2:3], s[0:1], v[138:139] op_sel_hi:[1,0,1]
	v_pk_fma_f32 v[140:141], v[4:5], s[0:1], v[140:141] op_sel_hi:[1,0,1]
	v_pk_fma_f32 v[142:143], v[6:7], s[0:1], v[142:143] op_sel_hi:[1,0,1]
	v_pk_fma_f32 v[128:129], v[8:9], s[0:1], v[128:129] op_sel_hi:[1,0,1]
	v_pk_fma_f32 v[132:133], v[10:11], s[0:1], v[132:133] op_sel_hi:[1,0,1]
	v_pk_fma_f32 v[134:135], v[12:13], s[0:1], v[134:135] op_sel_hi:[1,0,1]
	v_pk_fma_f32 v[136:137], v[14:15], s[0:1], v[136:137] op_sel_hi:[1,0,1]
	v_readlane_b32 s0, v167, 22
	s_waitcnt vmcnt(15)
	v_cvt_scalef32_pk_f32_fp4 v[0:1], v156, 1.0
	v_cvt_scalef32_pk_f32_fp4 v[2:3], v156, 1.0 op_sel:[1,0,0]
	v_cvt_scalef32_pk_f32_fp4 v[4:5], v156, 1.0 op_sel:[0,1,0]
	v_cvt_scalef32_pk_f32_fp4 v[6:7], v156, 1.0 op_sel:[1,1,0]
	v_cvt_scalef32_pk_f32_fp4 v[8:9], v157, 1.0
	v_cvt_scalef32_pk_f32_fp4 v[10:11], v157, 1.0 op_sel:[1,0,0]
	v_cvt_scalef32_pk_f32_fp4 v[12:13], v157, 1.0 op_sel:[0,1,0]
	v_cvt_scalef32_pk_f32_fp4 v[14:15], v157, 1.0 op_sel:[1,1,0]
	v_readlane_b32 s54, v90, 38
	s_lshl_b32 s56, s54, 9
	s_add_u32 s56, s64, s56
	s_addc_u32 s57, s65, 0
	global_load_dwordx2 v[156:157], v227, s[56:57]
	v_pk_fma_f32 v[130:131], v[0:1], s[0:1], v[130:131] op_sel_hi:[1,0,1]
	v_pk_fma_f32 v[138:139], v[2:3], s[0:1], v[138:139] op_sel_hi:[1,0,1]
	v_pk_fma_f32 v[140:141], v[4:5], s[0:1], v[140:141] op_sel_hi:[1,0,1]
	v_pk_fma_f32 v[142:143], v[6:7], s[0:1], v[142:143] op_sel_hi:[1,0,1]
	v_pk_fma_f32 v[128:129], v[8:9], s[0:1], v[128:129] op_sel_hi:[1,0,1]
	v_pk_fma_f32 v[132:133], v[10:11], s[0:1], v[132:133] op_sel_hi:[1,0,1]
	v_pk_fma_f32 v[134:135], v[12:13], s[0:1], v[134:135] op_sel_hi:[1,0,1]
	v_pk_fma_f32 v[136:137], v[14:15], s[0:1], v[136:137] op_sel_hi:[1,0,1]
	v_readlane_b32 s0, v167, 23
	s_waitcnt vmcnt(15)
; __device__ void peer_gather_phase(const Params& P, int l, bool do_store) {
;     ...
;         const int ea = __builtin_amdgcn_readlane(evs, kb + 2 * pr), eb = __builtin_amdgcn_readlane(evs, kb + 2 * pr + 1);
;         const uint2* up = (const uint2*)(U + (size_t)(uphi ? eb : ea) * 768);
;         u6[3 * pr] = up[0]; u6[3 * pr + 1] = up[1]; u6[3 * pr + 2] = up[2];
;         v8[2 * pr] = *(const uint2*)(V + (size_t)ea * 512);
;         v8[2 * pr + 1] = *(const uint2*)(V + (size_t)eb * 512);
;     ...
; #pragma unroll
;       for (int j = 0; j < 8; ++j) {
;         const float a = __builtin_bit_cast(float, __builtin_amdgcn_readlane(__builtin_bit_cast(int, avec), kb + j));
;         const f32x2 aa = f32x2{a, a};
;         y[0] += aa * __builtin_amdgcn_cvt_scalef32_pk_f32_fp4(v8[j].x, 1.0f, 0); y[1] += aa * __builtin_amdgcn_cvt_scalef32_pk_f32_fp4(v8[j].x, 1.0f, 1);
;         y[2] += aa * __builtin_amdgcn_cvt_scalef32_pk_f32_fp4(v8[j].x, 1.0f, 2); y[3] += aa * __builtin_amdgcn_cvt_scalef32_pk_f32_fp4(v8[j].x, 1.0f, 3);
;         y[4] += aa * __builtin_amdgcn_cvt_scalef32_pk_f32_fp4(v8[j].y, 1.0f, 0); y[5] += aa * __builtin_amdgcn_cvt_scalef32_pk_f32_fp4(v8[j].y, 1.0f, 1);
;         y[6] += aa * __builtin_amdgcn_cvt_scalef32_pk_f32_fp4(v8[j].y, 1.0f, 2); y[7] += aa * __builtin_amdgcn_cvt_scalef32_pk_f32_fp4(v8[j].y, 1.0f, 3);
;       }
	v_cvt_scalef32_pk_f32_fp4 v[0:1], v158, 1.0
	v_cvt_scalef32_pk_f32_fp4 v[2:3], v158, 1.0 op_sel:[1,0,0]
	v_cvt_scalef32_pk_f32_fp4 v[4:5], v158, 1.0 op_sel:[0,1,0]
	v_cvt_scalef32_pk_f32_fp4 v[6:7], v158, 1.0 op_sel:[1,1,0]
	v_cvt_scalef32_pk_f32_fp4 v[8:9], v159, 1.0
	v_cvt_scalef32_pk_f32_fp4 v[10:11], v159, 1.0 op_sel:[1,0,0]
	v_cvt_scalef32_pk_f32_fp4 v[12:13], v159, 1.0 op_sel:[0,1,0]
	v_cvt_scalef32_pk_f32_fp4 v[14:15], v159, 1.0 op_sel:[1,1,0]
	v_readlane_b32 s54, v90, 39
	s_lshl_b32 s56, s54, 9
	s_add_u32 s56, s64, s56
	s_addc_u32 s57, s65, 0
	global_load_dwordx2 v[158:159], v227, s[56:57]
	v_pk_fma_f32 v[130:131], v[0:1], s[0:1], v[130:131] op_sel_hi:[1,0,1]
	v_pk_fma_f32 v[138:139], v[2:3], s[0:1], v[138:139] op_sel_hi:[1,0,1]
	v_pk_fma_f32 v[140:141], v[4:5], s[0:1], v[140:141] op_sel_hi:[1,0,1]
	v_pk_fma_f32 v[142:143], v[6:7], s[0:1], v[142:143] op_sel_hi:[1,0,1]
	v_pk_fma_f32 v[128:129], v[8:9], s[0:1], v[128:129] op_sel_hi:[1,0,1]
	v_pk_fma_f32 v[132:133], v[10:11], s[0:1], v[132:133] op_sel_hi:[1,0,1]
	v_pk_fma_f32 v[134:135], v[12:13], s[0:1], v[134:135] op_sel_hi:[1,0,1]
	v_pk_fma_f32 v[136:137], v[14:15], s[0:1], v[136:137] op_sel_hi:[1,0,1]
	v_readlane_b32 s0, v167, 24
	s_waitcnt vmcnt(15)
	v_cvt_scalef32_pk_f32_fp4 v[0:1], v168, 1.0
	v_cvt_scalef32_pk_f32_fp4 v[2:3], v168, 1.0 op_sel:[1,0,0]
	v_cvt_scalef32_pk_f32_fp4 v[4:5], v168, 1.0 op_sel:[0,1,0]
	v_cvt_scalef32_pk_f32_fp4 v[6:7], v168, 1.0 op_sel:[1,1,0]
	v_cvt_scalef32_pk_f32_fp4 v[8:9], v169, 1.0
	v_cvt_scalef32_pk_f32_fp4 v[10:11], v169, 1.0 op_sel:[1,0,0]
	v_cvt_scalef32_pk_f32_fp4 v[12:13], v169, 1.0 op_sel:[0,1,0]
	v_cvt_scalef32_pk_f32_fp4 v[14:15], v169, 1.0 op_sel:[1,1,0]
	v_readlane_b32 s54, v90, 40
	s_lshl_b32 s56, s54, 9
	s_add_u32 s56, s64, s56
	s_addc_u32 s57, s65, 0
	global_load_dwordx2 v[168:169], v227, s[56:57]
	v_pk_fma_f32 v[130:131], v[0:1], s[0:1], v[130:131] op_sel_hi:[1,0,1]
	v_pk_fma_f32 v[138:139], v[2:3], s[0:1], v[138:139] op_sel_hi:[1,0,1]
	v_pk_fma_f32 v[140:141], v[4:5], s[0:1], v[140:141] op_sel_hi:[1,0,1]
	v_pk_fma_f32 v[142:143], v[6:7], s[0:1], v[142:143] op_sel_hi:[1,0,1]
	v_pk_fma_f32 v[128:129], v[8:9], s[0:1], v[128:129] op_sel_hi:[1,0,1]
	v_pk_fma_f32 v[132:133], v[10:11], s[0:1], v[132:133] op_sel_hi:[1,0,1]
	v_pk_fma_f32 v[134:135], v[12:13], s[0:1], v[134:135] op_sel_hi:[1,0,1]
	v_pk_fma_f32 v[136:137], v[14:15], s[0:1], v[136:137] op_sel_hi:[1,0,1]
	v_readlane_b32 s0, v167, 25
	s_waitcnt vmcnt(15)
	v_cvt_scalef32_pk_f32_fp4 v[0:1], v170, 1.0
	v_cvt_scalef32_pk_f32_fp4 v[2:3], v170, 1.0 op_sel:[1,0,0]
	v_cvt_scalef32_pk_f32_fp4 v[4:5], v170, 1.0 op_sel:[0,1,0]
	v_cvt_scalef32_pk_f32_fp4 v[6:7], v170, 1.0 op_sel:[1,1,0]
	v_cvt_scalef32_pk_f32_fp4 v[8:9], v171, 1.0
	v_cvt_scalef32_pk_f32_fp4 v[10:11], v171, 1.0 op_sel:[1,0,0]
	v_cvt_scalef32_pk_f32_fp4 v[12:13], v171, 1.0 op_sel:[0,1,0]
	v_cvt_scalef32_pk_f32_fp4 v[14:15], v171, 1.0 op_sel:[1,1,0]
	v_readlane_b32 s54, v90, 41
	s_lshl_b32 s56, s54, 9
	s_add_u32 s56, s64, s56
	s_addc_u32 s57, s65, 0
	global_load_dwordx2 v[170:171], v227, s[56:57]
	v_pk_fma_f32 v[130:131], v[0:1], s[0:1], v[130:131] op_sel_hi:[1,0,1]
	v_pk_fma_f32 v[138:139], v[2:3], s[0:1], v[138:139] op_sel_hi:[1,0,1]
	v_pk_fma_f32 v[140:141], v[4:5], s[0:1], v[140:141] op_sel_hi:[1,0,1]
	v_pk_fma_f32 v[142:143], v[6:7], s[0:1], v[142:143] op_sel_hi:[1,0,1]
	v_pk_fma_f32 v[128:129], v[8:9], s[0:1], v[128:129] op_sel_hi:[1,0,1]
	v_pk_fma_f32 v[132:133], v[10:11], s[0:1], v[132:133] op_sel_hi:[1,0,1]
	v_pk_fma_f32 v[134:135], v[12:13], s[0:1], v[134:135] op_sel_hi:[1,0,1]
	v_pk_fma_f32 v[136:137], v[14:15], s[0:1], v[136:137] op_sel_hi:[1,0,1]
	v_readlane_b32 s0, v167, 26
	s_waitcnt vmcnt(15)
	v_cvt_scalef32_pk_f32_fp4 v[0:1], v172, 1.0
	v_cvt_scalef32_pk_f32_fp4 v[2:3], v172, 1.0 op_sel:[1,0,0]
	v_cvt_scalef32_pk_f32_fp4 v[4:5], v172, 1.0 op_sel:[0,1,0]
	v_cvt_scalef32_pk_f32_fp4 v[6:7], v172, 1.0 op_sel:[1,1,0]
	v_cvt_scalef32_pk_f32_fp4 v[8:9], v173, 1.0
	v_cvt_scalef32_pk_f32_fp4 v[10:11], v173, 1.0 op_sel:[1,0,0]
	v_cvt_scalef32_pk_f32_fp4 v[12:13], v173, 1.0 op_sel:[0,1,0]
	v_cvt_scalef32_pk_f32_fp4 v[14:15], v173, 1.0 op_sel:[1,1,0]
	v_readlane_b32 s54, v90, 42
	s_lshl_b32 s56, s54, 9
	s_add_u32 s56, s64, s56
	s_addc_u32 s57, s65, 0
	global_load_dwordx2 v[172:173], v227, s[56:57]
	v_pk_fma_f32 v[130:131], v[0:1], s[0:1], v[130:131] op_sel_hi:[1,0,1]
	v_pk_fma_f32 v[138:139], v[2:3], s[0:1], v[138:139] op_sel_hi:[1,0,1]
	v_pk_fma_f32 v[140:141], v[4:5], s[0:1], v[140:141] op_sel_hi:[1,0,1]
	v_pk_fma_f32 v[142:143], v[6:7], s[0:1], v[142:143] op_sel_hi:[1,0,1]
	v_pk_fma_f32 v[128:129], v[8:9], s[0:1], v[128:129] op_sel_hi:[1,0,1]
	v_pk_fma_f32 v[132:133], v[10:11], s[0:1], v[132:133] op_sel_hi:[1,0,1]
	v_pk_fma_f32 v[134:135], v[12:13], s[0:1], v[134:135] op_sel_hi:[1,0,1]
	v_pk_fma_f32 v[136:137], v[14:15], s[0:1], v[136:137] op_sel_hi:[1,0,1]
	v_readlane_b32 s0, v167, 27
	s_waitcnt vmcnt(15)
	v_cvt_scalef32_pk_f32_fp4 v[0:1], v174, 1.0
	v_cvt_scalef32_pk_f32_fp4 v[2:3], v174, 1.0 op_sel:[1,0,0]
	v_cvt_scalef32_pk_f32_fp4 v[4:5], v174, 1.0 op_sel:[0,1,0]
	v_cvt_scalef32_pk_f32_fp4 v[6:7], v174, 1.0 op_sel:[1,1,0]
	v_cvt_scalef32_pk_f32_fp4 v[8:9], v175, 1.0
	v_cvt_scalef32_pk_f32_fp4 v[10:11], v175, 1.0 op_sel:[1,0,0]
	v_cvt_scalef32_pk_f32_fp4 v[12:13], v175, 1.0 op_sel:[0,1,0]
	v_cvt_scalef32_pk_f32_fp4 v[14:15], v175, 1.0 op_sel:[1,1,0]
	v_readlane_b32 s54, v90, 43
	s_lshl_b32 s56, s54, 9
	s_add_u32 s56, s64, s56
	s_addc_u32 s57, s65, 0
	global_load_dwordx2 v[174:175], v227, s[56:57]
	v_pk_fma_f32 v[130:131], v[0:1], s[0:1], v[130:131] op_sel_hi:[1,0,1]
	v_pk_fma_f32 v[138:139], v[2:3], s[0:1], v[138:139] op_sel_hi:[1,0,1]
	v_pk_fma_f32 v[140:141], v[4:5], s[0:1], v[140:141] op_sel_hi:[1,0,1]
	v_pk_fma_f32 v[142:143], v[6:7], s[0:1], v[142:143] op_sel_hi:[1,0,1]
	v_pk_fma_f32 v[128:129], v[8:9], s[0:1], v[128:129] op_sel_hi:[1,0,1]
	v_pk_fma_f32 v[132:133], v[10:11], s[0:1], v[132:133] op_sel_hi:[1,0,1]
	v_pk_fma_f32 v[134:135], v[12:13], s[0:1], v[134:135] op_sel_hi:[1,0,1]
	v_pk_fma_f32 v[136:137], v[14:15], s[0:1], v[136:137] op_sel_hi:[1,0,1]
	v_readlane_b32 s0, v167, 28
	s_waitcnt vmcnt(15)
; __device__ void peer_gather_phase(const Params& P, int l, bool do_store) {
;     ...
;         const int ea = __builtin_amdgcn_readlane(evs, kb + 2 * pr), eb = __builtin_amdgcn_readlane(evs, kb + 2 * pr + 1);
;         const uint2* up = (const uint2*)(U + (size_t)(uphi ? eb : ea) * 768);
;         u6[3 * pr] = up[0]; u6[3 * pr + 1] = up[1]; u6[3 * pr + 2] = up[2];
;         v8[2 * pr] = *(const uint2*)(V + (size_t)ea * 512);
;         v8[2 * pr + 1] = *(const uint2*)(V + (size_t)eb * 512);
;     ...
; #pragma unroll
;       for (int j = 0; j < 8; ++j) {
;         const float a = __builtin_bit_cast(float, __builtin_amdgcn_readlane(__builtin_bit_cast(int, avec), kb + j));
;         const f32x2 aa = f32x2{a, a};
;         y[0] += aa * __builtin_amdgcn_cvt_scalef32_pk_f32_fp4(v8[j].x, 1.0f, 0); y[1] += aa * __builtin_amdgcn_cvt_scalef32_pk_f32_fp4(v8[j].x, 1.0f, 1);
;         y[2] += aa * __builtin_amdgcn_cvt_scalef32_pk_f32_fp4(v8[j].x, 1.0f, 2); y[3] += aa * __builtin_amdgcn_cvt_scalef32_pk_f32_fp4(v8[j].x, 1.0f, 3);
;         y[4] += aa * __builtin_amdgcn_cvt_scalef32_pk_f32_fp4(v8[j].y, 1.0f, 0); y[5] += aa * __builtin_amdgcn_cvt_scalef32_pk_f32_fp4(v8[j].y, 1.0f, 1);
;         y[6] += aa * __builtin_amdgcn_cvt_scalef32_pk_f32_fp4(v8[j].y, 1.0f, 2); y[7] += aa * __builtin_amdgcn_cvt_scalef32_pk_f32_fp4(v8[j].y, 1.0f, 3);
;       }
	v_cvt_scalef32_pk_f32_fp4 v[0:1], v180, 1.0
	v_cvt_scalef32_pk_f32_fp4 v[2:3], v180, 1.0 op_sel:[1,0,0]
	v_cvt_scalef32_pk_f32_fp4 v[4:5], v180, 1.0 op_sel:[0,1,0]
	v_cvt_scalef32_pk_f32_fp4 v[6:7], v180, 1.0 op_sel:[1,1,0]
	v_cvt_scalef32_pk_f32_fp4 v[8:9], v181, 1.0
	v_cvt_scalef32_pk_f32_fp4 v[10:11], v181, 1.0 op_sel:[1,0,0]
	v_cvt_scalef32_pk_f32_fp4 v[12:13], v181, 1.0 op_sel:[0,1,0]
	v_cvt_scalef32_pk_f32_fp4 v[14:15], v181, 1.0 op_sel:[1,1,0]
	v_readlane_b32 s54, v90, 44
	s_lshl_b32 s56, s54, 9
	s_add_u32 s56, s64, s56
	s_addc_u32 s57, s65, 0
	global_load_dwordx2 v[180:181], v227, s[56:57]
	v_pk_fma_f32 v[130:131], v[0:1], s[0:1], v[130:131] op_sel_hi:[1,0,1]
	v_pk_fma_f32 v[138:139], v[2:3], s[0:1], v[138:139] op_sel_hi:[1,0,1]
	v_pk_fma_f32 v[140:141], v[4:5], s[0:1], v[140:141] op_sel_hi:[1,0,1]
	v_pk_fma_f32 v[142:143], v[6:7], s[0:1], v[142:143] op_sel_hi:[1,0,1]
	v_pk_fma_f32 v[128:129], v[8:9], s[0:1], v[128:129] op_sel_hi:[1,0,1]
	v_pk_fma_f32 v[132:133], v[10:11], s[0:1], v[132:133] op_sel_hi:[1,0,1]
	v_pk_fma_f32 v[134:135], v[12:13], s[0:1], v[134:135] op_sel_hi:[1,0,1]
	v_pk_fma_f32 v[136:137], v[14:15], s[0:1], v[136:137] op_sel_hi:[1,0,1]
	v_readlane_b32 s0, v167, 29
	s_waitcnt vmcnt(15)
	v_cvt_scalef32_pk_f32_fp4 v[0:1], v182, 1.0
	v_cvt_scalef32_pk_f32_fp4 v[2:3], v182, 1.0 op_sel:[1,0,0]
	v_cvt_scalef32_pk_f32_fp4 v[4:5], v182, 1.0 op_sel:[0,1,0]
	v_cvt_scalef32_pk_f32_fp4 v[6:7], v182, 1.0 op_sel:[1,1,0]
	v_cvt_scalef32_pk_f32_fp4 v[8:9], v183, 1.0
	v_cvt_scalef32_pk_f32_fp4 v[10:11], v183, 1.0 op_sel:[1,0,0]
	v_cvt_scalef32_pk_f32_fp4 v[12:13], v183, 1.0 op_sel:[0,1,0]
	v_cvt_scalef32_pk_f32_fp4 v[14:15], v183, 1.0 op_sel:[1,1,0]
	v_readlane_b32 s54, v90, 45
	s_lshl_b32 s56, s54, 9
	s_add_u32 s56, s64, s56
	s_addc_u32 s57, s65, 0
	global_load_dwordx2 v[182:183], v227, s[56:57]
	v_pk_fma_f32 v[130:131], v[0:1], s[0:1], v[130:131] op_sel_hi:[1,0,1]
	v_pk_fma_f32 v[138:139], v[2:3], s[0:1], v[138:139] op_sel_hi:[1,0,1]
	v_pk_fma_f32 v[140:141], v[4:5], s[0:1], v[140:141] op_sel_hi:[1,0,1]
	v_pk_fma_f32 v[142:143], v[6:7], s[0:1], v[142:143] op_sel_hi:[1,0,1]
	v_pk_fma_f32 v[128:129], v[8:9], s[0:1], v[128:129] op_sel_hi:[1,0,1]
	v_pk_fma_f32 v[132:133], v[10:11], s[0:1], v[132:133] op_sel_hi:[1,0,1]
	v_pk_fma_f32 v[134:135], v[12:13], s[0:1], v[134:135] op_sel_hi:[1,0,1]
	v_pk_fma_f32 v[136:137], v[14:15], s[0:1], v[136:137] op_sel_hi:[1,0,1]
	v_readlane_b32 s0, v167, 30
	s_waitcnt vmcnt(15)
	v_cvt_scalef32_pk_f32_fp4 v[0:1], v184, 1.0
	v_cvt_scalef32_pk_f32_fp4 v[2:3], v184, 1.0 op_sel:[1,0,0]
	v_cvt_scalef32_pk_f32_fp4 v[4:5], v184, 1.0 op_sel:[0,1,0]
	v_cvt_scalef32_pk_f32_fp4 v[6:7], v184, 1.0 op_sel:[1,1,0]
	v_cvt_scalef32_pk_f32_fp4 v[8:9], v185, 1.0
	v_cvt_scalef32_pk_f32_fp4 v[10:11], v185, 1.0 op_sel:[1,0,0]
	v_cvt_scalef32_pk_f32_fp4 v[12:13], v185, 1.0 op_sel:[0,1,0]
	v_cvt_scalef32_pk_f32_fp4 v[14:15], v185, 1.0 op_sel:[1,1,0]
	v_readlane_b32 s54, v90, 46
	s_lshl_b32 s56, s54, 9
	s_add_u32 s56, s64, s56
	s_addc_u32 s57, s65, 0
	global_load_dwordx2 v[184:185], v227, s[56:57]
	v_pk_fma_f32 v[130:131], v[0:1], s[0:1], v[130:131] op_sel_hi:[1,0,1]
	v_pk_fma_f32 v[138:139], v[2:3], s[0:1], v[138:139] op_sel_hi:[1,0,1]
	v_pk_fma_f32 v[140:141], v[4:5], s[0:1], v[140:141] op_sel_hi:[1,0,1]
	v_pk_fma_f32 v[142:143], v[6:7], s[0:1], v[142:143] op_sel_hi:[1,0,1]
	v_pk_fma_f32 v[128:129], v[8:9], s[0:1], v[128:129] op_sel_hi:[1,0,1]
	v_pk_fma_f32 v[132:133], v[10:11], s[0:1], v[132:133] op_sel_hi:[1,0,1]
	v_pk_fma_f32 v[134:135], v[12:13], s[0:1], v[134:135] op_sel_hi:[1,0,1]
	v_pk_fma_f32 v[136:137], v[14:15], s[0:1], v[136:137] op_sel_hi:[1,0,1]
	v_readlane_b32 s0, v167, 31
	s_waitcnt vmcnt(15)
	v_cvt_scalef32_pk_f32_fp4 v[0:1], v186, 1.0
	v_cvt_scalef32_pk_f32_fp4 v[2:3], v186, 1.0 op_sel:[1,0,0]
	v_cvt_scalef32_pk_f32_fp4 v[4:5], v186, 1.0 op_sel:[0,1,0]
	v_cvt_scalef32_pk_f32_fp4 v[6:7], v186, 1.0 op_sel:[1,1,0]
	v_cvt_scalef32_pk_f32_fp4 v[8:9], v187, 1.0
	v_cvt_scalef32_pk_f32_fp4 v[10:11], v187, 1.0 op_sel:[1,0,0]
	v_cvt_scalef32_pk_f32_fp4 v[12:13], v187, 1.0 op_sel:[0,1,0]
	v_cvt_scalef32_pk_f32_fp4 v[14:15], v187, 1.0 op_sel:[1,1,0]
	v_readlane_b32 s54, v90, 47
	s_lshl_b32 s56, s54, 9
	s_add_u32 s56, s64, s56
	s_addc_u32 s57, s65, 0
	global_load_dwordx2 v[186:187], v227, s[56:57]
	v_pk_fma_f32 v[130:131], v[0:1], s[0:1], v[130:131] op_sel_hi:[1,0,1]
	v_pk_fma_f32 v[138:139], v[2:3], s[0:1], v[138:139] op_sel_hi:[1,0,1]
	v_pk_fma_f32 v[140:141], v[4:5], s[0:1], v[140:141] op_sel_hi:[1,0,1]
	v_pk_fma_f32 v[142:143], v[6:7], s[0:1], v[142:143] op_sel_hi:[1,0,1]
	v_pk_fma_f32 v[128:129], v[8:9], s[0:1], v[128:129] op_sel_hi:[1,0,1]
	v_pk_fma_f32 v[132:133], v[10:11], s[0:1], v[132:133] op_sel_hi:[1,0,1]
	v_pk_fma_f32 v[134:135], v[12:13], s[0:1], v[134:135] op_sel_hi:[1,0,1]
	v_pk_fma_f32 v[136:137], v[14:15], s[0:1], v[136:137] op_sel_hi:[1,0,1]
	v_readlane_b32 s0, v167, 32
	s_waitcnt vmcnt(15)
	v_cvt_scalef32_pk_f32_fp4 v[0:1], v144, 1.0
	v_cvt_scalef32_pk_f32_fp4 v[2:3], v144, 1.0 op_sel:[1,0,0]
	v_cvt_scalef32_pk_f32_fp4 v[4:5], v144, 1.0 op_sel:[0,1,0]
	v_cvt_scalef32_pk_f32_fp4 v[6:7], v144, 1.0 op_sel:[1,1,0]
	v_cvt_scalef32_pk_f32_fp4 v[8:9], v145, 1.0
	v_cvt_scalef32_pk_f32_fp4 v[10:11], v145, 1.0 op_sel:[1,0,0]
	v_cvt_scalef32_pk_f32_fp4 v[12:13], v145, 1.0 op_sel:[0,1,0]
	v_cvt_scalef32_pk_f32_fp4 v[14:15], v145, 1.0 op_sel:[1,1,0]
	v_readlane_b32 s54, v90, 48
	s_lshl_b32 s56, s54, 9
	s_add_u32 s56, s64, s56
	s_addc_u32 s57, s65, 0
	global_load_dwordx2 v[144:145], v227, s[56:57]
	v_pk_fma_f32 v[130:131], v[0:1], s[0:1], v[130:131] op_sel_hi:[1,0,1]
	v_pk_fma_f32 v[138:139], v[2:3], s[0:1], v[138:139] op_sel_hi:[1,0,1]
	v_pk_fma_f32 v[140:141], v[4:5], s[0:1], v[140:141] op_sel_hi:[1,0,1]
	v_pk_fma_f32 v[142:143], v[6:7], s[0:1], v[142:143] op_sel_hi:[1,0,1]
	v_pk_fma_f32 v[128:129], v[8:9], s[0:1], v[128:129] op_sel_hi:[1,0,1]
	v_pk_fma_f32 v[132:133], v[10:11], s[0:1], v[132:133] op_sel_hi:[1,0,1]
	v_pk_fma_f32 v[134:135], v[12:13], s[0:1], v[134:135] op_sel_hi:[1,0,1]
	v_pk_fma_f32 v[136:137], v[14:15], s[0:1], v[136:137] op_sel_hi:[1,0,1]
	v_readlane_b32 s0, v167, 33
	s_waitcnt vmcnt(15)
; __device__ void peer_gather_phase(const Params& P, int l, bool do_store) {
;     ...
;         const int ea = __builtin_amdgcn_readlane(evs, kb + 2 * pr), eb = __builtin_amdgcn_readlane(evs, kb + 2 * pr + 1);
;         const uint2* up = (const uint2*)(U + (size_t)(uphi ? eb : ea) * 768);
;         u6[3 * pr] = up[0]; u6[3 * pr + 1] = up[1]; u6[3 * pr + 2] = up[2];
;         v8[2 * pr] = *(const uint2*)(V + (size_t)ea * 512);
;         v8[2 * pr + 1] = *(const uint2*)(V + (size_t)eb * 512);
;     ...
; #pragma unroll
;       for (int j = 0; j < 8; ++j) {
;         const float a = __builtin_bit_cast(float, __builtin_amdgcn_readlane(__builtin_bit_cast(int, avec), kb + j));
;         const f32x2 aa = f32x2{a, a};
;         y[0] += aa * __builtin_amdgcn_cvt_scalef32_pk_f32_fp4(v8[j].x, 1.0f, 0); y[1] += aa * __builtin_amdgcn_cvt_scalef32_pk_f32_fp4(v8[j].x, 1.0f, 1);
;         y[2] += aa * __builtin_amdgcn_cvt_scalef32_pk_f32_fp4(v8[j].x, 1.0f, 2); y[3] += aa * __builtin_amdgcn_cvt_scalef32_pk_f32_fp4(v8[j].x, 1.0f, 3);
;         y[4] += aa * __builtin_amdgcn_cvt_scalef32_pk_f32_fp4(v8[j].y, 1.0f, 0); y[5] += aa * __builtin_amdgcn_cvt_scalef32_pk_f32_fp4(v8[j].y, 1.0f, 1);
;         y[6] += aa * __builtin_amdgcn_cvt_scalef32_pk_f32_fp4(v8[j].y, 1.0f, 2); y[7] += aa * __builtin_amdgcn_cvt_scalef32_pk_f32_fp4(v8[j].y, 1.0f, 3);
;       }
	v_cvt_scalef32_pk_f32_fp4 v[0:1], v146, 1.0
	v_cvt_scalef32_pk_f32_fp4 v[2:3], v146, 1.0 op_sel:[1,0,0]
	v_cvt_scalef32_pk_f32_fp4 v[4:5], v146, 1.0 op_sel:[0,1,0]
	v_cvt_scalef32_pk_f32_fp4 v[6:7], v146, 1.0 op_sel:[1,1,0]
	v_cvt_scalef32_pk_f32_fp4 v[8:9], v147, 1.0
	v_cvt_scalef32_pk_f32_fp4 v[10:11], v147, 1.0 op_sel:[1,0,0]
	v_cvt_scalef32_pk_f32_fp4 v[12:13], v147, 1.0 op_sel:[0,1,0]
	v_cvt_scalef32_pk_f32_fp4 v[14:15], v147, 1.0 op_sel:[1,1,0]
	v_readlane_b32 s54, v90, 49
	s_lshl_b32 s56, s54, 9
	s_add_u32 s56, s64, s56
	s_addc_u32 s57, s65, 0
	global_load_dwordx2 v[146:147], v227, s[56:57]
	v_pk_fma_f32 v[130:131], v[0:1], s[0:1], v[130:131] op_sel_hi:[1,0,1]
	v_pk_fma_f32 v[138:139], v[2:3], s[0:1], v[138:139] op_sel_hi:[1,0,1]
	v_pk_fma_f32 v[140:141], v[4:5], s[0:1], v[140:141] op_sel_hi:[1,0,1]
	v_pk_fma_f32 v[142:143], v[6:7], s[0:1], v[142:143] op_sel_hi:[1,0,1]
	v_pk_fma_f32 v[128:129], v[8:9], s[0:1], v[128:129] op_sel_hi:[1,0,1]
	v_pk_fma_f32 v[132:133], v[10:11], s[0:1], v[132:133] op_sel_hi:[1,0,1]
	v_pk_fma_f32 v[134:135], v[12:13], s[0:1], v[134:135] op_sel_hi:[1,0,1]
	v_pk_fma_f32 v[136:137], v[14:15], s[0:1], v[136:137] op_sel_hi:[1,0,1]
	v_readlane_b32 s0, v167, 34
	s_waitcnt vmcnt(15)
	v_cvt_scalef32_pk_f32_fp4 v[0:1], v148, 1.0
	v_cvt_scalef32_pk_f32_fp4 v[2:3], v148, 1.0 op_sel:[1,0,0]
	v_cvt_scalef32_pk_f32_fp4 v[4:5], v148, 1.0 op_sel:[0,1,0]
	v_cvt_scalef32_pk_f32_fp4 v[6:7], v148, 1.0 op_sel:[1,1,0]
	v_cvt_scalef32_pk_f32_fp4 v[8:9], v149, 1.0
	v_cvt_scalef32_pk_f32_fp4 v[10:11], v149, 1.0 op_sel:[1,0,0]
	v_cvt_scalef32_pk_f32_fp4 v[12:13], v149, 1.0 op_sel:[0,1,0]
	v_cvt_scalef32_pk_f32_fp4 v[14:15], v149, 1.0 op_sel:[1,1,0]
	v_readlane_b32 s54, v90, 50
	s_lshl_b32 s56, s54, 9
	s_add_u32 s56, s64, s56
	s_addc_u32 s57, s65, 0
	global_load_dwordx2 v[148:149], v227, s[56:57]
	v_pk_fma_f32 v[130:131], v[0:1], s[0:1], v[130:131] op_sel_hi:[1,0,1]
	v_pk_fma_f32 v[138:139], v[2:3], s[0:1], v[138:139] op_sel_hi:[1,0,1]
	v_pk_fma_f32 v[140:141], v[4:5], s[0:1], v[140:141] op_sel_hi:[1,0,1]
	v_pk_fma_f32 v[142:143], v[6:7], s[0:1], v[142:143] op_sel_hi:[1,0,1]
	v_pk_fma_f32 v[128:129], v[8:9], s[0:1], v[128:129] op_sel_hi:[1,0,1]
	v_pk_fma_f32 v[132:133], v[10:11], s[0:1], v[132:133] op_sel_hi:[1,0,1]
	v_pk_fma_f32 v[134:135], v[12:13], s[0:1], v[134:135] op_sel_hi:[1,0,1]
	v_pk_fma_f32 v[136:137], v[14:15], s[0:1], v[136:137] op_sel_hi:[1,0,1]
	v_readlane_b32 s0, v167, 35
	s_waitcnt vmcnt(15)
	v_cvt_scalef32_pk_f32_fp4 v[0:1], v150, 1.0
	v_cvt_scalef32_pk_f32_fp4 v[2:3], v150, 1.0 op_sel:[1,0,0]
	v_cvt_scalef32_pk_f32_fp4 v[4:5], v150, 1.0 op_sel:[0,1,0]
	v_cvt_scalef32_pk_f32_fp4 v[6:7], v150, 1.0 op_sel:[1,1,0]
	v_cvt_scalef32_pk_f32_fp4 v[8:9], v151, 1.0
	v_cvt_scalef32_pk_f32_fp4 v[10:11], v151, 1.0 op_sel:[1,0,0]
	v_cvt_scalef32_pk_f32_fp4 v[12:13], v151, 1.0 op_sel:[0,1,0]
	v_cvt_scalef32_pk_f32_fp4 v[14:15], v151, 1.0 op_sel:[1,1,0]
	v_readlane_b32 s54, v90, 51
	s_lshl_b32 s56, s54, 9
	s_add_u32 s56, s64, s56
	s_addc_u32 s57, s65, 0
	global_load_dwordx2 v[150:151], v227, s[56:57]
	v_pk_fma_f32 v[130:131], v[0:1], s[0:1], v[130:131] op_sel_hi:[1,0,1]
	v_pk_fma_f32 v[138:139], v[2:3], s[0:1], v[138:139] op_sel_hi:[1,0,1]
	v_pk_fma_f32 v[140:141], v[4:5], s[0:1], v[140:141] op_sel_hi:[1,0,1]
	v_pk_fma_f32 v[142:143], v[6:7], s[0:1], v[142:143] op_sel_hi:[1,0,1]
	v_pk_fma_f32 v[128:129], v[8:9], s[0:1], v[128:129] op_sel_hi:[1,0,1]
	v_pk_fma_f32 v[132:133], v[10:11], s[0:1], v[132:133] op_sel_hi:[1,0,1]
	v_pk_fma_f32 v[134:135], v[12:13], s[0:1], v[134:135] op_sel_hi:[1,0,1]
	v_pk_fma_f32 v[136:137], v[14:15], s[0:1], v[136:137] op_sel_hi:[1,0,1]
	v_readlane_b32 s0, v167, 36
	s_waitcnt vmcnt(15)
	v_cvt_scalef32_pk_f32_fp4 v[0:1], v152, 1.0
	v_cvt_scalef32_pk_f32_fp4 v[2:3], v152, 1.0 op_sel:[1,0,0]
	v_cvt_scalef32_pk_f32_fp4 v[4:5], v152, 1.0 op_sel:[0,1,0]
	v_cvt_scalef32_pk_f32_fp4 v[6:7], v152, 1.0 op_sel:[1,1,0]
	v_cvt_scalef32_pk_f32_fp4 v[8:9], v153, 1.0
	v_cvt_scalef32_pk_f32_fp4 v[10:11], v153, 1.0 op_sel:[1,0,0]
	v_cvt_scalef32_pk_f32_fp4 v[12:13], v153, 1.0 op_sel:[0,1,0]
	v_cvt_scalef32_pk_f32_fp4 v[14:15], v153, 1.0 op_sel:[1,1,0]
	v_readlane_b32 s54, v90, 52
	s_lshl_b32 s56, s54, 9
	s_add_u32 s56, s64, s56
	s_addc_u32 s57, s65, 0
	global_load_dwordx2 v[152:153], v227, s[56:57]
	v_pk_fma_f32 v[130:131], v[0:1], s[0:1], v[130:131] op_sel_hi:[1,0,1]
	v_pk_fma_f32 v[138:139], v[2:3], s[0:1], v[138:139] op_sel_hi:[1,0,1]
	v_pk_fma_f32 v[140:141], v[4:5], s[0:1], v[140:141] op_sel_hi:[1,0,1]
	v_pk_fma_f32 v[142:143], v[6:7], s[0:1], v[142:143] op_sel_hi:[1,0,1]
	v_pk_fma_f32 v[128:129], v[8:9], s[0:1], v[128:129] op_sel_hi:[1,0,1]
	v_pk_fma_f32 v[132:133], v[10:11], s[0:1], v[132:133] op_sel_hi:[1,0,1]
	v_pk_fma_f32 v[134:135], v[12:13], s[0:1], v[134:135] op_sel_hi:[1,0,1]
	v_pk_fma_f32 v[136:137], v[14:15], s[0:1], v[136:137] op_sel_hi:[1,0,1]
	v_readlane_b32 s0, v167, 37
	s_waitcnt vmcnt(15)
	v_cvt_scalef32_pk_f32_fp4 v[0:1], v154, 1.0
	v_cvt_scalef32_pk_f32_fp4 v[2:3], v154, 1.0 op_sel:[1,0,0]
	v_cvt_scalef32_pk_f32_fp4 v[4:5], v154, 1.0 op_sel:[0,1,0]
	v_cvt_scalef32_pk_f32_fp4 v[6:7], v154, 1.0 op_sel:[1,1,0]
	v_cvt_scalef32_pk_f32_fp4 v[8:9], v155, 1.0
	v_cvt_scalef32_pk_f32_fp4 v[10:11], v155, 1.0 op_sel:[1,0,0]
	v_cvt_scalef32_pk_f32_fp4 v[12:13], v155, 1.0 op_sel:[0,1,0]
	v_cvt_scalef32_pk_f32_fp4 v[14:15], v155, 1.0 op_sel:[1,1,0]
	v_readlane_b32 s54, v90, 53
	s_lshl_b32 s56, s54, 9
	s_add_u32 s56, s64, s56
	s_addc_u32 s57, s65, 0
	global_load_dwordx2 v[154:155], v227, s[56:57]
	v_pk_fma_f32 v[130:131], v[0:1], s[0:1], v[130:131] op_sel_hi:[1,0,1]
	v_pk_fma_f32 v[138:139], v[2:3], s[0:1], v[138:139] op_sel_hi:[1,0,1]
	v_pk_fma_f32 v[140:141], v[4:5], s[0:1], v[140:141] op_sel_hi:[1,0,1]
	v_pk_fma_f32 v[142:143], v[6:7], s[0:1], v[142:143] op_sel_hi:[1,0,1]
	v_pk_fma_f32 v[128:129], v[8:9], s[0:1], v[128:129] op_sel_hi:[1,0,1]
	v_pk_fma_f32 v[132:133], v[10:11], s[0:1], v[132:133] op_sel_hi:[1,0,1]
	v_pk_fma_f32 v[134:135], v[12:13], s[0:1], v[134:135] op_sel_hi:[1,0,1]
	v_pk_fma_f32 v[136:137], v[14:15], s[0:1], v[136:137] op_sel_hi:[1,0,1]
	v_readlane_b32 s0, v167, 38
	s_waitcnt vmcnt(15)
; __device__ void peer_gather_phase(const Params& P, int l, bool do_store) {
;     ...
;         const int ea = __builtin_amdgcn_readlane(evs, kb + 2 * pr), eb = __builtin_amdgcn_readlane(evs, kb + 2 * pr + 1);
;         const uint2* up = (const uint2*)(U + (size_t)(uphi ? eb : ea) * 768);
;         u6[3 * pr] = up[0]; u6[3 * pr + 1] = up[1]; u6[3 * pr + 2] = up[2];
;         v8[2 * pr] = *(const uint2*)(V + (size_t)ea * 512);
;         v8[2 * pr + 1] = *(const uint2*)(V + (size_t)eb * 512);
;     ...
; #pragma unroll
;       for (int j = 0; j < 8; ++j) {
;         const float a = __builtin_bit_cast(float, __builtin_amdgcn_readlane(__builtin_bit_cast(int, avec), kb + j));
;         const f32x2 aa = f32x2{a, a};
;         y[0] += aa * __builtin_amdgcn_cvt_scalef32_pk_f32_fp4(v8[j].x, 1.0f, 0); y[1] += aa * __builtin_amdgcn_cvt_scalef32_pk_f32_fp4(v8[j].x, 1.0f, 1);
;         y[2] += aa * __builtin_amdgcn_cvt_scalef32_pk_f32_fp4(v8[j].x, 1.0f, 2); y[3] += aa * __builtin_amdgcn_cvt_scalef32_pk_f32_fp4(v8[j].x, 1.0f, 3);
;         y[4] += aa * __builtin_amdgcn_cvt_scalef32_pk_f32_fp4(v8[j].y, 1.0f, 0); y[5] += aa * __builtin_amdgcn_cvt_scalef32_pk_f32_fp4(v8[j].y, 1.0f, 1);
;         y[6] += aa * __builtin_amdgcn_cvt_scalef32_pk_f32_fp4(v8[j].y, 1.0f, 2); y[7] += aa * __builtin_amdgcn_cvt_scalef32_pk_f32_fp4(v8[j].y, 1.0f, 3);
;       }
	v_cvt_scalef32_pk_f32_fp4 v[0:1], v156, 1.0
	v_cvt_scalef32_pk_f32_fp4 v[2:3], v156, 1.0 op_sel:[1,0,0]
	v_cvt_scalef32_pk_f32_fp4 v[4:5], v156, 1.0 op_sel:[0,1,0]
	v_cvt_scalef32_pk_f32_fp4 v[6:7], v156, 1.0 op_sel:[1,1,0]
	v_cvt_scalef32_pk_f32_fp4 v[8:9], v157, 1.0
	v_cvt_scalef32_pk_f32_fp4 v[10:11], v157, 1.0 op_sel:[1,0,0]
	v_cvt_scalef32_pk_f32_fp4 v[12:13], v157, 1.0 op_sel:[0,1,0]
	v_cvt_scalef32_pk_f32_fp4 v[14:15], v157, 1.0 op_sel:[1,1,0]
	v_readlane_b32 s54, v90, 54
	s_lshl_b32 s56, s54, 9
	s_add_u32 s56, s64, s56
	s_addc_u32 s57, s65, 0
	global_load_dwordx2 v[156:157], v227, s[56:57]
	v_pk_fma_f32 v[130:131], v[0:1], s[0:1], v[130:131] op_sel_hi:[1,0,1]
	v_pk_fma_f32 v[138:139], v[2:3], s[0:1], v[138:139] op_sel_hi:[1,0,1]
	v_pk_fma_f32 v[140:141], v[4:5], s[0:1], v[140:141] op_sel_hi:[1,0,1]
	v_pk_fma_f32 v[142:143], v[6:7], s[0:1], v[142:143] op_sel_hi:[1,0,1]
	v_pk_fma_f32 v[128:129], v[8:9], s[0:1], v[128:129] op_sel_hi:[1,0,1]
	v_pk_fma_f32 v[132:133], v[10:11], s[0:1], v[132:133] op_sel_hi:[1,0,1]
	v_pk_fma_f32 v[134:135], v[12:13], s[0:1], v[134:135] op_sel_hi:[1,0,1]
	v_pk_fma_f32 v[136:137], v[14:15], s[0:1], v[136:137] op_sel_hi:[1,0,1]
	v_readlane_b32 s0, v167, 39
	s_waitcnt vmcnt(15)
	v_cvt_scalef32_pk_f32_fp4 v[0:1], v158, 1.0
	v_cvt_scalef32_pk_f32_fp4 v[2:3], v158, 1.0 op_sel:[1,0,0]
	v_cvt_scalef32_pk_f32_fp4 v[4:5], v158, 1.0 op_sel:[0,1,0]
	v_cvt_scalef32_pk_f32_fp4 v[6:7], v158, 1.0 op_sel:[1,1,0]
	v_cvt_scalef32_pk_f32_fp4 v[8:9], v159, 1.0
	v_cvt_scalef32_pk_f32_fp4 v[10:11], v159, 1.0 op_sel:[1,0,0]
	v_cvt_scalef32_pk_f32_fp4 v[12:13], v159, 1.0 op_sel:[0,1,0]
	v_cvt_scalef32_pk_f32_fp4 v[14:15], v159, 1.0 op_sel:[1,1,0]
	v_readlane_b32 s54, v90, 55
	s_lshl_b32 s56, s54, 9
	s_add_u32 s56, s64, s56
	s_addc_u32 s57, s65, 0
	global_load_dwordx2 v[158:159], v227, s[56:57]
	v_pk_fma_f32 v[130:131], v[0:1], s[0:1], v[130:131] op_sel_hi:[1,0,1]
	v_pk_fma_f32 v[138:139], v[2:3], s[0:1], v[138:139] op_sel_hi:[1,0,1]
	v_pk_fma_f32 v[140:141], v[4:5], s[0:1], v[140:141] op_sel_hi:[1,0,1]
	v_pk_fma_f32 v[142:143], v[6:7], s[0:1], v[142:143] op_sel_hi:[1,0,1]
	v_pk_fma_f32 v[128:129], v[8:9], s[0:1], v[128:129] op_sel_hi:[1,0,1]
	v_pk_fma_f32 v[132:133], v[10:11], s[0:1], v[132:133] op_sel_hi:[1,0,1]
	v_pk_fma_f32 v[134:135], v[12:13], s[0:1], v[134:135] op_sel_hi:[1,0,1]
	v_pk_fma_f32 v[136:137], v[14:15], s[0:1], v[136:137] op_sel_hi:[1,0,1]
	v_readlane_b32 s0, v167, 40
	s_waitcnt vmcnt(15)
	v_cvt_scalef32_pk_f32_fp4 v[0:1], v168, 1.0
	v_cvt_scalef32_pk_f32_fp4 v[2:3], v168, 1.0 op_sel:[1,0,0]
	v_cvt_scalef32_pk_f32_fp4 v[4:5], v168, 1.0 op_sel:[0,1,0]
	v_cvt_scalef32_pk_f32_fp4 v[6:7], v168, 1.0 op_sel:[1,1,0]
	v_cvt_scalef32_pk_f32_fp4 v[8:9], v169, 1.0
	v_cvt_scalef32_pk_f32_fp4 v[10:11], v169, 1.0 op_sel:[1,0,0]
	v_cvt_scalef32_pk_f32_fp4 v[12:13], v169, 1.0 op_sel:[0,1,0]
	v_cvt_scalef32_pk_f32_fp4 v[14:15], v169, 1.0 op_sel:[1,1,0]
	v_readlane_b32 s54, v90, 56
	s_lshl_b32 s56, s54, 9
	s_add_u32 s56, s64, s56
	s_addc_u32 s57, s65, 0
	global_load_dwordx2 v[168:169], v227, s[56:57]
	v_pk_fma_f32 v[130:131], v[0:1], s[0:1], v[130:131] op_sel_hi:[1,0,1]
	v_pk_fma_f32 v[138:139], v[2:3], s[0:1], v[138:139] op_sel_hi:[1,0,1]
	v_pk_fma_f32 v[140:141], v[4:5], s[0:1], v[140:141] op_sel_hi:[1,0,1]
	v_pk_fma_f32 v[142:143], v[6:7], s[0:1], v[142:143] op_sel_hi:[1,0,1]
	v_pk_fma_f32 v[128:129], v[8:9], s[0:1], v[128:129] op_sel_hi:[1,0,1]
	v_pk_fma_f32 v[132:133], v[10:11], s[0:1], v[132:133] op_sel_hi:[1,0,1]
	v_pk_fma_f32 v[134:135], v[12:13], s[0:1], v[134:135] op_sel_hi:[1,0,1]
	v_pk_fma_f32 v[136:137], v[14:15], s[0:1], v[136:137] op_sel_hi:[1,0,1]
	v_readlane_b32 s0, v167, 41
	s_waitcnt vmcnt(15)
	v_cvt_scalef32_pk_f32_fp4 v[0:1], v170, 1.0
	v_cvt_scalef32_pk_f32_fp4 v[2:3], v170, 1.0 op_sel:[1,0,0]
	v_cvt_scalef32_pk_f32_fp4 v[4:5], v170, 1.0 op_sel:[0,1,0]
	v_cvt_scalef32_pk_f32_fp4 v[6:7], v170, 1.0 op_sel:[1,1,0]
	v_cvt_scalef32_pk_f32_fp4 v[8:9], v171, 1.0
	v_cvt_scalef32_pk_f32_fp4 v[10:11], v171, 1.0 op_sel:[1,0,0]
	v_cvt_scalef32_pk_f32_fp4 v[12:13], v171, 1.0 op_sel:[0,1,0]
	v_cvt_scalef32_pk_f32_fp4 v[14:15], v171, 1.0 op_sel:[1,1,0]
	v_readlane_b32 s54, v90, 57
	s_lshl_b32 s56, s54, 9
	s_add_u32 s56, s64, s56
	s_addc_u32 s57, s65, 0
	global_load_dwordx2 v[170:171], v227, s[56:57]
	v_pk_fma_f32 v[130:131], v[0:1], s[0:1], v[130:131] op_sel_hi:[1,0,1]
	v_pk_fma_f32 v[138:139], v[2:3], s[0:1], v[138:139] op_sel_hi:[1,0,1]
	v_pk_fma_f32 v[140:141], v[4:5], s[0:1], v[140:141] op_sel_hi:[1,0,1]
	v_pk_fma_f32 v[142:143], v[6:7], s[0:1], v[142:143] op_sel_hi:[1,0,1]
	v_pk_fma_f32 v[128:129], v[8:9], s[0:1], v[128:129] op_sel_hi:[1,0,1]
	v_pk_fma_f32 v[132:133], v[10:11], s[0:1], v[132:133] op_sel_hi:[1,0,1]
	v_pk_fma_f32 v[134:135], v[12:13], s[0:1], v[134:135] op_sel_hi:[1,0,1]
	v_pk_fma_f32 v[136:137], v[14:15], s[0:1], v[136:137] op_sel_hi:[1,0,1]
	v_readlane_b32 s0, v167, 42
	s_waitcnt vmcnt(15)
	v_cvt_scalef32_pk_f32_fp4 v[0:1], v172, 1.0
	v_cvt_scalef32_pk_f32_fp4 v[2:3], v172, 1.0 op_sel:[1,0,0]
	v_cvt_scalef32_pk_f32_fp4 v[4:5], v172, 1.0 op_sel:[0,1,0]
	v_cvt_scalef32_pk_f32_fp4 v[6:7], v172, 1.0 op_sel:[1,1,0]
	v_cvt_scalef32_pk_f32_fp4 v[8:9], v173, 1.0
	v_cvt_scalef32_pk_f32_fp4 v[10:11], v173, 1.0 op_sel:[1,0,0]
	v_cvt_scalef32_pk_f32_fp4 v[12:13], v173, 1.0 op_sel:[0,1,0]
	v_cvt_scalef32_pk_f32_fp4 v[14:15], v173, 1.0 op_sel:[1,1,0]
	v_readlane_b32 s54, v90, 58
	s_lshl_b32 s56, s54, 9
	s_add_u32 s56, s64, s56
	s_addc_u32 s57, s65, 0
	global_load_dwordx2 v[172:173], v227, s[56:57]
	v_pk_fma_f32 v[130:131], v[0:1], s[0:1], v[130:131] op_sel_hi:[1,0,1]
	v_pk_fma_f32 v[138:139], v[2:3], s[0:1], v[138:139] op_sel_hi:[1,0,1]
	v_pk_fma_f32 v[140:141], v[4:5], s[0:1], v[140:141] op_sel_hi:[1,0,1]
	v_pk_fma_f32 v[142:143], v[6:7], s[0:1], v[142:143] op_sel_hi:[1,0,1]
	v_pk_fma_f32 v[128:129], v[8:9], s[0:1], v[128:129] op_sel_hi:[1,0,1]
	v_pk_fma_f32 v[132:133], v[10:11], s[0:1], v[132:133] op_sel_hi:[1,0,1]
	v_pk_fma_f32 v[134:135], v[12:13], s[0:1], v[134:135] op_sel_hi:[1,0,1]
	v_pk_fma_f32 v[136:137], v[14:15], s[0:1], v[136:137] op_sel_hi:[1,0,1]
	v_readlane_b32 s0, v167, 43
	s_waitcnt vmcnt(15)
; __device__ void peer_gather_phase(const Params& P, int l, bool do_store) {
;     ...
;         const int ea = __builtin_amdgcn_readlane(evs, kb + 2 * pr), eb = __builtin_amdgcn_readlane(evs, kb + 2 * pr + 1);
;         const uint2* up = (const uint2*)(U + (size_t)(uphi ? eb : ea) * 768);
;         u6[3 * pr] = up[0]; u6[3 * pr + 1] = up[1]; u6[3 * pr + 2] = up[2];
;         v8[2 * pr] = *(const uint2*)(V + (size_t)ea * 512);
;         v8[2 * pr + 1] = *(const uint2*)(V + (size_t)eb * 512);
;     ...
; #pragma unroll
;       for (int j = 0; j < 8; ++j) {
;         const float a = __builtin_bit_cast(float, __builtin_amdgcn_readlane(__builtin_bit_cast(int, avec), kb + j));
;         const f32x2 aa = f32x2{a, a};
;         y[0] += aa * __builtin_amdgcn_cvt_scalef32_pk_f32_fp4(v8[j].x, 1.0f, 0); y[1] += aa * __builtin_amdgcn_cvt_scalef32_pk_f32_fp4(v8[j].x, 1.0f, 1);
;         y[2] += aa * __builtin_amdgcn_cvt_scalef32_pk_f32_fp4(v8[j].x, 1.0f, 2); y[3] += aa * __builtin_amdgcn_cvt_scalef32_pk_f32_fp4(v8[j].x, 1.0f, 3);
;         y[4] += aa * __builtin_amdgcn_cvt_scalef32_pk_f32_fp4(v8[j].y, 1.0f, 0); y[5] += aa * __builtin_amdgcn_cvt_scalef32_pk_f32_fp4(v8[j].y, 1.0f, 1);
;         y[6] += aa * __builtin_amdgcn_cvt_scalef32_pk_f32_fp4(v8[j].y, 1.0f, 2); y[7] += aa * __builtin_amdgcn_cvt_scalef32_pk_f32_fp4(v8[j].y, 1.0f, 3);
;       }
	v_cvt_scalef32_pk_f32_fp4 v[0:1], v174, 1.0
	v_cvt_scalef32_pk_f32_fp4 v[2:3], v174, 1.0 op_sel:[1,0,0]
	v_cvt_scalef32_pk_f32_fp4 v[4:5], v174, 1.0 op_sel:[0,1,0]
	v_cvt_scalef32_pk_f32_fp4 v[6:7], v174, 1.0 op_sel:[1,1,0]
	v_cvt_scalef32_pk_f32_fp4 v[8:9], v175, 1.0
	v_cvt_scalef32_pk_f32_fp4 v[10:11], v175, 1.0 op_sel:[1,0,0]
	v_cvt_scalef32_pk_f32_fp4 v[12:13], v175, 1.0 op_sel:[0,1,0]
	v_cvt_scalef32_pk_f32_fp4 v[14:15], v175, 1.0 op_sel:[1,1,0]
	v_readlane_b32 s54, v90, 59
	s_lshl_b32 s56, s54, 9
	s_add_u32 s56, s64, s56
	s_addc_u32 s57, s65, 0
	global_load_dwordx2 v[174:175], v227, s[56:57]
	v_pk_fma_f32 v[130:131], v[0:1], s[0:1], v[130:131] op_sel_hi:[1,0,1]
	v_pk_fma_f32 v[138:139], v[2:3], s[0:1], v[138:139] op_sel_hi:[1,0,1]
	v_pk_fma_f32 v[140:141], v[4:5], s[0:1], v[140:141] op_sel_hi:[1,0,1]
	v_pk_fma_f32 v[142:143], v[6:7], s[0:1], v[142:143] op_sel_hi:[1,0,1]
	v_pk_fma_f32 v[128:129], v[8:9], s[0:1], v[128:129] op_sel_hi:[1,0,1]
	v_pk_fma_f32 v[132:133], v[10:11], s[0:1], v[132:133] op_sel_hi:[1,0,1]
	v_pk_fma_f32 v[134:135], v[12:13], s[0:1], v[134:135] op_sel_hi:[1,0,1]
	v_pk_fma_f32 v[136:137], v[14:15], s[0:1], v[136:137] op_sel_hi:[1,0,1]
	v_readlane_b32 s0, v167, 44
	s_waitcnt vmcnt(15)
	v_cvt_scalef32_pk_f32_fp4 v[0:1], v180, 1.0
	v_cvt_scalef32_pk_f32_fp4 v[2:3], v180, 1.0 op_sel:[1,0,0]
	v_cvt_scalef32_pk_f32_fp4 v[4:5], v180, 1.0 op_sel:[0,1,0]
	v_cvt_scalef32_pk_f32_fp4 v[6:7], v180, 1.0 op_sel:[1,1,0]
	v_cvt_scalef32_pk_f32_fp4 v[8:9], v181, 1.0
	v_cvt_scalef32_pk_f32_fp4 v[10:11], v181, 1.0 op_sel:[1,0,0]
	v_cvt_scalef32_pk_f32_fp4 v[12:13], v181, 1.0 op_sel:[0,1,0]
	v_cvt_scalef32_pk_f32_fp4 v[14:15], v181, 1.0 op_sel:[1,1,0]
	v_readlane_b32 s54, v90, 60
	s_lshl_b32 s56, s54, 9
	s_add_u32 s56, s64, s56
	s_addc_u32 s57, s65, 0
	global_load_dwordx2 v[180:181], v227, s[56:57]
	v_pk_fma_f32 v[130:131], v[0:1], s[0:1], v[130:131] op_sel_hi:[1,0,1]
	v_pk_fma_f32 v[138:139], v[2:3], s[0:1], v[138:139] op_sel_hi:[1,0,1]
	v_pk_fma_f32 v[140:141], v[4:5], s[0:1], v[140:141] op_sel_hi:[1,0,1]
	v_pk_fma_f32 v[142:143], v[6:7], s[0:1], v[142:143] op_sel_hi:[1,0,1]
	v_pk_fma_f32 v[128:129], v[8:9], s[0:1], v[128:129] op_sel_hi:[1,0,1]
	v_pk_fma_f32 v[132:133], v[10:11], s[0:1], v[132:133] op_sel_hi:[1,0,1]
	v_pk_fma_f32 v[134:135], v[12:13], s[0:1], v[134:135] op_sel_hi:[1,0,1]
	v_pk_fma_f32 v[136:137], v[14:15], s[0:1], v[136:137] op_sel_hi:[1,0,1]
	v_readlane_b32 s0, v167, 45
	s_waitcnt vmcnt(15)
	v_cvt_scalef32_pk_f32_fp4 v[0:1], v182, 1.0
	v_cvt_scalef32_pk_f32_fp4 v[2:3], v182, 1.0 op_sel:[1,0,0]
	v_cvt_scalef32_pk_f32_fp4 v[4:5], v182, 1.0 op_sel:[0,1,0]
	v_cvt_scalef32_pk_f32_fp4 v[6:7], v182, 1.0 op_sel:[1,1,0]
	v_cvt_scalef32_pk_f32_fp4 v[8:9], v183, 1.0
	v_cvt_scalef32_pk_f32_fp4 v[10:11], v183, 1.0 op_sel:[1,0,0]
	v_cvt_scalef32_pk_f32_fp4 v[12:13], v183, 1.0 op_sel:[0,1,0]
	v_cvt_scalef32_pk_f32_fp4 v[14:15], v183, 1.0 op_sel:[1,1,0]
	v_readlane_b32 s54, v90, 61
	s_lshl_b32 s56, s54, 9
	s_add_u32 s56, s64, s56
	s_addc_u32 s57, s65, 0
	global_load_dwordx2 v[182:183], v227, s[56:57]
	v_pk_fma_f32 v[130:131], v[0:1], s[0:1], v[130:131] op_sel_hi:[1,0,1]
	v_pk_fma_f32 v[138:139], v[2:3], s[0:1], v[138:139] op_sel_hi:[1,0,1]
	v_pk_fma_f32 v[140:141], v[4:5], s[0:1], v[140:141] op_sel_hi:[1,0,1]
	v_pk_fma_f32 v[142:143], v[6:7], s[0:1], v[142:143] op_sel_hi:[1,0,1]
	v_pk_fma_f32 v[128:129], v[8:9], s[0:1], v[128:129] op_sel_hi:[1,0,1]
	v_pk_fma_f32 v[132:133], v[10:11], s[0:1], v[132:133] op_sel_hi:[1,0,1]
	v_pk_fma_f32 v[134:135], v[12:13], s[0:1], v[134:135] op_sel_hi:[1,0,1]
	v_pk_fma_f32 v[136:137], v[14:15], s[0:1], v[136:137] op_sel_hi:[1,0,1]
	v_readlane_b32 s0, v167, 46
	s_waitcnt vmcnt(15)
	v_cvt_scalef32_pk_f32_fp4 v[0:1], v184, 1.0
	v_cvt_scalef32_pk_f32_fp4 v[2:3], v184, 1.0 op_sel:[1,0,0]
	v_cvt_scalef32_pk_f32_fp4 v[4:5], v184, 1.0 op_sel:[0,1,0]
	v_cvt_scalef32_pk_f32_fp4 v[6:7], v184, 1.0 op_sel:[1,1,0]
	v_cvt_scalef32_pk_f32_fp4 v[8:9], v185, 1.0
	v_cvt_scalef32_pk_f32_fp4 v[10:11], v185, 1.0 op_sel:[1,0,0]
	v_cvt_scalef32_pk_f32_fp4 v[12:13], v185, 1.0 op_sel:[0,1,0]
	v_cvt_scalef32_pk_f32_fp4 v[14:15], v185, 1.0 op_sel:[1,1,0]
	v_readlane_b32 s54, v90, 62
	s_lshl_b32 s56, s54, 9
	s_add_u32 s56, s64, s56
	s_addc_u32 s57, s65, 0
	global_load_dwordx2 v[184:185], v227, s[56:57]
	v_pk_fma_f32 v[130:131], v[0:1], s[0:1], v[130:131] op_sel_hi:[1,0,1]
	v_pk_fma_f32 v[138:139], v[2:3], s[0:1], v[138:139] op_sel_hi:[1,0,1]
	v_pk_fma_f32 v[140:141], v[4:5], s[0:1], v[140:141] op_sel_hi:[1,0,1]
	v_pk_fma_f32 v[142:143], v[6:7], s[0:1], v[142:143] op_sel_hi:[1,0,1]
	v_pk_fma_f32 v[128:129], v[8:9], s[0:1], v[128:129] op_sel_hi:[1,0,1]
	v_pk_fma_f32 v[132:133], v[10:11], s[0:1], v[132:133] op_sel_hi:[1,0,1]
	v_pk_fma_f32 v[134:135], v[12:13], s[0:1], v[134:135] op_sel_hi:[1,0,1]
	v_pk_fma_f32 v[136:137], v[14:15], s[0:1], v[136:137] op_sel_hi:[1,0,1]
	v_readlane_b32 s0, v167, 47
	s_waitcnt vmcnt(15)
	v_cvt_scalef32_pk_f32_fp4 v[0:1], v186, 1.0
	v_cvt_scalef32_pk_f32_fp4 v[2:3], v186, 1.0 op_sel:[1,0,0]
	v_cvt_scalef32_pk_f32_fp4 v[4:5], v186, 1.0 op_sel:[0,1,0]
	v_cvt_scalef32_pk_f32_fp4 v[6:7], v186, 1.0 op_sel:[1,1,0]
	v_cvt_scalef32_pk_f32_fp4 v[8:9], v187, 1.0
	v_cvt_scalef32_pk_f32_fp4 v[10:11], v187, 1.0 op_sel:[1,0,0]
	v_cvt_scalef32_pk_f32_fp4 v[12:13], v187, 1.0 op_sel:[0,1,0]
	v_cvt_scalef32_pk_f32_fp4 v[14:15], v187, 1.0 op_sel:[1,1,0]
	v_readlane_b32 s54, v90, 63
	s_lshl_b32 s56, s54, 9
	s_add_u32 s56, s64, s56
	s_addc_u32 s57, s65, 0
	global_load_dwordx2 v[186:187], v227, s[56:57]
	v_pk_fma_f32 v[130:131], v[0:1], s[0:1], v[130:131] op_sel_hi:[1,0,1]
	v_pk_fma_f32 v[138:139], v[2:3], s[0:1], v[138:139] op_sel_hi:[1,0,1]
	v_pk_fma_f32 v[140:141], v[4:5], s[0:1], v[140:141] op_sel_hi:[1,0,1]
	v_pk_fma_f32 v[142:143], v[6:7], s[0:1], v[142:143] op_sel_hi:[1,0,1]
	v_pk_fma_f32 v[128:129], v[8:9], s[0:1], v[128:129] op_sel_hi:[1,0,1]
	v_pk_fma_f32 v[132:133], v[10:11], s[0:1], v[132:133] op_sel_hi:[1,0,1]
	v_pk_fma_f32 v[134:135], v[12:13], s[0:1], v[134:135] op_sel_hi:[1,0,1]
	v_pk_fma_f32 v[136:137], v[14:15], s[0:1], v[136:137] op_sel_hi:[1,0,1]
	v_readlane_b32 s0, v167, 48
	s_waitcnt vmcnt(15)
; __device__ void peer_gather_phase(const Params& P, int l, bool do_store) {
;     ...
; #pragma unroll
;       for (int j = 0; j < 8; ++j) {
;         const float a = __builtin_bit_cast(float, __builtin_amdgcn_readlane(__builtin_bit_cast(int, avec), kb + j));
;         const f32x2 aa = f32x2{a, a};
;         y[0] += aa * __builtin_amdgcn_cvt_scalef32_pk_f32_fp4(v8[j].x, 1.0f, 0); y[1] += aa * __builtin_amdgcn_cvt_scalef32_pk_f32_fp4(v8[j].x, 1.0f, 1);
;         y[2] += aa * __builtin_amdgcn_cvt_scalef32_pk_f32_fp4(v8[j].x, 1.0f, 2); y[3] += aa * __builtin_amdgcn_cvt_scalef32_pk_f32_fp4(v8[j].x, 1.0f, 3);
;         y[4] += aa * __builtin_amdgcn_cvt_scalef32_pk_f32_fp4(v8[j].y, 1.0f, 0); y[5] += aa * __builtin_amdgcn_cvt_scalef32_pk_f32_fp4(v8[j].y, 1.0f, 1);
;         y[6] += aa * __builtin_amdgcn_cvt_scalef32_pk_f32_fp4(v8[j].y, 1.0f, 2); y[7] += aa * __builtin_amdgcn_cvt_scalef32_pk_f32_fp4(v8[j].y, 1.0f, 3);
;       }
	v_cvt_scalef32_pk_f32_fp4 v[0:1], v144, 1.0
	v_cvt_scalef32_pk_f32_fp4 v[2:3], v144, 1.0 op_sel:[1,0,0]
	v_cvt_scalef32_pk_f32_fp4 v[4:5], v144, 1.0 op_sel:[0,1,0]
	v_cvt_scalef32_pk_f32_fp4 v[6:7], v144, 1.0 op_sel:[1,1,0]
	v_cvt_scalef32_pk_f32_fp4 v[8:9], v145, 1.0
	v_cvt_scalef32_pk_f32_fp4 v[10:11], v145, 1.0 op_sel:[1,0,0]
	v_cvt_scalef32_pk_f32_fp4 v[12:13], v145, 1.0 op_sel:[0,1,0]
	v_cvt_scalef32_pk_f32_fp4 v[14:15], v145, 1.0 op_sel:[1,1,0]
	v_pk_fma_f32 v[130:131], v[0:1], s[0:1], v[130:131] op_sel_hi:[1,0,1]
	v_pk_fma_f32 v[138:139], v[2:3], s[0:1], v[138:139] op_sel_hi:[1,0,1]
	v_pk_fma_f32 v[140:141], v[4:5], s[0:1], v[140:141] op_sel_hi:[1,0,1]
	v_pk_fma_f32 v[142:143], v[6:7], s[0:1], v[142:143] op_sel_hi:[1,0,1]
	v_pk_fma_f32 v[128:129], v[8:9], s[0:1], v[128:129] op_sel_hi:[1,0,1]
	v_pk_fma_f32 v[132:133], v[10:11], s[0:1], v[132:133] op_sel_hi:[1,0,1]
	v_pk_fma_f32 v[134:135], v[12:13], s[0:1], v[134:135] op_sel_hi:[1,0,1]
	v_pk_fma_f32 v[136:137], v[14:15], s[0:1], v[136:137] op_sel_hi:[1,0,1]
	v_readlane_b32 s0, v167, 49
	s_waitcnt vmcnt(14)
	v_cvt_scalef32_pk_f32_fp4 v[0:1], v146, 1.0
	v_cvt_scalef32_pk_f32_fp4 v[2:3], v146, 1.0 op_sel:[1,0,0]
	v_cvt_scalef32_pk_f32_fp4 v[4:5], v146, 1.0 op_sel:[0,1,0]
	v_cvt_scalef32_pk_f32_fp4 v[6:7], v146, 1.0 op_sel:[1,1,0]
	v_cvt_scalef32_pk_f32_fp4 v[8:9], v147, 1.0
	v_cvt_scalef32_pk_f32_fp4 v[10:11], v147, 1.0 op_sel:[1,0,0]
	v_cvt_scalef32_pk_f32_fp4 v[12:13], v147, 1.0 op_sel:[0,1,0]
	v_cvt_scalef32_pk_f32_fp4 v[14:15], v147, 1.0 op_sel:[1,1,0]
	v_pk_fma_f32 v[130:131], v[0:1], s[0:1], v[130:131] op_sel_hi:[1,0,1]
	v_pk_fma_f32 v[138:139], v[2:3], s[0:1], v[138:139] op_sel_hi:[1,0,1]
	v_pk_fma_f32 v[140:141], v[4:5], s[0:1], v[140:141] op_sel_hi:[1,0,1]
	v_pk_fma_f32 v[142:143], v[6:7], s[0:1], v[142:143] op_sel_hi:[1,0,1]
	v_pk_fma_f32 v[128:129], v[8:9], s[0:1], v[128:129] op_sel_hi:[1,0,1]
	v_pk_fma_f32 v[132:133], v[10:11], s[0:1], v[132:133] op_sel_hi:[1,0,1]
	v_pk_fma_f32 v[134:135], v[12:13], s[0:1], v[134:135] op_sel_hi:[1,0,1]
	v_pk_fma_f32 v[136:137], v[14:15], s[0:1], v[136:137] op_sel_hi:[1,0,1]
	v_readlane_b32 s0, v167, 50
	s_waitcnt vmcnt(13)
	v_cvt_scalef32_pk_f32_fp4 v[0:1], v148, 1.0
	v_cvt_scalef32_pk_f32_fp4 v[2:3], v148, 1.0 op_sel:[1,0,0]
	v_cvt_scalef32_pk_f32_fp4 v[4:5], v148, 1.0 op_sel:[0,1,0]
	v_cvt_scalef32_pk_f32_fp4 v[6:7], v148, 1.0 op_sel:[1,1,0]
	v_cvt_scalef32_pk_f32_fp4 v[8:9], v149, 1.0
	v_cvt_scalef32_pk_f32_fp4 v[10:11], v149, 1.0 op_sel:[1,0,0]
	v_cvt_scalef32_pk_f32_fp4 v[12:13], v149, 1.0 op_sel:[0,1,0]
	v_cvt_scalef32_pk_f32_fp4 v[14:15], v149, 1.0 op_sel:[1,1,0]
	v_pk_fma_f32 v[130:131], v[0:1], s[0:1], v[130:131] op_sel_hi:[1,0,1]
	v_pk_fma_f32 v[138:139], v[2:3], s[0:1], v[138:139] op_sel_hi:[1,0,1]
	v_pk_fma_f32 v[140:141], v[4:5], s[0:1], v[140:141] op_sel_hi:[1,0,1]
	v_pk_fma_f32 v[142:143], v[6:7], s[0:1], v[142:143] op_sel_hi:[1,0,1]
	v_pk_fma_f32 v[128:129], v[8:9], s[0:1], v[128:129] op_sel_hi:[1,0,1]
	v_pk_fma_f32 v[132:133], v[10:11], s[0:1], v[132:133] op_sel_hi:[1,0,1]
	v_pk_fma_f32 v[134:135], v[12:13], s[0:1], v[134:135] op_sel_hi:[1,0,1]
	v_pk_fma_f32 v[136:137], v[14:15], s[0:1], v[136:137] op_sel_hi:[1,0,1]
	v_readlane_b32 s0, v167, 51
	s_waitcnt vmcnt(12)
	v_cvt_scalef32_pk_f32_fp4 v[0:1], v150, 1.0
	v_cvt_scalef32_pk_f32_fp4 v[2:3], v150, 1.0 op_sel:[1,0,0]
	v_cvt_scalef32_pk_f32_fp4 v[4:5], v150, 1.0 op_sel:[0,1,0]
	v_cvt_scalef32_pk_f32_fp4 v[6:7], v150, 1.0 op_sel:[1,1,0]
	v_cvt_scalef32_pk_f32_fp4 v[8:9], v151, 1.0
	v_cvt_scalef32_pk_f32_fp4 v[10:11], v151, 1.0 op_sel:[1,0,0]
	v_cvt_scalef32_pk_f32_fp4 v[12:13], v151, 1.0 op_sel:[0,1,0]
	v_cvt_scalef32_pk_f32_fp4 v[14:15], v151, 1.0 op_sel:[1,1,0]
	v_pk_fma_f32 v[130:131], v[0:1], s[0:1], v[130:131] op_sel_hi:[1,0,1]
	v_pk_fma_f32 v[138:139], v[2:3], s[0:1], v[138:139] op_sel_hi:[1,0,1]
	v_pk_fma_f32 v[140:141], v[4:5], s[0:1], v[140:141] op_sel_hi:[1,0,1]
	v_pk_fma_f32 v[142:143], v[6:7], s[0:1], v[142:143] op_sel_hi:[1,0,1]
	v_pk_fma_f32 v[128:129], v[8:9], s[0:1], v[128:129] op_sel_hi:[1,0,1]
	v_pk_fma_f32 v[132:133], v[10:11], s[0:1], v[132:133] op_sel_hi:[1,0,1]
	v_pk_fma_f32 v[134:135], v[12:13], s[0:1], v[134:135] op_sel_hi:[1,0,1]
	v_pk_fma_f32 v[136:137], v[14:15], s[0:1], v[136:137] op_sel_hi:[1,0,1]
	v_readlane_b32 s0, v167, 52
	s_waitcnt vmcnt(11)
	v_cvt_scalef32_pk_f32_fp4 v[0:1], v152, 1.0
	v_cvt_scalef32_pk_f32_fp4 v[2:3], v152, 1.0 op_sel:[1,0,0]
	v_cvt_scalef32_pk_f32_fp4 v[4:5], v152, 1.0 op_sel:[0,1,0]
	v_cvt_scalef32_pk_f32_fp4 v[6:7], v152, 1.0 op_sel:[1,1,0]
	v_cvt_scalef32_pk_f32_fp4 v[8:9], v153, 1.0
	v_cvt_scalef32_pk_f32_fp4 v[10:11], v153, 1.0 op_sel:[1,0,0]
	v_cvt_scalef32_pk_f32_fp4 v[12:13], v153, 1.0 op_sel:[0,1,0]
	v_cvt_scalef32_pk_f32_fp4 v[14:15], v153, 1.0 op_sel:[1,1,0]
	v_pk_fma_f32 v[130:131], v[0:1], s[0:1], v[130:131] op_sel_hi:[1,0,1]
	v_pk_fma_f32 v[138:139], v[2:3], s[0:1], v[138:139] op_sel_hi:[1,0,1]
	v_pk_fma_f32 v[140:141], v[4:5], s[0:1], v[140:141] op_sel_hi:[1,0,1]
	v_pk_fma_f32 v[142:143], v[6:7], s[0:1], v[142:143] op_sel_hi:[1,0,1]
	v_pk_fma_f32 v[128:129], v[8:9], s[0:1], v[128:129] op_sel_hi:[1,0,1]
	v_pk_fma_f32 v[132:133], v[10:11], s[0:1], v[132:133] op_sel_hi:[1,0,1]
	v_pk_fma_f32 v[134:135], v[12:13], s[0:1], v[134:135] op_sel_hi:[1,0,1]
	v_pk_fma_f32 v[136:137], v[14:15], s[0:1], v[136:137] op_sel_hi:[1,0,1]
	v_readlane_b32 s0, v167, 53
	s_waitcnt vmcnt(10)
; __device__ void peer_gather_phase(const Params& P, int l, bool do_store) {
;     ...
; #pragma unroll
;       for (int j = 0; j < 8; ++j) {
;         const float a = __builtin_bit_cast(float, __builtin_amdgcn_readlane(__builtin_bit_cast(int, avec), kb + j));
;         const f32x2 aa = f32x2{a, a};
;         y[0] += aa * __builtin_amdgcn_cvt_scalef32_pk_f32_fp4(v8[j].x, 1.0f, 0); y[1] += aa * __builtin_amdgcn_cvt_scalef32_pk_f32_fp4(v8[j].x, 1.0f, 1);
;         y[2] += aa * __builtin_amdgcn_cvt_scalef32_pk_f32_fp4(v8[j].x, 1.0f, 2); y[3] += aa * __builtin_amdgcn_cvt_scalef32_pk_f32_fp4(v8[j].x, 1.0f, 3);
;         y[4] += aa * __builtin_amdgcn_cvt_scalef32_pk_f32_fp4(v8[j].y, 1.0f, 0); y[5] += aa * __builtin_amdgcn_cvt_scalef32_pk_f32_fp4(v8[j].y, 1.0f, 1);
;         y[6] += aa * __builtin_amdgcn_cvt_scalef32_pk_f32_fp4(v8[j].y, 1.0f, 2); y[7] += aa * __builtin_amdgcn_cvt_scalef32_pk_f32_fp4(v8[j].y, 1.0f, 3);
;       }
	v_cvt_scalef32_pk_f32_fp4 v[0:1], v154, 1.0
	v_cvt_scalef32_pk_f32_fp4 v[2:3], v154, 1.0 op_sel:[1,0,0]
	v_cvt_scalef32_pk_f32_fp4 v[4:5], v154, 1.0 op_sel:[0,1,0]
	v_cvt_scalef32_pk_f32_fp4 v[6:7], v154, 1.0 op_sel:[1,1,0]
	v_cvt_scalef32_pk_f32_fp4 v[8:9], v155, 1.0
	v_cvt_scalef32_pk_f32_fp4 v[10:11], v155, 1.0 op_sel:[1,0,0]
	v_cvt_scalef32_pk_f32_fp4 v[12:13], v155, 1.0 op_sel:[0,1,0]
	v_cvt_scalef32_pk_f32_fp4 v[14:15], v155, 1.0 op_sel:[1,1,0]
	v_pk_fma_f32 v[130:131], v[0:1], s[0:1], v[130:131] op_sel_hi:[1,0,1]
	v_pk_fma_f32 v[138:139], v[2:3], s[0:1], v[138:139] op_sel_hi:[1,0,1]
	v_pk_fma_f32 v[140:141], v[4:5], s[0:1], v[140:141] op_sel_hi:[1,0,1]
	v_pk_fma_f32 v[142:143], v[6:7], s[0:1], v[142:143] op_sel_hi:[1,0,1]
	v_pk_fma_f32 v[128:129], v[8:9], s[0:1], v[128:129] op_sel_hi:[1,0,1]
	v_pk_fma_f32 v[132:133], v[10:11], s[0:1], v[132:133] op_sel_hi:[1,0,1]
	v_pk_fma_f32 v[134:135], v[12:13], s[0:1], v[134:135] op_sel_hi:[1,0,1]
	v_pk_fma_f32 v[136:137], v[14:15], s[0:1], v[136:137] op_sel_hi:[1,0,1]
	v_readlane_b32 s0, v167, 54
	s_waitcnt vmcnt(9)
	v_cvt_scalef32_pk_f32_fp4 v[0:1], v156, 1.0
	v_cvt_scalef32_pk_f32_fp4 v[2:3], v156, 1.0 op_sel:[1,0,0]
	v_cvt_scalef32_pk_f32_fp4 v[4:5], v156, 1.0 op_sel:[0,1,0]
	v_cvt_scalef32_pk_f32_fp4 v[6:7], v156, 1.0 op_sel:[1,1,0]
	v_cvt_scalef32_pk_f32_fp4 v[8:9], v157, 1.0
	v_cvt_scalef32_pk_f32_fp4 v[10:11], v157, 1.0 op_sel:[1,0,0]
	v_cvt_scalef32_pk_f32_fp4 v[12:13], v157, 1.0 op_sel:[0,1,0]
	v_cvt_scalef32_pk_f32_fp4 v[14:15], v157, 1.0 op_sel:[1,1,0]
	v_pk_fma_f32 v[130:131], v[0:1], s[0:1], v[130:131] op_sel_hi:[1,0,1]
	v_pk_fma_f32 v[138:139], v[2:3], s[0:1], v[138:139] op_sel_hi:[1,0,1]
	v_pk_fma_f32 v[140:141], v[4:5], s[0:1], v[140:141] op_sel_hi:[1,0,1]
	v_pk_fma_f32 v[142:143], v[6:7], s[0:1], v[142:143] op_sel_hi:[1,0,1]
	v_pk_fma_f32 v[128:129], v[8:9], s[0:1], v[128:129] op_sel_hi:[1,0,1]
	v_pk_fma_f32 v[132:133], v[10:11], s[0:1], v[132:133] op_sel_hi:[1,0,1]
	v_pk_fma_f32 v[134:135], v[12:13], s[0:1], v[134:135] op_sel_hi:[1,0,1]
	v_pk_fma_f32 v[136:137], v[14:15], s[0:1], v[136:137] op_sel_hi:[1,0,1]
	v_readlane_b32 s0, v167, 55
	s_waitcnt vmcnt(8)
	v_cvt_scalef32_pk_f32_fp4 v[0:1], v158, 1.0
	v_cvt_scalef32_pk_f32_fp4 v[2:3], v158, 1.0 op_sel:[1,0,0]
	v_cvt_scalef32_pk_f32_fp4 v[4:5], v158, 1.0 op_sel:[0,1,0]
	v_cvt_scalef32_pk_f32_fp4 v[6:7], v158, 1.0 op_sel:[1,1,0]
	v_cvt_scalef32_pk_f32_fp4 v[8:9], v159, 1.0
	v_cvt_scalef32_pk_f32_fp4 v[10:11], v159, 1.0 op_sel:[1,0,0]
	v_cvt_scalef32_pk_f32_fp4 v[12:13], v159, 1.0 op_sel:[0,1,0]
	v_cvt_scalef32_pk_f32_fp4 v[14:15], v159, 1.0 op_sel:[1,1,0]
	v_pk_fma_f32 v[130:131], v[0:1], s[0:1], v[130:131] op_sel_hi:[1,0,1]
	v_pk_fma_f32 v[138:139], v[2:3], s[0:1], v[138:139] op_sel_hi:[1,0,1]
	v_pk_fma_f32 v[140:141], v[4:5], s[0:1], v[140:141] op_sel_hi:[1,0,1]
	v_pk_fma_f32 v[142:143], v[6:7], s[0:1], v[142:143] op_sel_hi:[1,0,1]
	v_pk_fma_f32 v[128:129], v[8:9], s[0:1], v[128:129] op_sel_hi:[1,0,1]
	v_pk_fma_f32 v[132:133], v[10:11], s[0:1], v[132:133] op_sel_hi:[1,0,1]
	v_pk_fma_f32 v[134:135], v[12:13], s[0:1], v[134:135] op_sel_hi:[1,0,1]
	v_pk_fma_f32 v[136:137], v[14:15], s[0:1], v[136:137] op_sel_hi:[1,0,1]
	v_readlane_b32 s0, v167, 56
	s_waitcnt vmcnt(7)
	v_cvt_scalef32_pk_f32_fp4 v[0:1], v168, 1.0
	v_cvt_scalef32_pk_f32_fp4 v[2:3], v168, 1.0 op_sel:[1,0,0]
	v_cvt_scalef32_pk_f32_fp4 v[4:5], v168, 1.0 op_sel:[0,1,0]
	v_cvt_scalef32_pk_f32_fp4 v[6:7], v168, 1.0 op_sel:[1,1,0]
	v_cvt_scalef32_pk_f32_fp4 v[8:9], v169, 1.0
	v_cvt_scalef32_pk_f32_fp4 v[10:11], v169, 1.0 op_sel:[1,0,0]
	v_cvt_scalef32_pk_f32_fp4 v[12:13], v169, 1.0 op_sel:[0,1,0]
	v_cvt_scalef32_pk_f32_fp4 v[14:15], v169, 1.0 op_sel:[1,1,0]
	v_pk_fma_f32 v[130:131], v[0:1], s[0:1], v[130:131] op_sel_hi:[1,0,1]
	v_pk_fma_f32 v[138:139], v[2:3], s[0:1], v[138:139] op_sel_hi:[1,0,1]
	v_pk_fma_f32 v[140:141], v[4:5], s[0:1], v[140:141] op_sel_hi:[1,0,1]
	v_pk_fma_f32 v[142:143], v[6:7], s[0:1], v[142:143] op_sel_hi:[1,0,1]
	v_pk_fma_f32 v[128:129], v[8:9], s[0:1], v[128:129] op_sel_hi:[1,0,1]
	v_pk_fma_f32 v[132:133], v[10:11], s[0:1], v[132:133] op_sel_hi:[1,0,1]
	v_pk_fma_f32 v[134:135], v[12:13], s[0:1], v[134:135] op_sel_hi:[1,0,1]
	v_pk_fma_f32 v[136:137], v[14:15], s[0:1], v[136:137] op_sel_hi:[1,0,1]
	v_readlane_b32 s0, v167, 57
	s_waitcnt vmcnt(6)
	v_cvt_scalef32_pk_f32_fp4 v[0:1], v170, 1.0
	v_cvt_scalef32_pk_f32_fp4 v[2:3], v170, 1.0 op_sel:[1,0,0]
	v_cvt_scalef32_pk_f32_fp4 v[4:5], v170, 1.0 op_sel:[0,1,0]
	v_cvt_scalef32_pk_f32_fp4 v[6:7], v170, 1.0 op_sel:[1,1,0]
	v_cvt_scalef32_pk_f32_fp4 v[8:9], v171, 1.0
	v_cvt_scalef32_pk_f32_fp4 v[10:11], v171, 1.0 op_sel:[1,0,0]
	v_cvt_scalef32_pk_f32_fp4 v[12:13], v171, 1.0 op_sel:[0,1,0]
	v_cvt_scalef32_pk_f32_fp4 v[14:15], v171, 1.0 op_sel:[1,1,0]
	v_pk_fma_f32 v[130:131], v[0:1], s[0:1], v[130:131] op_sel_hi:[1,0,1]
	v_pk_fma_f32 v[138:139], v[2:3], s[0:1], v[138:139] op_sel_hi:[1,0,1]
	v_pk_fma_f32 v[140:141], v[4:5], s[0:1], v[140:141] op_sel_hi:[1,0,1]
	v_pk_fma_f32 v[142:143], v[6:7], s[0:1], v[142:143] op_sel_hi:[1,0,1]
	v_pk_fma_f32 v[128:129], v[8:9], s[0:1], v[128:129] op_sel_hi:[1,0,1]
	v_pk_fma_f32 v[132:133], v[10:11], s[0:1], v[132:133] op_sel_hi:[1,0,1]
	v_pk_fma_f32 v[134:135], v[12:13], s[0:1], v[134:135] op_sel_hi:[1,0,1]
	v_pk_fma_f32 v[136:137], v[14:15], s[0:1], v[136:137] op_sel_hi:[1,0,1]
	v_readlane_b32 s0, v167, 58
	s_waitcnt vmcnt(5)
; __device__ void peer_gather_phase(const Params& P, int l, bool do_store) {
;     ...
; #pragma unroll
;       for (int j = 0; j < 8; ++j) {
;         const float a = __builtin_bit_cast(float, __builtin_amdgcn_readlane(__builtin_bit_cast(int, avec), kb + j));
;         const f32x2 aa = f32x2{a, a};
;         y[0] += aa * __builtin_amdgcn_cvt_scalef32_pk_f32_fp4(v8[j].x, 1.0f, 0); y[1] += aa * __builtin_amdgcn_cvt_scalef32_pk_f32_fp4(v8[j].x, 1.0f, 1);
;         y[2] += aa * __builtin_amdgcn_cvt_scalef32_pk_f32_fp4(v8[j].x, 1.0f, 2); y[3] += aa * __builtin_amdgcn_cvt_scalef32_pk_f32_fp4(v8[j].x, 1.0f, 3);
;         y[4] += aa * __builtin_amdgcn_cvt_scalef32_pk_f32_fp4(v8[j].y, 1.0f, 0); y[5] += aa * __builtin_amdgcn_cvt_scalef32_pk_f32_fp4(v8[j].y, 1.0f, 1);
;         y[6] += aa * __builtin_amdgcn_cvt_scalef32_pk_f32_fp4(v8[j].y, 1.0f, 2); y[7] += aa * __builtin_amdgcn_cvt_scalef32_pk_f32_fp4(v8[j].y, 1.0f, 3);
;       }
	v_cvt_scalef32_pk_f32_fp4 v[0:1], v172, 1.0
	v_cvt_scalef32_pk_f32_fp4 v[2:3], v172, 1.0 op_sel:[1,0,0]
	v_cvt_scalef32_pk_f32_fp4 v[4:5], v172, 1.0 op_sel:[0,1,0]
	v_cvt_scalef32_pk_f32_fp4 v[6:7], v172, 1.0 op_sel:[1,1,0]
	v_cvt_scalef32_pk_f32_fp4 v[8:9], v173, 1.0
	v_cvt_scalef32_pk_f32_fp4 v[10:11], v173, 1.0 op_sel:[1,0,0]
	v_cvt_scalef32_pk_f32_fp4 v[12:13], v173, 1.0 op_sel:[0,1,0]
	v_cvt_scalef32_pk_f32_fp4 v[14:15], v173, 1.0 op_sel:[1,1,0]
	v_pk_fma_f32 v[130:131], v[0:1], s[0:1], v[130:131] op_sel_hi:[1,0,1]
	v_pk_fma_f32 v[138:139], v[2:3], s[0:1], v[138:139] op_sel_hi:[1,0,1]
	v_pk_fma_f32 v[140:141], v[4:5], s[0:1], v[140:141] op_sel_hi:[1,0,1]
	v_pk_fma_f32 v[142:143], v[6:7], s[0:1], v[142:143] op_sel_hi:[1,0,1]
	v_pk_fma_f32 v[128:129], v[8:9], s[0:1], v[128:129] op_sel_hi:[1,0,1]
	v_pk_fma_f32 v[132:133], v[10:11], s[0:1], v[132:133] op_sel_hi:[1,0,1]
	v_pk_fma_f32 v[134:135], v[12:13], s[0:1], v[134:135] op_sel_hi:[1,0,1]
	v_pk_fma_f32 v[136:137], v[14:15], s[0:1], v[136:137] op_sel_hi:[1,0,1]
	v_readlane_b32 s0, v167, 59
	s_waitcnt vmcnt(4)
	v_cvt_scalef32_pk_f32_fp4 v[0:1], v174, 1.0
	v_cvt_scalef32_pk_f32_fp4 v[2:3], v174, 1.0 op_sel:[1,0,0]
	v_cvt_scalef32_pk_f32_fp4 v[4:5], v174, 1.0 op_sel:[0,1,0]
	v_cvt_scalef32_pk_f32_fp4 v[6:7], v174, 1.0 op_sel:[1,1,0]
	v_cvt_scalef32_pk_f32_fp4 v[8:9], v175, 1.0
	v_cvt_scalef32_pk_f32_fp4 v[10:11], v175, 1.0 op_sel:[1,0,0]
	v_cvt_scalef32_pk_f32_fp4 v[12:13], v175, 1.0 op_sel:[0,1,0]
	v_cvt_scalef32_pk_f32_fp4 v[14:15], v175, 1.0 op_sel:[1,1,0]
	v_pk_fma_f32 v[130:131], v[0:1], s[0:1], v[130:131] op_sel_hi:[1,0,1]
	v_pk_fma_f32 v[138:139], v[2:3], s[0:1], v[138:139] op_sel_hi:[1,0,1]
	v_pk_fma_f32 v[140:141], v[4:5], s[0:1], v[140:141] op_sel_hi:[1,0,1]
	v_pk_fma_f32 v[142:143], v[6:7], s[0:1], v[142:143] op_sel_hi:[1,0,1]
	v_pk_fma_f32 v[128:129], v[8:9], s[0:1], v[128:129] op_sel_hi:[1,0,1]
	v_pk_fma_f32 v[132:133], v[10:11], s[0:1], v[132:133] op_sel_hi:[1,0,1]
	v_pk_fma_f32 v[134:135], v[12:13], s[0:1], v[134:135] op_sel_hi:[1,0,1]
	v_pk_fma_f32 v[136:137], v[14:15], s[0:1], v[136:137] op_sel_hi:[1,0,1]
	v_readlane_b32 s0, v167, 60
	s_waitcnt vmcnt(3)
	v_cvt_scalef32_pk_f32_fp4 v[0:1], v180, 1.0
	v_cvt_scalef32_pk_f32_fp4 v[2:3], v180, 1.0 op_sel:[1,0,0]
	v_cvt_scalef32_pk_f32_fp4 v[4:5], v180, 1.0 op_sel:[0,1,0]
	v_cvt_scalef32_pk_f32_fp4 v[6:7], v180, 1.0 op_sel:[1,1,0]
	v_cvt_scalef32_pk_f32_fp4 v[8:9], v181, 1.0
	v_cvt_scalef32_pk_f32_fp4 v[10:11], v181, 1.0 op_sel:[1,0,0]
	v_cvt_scalef32_pk_f32_fp4 v[12:13], v181, 1.0 op_sel:[0,1,0]
	v_cvt_scalef32_pk_f32_fp4 v[14:15], v181, 1.0 op_sel:[1,1,0]
	v_pk_fma_f32 v[130:131], v[0:1], s[0:1], v[130:131] op_sel_hi:[1,0,1]
	v_pk_fma_f32 v[138:139], v[2:3], s[0:1], v[138:139] op_sel_hi:[1,0,1]
	v_pk_fma_f32 v[140:141], v[4:5], s[0:1], v[140:141] op_sel_hi:[1,0,1]
	v_pk_fma_f32 v[142:143], v[6:7], s[0:1], v[142:143] op_sel_hi:[1,0,1]
	v_pk_fma_f32 v[128:129], v[8:9], s[0:1], v[128:129] op_sel_hi:[1,0,1]
	v_pk_fma_f32 v[132:133], v[10:11], s[0:1], v[132:133] op_sel_hi:[1,0,1]
	v_pk_fma_f32 v[134:135], v[12:13], s[0:1], v[134:135] op_sel_hi:[1,0,1]
	v_pk_fma_f32 v[136:137], v[14:15], s[0:1], v[136:137] op_sel_hi:[1,0,1]
	v_readlane_b32 s0, v167, 61
	s_waitcnt vmcnt(2)
	v_cvt_scalef32_pk_f32_fp4 v[0:1], v182, 1.0
	v_cvt_scalef32_pk_f32_fp4 v[2:3], v182, 1.0 op_sel:[1,0,0]
	v_cvt_scalef32_pk_f32_fp4 v[4:5], v182, 1.0 op_sel:[0,1,0]
	v_cvt_scalef32_pk_f32_fp4 v[6:7], v182, 1.0 op_sel:[1,1,0]
	v_cvt_scalef32_pk_f32_fp4 v[8:9], v183, 1.0
	v_cvt_scalef32_pk_f32_fp4 v[10:11], v183, 1.0 op_sel:[1,0,0]
	v_cvt_scalef32_pk_f32_fp4 v[12:13], v183, 1.0 op_sel:[0,1,0]
	v_cvt_scalef32_pk_f32_fp4 v[14:15], v183, 1.0 op_sel:[1,1,0]
	v_pk_fma_f32 v[130:131], v[0:1], s[0:1], v[130:131] op_sel_hi:[1,0,1]
	v_pk_fma_f32 v[138:139], v[2:3], s[0:1], v[138:139] op_sel_hi:[1,0,1]
	v_pk_fma_f32 v[140:141], v[4:5], s[0:1], v[140:141] op_sel_hi:[1,0,1]
	v_pk_fma_f32 v[142:143], v[6:7], s[0:1], v[142:143] op_sel_hi:[1,0,1]
	v_pk_fma_f32 v[128:129], v[8:9], s[0:1], v[128:129] op_sel_hi:[1,0,1]
	v_pk_fma_f32 v[132:133], v[10:11], s[0:1], v[132:133] op_sel_hi:[1,0,1]
	v_pk_fma_f32 v[134:135], v[12:13], s[0:1], v[134:135] op_sel_hi:[1,0,1]
	v_pk_fma_f32 v[136:137], v[14:15], s[0:1], v[136:137] op_sel_hi:[1,0,1]
	v_readlane_b32 s0, v167, 62
	s_waitcnt vmcnt(1)
	v_cvt_scalef32_pk_f32_fp4 v[0:1], v184, 1.0
	v_cvt_scalef32_pk_f32_fp4 v[2:3], v184, 1.0 op_sel:[1,0,0]
	v_cvt_scalef32_pk_f32_fp4 v[4:5], v184, 1.0 op_sel:[0,1,0]
	v_cvt_scalef32_pk_f32_fp4 v[6:7], v184, 1.0 op_sel:[1,1,0]
	v_cvt_scalef32_pk_f32_fp4 v[8:9], v185, 1.0
	v_cvt_scalef32_pk_f32_fp4 v[10:11], v185, 1.0 op_sel:[1,0,0]
	v_cvt_scalef32_pk_f32_fp4 v[12:13], v185, 1.0 op_sel:[0,1,0]
	v_cvt_scalef32_pk_f32_fp4 v[14:15], v185, 1.0 op_sel:[1,1,0]
	v_pk_fma_f32 v[130:131], v[0:1], s[0:1], v[130:131] op_sel_hi:[1,0,1]
	v_pk_fma_f32 v[138:139], v[2:3], s[0:1], v[138:139] op_sel_hi:[1,0,1]
	v_pk_fma_f32 v[140:141], v[4:5], s[0:1], v[140:141] op_sel_hi:[1,0,1]
	v_pk_fma_f32 v[142:143], v[6:7], s[0:1], v[142:143] op_sel_hi:[1,0,1]
	v_pk_fma_f32 v[128:129], v[8:9], s[0:1], v[128:129] op_sel_hi:[1,0,1]
	v_pk_fma_f32 v[132:133], v[10:11], s[0:1], v[132:133] op_sel_hi:[1,0,1]
	v_pk_fma_f32 v[134:135], v[12:13], s[0:1], v[134:135] op_sel_hi:[1,0,1]
	v_pk_fma_f32 v[136:137], v[14:15], s[0:1], v[136:137] op_sel_hi:[1,0,1]
	v_readlane_b32 s0, v167, 63
	s_waitcnt vmcnt(0)
; __device__ void peer_gather_phase(const Params& P, int l, bool do_store) {
;     ...
;     float* xfp = P.out + (size_t)t * 1024 + lane * 16;
;     float pre[16];
; #pragma unroll
;     for (int k2 = 0; k2 < 8; ++k2) {
;       pre[2 * k2 + 0] = ALPHA_C * xf[k2].x + y[k2].x;
;       pre[2 * k2 + 1] = ALPHA_C * xf[k2].y + y[k2].y;
;     }
;     float sm = 0.f;
; #pragma unroll
;     for (int k = 0; k < 16; ++k) sm += pre[k];
;     const float mean = wave_sum(sm) * (1.f / 1024.f);
;     float vs = 0.f;
; #pragma unroll
;     for (int k = 0; k < 16; ++k) { const float dd = pre[k] - mean; vs += dd * dd; }
;     const float rstd = rsqrtf(wave_sum(vs) * (1.f / 1024.f) + EPS_C);
;     const float* g2 = P.ln2_g + l * 1024 + lane * 16;
;     const float* b2 = P.ln2_b + l * 1024 + lane * 16;
;     float o[16];
; #pragma unroll
;     for (int k4 = 0; k4 < 4; ++k4) {
;       const float4 gg = *(const float4*)(g2 + 4 * k4), bb = *(const float4*)(b2 + 4 * k4);
;       o[4 * k4 + 0] = (pre[4 * k4 + 0] - mean) * rstd * gg.x + bb.x; o[4 * k4 + 1] = (pre[4 * k4 + 1] - mean) * rstd * gg.y + bb.y;
;       o[4 * k4 + 2] = (pre[4 * k4 + 2] - mean) * rstd * gg.z + bb.z; o[4 * k4 + 3] = (pre[4 * k4 + 3] - mean) * rstd * gg.w + bb.w;
;       float4 ov; ov.x = o[4 * k4]; ov.y = o[4 * k4 + 1]; ov.z = o[4 * k4 + 2]; ov.w = o[4 * k4 + 3];
;       if (do_store && l == 1) *(float4*)(xfp + 4 * k4) = ov;
;     }
	v_cvt_scalef32_pk_f32_fp4 v[0:1], v186, 1.0
	v_cvt_scalef32_pk_f32_fp4 v[2:3], v186, 1.0 op_sel:[1,0,0]
	v_cvt_scalef32_pk_f32_fp4 v[4:5], v186, 1.0 op_sel:[0,1,0]
	v_cvt_scalef32_pk_f32_fp4 v[6:7], v186, 1.0 op_sel:[1,1,0]
	v_cvt_scalef32_pk_f32_fp4 v[8:9], v187, 1.0
	v_cvt_scalef32_pk_f32_fp4 v[10:11], v187, 1.0 op_sel:[1,0,0]
	v_cvt_scalef32_pk_f32_fp4 v[12:13], v187, 1.0 op_sel:[0,1,0]
	v_cvt_scalef32_pk_f32_fp4 v[14:15], v187, 1.0 op_sel:[1,1,0]
	v_pk_fma_f32 v[130:131], v[0:1], s[0:1], v[130:131] op_sel_hi:[1,0,1]
	v_pk_fma_f32 v[138:139], v[2:3], s[0:1], v[138:139] op_sel_hi:[1,0,1]
	v_pk_fma_f32 v[140:141], v[4:5], s[0:1], v[140:141] op_sel_hi:[1,0,1]
	v_pk_fma_f32 v[142:143], v[6:7], s[0:1], v[142:143] op_sel_hi:[1,0,1]
	v_pk_fma_f32 v[128:129], v[8:9], s[0:1], v[128:129] op_sel_hi:[1,0,1]
	v_pk_fma_f32 v[132:133], v[10:11], s[0:1], v[132:133] op_sel_hi:[1,0,1]
	v_pk_fma_f32 v[134:135], v[12:13], s[0:1], v[134:135] op_sel_hi:[1,0,1]
	v_pk_fma_f32 v[136:137], v[14:15], s[0:1], v[136:137] op_sel_hi:[1,0,1]
	v_lshlrev_b32_e32 v0, 16, v70
	v_lshlrev_b32_e32 v2, 16, v69
	v_and_b32_e32 v3, 0xffff0000, v69
	v_and_b32_e32 v1, 0xffff0000, v70
	s_mov_b32 s0, 0x3fb504f3
	v_pk_fma_f32 v[16:17], v[0:1], s[0:1], v[140:141] op_sel_hi:[1,0,1]
	v_pk_fma_f32 v[18:19], v[2:3], s[0:1], v[138:139] op_sel_hi:[1,0,1]
	global_load_dwordx4 v[0:3], v[82:83], off
	global_load_dwordx4 v[20:23], v[84:85], off
	global_load_dwordx4 v[44:47], v[82:83], off offset:16
	global_load_dwordx4 v[48:51], v[84:85], off offset:16
	global_load_dwordx4 v[52:55], v[82:83], off offset:32
	global_load_dwordx4 v[228:231], v[84:85], off offset:32
	global_load_dwordx4 v[232:235], v[82:83], off offset:48
	global_load_dwordx4 v[236:239], v[84:85], off offset:48
	v_lshlrev_b32_e32 v4, 16, v68
	v_and_b32_e32 v5, 0xffff0000, v68
	v_pk_fma_f32 v[4:5], v[4:5], s[0:1], v[130:131] op_sel_hi:[1,0,1]
	v_lshlrev_b32_e32 v10, 16, v71
	v_add_f32_e32 v24, 0, v4
	v_add_f32_e32 v24, v5, v24
	v_add_f32_e32 v24, v18, v24
	v_add_f32_e32 v24, v19, v24
	v_and_b32_e32 v11, 0xffff0000, v71
	v_add_f32_e32 v24, v16, v24
	v_pk_fma_f32 v[10:11], v[10:11], s[0:1], v[142:143] op_sel_hi:[1,0,1]
	v_add_f32_e32 v24, v17, v24
	v_lshlrev_b32_e32 v6, 16, v64
	v_lshlrev_b32_e32 v8, 16, v66
	v_lshlrev_b32_e32 v12, 16, v65
	v_lshlrev_b32_e32 v14, 16, v67
	v_and_b32_e32 v7, 0xffff0000, v64
	v_and_b32_e32 v13, 0xffff0000, v65
	v_and_b32_e32 v9, 0xffff0000, v66
	v_and_b32_e32 v15, 0xffff0000, v67
	v_add_f32_e32 v24, v10, v24
	v_add_f32_e32 v26, v11, v24
	v_pk_fma_f32 v[24:25], v[14:15], s[0:1], v[136:137] op_sel_hi:[1,0,1]
	v_pk_fma_f32 v[14:15], v[8:9], s[0:1], v[134:135] op_sel_hi:[1,0,1]
	v_pk_fma_f32 v[8:9], v[12:13], s[0:1], v[132:133] op_sel_hi:[1,0,1]
	v_pk_fma_f32 v[12:13], v[6:7], s[0:1], v[128:129] op_sel_hi:[1,0,1]
	v_mov_b32_e32 v7, v177
	v_add_f32_e32 v6, v12, v26
	v_add_f32_e32 v6, v13, v6
	v_add_f32_e32 v6, v8, v6
	v_add_f32_e32 v6, v9, v6
	v_add_f32_e32 v6, v14, v6
	v_add_f32_e32 v6, v15, v6
	v_add_f32_e32 v6, v24, v6
	v_add_f32_e32 v6, v25, v6
	s_nop 1
	v_add_f32_dpp v6, v6, v6 row_shr:1 row_mask:0xf bank_mask:0xf bound_ctrl:1
	s_nop 1
	v_add_f32_dpp v6, v6, v6 row_shr:2 row_mask:0xf bank_mask:0xf bound_ctrl:1
	s_nop 1
	v_add_f32_dpp v6, v6, v6 row_shr:4 row_mask:0xf bank_mask:0xf bound_ctrl:1
	s_nop 1
	v_add_f32_dpp v6, v6, v6 row_shr:8 row_mask:0xf bank_mask:0xf bound_ctrl:1
	s_nop 1
	v_mov_b32_dpp v7, v6 row_bcast:15 row_mask:0xa bank_mask:0xf
	v_add_f32_e32 v6, v6, v7
	v_mov_b32_e32 v7, v177
	s_nop 1
	v_mov_b32_dpp v7, v6 row_bcast:31 row_mask:0xc bank_mask:0xf
	v_add_f32_e32 v6, v6, v7
	s_nop 0
	v_readlane_b32 s0, v6, 63
	s_nop 1
	v_mul_f32_e32 v26, s0, v210
	v_pk_add_f32 v[28:29], v[4:5], v[26:27] op_sel_hi:[1,0] neg_lo:[0,1] neg_hi:[0,1]
	v_pk_add_f32 v[32:33], v[18:19], v[26:27] op_sel_hi:[1,0] neg_lo:[0,1] neg_hi:[0,1]
	v_pk_mul_f32 v[30:31], v[28:29], v[28:29]
	v_pk_mul_f32 v[18:19], v[32:33], v[32:33]
	v_pk_add_f32 v[4:5], v[16:17], v[26:27] op_sel_hi:[1,0] neg_lo:[0,1] neg_hi:[0,1]
	v_pk_add_f32 v[6:7], v[10:11], v[26:27] op_sel_hi:[1,0] neg_lo:[0,1] neg_hi:[0,1]
	v_pk_add_f32 v[10:11], v[12:13], v[26:27] op_sel_hi:[1,0] neg_lo:[0,1] neg_hi:[0,1]
	v_pk_add_f32 v[8:9], v[8:9], v[26:27] op_sel_hi:[1,0] neg_lo:[0,1] neg_hi:[0,1]
	v_pk_add_f32 v[14:15], v[14:15], v[26:27] op_sel_hi:[1,0] neg_lo:[0,1] neg_hi:[0,1]
	v_pk_add_f32 v[12:13], v[24:25], v[26:27] op_sel_hi:[1,0] neg_lo:[0,1] neg_hi:[0,1]
	v_add_f32_e32 v26, v30, v31
	v_add_f32_e32 v18, v18, v26
	v_pk_mul_f32 v[16:17], v[4:5], v[4:5]
	v_add_f32_e32 v18, v19, v18
	v_add_f32_e32 v16, v16, v18
	v_pk_mul_f32 v[34:35], v[6:7], v[6:7]
	v_add_f32_e32 v16, v17, v16
	v_add_f32_e32 v16, v34, v16
	v_pk_mul_f32 v[36:37], v[10:11], v[10:11]
	v_add_f32_e32 v16, v35, v16
	v_add_f32_e32 v16, v36, v16
	v_pk_mul_f32 v[38:39], v[8:9], v[8:9]
	v_add_f32_e32 v16, v37, v16
	v_add_f32_e32 v16, v38, v16
	v_pk_mul_f32 v[40:41], v[14:15], v[14:15]
	v_add_f32_e32 v16, v39, v16
	v_add_f32_e32 v16, v40, v16
	v_pk_mul_f32 v[24:25], v[12:13], v[12:13]
	v_add_f32_e32 v16, v41, v16
	v_add_f32_e32 v16, v24, v16
	v_add_f32_e32 v16, v25, v16
	v_mov_b32_e32 v17, v177
	s_nop 0
	v_add_f32_dpp v16, v16, v16 row_shr:1 row_mask:0xf bank_mask:0xf bound_ctrl:1
	s_nop 1
	v_add_f32_dpp v16, v16, v16 row_shr:2 row_mask:0xf bank_mask:0xf bound_ctrl:1
	s_nop 1
	v_add_f32_dpp v16, v16, v16 row_shr:4 row_mask:0xf bank_mask:0xf bound_ctrl:1
	s_nop 1
	v_add_f32_dpp v16, v16, v16 row_shr:8 row_mask:0xf bank_mask:0xf bound_ctrl:1
	s_nop 1
	v_mov_b32_dpp v17, v16 row_bcast:15 row_mask:0xa bank_mask:0xf
	v_add_f32_e32 v16, v16, v17
	v_mov_b32_e32 v17, v177
	s_nop 1
	v_mov_b32_dpp v17, v16 row_bcast:31 row_mask:0xc bank_mask:0xf
	v_add_f32_e32 v16, v16, v17
	s_nop 0
	v_readlane_b32 s0, v16, 63
	s_nop 1
	v_fma_f32 v16, s0, v210, v203
	s_mov_b32 s0, 0x800000
	v_mul_f32_e32 v17, 0x4b800000, v16
	v_cmp_gt_f32_e32 vcc, s0, v16
	s_nop 1
	v_cndmask_b32_e32 v16, v16, v17, vcc
	v_rsq_f32_e32 v18, v16
	v_lshl_add_u64 v[16:17], v[94:95], 2, v[80:81]
	v_mul_f32_e32 v19, 0x45800000, v18
	v_cndmask_b32_e32 v18, v18, v19, vcc
	v_pk_mul_f32 v[24:25], v[28:29], v[18:19] op_sel_hi:[1,0]
	s_and_b64 vcc, exec, s[38:39]
	s_waitcnt vmcnt(0)
	v_pk_fma_f32 v[0:1], v[0:1], v[24:25], v[20:21]
	v_pk_mul_f32 v[20:21], v[32:33], v[18:19] op_sel_hi:[1,0]
	s_nop 0
	v_pk_fma_f32 v[2:3], v[2:3], v[20:21], v[22:23]
	s_cbranch_vccz .LBB0_25
	global_store_dwordx4 v[16:17], v[0:3], off
; __device__ void peer_gather_phase(const Params& P, int l, bool do_store) {
;     ...
;     for (int k4 = 0; k4 < 4; ++k4) {
;       const float4 gg = *(const float4*)(g2 + 4 * k4), bb = *(const float4*)(b2 + 4 * k4);
;       o[4 * k4 + 0] = (pre[4 * k4 + 0] - mean) * rstd * gg.x + bb.x; o[4 * k4 + 1] = (pre[4 * k4 + 1] - mean) * rstd * gg.y + bb.y;
;       o[4 * k4 + 2] = (pre[4 * k4 + 2] - mean) * rstd * gg.z + bb.z; o[4 * k4 + 3] = (pre[4 * k4 + 3] - mean) * rstd * gg.w + bb.w;
;       float4 ov; ov.x = o[4 * k4]; ov.y = o[4 * k4 + 1]; ov.z = o[4 * k4 + 2]; ov.w = o[4 * k4 + 3];
;       if (do_store && l == 1) *(float4*)(xfp + 4 * k4) = ov;
;     }
.LBB0_25:
	v_mov_b32_e32 v19, v18
	v_pk_mul_f32 v[4:5], v[4:5], v[18:19]
	v_pk_mul_f32 v[6:7], v[6:7], v[18:19]
	s_andn2_b64 vcc, exec, s[38:39]
	s_movk_i32 s33, 0x300
	v_pk_fma_f32 v[4:5], v[4:5], v[44:45], v[48:49]
	v_cndmask_b32_e64 v20, 0, 1, s[38:39]
	v_pk_fma_f32 v[6:7], v[6:7], v[46:47], v[50:51]
	v_cmp_ne_u32_e64 s[0:1], 1, v20
	s_cbranch_vccnz .LBB0_27
	global_store_dwordx4 v[16:17], v[4:7], off offset:16
.LBB0_27:
	v_pk_mul_f32 v[10:11], v[10:11], v[18:19]
	v_pk_mul_f32 v[28:29], v[8:9], v[18:19]
	s_and_b64 vcc, exec, s[0:1]
	v_pk_fma_f32 v[8:9], v[10:11], v[52:53], v[228:229]
	v_pk_fma_f32 v[10:11], v[28:29], v[54:55], v[230:231]
	s_cbranch_vccnz .LBB0_29
	global_store_dwordx4 v[16:17], v[8:11], off offset:32
.LBB0_29:
	v_pk_mul_f32 v[14:15], v[14:15], v[18:19]
	v_pk_mul_f32 v[18:19], v[12:13], v[18:19]
	v_readlane_b32 s98, v249, 19
	s_and_b64 vcc, exec, s[0:1]
	s_movk_i32 s65, 0x2000
	v_readlane_b32 s99, v249, 20
	s_movk_i32 s67, 0x110
	v_pk_fma_f32 v[12:13], v[14:15], v[232:233], v[236:237]
	v_pk_fma_f32 v[14:15], v[18:19], v[234:235], v[238:239]
	s_cbranch_vccnz .LBB0_31
	global_store_dwordx4 v[16:17], v[12:15], off offset:48
